# v87 with the next-stage LDS-DMA of each K-step issued at the start of the second MFMA half instead of its middle (all 256x256 hand tiles)
# speedup vs baseline: 1.0067x; 1.0067x over previous
.Lt_mlp2b:
	v_add_u32_e32 v169, s32, v164
	v_mfma_f32_16x16x32_f16 v[4:7], v[132:135], v[184:187], v[4:7]
	ds_read_b128 v[238:241], v169 offset:4112
	v_mfma_f32_16x16x32_f16 v[8:11], v[136:139], v[184:187], v[8:11]
	ds_read_b128 v[242:245], v169 offset:5136
	v_mfma_f32_16x16x32_f16 v[12:15], v[140:143], v[184:187], v[12:15]
	ds_read_b128 v[246:249], v169 offset:6160
	v_mfma_f32_16x16x32_f16 v[16:19], v[144:147], v[184:187], v[16:19]
	ds_read_b128 v[250:253], v169 offset:7184
	v_mfma_f32_16x16x32_f16 v[20:23], v[132:135], v[188:191], v[20:23]
	v_mfma_f32_16x16x32_f16 v[24:27], v[136:139], v[188:191], v[24:27]
	v_mfma_f32_16x16x32_f16 v[28:31], v[140:143], v[188:191], v[28:31]
	v_mfma_f32_16x16x32_f16 v[32:35], v[144:147], v[188:191], v[32:35]
	v_mfma_f32_16x16x32_f16 v[36:39], v[132:135], v[192:195], v[36:39]
	v_mfma_f32_16x16x32_f16 v[40:43], v[136:139], v[192:195], v[40:43]
	v_mfma_f32_16x16x32_f16 v[44:47], v[140:143], v[192:195], v[44:47]
	v_mfma_f32_16x16x32_f16 v[48:51], v[144:147], v[192:195], v[48:51]
	v_mfma_f32_16x16x32_f16 v[52:55], v[132:135], v[196:199], v[52:55]
	v_mfma_f32_16x16x32_f16 v[56:59], v[136:139], v[196:199], v[56:59]
	v_mfma_f32_16x16x32_f16 v[60:63], v[140:143], v[196:199], v[60:63]
	v_mfma_f32_16x16x32_f16 v[64:67], v[144:147], v[196:199], v[64:67]
	s_waitcnt vmcnt(8) lgkmcnt(0)
	s_barrier
	s_add_i32 s34, s32, 0x8000
	s_cmp_lg_u32 s32, 0x18000
	s_cselect_b32 s34, s34, 0
	v_add_u32_e32 v168, s34, v165
	v_add_u32_e32 v169, s34, v164
	s_add_u32 vcc_lo, s31, s32
	v_mfma_f32_16x16x32_f16 v[68:71], v[132:135], v[238:241], v[68:71]
	ds_read_b128 v[148:151], v168 offset:16
	ds_read_b128 v[184:187], v169 offset:16
	s_mov_b32 m0, vcc_lo
	s_nop 0
	global_load_lds_dwordx4 v170, s[36:37]
	v_mfma_f32_16x16x32_f16 v[72:75], v[136:139], v[238:241], v[72:75]
	ds_read_b128 v[152:155], v168 offset:1040
	ds_read_b128 v[188:191], v169 offset:1040
	s_add_u32 m0, vcc_lo, 0x400
	s_nop 0
	global_load_lds_dwordx4 v171, s[36:37]
	v_mfma_f32_16x16x32_f16 v[76:79], v[140:143], v[238:241], v[76:79]
	ds_read_b128 v[156:159], v168 offset:2064
	ds_read_b128 v[192:195], v169 offset:2064
	s_add_u32 m0, vcc_lo, 0x4000
	s_nop 0
	global_load_lds_dwordx4 v170, s[52:53]
	v_mfma_f32_16x16x32_f16 v[80:83], v[144:147], v[238:241], v[80:83]
	ds_read_b128 v[160:163], v168 offset:3088
	ds_read_b128 v[196:199], v169 offset:3088
	s_add_u32 m0, vcc_lo, 0x4400
	s_nop 0
	global_load_lds_dwordx4 v171, s[52:53]
	v_mfma_f32_16x16x32_f16 v[84:87], v[132:135], v[242:245], v[84:87]
	v_mfma_f32_16x16x32_f16 v[88:91], v[136:139], v[242:245], v[88:91]
	v_mfma_f32_16x16x32_f16 v[92:95], v[140:143], v[242:245], v[92:95]
	v_mfma_f32_16x16x32_f16 v[96:99], v[144:147], v[242:245], v[96:99]
	v_mfma_f32_16x16x32_f16 v[100:103], v[132:135], v[246:249], v[100:103]
	v_mfma_f32_16x16x32_f16 v[104:107], v[136:139], v[246:249], v[104:107]
	v_mfma_f32_16x16x32_f16 v[108:111], v[140:143], v[246:249], v[108:111]
	v_mfma_f32_16x16x32_f16 v[112:115], v[144:147], v[246:249], v[112:115]
	v_mfma_f32_16x16x32_f16 v[116:119], v[132:135], v[250:253], v[116:119]
	v_mfma_f32_16x16x32_f16 v[120:123], v[136:139], v[250:253], v[120:123]
	v_mfma_f32_16x16x32_f16 v[124:127], v[140:143], v[250:253], v[124:127]
	v_mfma_f32_16x16x32_f16 v[128:131], v[144:147], v[250:253], v[128:131]
	s_waitcnt lgkmcnt(0)
	s_mov_b32 s32, s34
	s_add_u32 s36, s36, 64
	s_addc_u32 s37, s37, 0
	s_add_u32 s52, s52, 64
	s_addc_u32 s53, s53, 0
	v_add_u32_e32 v169, s32, v164
	v_mfma_f32_16x16x32_f16 v[4:7], v[148:151], v[184:187], v[4:7]
	ds_read_b128 v[238:241], v169 offset:4112
	v_mfma_f32_16x16x32_f16 v[8:11], v[152:155], v[184:187], v[8:11]
	ds_read_b128 v[242:245], v169 offset:5136
	v_mfma_f32_16x16x32_f16 v[12:15], v[156:159], v[184:187], v[12:15]
	ds_read_b128 v[246:249], v169 offset:6160
	v_mfma_f32_16x16x32_f16 v[16:19], v[160:163], v[184:187], v[16:19]
	ds_read_b128 v[250:253], v169 offset:7184
	v_mfma_f32_16x16x32_f16 v[20:23], v[148:151], v[188:191], v[20:23]
	v_mfma_f32_16x16x32_f16 v[24:27], v[152:155], v[188:191], v[24:27]
	v_mfma_f32_16x16x32_f16 v[28:31], v[156:159], v[188:191], v[28:31]
	v_mfma_f32_16x16x32_f16 v[32:35], v[160:163], v[188:191], v[32:35]
	v_mfma_f32_16x16x32_f16 v[36:39], v[148:151], v[192:195], v[36:39]
	v_mfma_f32_16x16x32_f16 v[40:43], v[152:155], v[192:195], v[40:43]
	v_mfma_f32_16x16x32_f16 v[44:47], v[156:159], v[192:195], v[44:47]
	v_mfma_f32_16x16x32_f16 v[48:51], v[160:163], v[192:195], v[48:51]
	v_mfma_f32_16x16x32_f16 v[52:55], v[148:151], v[196:199], v[52:55]
	v_mfma_f32_16x16x32_f16 v[56:59], v[152:155], v[196:199], v[56:59]
	v_mfma_f32_16x16x32_f16 v[60:63], v[156:159], v[196:199], v[60:63]
	v_mfma_f32_16x16x32_f16 v[64:67], v[160:163], v[196:199], v[64:67]
	s_waitcnt vmcnt(8) lgkmcnt(0)
	s_barrier
	s_add_i32 s34, s32, 0x8000
	s_cmp_lg_u32 s32, 0x18000
	s_cselect_b32 s34, s34, 0
	v_add_u32_e32 v168, s34, v165
	v_add_u32_e32 v169, s34, v164
	s_add_u32 vcc_lo, s31, s32
	v_mfma_f32_16x16x32_f16 v[68:71], v[148:151], v[238:241], v[68:71]
	ds_read_b128 v[132:135], v168 offset:16
	ds_read_b128 v[184:187], v169 offset:16
	s_mov_b32 m0, vcc_lo
	s_nop 0
	global_load_lds_dwordx4 v170, s[36:37]
	v_mfma_f32_16x16x32_f16 v[72:75], v[152:155], v[238:241], v[72:75]
	ds_read_b128 v[136:139], v168 offset:1040
	ds_read_b128 v[188:191], v169 offset:1040
	s_add_u32 m0, vcc_lo, 0x400
	s_nop 0
	global_load_lds_dwordx4 v171, s[36:37]
	v_mfma_f32_16x16x32_f16 v[76:79], v[156:159], v[238:241], v[76:79]
	ds_read_b128 v[140:143], v168 offset:2064
	ds_read_b128 v[192:195], v169 offset:2064
	s_add_u32 m0, vcc_lo, 0x4000
	s_nop 0
	global_load_lds_dwordx4 v170, s[52:53]
	v_mfma_f32_16x16x32_f16 v[80:83], v[160:163], v[238:241], v[80:83]
	ds_read_b128 v[144:147], v168 offset:3088
	ds_read_b128 v[196:199], v169 offset:3088
	s_add_u32 m0, vcc_lo, 0x4400
	s_nop 0
	global_load_lds_dwordx4 v171, s[52:53]
	v_mfma_f32_16x16x32_f16 v[84:87], v[148:151], v[242:245], v[84:87]
	v_mfma_f32_16x16x32_f16 v[88:91], v[152:155], v[242:245], v[88:91]
	v_mfma_f32_16x16x32_f16 v[92:95], v[156:159], v[242:245], v[92:95]
	v_mfma_f32_16x16x32_f16 v[96:99], v[160:163], v[242:245], v[96:99]
	v_mfma_f32_16x16x32_f16 v[100:103], v[148:151], v[246:249], v[100:103]
	v_mfma_f32_16x16x32_f16 v[104:107], v[152:155], v[246:249], v[104:107]
	v_mfma_f32_16x16x32_f16 v[108:111], v[156:159], v[246:249], v[108:111]
	v_mfma_f32_16x16x32_f16 v[112:115], v[160:163], v[246:249], v[112:115]
	v_mfma_f32_16x16x32_f16 v[116:119], v[148:151], v[250:253], v[116:119]
	v_mfma_f32_16x16x32_f16 v[120:123], v[152:155], v[250:253], v[120:123]
	v_mfma_f32_16x16x32_f16 v[124:127], v[156:159], v[250:253], v[124:127]
	v_mfma_f32_16x16x32_f16 v[128:131], v[160:163], v[250:253], v[128:131]
	s_waitcnt lgkmcnt(0)
	s_mov_b32 s32, s34
	s_add_u32 s36, s36, 64
	s_addc_u32 s37, s37, 0
	s_add_u32 s52, s52, 64
	s_addc_u32 s53, s53, 0
	s_add_i32 s65, s65, 2
	s_cmp_lt_u32 s65, 124
	s_cbranch_scc1 .Lt_mlp2b
	v_add_u32_e32 v169, s32, v164
	v_mfma_f32_16x16x32_f16 v[4:7], v[132:135], v[184:187], v[4:7]
	ds_read_b128 v[238:241], v169 offset:4112
	v_mfma_f32_16x16x32_f16 v[8:11], v[136:139], v[184:187], v[8:11]
	ds_read_b128 v[242:245], v169 offset:5136
	v_mfma_f32_16x16x32_f16 v[12:15], v[140:143], v[184:187], v[12:15]
	ds_read_b128 v[246:249], v169 offset:6160
	v_mfma_f32_16x16x32_f16 v[16:19], v[144:147], v[184:187], v[16:19]
	ds_read_b128 v[250:253], v169 offset:7184
	v_mfma_f32_16x16x32_f16 v[20:23], v[132:135], v[188:191], v[20:23]
	v_mfma_f32_16x16x32_f16 v[24:27], v[136:139], v[188:191], v[24:27]
	v_mfma_f32_16x16x32_f16 v[28:31], v[140:143], v[188:191], v[28:31]
	v_mfma_f32_16x16x32_f16 v[32:35], v[144:147], v[188:191], v[32:35]
	v_mfma_f32_16x16x32_f16 v[36:39], v[132:135], v[192:195], v[36:39]
	v_mfma_f32_16x16x32_f16 v[40:43], v[136:139], v[192:195], v[40:43]
	v_mfma_f32_16x16x32_f16 v[44:47], v[140:143], v[192:195], v[44:47]
	v_mfma_f32_16x16x32_f16 v[48:51], v[144:147], v[192:195], v[48:51]
	v_mfma_f32_16x16x32_f16 v[52:55], v[132:135], v[196:199], v[52:55]
	v_mfma_f32_16x16x32_f16 v[56:59], v[136:139], v[196:199], v[56:59]
	v_mfma_f32_16x16x32_f16 v[60:63], v[140:143], v[196:199], v[60:63]
	v_mfma_f32_16x16x32_f16 v[64:67], v[144:147], v[196:199], v[64:67]
	s_waitcnt vmcnt(8) lgkmcnt(0)
	s_barrier
	s_add_i32 s34, s32, 0x8000
	s_cmp_lg_u32 s32, 0x18000
	s_cselect_b32 s34, s34, 0
	v_add_u32_e32 v168, s34, v165
	v_add_u32_e32 v169, s34, v164
	v_mfma_f32_16x16x32_f16 v[68:71], v[132:135], v[238:241], v[68:71]
	ds_read_b128 v[148:151], v168 offset:16
	ds_read_b128 v[184:187], v169 offset:16
	v_mfma_f32_16x16x32_f16 v[72:75], v[136:139], v[238:241], v[72:75]
	ds_read_b128 v[152:155], v168 offset:1040
	ds_read_b128 v[188:191], v169 offset:1040
	v_mfma_f32_16x16x32_f16 v[76:79], v[140:143], v[238:241], v[76:79]
	ds_read_b128 v[156:159], v168 offset:2064
	ds_read_b128 v[192:195], v169 offset:2064
	v_mfma_f32_16x16x32_f16 v[80:83], v[144:147], v[238:241], v[80:83]
	ds_read_b128 v[160:163], v168 offset:3088
	ds_read_b128 v[196:199], v169 offset:3088
	v_mfma_f32_16x16x32_f16 v[84:87], v[132:135], v[242:245], v[84:87]
	v_mfma_f32_16x16x32_f16 v[88:91], v[136:139], v[242:245], v[88:91]
	v_mfma_f32_16x16x32_f16 v[92:95], v[140:143], v[242:245], v[92:95]
	v_mfma_f32_16x16x32_f16 v[96:99], v[144:147], v[242:245], v[96:99]
	v_mfma_f32_16x16x32_f16 v[100:103], v[132:135], v[246:249], v[100:103]
	v_mfma_f32_16x16x32_f16 v[104:107], v[136:139], v[246:249], v[104:107]
	v_mfma_f32_16x16x32_f16 v[108:111], v[140:143], v[246:249], v[108:111]
	v_mfma_f32_16x16x32_f16 v[112:115], v[144:147], v[246:249], v[112:115]
	v_mfma_f32_16x16x32_f16 v[116:119], v[132:135], v[250:253], v[116:119]
	v_mfma_f32_16x16x32_f16 v[120:123], v[136:139], v[250:253], v[120:123]
	v_mfma_f32_16x16x32_f16 v[124:127], v[140:143], v[250:253], v[124:127]
	v_mfma_f32_16x16x32_f16 v[128:131], v[144:147], v[250:253], v[128:131]
	s_waitcnt lgkmcnt(0)
	s_mov_b32 s32, s34
	v_add_u32_e32 v169, s32, v164
	v_mfma_f32_16x16x32_f16 v[4:7], v[148:151], v[184:187], v[4:7]
	ds_read_b128 v[238:241], v169 offset:4112
	v_mfma_f32_16x16x32_f16 v[8:11], v[152:155], v[184:187], v[8:11]
	ds_read_b128 v[242:245], v169 offset:5136
	v_mfma_f32_16x16x32_f16 v[12:15], v[156:159], v[184:187], v[12:15]
	ds_read_b128 v[246:249], v169 offset:6160
	v_mfma_f32_16x16x32_f16 v[16:19], v[160:163], v[184:187], v[16:19]
	ds_read_b128 v[250:253], v169 offset:7184
	v_mfma_f32_16x16x32_f16 v[20:23], v[148:151], v[188:191], v[20:23]
	v_mfma_f32_16x16x32_f16 v[24:27], v[152:155], v[188:191], v[24:27]
	v_mfma_f32_16x16x32_f16 v[28:31], v[156:159], v[188:191], v[28:31]
	v_mfma_f32_16x16x32_f16 v[32:35], v[160:163], v[188:191], v[32:35]
	v_mfma_f32_16x16x32_f16 v[36:39], v[148:151], v[192:195], v[36:39]
	v_mfma_f32_16x16x32_f16 v[40:43], v[152:155], v[192:195], v[40:43]
	v_mfma_f32_16x16x32_f16 v[44:47], v[156:159], v[192:195], v[44:47]
	v_mfma_f32_16x16x32_f16 v[48:51], v[160:163], v[192:195], v[48:51]
	v_mfma_f32_16x16x32_f16 v[52:55], v[148:151], v[196:199], v[52:55]
	v_mfma_f32_16x16x32_f16 v[56:59], v[152:155], v[196:199], v[56:59]
	v_mfma_f32_16x16x32_f16 v[60:63], v[156:159], v[196:199], v[60:63]
	v_mfma_f32_16x16x32_f16 v[64:67], v[160:163], v[196:199], v[64:67]
	s_waitcnt vmcnt(4) lgkmcnt(0)
	s_barrier
	s_add_i32 s34, s32, 0x8000
	s_cmp_lg_u32 s32, 0x18000
	s_cselect_b32 s34, s34, 0
	v_add_u32_e32 v168, s34, v165
	v_add_u32_e32 v169, s34, v164
	v_mfma_f32_16x16x32_f16 v[68:71], v[148:151], v[238:241], v[68:71]
	ds_read_b128 v[132:135], v168 offset:16
	ds_read_b128 v[184:187], v169 offset:16
	v_mfma_f32_16x16x32_f16 v[72:75], v[152:155], v[238:241], v[72:75]
	ds_read_b128 v[136:139], v168 offset:1040
	ds_read_b128 v[188:191], v169 offset:1040
	v_mfma_f32_16x16x32_f16 v[76:79], v[156:159], v[238:241], v[76:79]
	ds_read_b128 v[140:143], v168 offset:2064
	ds_read_b128 v[192:195], v169 offset:2064
	v_mfma_f32_16x16x32_f16 v[80:83], v[160:163], v[238:241], v[80:83]
	ds_read_b128 v[144:147], v168 offset:3088
	ds_read_b128 v[196:199], v169 offset:3088
	v_mfma_f32_16x16x32_f16 v[84:87], v[148:151], v[242:245], v[84:87]
	v_mfma_f32_16x16x32_f16 v[88:91], v[152:155], v[242:245], v[88:91]
	v_mfma_f32_16x16x32_f16 v[92:95], v[156:159], v[242:245], v[92:95]
	v_mfma_f32_16x16x32_f16 v[96:99], v[160:163], v[242:245], v[96:99]
	v_mfma_f32_16x16x32_f16 v[100:103], v[148:151], v[246:249], v[100:103]
	v_mfma_f32_16x16x32_f16 v[104:107], v[152:155], v[246:249], v[104:107]
	v_mfma_f32_16x16x32_f16 v[108:111], v[156:159], v[246:249], v[108:111]
	v_mfma_f32_16x16x32_f16 v[112:115], v[160:163], v[246:249], v[112:115]
	v_mfma_f32_16x16x32_f16 v[116:119], v[148:151], v[250:253], v[116:119]
	v_mfma_f32_16x16x32_f16 v[120:123], v[152:155], v[250:253], v[120:123]
	v_mfma_f32_16x16x32_f16 v[124:127], v[156:159], v[250:253], v[124:127]
	v_mfma_f32_16x16x32_f16 v[128:131], v[160:163], v[250:253], v[128:131]
	s_waitcnt lgkmcnt(0)
	s_mov_b32 s32, s34
	v_add_u32_e32 v169, s32, v164
	v_mfma_f32_16x16x32_f16 v[4:7], v[132:135], v[184:187], v[4:7]
	ds_read_b128 v[238:241], v169 offset:4112
	v_mfma_f32_16x16x32_f16 v[8:11], v[136:139], v[184:187], v[8:11]
	ds_read_b128 v[242:245], v169 offset:5136
	v_mfma_f32_16x16x32_f16 v[12:15], v[140:143], v[184:187], v[12:15]
	ds_read_b128 v[246:249], v169 offset:6160
	v_mfma_f32_16x16x32_f16 v[16:19], v[144:147], v[184:187], v[16:19]
	ds_read_b128 v[250:253], v169 offset:7184
	v_mfma_f32_16x16x32_f16 v[20:23], v[132:135], v[188:191], v[20:23]
	v_mfma_f32_16x16x32_f16 v[24:27], v[136:139], v[188:191], v[24:27]
	v_mfma_f32_16x16x32_f16 v[28:31], v[140:143], v[188:191], v[28:31]
	v_mfma_f32_16x16x32_f16 v[32:35], v[144:147], v[188:191], v[32:35]
	v_mfma_f32_16x16x32_f16 v[36:39], v[132:135], v[192:195], v[36:39]
	v_mfma_f32_16x16x32_f16 v[40:43], v[136:139], v[192:195], v[40:43]
	v_mfma_f32_16x16x32_f16 v[44:47], v[140:143], v[192:195], v[44:47]
	v_mfma_f32_16x16x32_f16 v[48:51], v[144:147], v[192:195], v[48:51]
	v_mfma_f32_16x16x32_f16 v[52:55], v[132:135], v[196:199], v[52:55]
	v_mfma_f32_16x16x32_f16 v[56:59], v[136:139], v[196:199], v[56:59]
	v_mfma_f32_16x16x32_f16 v[60:63], v[140:143], v[196:199], v[60:63]
	v_mfma_f32_16x16x32_f16 v[64:67], v[144:147], v[196:199], v[64:67]
	s_waitcnt vmcnt(0) lgkmcnt(0)
	s_barrier
	s_add_i32 s34, s32, 0x8000
	s_cmp_lg_u32 s32, 0x18000
	s_cselect_b32 s34, s34, 0
	v_add_u32_e32 v168, s34, v165
	v_add_u32_e32 v169, s34, v164
	v_mfma_f32_16x16x32_f16 v[68:71], v[132:135], v[238:241], v[68:71]
	ds_read_b128 v[148:151], v168 offset:16
	ds_read_b128 v[184:187], v169 offset:16
	v_mfma_f32_16x16x32_f16 v[72:75], v[136:139], v[238:241], v[72:75]
	ds_read_b128 v[152:155], v168 offset:1040
	ds_read_b128 v[188:191], v169 offset:1040
	v_mfma_f32_16x16x32_f16 v[76:79], v[140:143], v[238:241], v[76:79]
	ds_read_b128 v[156:159], v168 offset:2064
	ds_read_b128 v[192:195], v169 offset:2064
	v_mfma_f32_16x16x32_f16 v[80:83], v[144:147], v[238:241], v[80:83]
	ds_read_b128 v[160:163], v168 offset:3088
	ds_read_b128 v[196:199], v169 offset:3088
	v_mfma_f32_16x16x32_f16 v[84:87], v[132:135], v[242:245], v[84:87]
	v_mfma_f32_16x16x32_f16 v[88:91], v[136:139], v[242:245], v[88:91]
	v_mfma_f32_16x16x32_f16 v[92:95], v[140:143], v[242:245], v[92:95]
	v_mfma_f32_16x16x32_f16 v[96:99], v[144:147], v[242:245], v[96:99]
	v_mfma_f32_16x16x32_f16 v[100:103], v[132:135], v[246:249], v[100:103]
	v_mfma_f32_16x16x32_f16 v[104:107], v[136:139], v[246:249], v[104:107]
	v_mfma_f32_16x16x32_f16 v[108:111], v[140:143], v[246:249], v[108:111]
	v_mfma_f32_16x16x32_f16 v[112:115], v[144:147], v[246:249], v[112:115]
	v_mfma_f32_16x16x32_f16 v[116:119], v[132:135], v[250:253], v[116:119]
	v_mfma_f32_16x16x32_f16 v[120:123], v[136:139], v[250:253], v[120:123]
	v_mfma_f32_16x16x32_f16 v[124:127], v[140:143], v[250:253], v[124:127]
	v_mfma_f32_16x16x32_f16 v[128:131], v[144:147], v[250:253], v[128:131]
	s_waitcnt lgkmcnt(0)
	s_mov_b32 s32, s34
	v_add_u32_e32 v169, s32, v164
	v_mfma_f32_16x16x32_f16 v[4:7], v[148:151], v[184:187], v[4:7]
	ds_read_b128 v[238:241], v169 offset:4112
	v_mfma_f32_16x16x32_f16 v[8:11], v[152:155], v[184:187], v[8:11]
	ds_read_b128 v[242:245], v169 offset:5136
	v_mfma_f32_16x16x32_f16 v[12:15], v[156:159], v[184:187], v[12:15]
	ds_read_b128 v[246:249], v169 offset:6160
	v_mfma_f32_16x16x32_f16 v[16:19], v[160:163], v[184:187], v[16:19]
	ds_read_b128 v[250:253], v169 offset:7184
	v_mfma_f32_16x16x32_f16 v[20:23], v[148:151], v[188:191], v[20:23]
	v_mfma_f32_16x16x32_f16 v[24:27], v[152:155], v[188:191], v[24:27]
	v_mfma_f32_16x16x32_f16 v[28:31], v[156:159], v[188:191], v[28:31]
	v_mfma_f32_16x16x32_f16 v[32:35], v[160:163], v[188:191], v[32:35]
	v_mfma_f32_16x16x32_f16 v[36:39], v[148:151], v[192:195], v[36:39]
	v_mfma_f32_16x16x32_f16 v[40:43], v[152:155], v[192:195], v[40:43]
	v_mfma_f32_16x16x32_f16 v[44:47], v[156:159], v[192:195], v[44:47]
	v_mfma_f32_16x16x32_f16 v[48:51], v[160:163], v[192:195], v[48:51]
	v_mfma_f32_16x16x32_f16 v[52:55], v[148:151], v[196:199], v[52:55]
	v_mfma_f32_16x16x32_f16 v[56:59], v[152:155], v[196:199], v[56:59]
	v_mfma_f32_16x16x32_f16 v[60:63], v[156:159], v[196:199], v[60:63]
	v_mfma_f32_16x16x32_f16 v[64:67], v[160:163], v[196:199], v[64:67]
	s_waitcnt lgkmcnt(0)
	s_barrier
	v_mfma_f32_16x16x32_f16 v[68:71], v[148:151], v[238:241], v[68:71]
	v_mfma_f32_16x16x32_f16 v[72:75], v[152:155], v[238:241], v[72:75]
	v_mfma_f32_16x16x32_f16 v[76:79], v[156:159], v[238:241], v[76:79]
	v_mfma_f32_16x16x32_f16 v[80:83], v[160:163], v[238:241], v[80:83]
	v_mfma_f32_16x16x32_f16 v[84:87], v[148:151], v[242:245], v[84:87]
	v_mfma_f32_16x16x32_f16 v[88:91], v[152:155], v[242:245], v[88:91]
	v_mfma_f32_16x16x32_f16 v[92:95], v[156:159], v[242:245], v[92:95]
	v_mfma_f32_16x16x32_f16 v[96:99], v[160:163], v[242:245], v[96:99]
	v_mfma_f32_16x16x32_f16 v[100:103], v[148:151], v[246:249], v[100:103]
	v_mfma_f32_16x16x32_f16 v[104:107], v[152:155], v[246:249], v[104:107]
	v_mfma_f32_16x16x32_f16 v[108:111], v[156:159], v[246:249], v[108:111]
	v_mfma_f32_16x16x32_f16 v[112:115], v[160:163], v[246:249], v[112:115]
	v_mfma_f32_16x16x32_f16 v[116:119], v[148:151], v[250:253], v[116:119]
	v_mfma_f32_16x16x32_f16 v[120:123], v[152:155], v[250:253], v[120:123]
	v_mfma_f32_16x16x32_f16 v[124:127], v[156:159], v[250:253], v[124:127]
	v_mfma_f32_16x16x32_f16 v[128:131], v[160:163], v[250:253], v[128:131]
	s_sub_u32 s77, s35, 0x1000
	s_lshr_b32 s77, s77, 12
	s_add_u32 s77, s77, 1
	s_cmp_lt_u32 s35, 0x1000
	s_cselect_b32 s77, 0, s77
	s_mul_i32 s77, s77, 0x6000
	s_add_u32 s68, s46, s77
	s_addc_u32 s69, s47, 0
	s_add_u32 s68, s68, 0xfa2e600
	s_addc_u32 s69, s69, 0
	s_lshl_b32 s82, s35, 11
	s_add_u32 s80, s48, s82
	s_addc_u32 s81, s49, 0
	s_lshl_b32 s82, s30, 1
	s_add_u32 s80, s80, s82
	s_addc_u32 s81, s81, 0
	v_and_b32_e32 v172, 15, v200
	v_bfe_u32 v173, v200, 4, 2
	v_bfe_u32 v174, v200, 6, 2
	v_bfe_u32 v175, v200, 8, 1
	v_lshlrev_b32_e32 v176, 6, v174
	v_lshl_or_b32 v176, v173, 2, v176
	v_lshl_or_b32 v175, v175, 7, v172
	v_lshlrev_b32_e32 v175, 11, v175
	v_lshl_add_u32 v177, v176, 1, v175
	v_add_u32_e32 v176, s30, v176
	v_lshlrev_b32_e32 v176, 2, v176
	global_load_dwordx4 v[132:135], v176, s[68:69]
	global_load_dwordx4 v[136:139], v176, s[68:69] offset:64
	global_load_dwordx4 v[140:143], v176, s[68:69] offset:128
	global_load_dwordx4 v[144:147], v176, s[68:69] offset:192
	v_and_b32_e32 v172, 1, v173
	v_mul_u32_u24_e32 v172, 24, v172
	v_add_u32_e32 v177, v177, v172
	v_mov_b32_e32 v178, v177
	global_load_dwordx4 v[184:187], v178, s[80:81]
	global_load_dwordx4 v[188:191], v178, s[80:81] offset:64
	v_add_u32_e32 v178, 0x8000, v178
	global_load_dwordx4 v[238:241], v178, s[80:81]
	global_load_dwordx4 v[242:245], v178, s[80:81] offset:64
	s_waitcnt vmcnt(3)
	v_permlane16_swap_b32_e32 v184, v186
	v_permlane16_swap_b32_e32 v185, v187
	v_cvt_f32_f16_e32 v164, v184
	v_cvt_f32_f16_sdwa v165, v184 dst_sel:DWORD dst_unused:UNUSED_PAD src0_sel:WORD_1
	v_cvt_f32_f16_e32 v166, v185
	v_cvt_f32_f16_sdwa v167, v185 dst_sel:DWORD dst_unused:UNUSED_PAD src0_sel:WORD_1
	v_pk_mul_f32 v[164:165], v[164:165], s[84:85] op_sel_hi:[1,0]
	v_pk_mul_f32 v[166:167], v[166:167], s[84:85] op_sel_hi:[1,0]
	v_pk_fma_f32 v[4:5], v[4:5], v[132:133], v[164:165]
	v_pk_fma_f32 v[6:7], v[6:7], v[134:135], v[166:167]
	v_cvt_pk_f16_f32 v172, v4, v5
	v_cvt_pk_f16_f32 v173, v6, v7
	v_cvt_f32_f16_e32 v164, v186
	v_cvt_f32_f16_sdwa v165, v186 dst_sel:DWORD dst_unused:UNUSED_PAD src0_sel:WORD_1
	v_cvt_f32_f16_e32 v166, v187
	v_cvt_f32_f16_sdwa v167, v187 dst_sel:DWORD dst_unused:UNUSED_PAD src0_sel:WORD_1
	v_pk_mul_f32 v[164:165], v[164:165], s[84:85] op_sel_hi:[1,0]
	v_pk_mul_f32 v[166:167], v[166:167], s[84:85] op_sel_hi:[1,0]
	v_pk_fma_f32 v[8:9], v[8:9], v[136:137], v[164:165]
	v_pk_fma_f32 v[10:11], v[10:11], v[138:139], v[166:167]
	v_cvt_pk_f16_f32 v174, v8, v9
	v_cvt_pk_f16_f32 v175, v10, v11
	s_nop 1
	v_permlane16_swap_b32_e32 v172, v174
	v_permlane16_swap_b32_e32 v173, v175
	global_store_dwordx4 v177, v[172:175], s[80:81]
	s_waitcnt vmcnt(3)
	v_permlane16_swap_b32_e32 v188, v190
	v_permlane16_swap_b32_e32 v189, v191
	v_cvt_f32_f16_e32 v164, v188
	v_cvt_f32_f16_sdwa v165, v188 dst_sel:DWORD dst_unused:UNUSED_PAD src0_sel:WORD_1
	v_cvt_f32_f16_e32 v166, v189
	v_cvt_f32_f16_sdwa v167, v189 dst_sel:DWORD dst_unused:UNUSED_PAD src0_sel:WORD_1
	v_pk_mul_f32 v[164:165], v[164:165], s[84:85] op_sel_hi:[1,0]
	v_pk_mul_f32 v[166:167], v[166:167], s[84:85] op_sel_hi:[1,0]
	v_pk_fma_f32 v[12:13], v[12:13], v[140:141], v[164:165]
	v_pk_fma_f32 v[14:15], v[14:15], v[142:143], v[166:167]
	v_cvt_pk_f16_f32 v228, v12, v13
	v_cvt_pk_f16_f32 v229, v14, v15
	v_cvt_f32_f16_e32 v164, v190
	v_cvt_f32_f16_sdwa v165, v190 dst_sel:DWORD dst_unused:UNUSED_PAD src0_sel:WORD_1
	v_cvt_f32_f16_e32 v166, v191
	v_cvt_f32_f16_sdwa v167, v191 dst_sel:DWORD dst_unused:UNUSED_PAD src0_sel:WORD_1
	v_pk_mul_f32 v[164:165], v[164:165], s[84:85] op_sel_hi:[1,0]
	v_pk_mul_f32 v[166:167], v[166:167], s[84:85] op_sel_hi:[1,0]
	v_pk_fma_f32 v[16:17], v[16:17], v[144:145], v[164:165]
	v_pk_fma_f32 v[18:19], v[18:19], v[146:147], v[166:167]
	v_cvt_pk_f16_f32 v230, v16, v17
	v_cvt_pk_f16_f32 v231, v18, v19
	s_nop 1
	v_permlane16_swap_b32_e32 v228, v230
	v_permlane16_swap_b32_e32 v229, v231
	global_store_dwordx4 v177, v[228:231], s[80:81] offset:64
	v_add_u32_e32 v177, 0x8000, v177
	v_add_u32_e32 v178, 0x8000, v178
	global_load_dwordx4 v[184:187], v178, s[80:81]
	global_load_dwordx4 v[188:191], v178, s[80:81] offset:64
	s_waitcnt vmcnt(5)
	v_permlane16_swap_b32_e32 v238, v240
	v_permlane16_swap_b32_e32 v239, v241
	v_cvt_f32_f16_e32 v164, v238
	v_cvt_f32_f16_sdwa v165, v238 dst_sel:DWORD dst_unused:UNUSED_PAD src0_sel:WORD_1
	v_cvt_f32_f16_e32 v166, v239
	v_cvt_f32_f16_sdwa v167, v239 dst_sel:DWORD dst_unused:UNUSED_PAD src0_sel:WORD_1
	v_pk_mul_f32 v[164:165], v[164:165], s[84:85] op_sel_hi:[1,0]
	v_pk_mul_f32 v[166:167], v[166:167], s[84:85] op_sel_hi:[1,0]
	v_pk_fma_f32 v[20:21], v[20:21], v[132:133], v[164:165]
	v_pk_fma_f32 v[22:23], v[22:23], v[134:135], v[166:167]
	v_cvt_pk_f16_f32 v172, v20, v21
	v_cvt_pk_f16_f32 v173, v22, v23
	v_cvt_f32_f16_e32 v164, v240
	v_cvt_f32_f16_sdwa v165, v240 dst_sel:DWORD dst_unused:UNUSED_PAD src0_sel:WORD_1
	v_cvt_f32_f16_e32 v166, v241
	v_cvt_f32_f16_sdwa v167, v241 dst_sel:DWORD dst_unused:UNUSED_PAD src0_sel:WORD_1
	v_pk_mul_f32 v[164:165], v[164:165], s[84:85] op_sel_hi:[1,0]
	v_pk_mul_f32 v[166:167], v[166:167], s[84:85] op_sel_hi:[1,0]
	v_pk_fma_f32 v[24:25], v[24:25], v[136:137], v[164:165]
	v_pk_fma_f32 v[26:27], v[26:27], v[138:139], v[166:167]
	v_cvt_pk_f16_f32 v174, v24, v25
	v_cvt_pk_f16_f32 v175, v26, v27
	s_nop 1
	v_permlane16_swap_b32_e32 v172, v174
	v_permlane16_swap_b32_e32 v173, v175
	global_store_dwordx4 v177, v[172:175], s[80:81]
	s_waitcnt vmcnt(5)
	v_permlane16_swap_b32_e32 v242, v244
	v_permlane16_swap_b32_e32 v243, v245
	v_cvt_f32_f16_e32 v164, v242
	v_cvt_f32_f16_sdwa v165, v242 dst_sel:DWORD dst_unused:UNUSED_PAD src0_sel:WORD_1
	v_cvt_f32_f16_e32 v166, v243
	v_cvt_f32_f16_sdwa v167, v243 dst_sel:DWORD dst_unused:UNUSED_PAD src0_sel:WORD_1
	v_pk_mul_f32 v[164:165], v[164:165], s[84:85] op_sel_hi:[1,0]
	v_pk_mul_f32 v[166:167], v[166:167], s[84:85] op_sel_hi:[1,0]
	v_pk_fma_f32 v[28:29], v[28:29], v[140:141], v[164:165]
	v_pk_fma_f32 v[30:31], v[30:31], v[142:143], v[166:167]
	v_cvt_pk_f16_f32 v228, v28, v29
	v_cvt_pk_f16_f32 v229, v30, v31
	v_cvt_f32_f16_e32 v164, v244
	v_cvt_f32_f16_sdwa v165, v244 dst_sel:DWORD dst_unused:UNUSED_PAD src0_sel:WORD_1
	v_cvt_f32_f16_e32 v166, v245
	v_cvt_f32_f16_sdwa v167, v245 dst_sel:DWORD dst_unused:UNUSED_PAD src0_sel:WORD_1
	v_pk_mul_f32 v[164:165], v[164:165], s[84:85] op_sel_hi:[1,0]
	v_pk_mul_f32 v[166:167], v[166:167], s[84:85] op_sel_hi:[1,0]
	v_pk_fma_f32 v[32:33], v[32:33], v[144:145], v[164:165]
	v_pk_fma_f32 v[34:35], v[34:35], v[146:147], v[166:167]
	v_cvt_pk_f16_f32 v230, v32, v33
	v_cvt_pk_f16_f32 v231, v34, v35
	s_nop 1
	v_permlane16_swap_b32_e32 v228, v230
	v_permlane16_swap_b32_e32 v229, v231
	global_store_dwordx4 v177, v[228:231], s[80:81] offset:64
	v_add_u32_e32 v177, 0x8000, v177
	v_add_u32_e32 v178, 0x8000, v178
	global_load_dwordx4 v[238:241], v178, s[80:81]
	global_load_dwordx4 v[242:245], v178, s[80:81] offset:64
	s_waitcnt vmcnt(5)
	v_permlane16_swap_b32_e32 v184, v186
	v_permlane16_swap_b32_e32 v185, v187
	v_cvt_f32_f16_e32 v164, v184
	v_cvt_f32_f16_sdwa v165, v184 dst_sel:DWORD dst_unused:UNUSED_PAD src0_sel:WORD_1
	v_cvt_f32_f16_e32 v166, v185
	v_cvt_f32_f16_sdwa v167, v185 dst_sel:DWORD dst_unused:UNUSED_PAD src0_sel:WORD_1
	v_pk_mul_f32 v[164:165], v[164:165], s[84:85] op_sel_hi:[1,0]
	v_pk_mul_f32 v[166:167], v[166:167], s[84:85] op_sel_hi:[1,0]
	v_pk_fma_f32 v[36:37], v[36:37], v[132:133], v[164:165]
	v_pk_fma_f32 v[38:39], v[38:39], v[134:135], v[166:167]
	v_cvt_pk_f16_f32 v172, v36, v37
	v_cvt_pk_f16_f32 v173, v38, v39
	v_cvt_f32_f16_e32 v164, v186
	v_cvt_f32_f16_sdwa v165, v186 dst_sel:DWORD dst_unused:UNUSED_PAD src0_sel:WORD_1
	v_cvt_f32_f16_e32 v166, v187
	v_cvt_f32_f16_sdwa v167, v187 dst_sel:DWORD dst_unused:UNUSED_PAD src0_sel:WORD_1
	v_pk_mul_f32 v[164:165], v[164:165], s[84:85] op_sel_hi:[1,0]
	v_pk_mul_f32 v[166:167], v[166:167], s[84:85] op_sel_hi:[1,0]
	v_pk_fma_f32 v[40:41], v[40:41], v[136:137], v[164:165]
	v_pk_fma_f32 v[42:43], v[42:43], v[138:139], v[166:167]
	v_cvt_pk_f16_f32 v174, v40, v41
	v_cvt_pk_f16_f32 v175, v42, v43
	s_nop 1
	v_permlane16_swap_b32_e32 v172, v174
	v_permlane16_swap_b32_e32 v173, v175
	global_store_dwordx4 v177, v[172:175], s[80:81]
	s_waitcnt vmcnt(5)
	v_permlane16_swap_b32_e32 v188, v190
	v_permlane16_swap_b32_e32 v189, v191
	v_cvt_f32_f16_e32 v164, v188
	v_cvt_f32_f16_sdwa v165, v188 dst_sel:DWORD dst_unused:UNUSED_PAD src0_sel:WORD_1
	v_cvt_f32_f16_e32 v166, v189
	v_cvt_f32_f16_sdwa v167, v189 dst_sel:DWORD dst_unused:UNUSED_PAD src0_sel:WORD_1
	v_pk_mul_f32 v[164:165], v[164:165], s[84:85] op_sel_hi:[1,0]
	v_pk_mul_f32 v[166:167], v[166:167], s[84:85] op_sel_hi:[1,0]
	v_pk_fma_f32 v[44:45], v[44:45], v[140:141], v[164:165]
	v_pk_fma_f32 v[46:47], v[46:47], v[142:143], v[166:167]
	v_cvt_pk_f16_f32 v228, v44, v45
	v_cvt_pk_f16_f32 v229, v46, v47
	v_cvt_f32_f16_e32 v164, v190
	v_cvt_f32_f16_sdwa v165, v190 dst_sel:DWORD dst_unused:UNUSED_PAD src0_sel:WORD_1
	v_cvt_f32_f16_e32 v166, v191
	v_cvt_f32_f16_sdwa v167, v191 dst_sel:DWORD dst_unused:UNUSED_PAD src0_sel:WORD_1
	v_pk_mul_f32 v[164:165], v[164:165], s[84:85] op_sel_hi:[1,0]
	v_pk_mul_f32 v[166:167], v[166:167], s[84:85] op_sel_hi:[1,0]
	v_pk_fma_f32 v[48:49], v[48:49], v[144:145], v[164:165]
	v_pk_fma_f32 v[50:51], v[50:51], v[146:147], v[166:167]
	v_cvt_pk_f16_f32 v230, v48, v49
	v_cvt_pk_f16_f32 v231, v50, v51
	s_nop 1
	v_permlane16_swap_b32_e32 v228, v230
	v_permlane16_swap_b32_e32 v229, v231
	global_store_dwordx4 v177, v[228:231], s[80:81] offset:64
	v_add_u32_e32 v177, 0x8000, v177
	v_add_u32_e32 v178, 0x8000, v178
	global_load_dwordx4 v[184:187], v178, s[80:81]
	global_load_dwordx4 v[188:191], v178, s[80:81] offset:64
	s_waitcnt vmcnt(5)
	v_permlane16_swap_b32_e32 v238, v240
	v_permlane16_swap_b32_e32 v239, v241
	v_cvt_f32_f16_e32 v164, v238
	v_cvt_f32_f16_sdwa v165, v238 dst_sel:DWORD dst_unused:UNUSED_PAD src0_sel:WORD_1
	v_cvt_f32_f16_e32 v166, v239
	v_cvt_f32_f16_sdwa v167, v239 dst_sel:DWORD dst_unused:UNUSED_PAD src0_sel:WORD_1
	v_pk_mul_f32 v[164:165], v[164:165], s[84:85] op_sel_hi:[1,0]
	v_pk_mul_f32 v[166:167], v[166:167], s[84:85] op_sel_hi:[1,0]
	v_pk_fma_f32 v[52:53], v[52:53], v[132:133], v[164:165]
	v_pk_fma_f32 v[54:55], v[54:55], v[134:135], v[166:167]
	v_cvt_pk_f16_f32 v172, v52, v53
	v_cvt_pk_f16_f32 v173, v54, v55
	v_cvt_f32_f16_e32 v164, v240
	v_cvt_f32_f16_sdwa v165, v240 dst_sel:DWORD dst_unused:UNUSED_PAD src0_sel:WORD_1
	v_cvt_f32_f16_e32 v166, v241
	v_cvt_f32_f16_sdwa v167, v241 dst_sel:DWORD dst_unused:UNUSED_PAD src0_sel:WORD_1
	v_pk_mul_f32 v[164:165], v[164:165], s[84:85] op_sel_hi:[1,0]
	v_pk_mul_f32 v[166:167], v[166:167], s[84:85] op_sel_hi:[1,0]
	v_pk_fma_f32 v[56:57], v[56:57], v[136:137], v[164:165]
	v_pk_fma_f32 v[58:59], v[58:59], v[138:139], v[166:167]
	v_cvt_pk_f16_f32 v174, v56, v57
	v_cvt_pk_f16_f32 v175, v58, v59
	s_nop 1
	v_permlane16_swap_b32_e32 v172, v174
	v_permlane16_swap_b32_e32 v173, v175
	global_store_dwordx4 v177, v[172:175], s[80:81]
	s_waitcnt vmcnt(5)
	v_permlane16_swap_b32_e32 v242, v244
	v_permlane16_swap_b32_e32 v243, v245
	v_cvt_f32_f16_e32 v164, v242
	v_cvt_f32_f16_sdwa v165, v242 dst_sel:DWORD dst_unused:UNUSED_PAD src0_sel:WORD_1
	v_cvt_f32_f16_e32 v166, v243
	v_cvt_f32_f16_sdwa v167, v243 dst_sel:DWORD dst_unused:UNUSED_PAD src0_sel:WORD_1
	v_pk_mul_f32 v[164:165], v[164:165], s[84:85] op_sel_hi:[1,0]
	v_pk_mul_f32 v[166:167], v[166:167], s[84:85] op_sel_hi:[1,0]
	v_pk_fma_f32 v[60:61], v[60:61], v[140:141], v[164:165]
	v_pk_fma_f32 v[62:63], v[62:63], v[142:143], v[166:167]
	v_cvt_pk_f16_f32 v228, v60, v61
	v_cvt_pk_f16_f32 v229, v62, v63
	v_cvt_f32_f16_e32 v164, v244
	v_cvt_f32_f16_sdwa v165, v244 dst_sel:DWORD dst_unused:UNUSED_PAD src0_sel:WORD_1
	v_cvt_f32_f16_e32 v166, v245
	v_cvt_f32_f16_sdwa v167, v245 dst_sel:DWORD dst_unused:UNUSED_PAD src0_sel:WORD_1
	v_pk_mul_f32 v[164:165], v[164:165], s[84:85] op_sel_hi:[1,0]
	v_pk_mul_f32 v[166:167], v[166:167], s[84:85] op_sel_hi:[1,0]
	v_pk_fma_f32 v[64:65], v[64:65], v[144:145], v[164:165]
	v_pk_fma_f32 v[66:67], v[66:67], v[146:147], v[166:167]
	v_cvt_pk_f16_f32 v230, v64, v65
	v_cvt_pk_f16_f32 v231, v66, v67
	s_nop 1
	v_permlane16_swap_b32_e32 v228, v230
	v_permlane16_swap_b32_e32 v229, v231
	global_store_dwordx4 v177, v[228:231], s[80:81] offset:64
	v_add_u32_e32 v177, 0x8000, v177
	v_add_u32_e32 v178, 0x8000, v178
	global_load_dwordx4 v[238:241], v178, s[80:81]
	global_load_dwordx4 v[242:245], v178, s[80:81] offset:64
	s_waitcnt vmcnt(5)
	v_permlane16_swap_b32_e32 v184, v186
	v_permlane16_swap_b32_e32 v185, v187
	v_cvt_f32_f16_e32 v164, v184
	v_cvt_f32_f16_sdwa v165, v184 dst_sel:DWORD dst_unused:UNUSED_PAD src0_sel:WORD_1
	v_cvt_f32_f16_e32 v166, v185
	v_cvt_f32_f16_sdwa v167, v185 dst_sel:DWORD dst_unused:UNUSED_PAD src0_sel:WORD_1
	v_pk_mul_f32 v[164:165], v[164:165], s[84:85] op_sel_hi:[1,0]
	v_pk_mul_f32 v[166:167], v[166:167], s[84:85] op_sel_hi:[1,0]
	v_pk_fma_f32 v[68:69], v[68:69], v[132:133], v[164:165]
	v_pk_fma_f32 v[70:71], v[70:71], v[134:135], v[166:167]
	v_cvt_pk_f16_f32 v172, v68, v69
	v_cvt_pk_f16_f32 v173, v70, v71
	v_cvt_f32_f16_e32 v164, v186
	v_cvt_f32_f16_sdwa v165, v186 dst_sel:DWORD dst_unused:UNUSED_PAD src0_sel:WORD_1
	v_cvt_f32_f16_e32 v166, v187
	v_cvt_f32_f16_sdwa v167, v187 dst_sel:DWORD dst_unused:UNUSED_PAD src0_sel:WORD_1
	v_pk_mul_f32 v[164:165], v[164:165], s[84:85] op_sel_hi:[1,0]
	v_pk_mul_f32 v[166:167], v[166:167], s[84:85] op_sel_hi:[1,0]
	v_pk_fma_f32 v[72:73], v[72:73], v[136:137], v[164:165]
	v_pk_fma_f32 v[74:75], v[74:75], v[138:139], v[166:167]
	v_cvt_pk_f16_f32 v174, v72, v73
	v_cvt_pk_f16_f32 v175, v74, v75
	s_nop 1
	v_permlane16_swap_b32_e32 v172, v174
	v_permlane16_swap_b32_e32 v173, v175
	global_store_dwordx4 v177, v[172:175], s[80:81]
	s_waitcnt vmcnt(5)
	v_permlane16_swap_b32_e32 v188, v190
	v_permlane16_swap_b32_e32 v189, v191
	v_cvt_f32_f16_e32 v164, v188
	v_cvt_f32_f16_sdwa v165, v188 dst_sel:DWORD dst_unused:UNUSED_PAD src0_sel:WORD_1
	v_cvt_f32_f16_e32 v166, v189
	v_cvt_f32_f16_sdwa v167, v189 dst_sel:DWORD dst_unused:UNUSED_PAD src0_sel:WORD_1
	v_pk_mul_f32 v[164:165], v[164:165], s[84:85] op_sel_hi:[1,0]
	v_pk_mul_f32 v[166:167], v[166:167], s[84:85] op_sel_hi:[1,0]
	v_pk_fma_f32 v[76:77], v[76:77], v[140:141], v[164:165]
	v_pk_fma_f32 v[78:79], v[78:79], v[142:143], v[166:167]
	v_cvt_pk_f16_f32 v228, v76, v77
	v_cvt_pk_f16_f32 v229, v78, v79
	v_cvt_f32_f16_e32 v164, v190
	v_cvt_f32_f16_sdwa v165, v190 dst_sel:DWORD dst_unused:UNUSED_PAD src0_sel:WORD_1
	v_cvt_f32_f16_e32 v166, v191
	v_cvt_f32_f16_sdwa v167, v191 dst_sel:DWORD dst_unused:UNUSED_PAD src0_sel:WORD_1
	v_pk_mul_f32 v[164:165], v[164:165], s[84:85] op_sel_hi:[1,0]
	v_pk_mul_f32 v[166:167], v[166:167], s[84:85] op_sel_hi:[1,0]
	v_pk_fma_f32 v[80:81], v[80:81], v[144:145], v[164:165]
	v_pk_fma_f32 v[82:83], v[82:83], v[146:147], v[166:167]
	v_cvt_pk_f16_f32 v230, v80, v81
	v_cvt_pk_f16_f32 v231, v82, v83
	s_nop 1
	v_permlane16_swap_b32_e32 v228, v230
	v_permlane16_swap_b32_e32 v229, v231
	global_store_dwordx4 v177, v[228:231], s[80:81] offset:64
	v_add_u32_e32 v177, 0x8000, v177
	v_add_u32_e32 v178, 0x8000, v178
	global_load_dwordx4 v[184:187], v178, s[80:81]
	global_load_dwordx4 v[188:191], v178, s[80:81] offset:64
	s_waitcnt vmcnt(5)
	v_permlane16_swap_b32_e32 v238, v240
	v_permlane16_swap_b32_e32 v239, v241
	v_cvt_f32_f16_e32 v164, v238
	v_cvt_f32_f16_sdwa v165, v238 dst_sel:DWORD dst_unused:UNUSED_PAD src0_sel:WORD_1
	v_cvt_f32_f16_e32 v166, v239
	v_cvt_f32_f16_sdwa v167, v239 dst_sel:DWORD dst_unused:UNUSED_PAD src0_sel:WORD_1
	v_pk_mul_f32 v[164:165], v[164:165], s[84:85] op_sel_hi:[1,0]
	v_pk_mul_f32 v[166:167], v[166:167], s[84:85] op_sel_hi:[1,0]
	v_pk_fma_f32 v[84:85], v[84:85], v[132:133], v[164:165]
	v_pk_fma_f32 v[86:87], v[86:87], v[134:135], v[166:167]
	v_cvt_pk_f16_f32 v172, v84, v85
	v_cvt_pk_f16_f32 v173, v86, v87
	v_cvt_f32_f16_e32 v164, v240
	v_cvt_f32_f16_sdwa v165, v240 dst_sel:DWORD dst_unused:UNUSED_PAD src0_sel:WORD_1
	v_cvt_f32_f16_e32 v166, v241
	v_cvt_f32_f16_sdwa v167, v241 dst_sel:DWORD dst_unused:UNUSED_PAD src0_sel:WORD_1
	v_pk_mul_f32 v[164:165], v[164:165], s[84:85] op_sel_hi:[1,0]
	v_pk_mul_f32 v[166:167], v[166:167], s[84:85] op_sel_hi:[1,0]
	v_pk_fma_f32 v[88:89], v[88:89], v[136:137], v[164:165]
	v_pk_fma_f32 v[90:91], v[90:91], v[138:139], v[166:167]
	v_cvt_pk_f16_f32 v174, v88, v89
	v_cvt_pk_f16_f32 v175, v90, v91
	s_nop 1
	v_permlane16_swap_b32_e32 v172, v174
	v_permlane16_swap_b32_e32 v173, v175
	global_store_dwordx4 v177, v[172:175], s[80:81]
	s_waitcnt vmcnt(5)
	v_permlane16_swap_b32_e32 v242, v244
	v_permlane16_swap_b32_e32 v243, v245
	v_cvt_f32_f16_e32 v164, v242
	v_cvt_f32_f16_sdwa v165, v242 dst_sel:DWORD dst_unused:UNUSED_PAD src0_sel:WORD_1
	v_cvt_f32_f16_e32 v166, v243
	v_cvt_f32_f16_sdwa v167, v243 dst_sel:DWORD dst_unused:UNUSED_PAD src0_sel:WORD_1
	v_pk_mul_f32 v[164:165], v[164:165], s[84:85] op_sel_hi:[1,0]
	v_pk_mul_f32 v[166:167], v[166:167], s[84:85] op_sel_hi:[1,0]
	v_pk_fma_f32 v[92:93], v[92:93], v[140:141], v[164:165]
	v_pk_fma_f32 v[94:95], v[94:95], v[142:143], v[166:167]
	v_cvt_pk_f16_f32 v228, v92, v93
	v_cvt_pk_f16_f32 v229, v94, v95
	v_cvt_f32_f16_e32 v164, v244
	v_cvt_f32_f16_sdwa v165, v244 dst_sel:DWORD dst_unused:UNUSED_PAD src0_sel:WORD_1
	v_cvt_f32_f16_e32 v166, v245
	v_cvt_f32_f16_sdwa v167, v245 dst_sel:DWORD dst_unused:UNUSED_PAD src0_sel:WORD_1
	v_pk_mul_f32 v[164:165], v[164:165], s[84:85] op_sel_hi:[1,0]
	v_pk_mul_f32 v[166:167], v[166:167], s[84:85] op_sel_hi:[1,0]
	v_pk_fma_f32 v[96:97], v[96:97], v[144:145], v[164:165]
	v_pk_fma_f32 v[98:99], v[98:99], v[146:147], v[166:167]
	v_cvt_pk_f16_f32 v230, v96, v97
	v_cvt_pk_f16_f32 v231, v98, v99
	s_nop 1
	v_permlane16_swap_b32_e32 v228, v230
	v_permlane16_swap_b32_e32 v229, v231
	global_store_dwordx4 v177, v[228:231], s[80:81] offset:64
	v_add_u32_e32 v177, 0x8000, v177
	v_add_u32_e32 v178, 0x8000, v178
	global_load_dwordx4 v[238:241], v178, s[80:81]
	global_load_dwordx4 v[242:245], v178, s[80:81] offset:64
	s_waitcnt vmcnt(5)
	v_permlane16_swap_b32_e32 v184, v186
	v_permlane16_swap_b32_e32 v185, v187
	v_cvt_f32_f16_e32 v164, v184
	v_cvt_f32_f16_sdwa v165, v184 dst_sel:DWORD dst_unused:UNUSED_PAD src0_sel:WORD_1
	v_cvt_f32_f16_e32 v166, v185
	v_cvt_f32_f16_sdwa v167, v185 dst_sel:DWORD dst_unused:UNUSED_PAD src0_sel:WORD_1
	v_pk_mul_f32 v[164:165], v[164:165], s[84:85] op_sel_hi:[1,0]
	v_pk_mul_f32 v[166:167], v[166:167], s[84:85] op_sel_hi:[1,0]
	v_pk_fma_f32 v[100:101], v[100:101], v[132:133], v[164:165]
	v_pk_fma_f32 v[102:103], v[102:103], v[134:135], v[166:167]
	v_cvt_pk_f16_f32 v172, v100, v101
	v_cvt_pk_f16_f32 v173, v102, v103
	v_cvt_f32_f16_e32 v164, v186
	v_cvt_f32_f16_sdwa v165, v186 dst_sel:DWORD dst_unused:UNUSED_PAD src0_sel:WORD_1
	v_cvt_f32_f16_e32 v166, v187
	v_cvt_f32_f16_sdwa v167, v187 dst_sel:DWORD dst_unused:UNUSED_PAD src0_sel:WORD_1
	v_pk_mul_f32 v[164:165], v[164:165], s[84:85] op_sel_hi:[1,0]
	v_pk_mul_f32 v[166:167], v[166:167], s[84:85] op_sel_hi:[1,0]
	v_pk_fma_f32 v[104:105], v[104:105], v[136:137], v[164:165]
	v_pk_fma_f32 v[106:107], v[106:107], v[138:139], v[166:167]
	v_cvt_pk_f16_f32 v174, v104, v105
	v_cvt_pk_f16_f32 v175, v106, v107
	s_nop 1
	v_permlane16_swap_b32_e32 v172, v174
	v_permlane16_swap_b32_e32 v173, v175
	global_store_dwordx4 v177, v[172:175], s[80:81]
	s_waitcnt vmcnt(5)
	v_permlane16_swap_b32_e32 v188, v190
	v_permlane16_swap_b32_e32 v189, v191
	v_cvt_f32_f16_e32 v164, v188
	v_cvt_f32_f16_sdwa v165, v188 dst_sel:DWORD dst_unused:UNUSED_PAD src0_sel:WORD_1
	v_cvt_f32_f16_e32 v166, v189
	v_cvt_f32_f16_sdwa v167, v189 dst_sel:DWORD dst_unused:UNUSED_PAD src0_sel:WORD_1
	v_pk_mul_f32 v[164:165], v[164:165], s[84:85] op_sel_hi:[1,0]
	v_pk_mul_f32 v[166:167], v[166:167], s[84:85] op_sel_hi:[1,0]
	v_pk_fma_f32 v[108:109], v[108:109], v[140:141], v[164:165]
	v_pk_fma_f32 v[110:111], v[110:111], v[142:143], v[166:167]
	v_cvt_pk_f16_f32 v228, v108, v109
	v_cvt_pk_f16_f32 v229, v110, v111
	v_cvt_f32_f16_e32 v164, v190
	v_cvt_f32_f16_sdwa v165, v190 dst_sel:DWORD dst_unused:UNUSED_PAD src0_sel:WORD_1
	v_cvt_f32_f16_e32 v166, v191
	v_cvt_f32_f16_sdwa v167, v191 dst_sel:DWORD dst_unused:UNUSED_PAD src0_sel:WORD_1
	v_pk_mul_f32 v[164:165], v[164:165], s[84:85] op_sel_hi:[1,0]
	v_pk_mul_f32 v[166:167], v[166:167], s[84:85] op_sel_hi:[1,0]
	v_pk_fma_f32 v[112:113], v[112:113], v[144:145], v[164:165]
	v_pk_fma_f32 v[114:115], v[114:115], v[146:147], v[166:167]
	v_cvt_pk_f16_f32 v230, v112, v113
	v_cvt_pk_f16_f32 v231, v114, v115
	s_nop 1
	v_permlane16_swap_b32_e32 v228, v230
	v_permlane16_swap_b32_e32 v229, v231
	global_store_dwordx4 v177, v[228:231], s[80:81] offset:64
	v_add_u32_e32 v177, 0x8000, v177
	s_waitcnt vmcnt(3)
	v_permlane16_swap_b32_e32 v238, v240
	v_permlane16_swap_b32_e32 v239, v241
	v_cvt_f32_f16_e32 v164, v238
	v_cvt_f32_f16_sdwa v165, v238 dst_sel:DWORD dst_unused:UNUSED_PAD src0_sel:WORD_1
	v_cvt_f32_f16_e32 v166, v239
	v_cvt_f32_f16_sdwa v167, v239 dst_sel:DWORD dst_unused:UNUSED_PAD src0_sel:WORD_1
	v_pk_mul_f32 v[164:165], v[164:165], s[84:85] op_sel_hi:[1,0]
	v_pk_mul_f32 v[166:167], v[166:167], s[84:85] op_sel_hi:[1,0]
	v_pk_fma_f32 v[116:117], v[116:117], v[132:133], v[164:165]
	v_pk_fma_f32 v[118:119], v[118:119], v[134:135], v[166:167]
	v_cvt_pk_f16_f32 v172, v116, v117
	v_cvt_pk_f16_f32 v173, v118, v119
	v_cvt_f32_f16_e32 v164, v240
	v_cvt_f32_f16_sdwa v165, v240 dst_sel:DWORD dst_unused:UNUSED_PAD src0_sel:WORD_1
	v_cvt_f32_f16_e32 v166, v241
	v_cvt_f32_f16_sdwa v167, v241 dst_sel:DWORD dst_unused:UNUSED_PAD src0_sel:WORD_1
	v_pk_mul_f32 v[164:165], v[164:165], s[84:85] op_sel_hi:[1,0]
	v_pk_mul_f32 v[166:167], v[166:167], s[84:85] op_sel_hi:[1,0]
	v_pk_fma_f32 v[120:121], v[120:121], v[136:137], v[164:165]
	v_pk_fma_f32 v[122:123], v[122:123], v[138:139], v[166:167]
	v_cvt_pk_f16_f32 v174, v120, v121
	v_cvt_pk_f16_f32 v175, v122, v123
	s_nop 1
	v_permlane16_swap_b32_e32 v172, v174
	v_permlane16_swap_b32_e32 v173, v175
	global_store_dwordx4 v177, v[172:175], s[80:81]
	s_waitcnt vmcnt(3)
	v_permlane16_swap_b32_e32 v242, v244
	v_permlane16_swap_b32_e32 v243, v245
	v_cvt_f32_f16_e32 v164, v242
	v_cvt_f32_f16_sdwa v165, v242 dst_sel:DWORD dst_unused:UNUSED_PAD src0_sel:WORD_1
	v_cvt_f32_f16_e32 v166, v243
	v_cvt_f32_f16_sdwa v167, v243 dst_sel:DWORD dst_unused:UNUSED_PAD src0_sel:WORD_1
	v_pk_mul_f32 v[164:165], v[164:165], s[84:85] op_sel_hi:[1,0]
	v_pk_mul_f32 v[166:167], v[166:167], s[84:85] op_sel_hi:[1,0]
	v_pk_fma_f32 v[124:125], v[124:125], v[140:141], v[164:165]
	v_pk_fma_f32 v[126:127], v[126:127], v[142:143], v[166:167]
	v_cvt_pk_f16_f32 v228, v124, v125
	v_cvt_pk_f16_f32 v229, v126, v127
	v_cvt_f32_f16_e32 v164, v244
	v_cvt_f32_f16_sdwa v165, v244 dst_sel:DWORD dst_unused:UNUSED_PAD src0_sel:WORD_1
	v_cvt_f32_f16_e32 v166, v245
	v_cvt_f32_f16_sdwa v167, v245 dst_sel:DWORD dst_unused:UNUSED_PAD src0_sel:WORD_1
	v_pk_mul_f32 v[164:165], v[164:165], s[84:85] op_sel_hi:[1,0]
	v_pk_mul_f32 v[166:167], v[166:167], s[84:85] op_sel_hi:[1,0]
	v_pk_fma_f32 v[128:129], v[128:129], v[144:145], v[164:165]
	v_pk_fma_f32 v[130:131], v[130:131], v[146:147], v[166:167]
	v_cvt_pk_f16_f32 v230, v128, v129
	v_cvt_pk_f16_f32 v231, v130, v131
	s_nop 1
	v_permlane16_swap_b32_e32 v228, v230
	v_permlane16_swap_b32_e32 v229, v231
	global_store_dwordx4 v177, v[228:231], s[80:81] offset:64
	s_nop 1
	s_branch .LBB0_88

.Lt_mlp1b:
	v_add_u32_e32 v169, s32, v164
	v_mfma_f32_16x16x32_f16 v[4:7], v[132:135], v[184:187], v[4:7]
	ds_read_b128 v[238:241], v169 offset:4112
	v_mfma_f32_16x16x32_f16 v[8:11], v[136:139], v[184:187], v[8:11]
	ds_read_b128 v[242:245], v169 offset:5136
	v_mfma_f32_16x16x32_f16 v[12:15], v[140:143], v[184:187], v[12:15]
	ds_read_b128 v[246:249], v169 offset:6160
	v_mfma_f32_16x16x32_f16 v[16:19], v[144:147], v[184:187], v[16:19]
	ds_read_b128 v[250:253], v169 offset:7184
	v_mfma_f32_16x16x32_f16 v[20:23], v[132:135], v[188:191], v[20:23]
	v_mfma_f32_16x16x32_f16 v[24:27], v[136:139], v[188:191], v[24:27]
	v_mfma_f32_16x16x32_f16 v[28:31], v[140:143], v[188:191], v[28:31]
	v_mfma_f32_16x16x32_f16 v[32:35], v[144:147], v[188:191], v[32:35]
	v_mfma_f32_16x16x32_f16 v[36:39], v[132:135], v[192:195], v[36:39]
	v_mfma_f32_16x16x32_f16 v[40:43], v[136:139], v[192:195], v[40:43]
	v_mfma_f32_16x16x32_f16 v[44:47], v[140:143], v[192:195], v[44:47]
	v_mfma_f32_16x16x32_f16 v[48:51], v[144:147], v[192:195], v[48:51]
	v_mfma_f32_16x16x32_f16 v[52:55], v[132:135], v[196:199], v[52:55]
	v_mfma_f32_16x16x32_f16 v[56:59], v[136:139], v[196:199], v[56:59]
	v_mfma_f32_16x16x32_f16 v[60:63], v[140:143], v[196:199], v[60:63]
	v_mfma_f32_16x16x32_f16 v[64:67], v[144:147], v[196:199], v[64:67]
	s_waitcnt vmcnt(8) lgkmcnt(0)
	s_barrier
	s_add_i32 s37, s32, 0x8000
	s_cmp_lg_u32 s32, 0x18000
	s_cselect_b32 s37, s37, 0
	v_add_u32_e32 v168, s37, v165
	v_add_u32_e32 v169, s37, v164
	s_add_u32 vcc_lo, s24, s32
	v_mfma_f32_16x16x32_f16 v[68:71], v[132:135], v[238:241], v[68:71]
	ds_read_b128 v[148:151], v168 offset:16
	ds_read_b128 v[184:187], v169 offset:16
	s_mov_b32 m0, vcc_lo
	s_nop 0
	global_load_lds_dwordx4 v170, s[30:31]
	v_mfma_f32_16x16x32_f16 v[72:75], v[136:139], v[238:241], v[72:75]
	ds_read_b128 v[152:155], v168 offset:1040
	ds_read_b128 v[188:191], v169 offset:1040
	s_add_u32 m0, vcc_lo, 0x400
	s_nop 0
	global_load_lds_dwordx4 v171, s[30:31]
	v_mfma_f32_16x16x32_f16 v[76:79], v[140:143], v[238:241], v[76:79]
	ds_read_b128 v[156:159], v168 offset:2064
	ds_read_b128 v[192:195], v169 offset:2064
	s_add_u32 m0, vcc_lo, 0x4000
	s_nop 0
	global_load_lds_dwordx4 v170, s[52:53]
	v_mfma_f32_16x16x32_f16 v[80:83], v[144:147], v[238:241], v[80:83]
	ds_read_b128 v[160:163], v168 offset:3088
	ds_read_b128 v[196:199], v169 offset:3088
	s_add_u32 m0, vcc_lo, 0x4400
	s_nop 0
	global_load_lds_dwordx4 v171, s[52:53]
	v_mfma_f32_16x16x32_f16 v[84:87], v[132:135], v[242:245], v[84:87]
	v_mfma_f32_16x16x32_f16 v[88:91], v[136:139], v[242:245], v[88:91]
	v_mfma_f32_16x16x32_f16 v[92:95], v[140:143], v[242:245], v[92:95]
	v_mfma_f32_16x16x32_f16 v[96:99], v[144:147], v[242:245], v[96:99]
	v_mfma_f32_16x16x32_f16 v[100:103], v[132:135], v[246:249], v[100:103]
	v_mfma_f32_16x16x32_f16 v[104:107], v[136:139], v[246:249], v[104:107]
	v_mfma_f32_16x16x32_f16 v[108:111], v[140:143], v[246:249], v[108:111]
	v_mfma_f32_16x16x32_f16 v[112:115], v[144:147], v[246:249], v[112:115]
	v_mfma_f32_16x16x32_f16 v[116:119], v[132:135], v[250:253], v[116:119]
	v_mfma_f32_16x16x32_f16 v[120:123], v[136:139], v[250:253], v[120:123]
	v_mfma_f32_16x16x32_f16 v[124:127], v[140:143], v[250:253], v[124:127]
	v_mfma_f32_16x16x32_f16 v[128:131], v[144:147], v[250:253], v[128:131]
	s_waitcnt lgkmcnt(0)
	s_mov_b32 s32, s37
	s_add_u32 s30, s30, 64
	s_addc_u32 s31, s31, 0
	s_add_u32 s52, s52, 64
	s_addc_u32 s53, s53, 0
	v_add_u32_e32 v169, s32, v164
	v_mfma_f32_16x16x32_f16 v[4:7], v[148:151], v[184:187], v[4:7]
	ds_read_b128 v[238:241], v169 offset:4112
	v_mfma_f32_16x16x32_f16 v[8:11], v[152:155], v[184:187], v[8:11]
	ds_read_b128 v[242:245], v169 offset:5136
	v_mfma_f32_16x16x32_f16 v[12:15], v[156:159], v[184:187], v[12:15]
	ds_read_b128 v[246:249], v169 offset:6160
	v_mfma_f32_16x16x32_f16 v[16:19], v[160:163], v[184:187], v[16:19]
	ds_read_b128 v[250:253], v169 offset:7184
	v_mfma_f32_16x16x32_f16 v[20:23], v[148:151], v[188:191], v[20:23]
	v_mfma_f32_16x16x32_f16 v[24:27], v[152:155], v[188:191], v[24:27]
	v_mfma_f32_16x16x32_f16 v[28:31], v[156:159], v[188:191], v[28:31]
	v_mfma_f32_16x16x32_f16 v[32:35], v[160:163], v[188:191], v[32:35]
	v_mfma_f32_16x16x32_f16 v[36:39], v[148:151], v[192:195], v[36:39]
	v_mfma_f32_16x16x32_f16 v[40:43], v[152:155], v[192:195], v[40:43]
	v_mfma_f32_16x16x32_f16 v[44:47], v[156:159], v[192:195], v[44:47]
	v_mfma_f32_16x16x32_f16 v[48:51], v[160:163], v[192:195], v[48:51]
	v_mfma_f32_16x16x32_f16 v[52:55], v[148:151], v[196:199], v[52:55]
	v_mfma_f32_16x16x32_f16 v[56:59], v[152:155], v[196:199], v[56:59]
	v_mfma_f32_16x16x32_f16 v[60:63], v[156:159], v[196:199], v[60:63]
	v_mfma_f32_16x16x32_f16 v[64:67], v[160:163], v[196:199], v[64:67]
	s_waitcnt vmcnt(8) lgkmcnt(0)
	s_barrier
	s_add_i32 s37, s32, 0x8000
	s_cmp_lg_u32 s32, 0x18000
	s_cselect_b32 s37, s37, 0
	v_add_u32_e32 v168, s37, v165
	v_add_u32_e32 v169, s37, v164
	s_add_u32 vcc_lo, s24, s32
	v_mfma_f32_16x16x32_f16 v[68:71], v[148:151], v[238:241], v[68:71]
	ds_read_b128 v[132:135], v168 offset:16
	ds_read_b128 v[184:187], v169 offset:16
	s_mov_b32 m0, vcc_lo
	s_nop 0
	global_load_lds_dwordx4 v170, s[30:31]
	v_mfma_f32_16x16x32_f16 v[72:75], v[152:155], v[238:241], v[72:75]
	ds_read_b128 v[136:139], v168 offset:1040
	ds_read_b128 v[188:191], v169 offset:1040
	s_add_u32 m0, vcc_lo, 0x400
	s_nop 0
	global_load_lds_dwordx4 v171, s[30:31]
	v_mfma_f32_16x16x32_f16 v[76:79], v[156:159], v[238:241], v[76:79]
	ds_read_b128 v[140:143], v168 offset:2064
	ds_read_b128 v[192:195], v169 offset:2064
	s_add_u32 m0, vcc_lo, 0x4000
	s_nop 0
	global_load_lds_dwordx4 v170, s[52:53]
	v_mfma_f32_16x16x32_f16 v[80:83], v[160:163], v[238:241], v[80:83]
	ds_read_b128 v[144:147], v168 offset:3088
	ds_read_b128 v[196:199], v169 offset:3088
	s_add_u32 m0, vcc_lo, 0x4400
	s_nop 0
	global_load_lds_dwordx4 v171, s[52:53]
	v_mfma_f32_16x16x32_f16 v[84:87], v[148:151], v[242:245], v[84:87]
	v_mfma_f32_16x16x32_f16 v[88:91], v[152:155], v[242:245], v[88:91]
	v_mfma_f32_16x16x32_f16 v[92:95], v[156:159], v[242:245], v[92:95]
	v_mfma_f32_16x16x32_f16 v[96:99], v[160:163], v[242:245], v[96:99]
	v_mfma_f32_16x16x32_f16 v[100:103], v[148:151], v[246:249], v[100:103]
	v_mfma_f32_16x16x32_f16 v[104:107], v[152:155], v[246:249], v[104:107]
	v_mfma_f32_16x16x32_f16 v[108:111], v[156:159], v[246:249], v[108:111]
	v_mfma_f32_16x16x32_f16 v[112:115], v[160:163], v[246:249], v[112:115]
	v_mfma_f32_16x16x32_f16 v[116:119], v[148:151], v[250:253], v[116:119]
	v_mfma_f32_16x16x32_f16 v[120:123], v[152:155], v[250:253], v[120:123]
	v_mfma_f32_16x16x32_f16 v[124:127], v[156:159], v[250:253], v[124:127]
	v_mfma_f32_16x16x32_f16 v[128:131], v[160:163], v[250:253], v[128:131]
	s_waitcnt lgkmcnt(0)
	s_mov_b32 s32, s37
	s_add_u32 s30, s30, 64
	s_addc_u32 s31, s31, 0
	s_add_u32 s52, s52, 64
	s_addc_u32 s53, s53, 0
	s_add_i32 s57, s57, 2
	s_cmp_lt_u32 s57, 28
	s_cbranch_scc1 .Lt_mlp1b
	v_add_u32_e32 v169, s32, v164
	v_mfma_f32_16x16x32_f16 v[4:7], v[132:135], v[184:187], v[4:7]
	ds_read_b128 v[238:241], v169 offset:4112
	v_mfma_f32_16x16x32_f16 v[8:11], v[136:139], v[184:187], v[8:11]
	ds_read_b128 v[242:245], v169 offset:5136
	v_mfma_f32_16x16x32_f16 v[12:15], v[140:143], v[184:187], v[12:15]
	ds_read_b128 v[246:249], v169 offset:6160
	v_mfma_f32_16x16x32_f16 v[16:19], v[144:147], v[184:187], v[16:19]
	ds_read_b128 v[250:253], v169 offset:7184
	v_mfma_f32_16x16x32_f16 v[20:23], v[132:135], v[188:191], v[20:23]
	v_mfma_f32_16x16x32_f16 v[24:27], v[136:139], v[188:191], v[24:27]
	v_mfma_f32_16x16x32_f16 v[28:31], v[140:143], v[188:191], v[28:31]
	v_mfma_f32_16x16x32_f16 v[32:35], v[144:147], v[188:191], v[32:35]
	v_mfma_f32_16x16x32_f16 v[36:39], v[132:135], v[192:195], v[36:39]
	v_mfma_f32_16x16x32_f16 v[40:43], v[136:139], v[192:195], v[40:43]
	v_mfma_f32_16x16x32_f16 v[44:47], v[140:143], v[192:195], v[44:47]
	v_mfma_f32_16x16x32_f16 v[48:51], v[144:147], v[192:195], v[48:51]
	v_mfma_f32_16x16x32_f16 v[52:55], v[132:135], v[196:199], v[52:55]
	v_mfma_f32_16x16x32_f16 v[56:59], v[136:139], v[196:199], v[56:59]
	v_mfma_f32_16x16x32_f16 v[60:63], v[140:143], v[196:199], v[60:63]
	v_mfma_f32_16x16x32_f16 v[64:67], v[144:147], v[196:199], v[64:67]
	s_waitcnt vmcnt(8) lgkmcnt(0)
	s_barrier
	s_add_i32 s37, s32, 0x8000
	s_cmp_lg_u32 s32, 0x18000
	s_cselect_b32 s37, s37, 0
	v_add_u32_e32 v168, s37, v165
	v_add_u32_e32 v169, s37, v164
	v_mfma_f32_16x16x32_f16 v[68:71], v[132:135], v[238:241], v[68:71]
	ds_read_b128 v[148:151], v168 offset:16
	ds_read_b128 v[184:187], v169 offset:16
	v_mfma_f32_16x16x32_f16 v[72:75], v[136:139], v[238:241], v[72:75]
	ds_read_b128 v[152:155], v168 offset:1040
	ds_read_b128 v[188:191], v169 offset:1040
	v_mfma_f32_16x16x32_f16 v[76:79], v[140:143], v[238:241], v[76:79]
	ds_read_b128 v[156:159], v168 offset:2064
	ds_read_b128 v[192:195], v169 offset:2064
	v_mfma_f32_16x16x32_f16 v[80:83], v[144:147], v[238:241], v[80:83]
	ds_read_b128 v[160:163], v168 offset:3088
	ds_read_b128 v[196:199], v169 offset:3088
	v_mfma_f32_16x16x32_f16 v[84:87], v[132:135], v[242:245], v[84:87]
	v_mfma_f32_16x16x32_f16 v[88:91], v[136:139], v[242:245], v[88:91]
	v_mfma_f32_16x16x32_f16 v[92:95], v[140:143], v[242:245], v[92:95]
	v_mfma_f32_16x16x32_f16 v[96:99], v[144:147], v[242:245], v[96:99]
	v_mfma_f32_16x16x32_f16 v[100:103], v[132:135], v[246:249], v[100:103]
	v_mfma_f32_16x16x32_f16 v[104:107], v[136:139], v[246:249], v[104:107]
	v_mfma_f32_16x16x32_f16 v[108:111], v[140:143], v[246:249], v[108:111]
	v_mfma_f32_16x16x32_f16 v[112:115], v[144:147], v[246:249], v[112:115]
	v_mfma_f32_16x16x32_f16 v[116:119], v[132:135], v[250:253], v[116:119]
	v_mfma_f32_16x16x32_f16 v[120:123], v[136:139], v[250:253], v[120:123]
	v_mfma_f32_16x16x32_f16 v[124:127], v[140:143], v[250:253], v[124:127]
	v_mfma_f32_16x16x32_f16 v[128:131], v[144:147], v[250:253], v[128:131]
	s_waitcnt lgkmcnt(0)
	s_mov_b32 s32, s37
	v_add_u32_e32 v169, s32, v164
	v_mfma_f32_16x16x32_f16 v[4:7], v[148:151], v[184:187], v[4:7]
	ds_read_b128 v[238:241], v169 offset:4112
	v_mfma_f32_16x16x32_f16 v[8:11], v[152:155], v[184:187], v[8:11]
	ds_read_b128 v[242:245], v169 offset:5136
	v_mfma_f32_16x16x32_f16 v[12:15], v[156:159], v[184:187], v[12:15]
	ds_read_b128 v[246:249], v169 offset:6160
	v_mfma_f32_16x16x32_f16 v[16:19], v[160:163], v[184:187], v[16:19]
	ds_read_b128 v[250:253], v169 offset:7184
	v_mfma_f32_16x16x32_f16 v[20:23], v[148:151], v[188:191], v[20:23]
	v_mfma_f32_16x16x32_f16 v[24:27], v[152:155], v[188:191], v[24:27]
	v_mfma_f32_16x16x32_f16 v[28:31], v[156:159], v[188:191], v[28:31]
	v_mfma_f32_16x16x32_f16 v[32:35], v[160:163], v[188:191], v[32:35]
	v_mfma_f32_16x16x32_f16 v[36:39], v[148:151], v[192:195], v[36:39]
	v_mfma_f32_16x16x32_f16 v[40:43], v[152:155], v[192:195], v[40:43]
	v_mfma_f32_16x16x32_f16 v[44:47], v[156:159], v[192:195], v[44:47]
	v_mfma_f32_16x16x32_f16 v[48:51], v[160:163], v[192:195], v[48:51]
	v_mfma_f32_16x16x32_f16 v[52:55], v[148:151], v[196:199], v[52:55]
	v_mfma_f32_16x16x32_f16 v[56:59], v[152:155], v[196:199], v[56:59]
	v_mfma_f32_16x16x32_f16 v[60:63], v[156:159], v[196:199], v[60:63]
	v_mfma_f32_16x16x32_f16 v[64:67], v[160:163], v[196:199], v[64:67]
	s_waitcnt vmcnt(4) lgkmcnt(0)
	s_barrier
	s_add_i32 s37, s32, 0x8000
	s_cmp_lg_u32 s32, 0x18000
	s_cselect_b32 s37, s37, 0
	v_add_u32_e32 v168, s37, v165
	v_add_u32_e32 v169, s37, v164
	v_mfma_f32_16x16x32_f16 v[68:71], v[148:151], v[238:241], v[68:71]
	ds_read_b128 v[132:135], v168 offset:16
	ds_read_b128 v[184:187], v169 offset:16
	v_mfma_f32_16x16x32_f16 v[72:75], v[152:155], v[238:241], v[72:75]
	ds_read_b128 v[136:139], v168 offset:1040
	ds_read_b128 v[188:191], v169 offset:1040
	v_mfma_f32_16x16x32_f16 v[76:79], v[156:159], v[238:241], v[76:79]
	ds_read_b128 v[140:143], v168 offset:2064
	ds_read_b128 v[192:195], v169 offset:2064
	v_mfma_f32_16x16x32_f16 v[80:83], v[160:163], v[238:241], v[80:83]
	ds_read_b128 v[144:147], v168 offset:3088
	ds_read_b128 v[196:199], v169 offset:3088
	v_mfma_f32_16x16x32_f16 v[84:87], v[148:151], v[242:245], v[84:87]
	v_mfma_f32_16x16x32_f16 v[88:91], v[152:155], v[242:245], v[88:91]
	v_mfma_f32_16x16x32_f16 v[92:95], v[156:159], v[242:245], v[92:95]
	v_mfma_f32_16x16x32_f16 v[96:99], v[160:163], v[242:245], v[96:99]
	v_mfma_f32_16x16x32_f16 v[100:103], v[148:151], v[246:249], v[100:103]
	v_mfma_f32_16x16x32_f16 v[104:107], v[152:155], v[246:249], v[104:107]
	v_mfma_f32_16x16x32_f16 v[108:111], v[156:159], v[246:249], v[108:111]
	v_mfma_f32_16x16x32_f16 v[112:115], v[160:163], v[246:249], v[112:115]
	v_mfma_f32_16x16x32_f16 v[116:119], v[148:151], v[250:253], v[116:119]
	v_mfma_f32_16x16x32_f16 v[120:123], v[152:155], v[250:253], v[120:123]
	v_mfma_f32_16x16x32_f16 v[124:127], v[156:159], v[250:253], v[124:127]
	v_mfma_f32_16x16x32_f16 v[128:131], v[160:163], v[250:253], v[128:131]
	s_waitcnt lgkmcnt(0)
	s_mov_b32 s32, s37
	v_add_u32_e32 v169, s32, v164
	v_mfma_f32_16x16x32_f16 v[4:7], v[132:135], v[184:187], v[4:7]
	ds_read_b128 v[238:241], v169 offset:4112
	v_mfma_f32_16x16x32_f16 v[8:11], v[136:139], v[184:187], v[8:11]
	ds_read_b128 v[242:245], v169 offset:5136
	v_mfma_f32_16x16x32_f16 v[12:15], v[140:143], v[184:187], v[12:15]
	ds_read_b128 v[246:249], v169 offset:6160
	v_mfma_f32_16x16x32_f16 v[16:19], v[144:147], v[184:187], v[16:19]
	ds_read_b128 v[250:253], v169 offset:7184
	v_mfma_f32_16x16x32_f16 v[20:23], v[132:135], v[188:191], v[20:23]
	v_mfma_f32_16x16x32_f16 v[24:27], v[136:139], v[188:191], v[24:27]
	v_mfma_f32_16x16x32_f16 v[28:31], v[140:143], v[188:191], v[28:31]
	v_mfma_f32_16x16x32_f16 v[32:35], v[144:147], v[188:191], v[32:35]
	v_mfma_f32_16x16x32_f16 v[36:39], v[132:135], v[192:195], v[36:39]
	v_mfma_f32_16x16x32_f16 v[40:43], v[136:139], v[192:195], v[40:43]
	v_mfma_f32_16x16x32_f16 v[44:47], v[140:143], v[192:195], v[44:47]
	v_mfma_f32_16x16x32_f16 v[48:51], v[144:147], v[192:195], v[48:51]
	v_mfma_f32_16x16x32_f16 v[52:55], v[132:135], v[196:199], v[52:55]
	v_mfma_f32_16x16x32_f16 v[56:59], v[136:139], v[196:199], v[56:59]
	v_mfma_f32_16x16x32_f16 v[60:63], v[140:143], v[196:199], v[60:63]
	v_mfma_f32_16x16x32_f16 v[64:67], v[144:147], v[196:199], v[64:67]
	s_waitcnt vmcnt(0) lgkmcnt(0)
	s_barrier
	s_add_i32 s37, s32, 0x8000
	s_cmp_lg_u32 s32, 0x18000
	s_cselect_b32 s37, s37, 0
	v_add_u32_e32 v168, s37, v165
	v_add_u32_e32 v169, s37, v164
	v_mfma_f32_16x16x32_f16 v[68:71], v[132:135], v[238:241], v[68:71]
	ds_read_b128 v[148:151], v168 offset:16
	ds_read_b128 v[184:187], v169 offset:16
	v_mfma_f32_16x16x32_f16 v[72:75], v[136:139], v[238:241], v[72:75]
	ds_read_b128 v[152:155], v168 offset:1040
	ds_read_b128 v[188:191], v169 offset:1040
	v_mfma_f32_16x16x32_f16 v[76:79], v[140:143], v[238:241], v[76:79]
	ds_read_b128 v[156:159], v168 offset:2064
	ds_read_b128 v[192:195], v169 offset:2064
	v_mfma_f32_16x16x32_f16 v[80:83], v[144:147], v[238:241], v[80:83]
	ds_read_b128 v[160:163], v168 offset:3088
	ds_read_b128 v[196:199], v169 offset:3088
	v_mfma_f32_16x16x32_f16 v[84:87], v[132:135], v[242:245], v[84:87]
	v_mfma_f32_16x16x32_f16 v[88:91], v[136:139], v[242:245], v[88:91]
	v_mfma_f32_16x16x32_f16 v[92:95], v[140:143], v[242:245], v[92:95]
	v_mfma_f32_16x16x32_f16 v[96:99], v[144:147], v[242:245], v[96:99]
	v_mfma_f32_16x16x32_f16 v[100:103], v[132:135], v[246:249], v[100:103]
	v_mfma_f32_16x16x32_f16 v[104:107], v[136:139], v[246:249], v[104:107]
	v_mfma_f32_16x16x32_f16 v[108:111], v[140:143], v[246:249], v[108:111]
	v_mfma_f32_16x16x32_f16 v[112:115], v[144:147], v[246:249], v[112:115]
	v_mfma_f32_16x16x32_f16 v[116:119], v[132:135], v[250:253], v[116:119]
	v_mfma_f32_16x16x32_f16 v[120:123], v[136:139], v[250:253], v[120:123]
	v_mfma_f32_16x16x32_f16 v[124:127], v[140:143], v[250:253], v[124:127]
	v_mfma_f32_16x16x32_f16 v[128:131], v[144:147], v[250:253], v[128:131]
	s_waitcnt lgkmcnt(0)
	s_mov_b32 s32, s37
	v_add_u32_e32 v169, s32, v164
	v_mfma_f32_16x16x32_f16 v[4:7], v[148:151], v[184:187], v[4:7]
	ds_read_b128 v[238:241], v169 offset:4112
	v_mfma_f32_16x16x32_f16 v[8:11], v[152:155], v[184:187], v[8:11]
	ds_read_b128 v[242:245], v169 offset:5136
	v_mfma_f32_16x16x32_f16 v[12:15], v[156:159], v[184:187], v[12:15]
	ds_read_b128 v[246:249], v169 offset:6160
	v_mfma_f32_16x16x32_f16 v[16:19], v[160:163], v[184:187], v[16:19]
	ds_read_b128 v[250:253], v169 offset:7184
	v_mfma_f32_16x16x32_f16 v[20:23], v[148:151], v[188:191], v[20:23]
	v_mfma_f32_16x16x32_f16 v[24:27], v[152:155], v[188:191], v[24:27]
	v_mfma_f32_16x16x32_f16 v[28:31], v[156:159], v[188:191], v[28:31]
	v_mfma_f32_16x16x32_f16 v[32:35], v[160:163], v[188:191], v[32:35]
	v_mfma_f32_16x16x32_f16 v[36:39], v[148:151], v[192:195], v[36:39]
	v_mfma_f32_16x16x32_f16 v[40:43], v[152:155], v[192:195], v[40:43]
	v_mfma_f32_16x16x32_f16 v[44:47], v[156:159], v[192:195], v[44:47]
	v_mfma_f32_16x16x32_f16 v[48:51], v[160:163], v[192:195], v[48:51]
	v_mfma_f32_16x16x32_f16 v[52:55], v[148:151], v[196:199], v[52:55]
	v_mfma_f32_16x16x32_f16 v[56:59], v[152:155], v[196:199], v[56:59]
	v_mfma_f32_16x16x32_f16 v[60:63], v[156:159], v[196:199], v[60:63]
	v_mfma_f32_16x16x32_f16 v[64:67], v[160:163], v[196:199], v[64:67]
	s_waitcnt lgkmcnt(0)
	s_barrier
	v_mfma_f32_16x16x32_f16 v[68:71], v[148:151], v[238:241], v[68:71]
	v_mfma_f32_16x16x32_f16 v[72:75], v[152:155], v[238:241], v[72:75]
	v_mfma_f32_16x16x32_f16 v[76:79], v[156:159], v[238:241], v[76:79]
	v_mfma_f32_16x16x32_f16 v[80:83], v[160:163], v[238:241], v[80:83]
	v_mfma_f32_16x16x32_f16 v[84:87], v[148:151], v[242:245], v[84:87]
	v_mfma_f32_16x16x32_f16 v[88:91], v[152:155], v[242:245], v[88:91]
	v_mfma_f32_16x16x32_f16 v[92:95], v[156:159], v[242:245], v[92:95]
	v_mfma_f32_16x16x32_f16 v[96:99], v[160:163], v[242:245], v[96:99]
	v_mfma_f32_16x16x32_f16 v[100:103], v[148:151], v[246:249], v[100:103]
	v_mfma_f32_16x16x32_f16 v[104:107], v[152:155], v[246:249], v[104:107]
	v_mfma_f32_16x16x32_f16 v[108:111], v[156:159], v[246:249], v[108:111]
	v_mfma_f32_16x16x32_f16 v[112:115], v[160:163], v[246:249], v[112:115]
	v_mfma_f32_16x16x32_f16 v[116:119], v[148:151], v[250:253], v[116:119]
	v_mfma_f32_16x16x32_f16 v[120:123], v[152:155], v[250:253], v[120:123]
	v_mfma_f32_16x16x32_f16 v[124:127], v[156:159], v[250:253], v[124:127]
	v_mfma_f32_16x16x32_f16 v[128:131], v[160:163], v[250:253], v[128:131]
	s_lshl_b64 s[80:81], s[28:29], 13
	s_add_u32 s80, s80, s34
	s_addc_u32 s81, s81, s35
	s_lshl_b32 s82, s65, 1
	s_add_u32 s80, s80, s82
	s_addc_u32 s81, s81, 0
	v_and_b32_e32 v172, 15, v200
	v_bfe_u32 v173, v200, 4, 2
	v_bfe_u32 v174, v200, 6, 2
	v_bfe_u32 v175, v200, 8, 1
	v_lshl_or_b32 v175, v175, 7, v172
	v_lshlrev_b32_e32 v175, 13, v175
	v_lshlrev_b32_e32 v174, 6, v174
	v_lshl_or_b32 v174, v173, 2, v174
	v_lshl_add_u32 v177, v174, 1, v175
	v_and_b32_e32 v172, 1, v173
	v_mul_u32_u24_e32 v172, 24, v172
	v_add_u32_e32 v177, v177, v172
	v_max_f32_e32 v4, 0, v4
	v_max_f32_e32 v5, 0, v5
	v_max_f32_e32 v6, 0, v6
	v_max_f32_e32 v7, 0, v7
	v_pk_mul_f32 v[4:5], v[4:5], v[4:5]
	v_pk_mul_f32 v[6:7], v[6:7], v[6:7]
	v_cvt_pk_f16_f32 v172, v4, v5
	v_cvt_pk_f16_f32 v173, v6, v7
	v_max_f32_e32 v8, 0, v8
	v_max_f32_e32 v9, 0, v9
	v_max_f32_e32 v10, 0, v10
	v_max_f32_e32 v11, 0, v11
	v_pk_mul_f32 v[8:9], v[8:9], v[8:9]
	v_pk_mul_f32 v[10:11], v[10:11], v[10:11]
	v_cvt_pk_f16_f32 v174, v8, v9
	v_cvt_pk_f16_f32 v175, v10, v11
	s_nop 1
	v_permlane16_swap_b32_e32 v172, v174
	v_permlane16_swap_b32_e32 v173, v175
	global_store_dwordx4 v177, v[172:175], s[80:81]
	v_max_f32_e32 v12, 0, v12
	v_max_f32_e32 v13, 0, v13
	v_max_f32_e32 v14, 0, v14
	v_max_f32_e32 v15, 0, v15
	v_pk_mul_f32 v[12:13], v[12:13], v[12:13]
	v_pk_mul_f32 v[14:15], v[14:15], v[14:15]
	v_cvt_pk_f16_f32 v228, v12, v13
	v_cvt_pk_f16_f32 v229, v14, v15
	v_max_f32_e32 v16, 0, v16
	v_max_f32_e32 v17, 0, v17
	v_max_f32_e32 v18, 0, v18
	v_max_f32_e32 v19, 0, v19
	v_pk_mul_f32 v[16:17], v[16:17], v[16:17]
	v_pk_mul_f32 v[18:19], v[18:19], v[18:19]
	v_cvt_pk_f16_f32 v230, v16, v17
	v_cvt_pk_f16_f32 v231, v18, v19
	s_nop 1
	v_permlane16_swap_b32_e32 v228, v230
	v_permlane16_swap_b32_e32 v229, v231
	global_store_dwordx4 v177, v[228:231], s[80:81] offset:64
	v_add_u32_e32 v177, 0x20000, v177
	v_max_f32_e32 v20, 0, v20
	v_max_f32_e32 v21, 0, v21
	v_max_f32_e32 v22, 0, v22
	v_max_f32_e32 v23, 0, v23
	v_pk_mul_f32 v[20:21], v[20:21], v[20:21]
	v_pk_mul_f32 v[22:23], v[22:23], v[22:23]
	v_cvt_pk_f16_f32 v172, v20, v21
	v_cvt_pk_f16_f32 v173, v22, v23
	v_max_f32_e32 v24, 0, v24
	v_max_f32_e32 v25, 0, v25
	v_max_f32_e32 v26, 0, v26
	v_max_f32_e32 v27, 0, v27
	v_pk_mul_f32 v[24:25], v[24:25], v[24:25]
	v_pk_mul_f32 v[26:27], v[26:27], v[26:27]
	v_cvt_pk_f16_f32 v174, v24, v25
	v_cvt_pk_f16_f32 v175, v26, v27
	s_nop 1
	v_permlane16_swap_b32_e32 v172, v174
	v_permlane16_swap_b32_e32 v173, v175
	global_store_dwordx4 v177, v[172:175], s[80:81]
	v_max_f32_e32 v28, 0, v28
	v_max_f32_e32 v29, 0, v29
	v_max_f32_e32 v30, 0, v30
	v_max_f32_e32 v31, 0, v31
	v_pk_mul_f32 v[28:29], v[28:29], v[28:29]
	v_pk_mul_f32 v[30:31], v[30:31], v[30:31]
	v_cvt_pk_f16_f32 v228, v28, v29
	v_cvt_pk_f16_f32 v229, v30, v31
	v_max_f32_e32 v32, 0, v32
	v_max_f32_e32 v33, 0, v33
	v_max_f32_e32 v34, 0, v34
	v_max_f32_e32 v35, 0, v35
	v_pk_mul_f32 v[32:33], v[32:33], v[32:33]
	v_pk_mul_f32 v[34:35], v[34:35], v[34:35]
	v_cvt_pk_f16_f32 v230, v32, v33
	v_cvt_pk_f16_f32 v231, v34, v35
	s_nop 1
	v_permlane16_swap_b32_e32 v228, v230
	v_permlane16_swap_b32_e32 v229, v231
	global_store_dwordx4 v177, v[228:231], s[80:81] offset:64
	v_add_u32_e32 v177, 0x20000, v177
	v_max_f32_e32 v36, 0, v36
	v_max_f32_e32 v37, 0, v37
	v_max_f32_e32 v38, 0, v38
	v_max_f32_e32 v39, 0, v39
	v_pk_mul_f32 v[36:37], v[36:37], v[36:37]
	v_pk_mul_f32 v[38:39], v[38:39], v[38:39]
	v_cvt_pk_f16_f32 v172, v36, v37
	v_cvt_pk_f16_f32 v173, v38, v39
	v_max_f32_e32 v40, 0, v40
	v_max_f32_e32 v41, 0, v41
	v_max_f32_e32 v42, 0, v42
	v_max_f32_e32 v43, 0, v43
	v_pk_mul_f32 v[40:41], v[40:41], v[40:41]
	v_pk_mul_f32 v[42:43], v[42:43], v[42:43]
	v_cvt_pk_f16_f32 v174, v40, v41
	v_cvt_pk_f16_f32 v175, v42, v43
	s_nop 1
	v_permlane16_swap_b32_e32 v172, v174
	v_permlane16_swap_b32_e32 v173, v175
	global_store_dwordx4 v177, v[172:175], s[80:81]
	v_max_f32_e32 v44, 0, v44
	v_max_f32_e32 v45, 0, v45
	v_max_f32_e32 v46, 0, v46
	v_max_f32_e32 v47, 0, v47
	v_pk_mul_f32 v[44:45], v[44:45], v[44:45]
	v_pk_mul_f32 v[46:47], v[46:47], v[46:47]
	v_cvt_pk_f16_f32 v228, v44, v45
	v_cvt_pk_f16_f32 v229, v46, v47
	v_max_f32_e32 v48, 0, v48
	v_max_f32_e32 v49, 0, v49
	v_max_f32_e32 v50, 0, v50
	v_max_f32_e32 v51, 0, v51
	v_pk_mul_f32 v[48:49], v[48:49], v[48:49]
	v_pk_mul_f32 v[50:51], v[50:51], v[50:51]
	v_cvt_pk_f16_f32 v230, v48, v49
	v_cvt_pk_f16_f32 v231, v50, v51
	s_nop 1
	v_permlane16_swap_b32_e32 v228, v230
	v_permlane16_swap_b32_e32 v229, v231
	global_store_dwordx4 v177, v[228:231], s[80:81] offset:64
	v_add_u32_e32 v177, 0x20000, v177
	v_max_f32_e32 v52, 0, v52
	v_max_f32_e32 v53, 0, v53
	v_max_f32_e32 v54, 0, v54
	v_max_f32_e32 v55, 0, v55
	v_pk_mul_f32 v[52:53], v[52:53], v[52:53]
	v_pk_mul_f32 v[54:55], v[54:55], v[54:55]
	v_cvt_pk_f16_f32 v172, v52, v53
	v_cvt_pk_f16_f32 v173, v54, v55
	v_max_f32_e32 v56, 0, v56
	v_max_f32_e32 v57, 0, v57
	v_max_f32_e32 v58, 0, v58
	v_max_f32_e32 v59, 0, v59
	v_pk_mul_f32 v[56:57], v[56:57], v[56:57]
	v_pk_mul_f32 v[58:59], v[58:59], v[58:59]
	v_cvt_pk_f16_f32 v174, v56, v57
	v_cvt_pk_f16_f32 v175, v58, v59
	s_nop 1
	v_permlane16_swap_b32_e32 v172, v174
	v_permlane16_swap_b32_e32 v173, v175
	global_store_dwordx4 v177, v[172:175], s[80:81]
	v_max_f32_e32 v60, 0, v60
	v_max_f32_e32 v61, 0, v61
	v_max_f32_e32 v62, 0, v62
	v_max_f32_e32 v63, 0, v63
	v_pk_mul_f32 v[60:61], v[60:61], v[60:61]
	v_pk_mul_f32 v[62:63], v[62:63], v[62:63]
	v_cvt_pk_f16_f32 v228, v60, v61
	v_cvt_pk_f16_f32 v229, v62, v63
	v_max_f32_e32 v64, 0, v64
	v_max_f32_e32 v65, 0, v65
	v_max_f32_e32 v66, 0, v66
	v_max_f32_e32 v67, 0, v67
	v_pk_mul_f32 v[64:65], v[64:65], v[64:65]
	v_pk_mul_f32 v[66:67], v[66:67], v[66:67]
	v_cvt_pk_f16_f32 v230, v64, v65
	v_cvt_pk_f16_f32 v231, v66, v67
	s_nop 1
	v_permlane16_swap_b32_e32 v228, v230
	v_permlane16_swap_b32_e32 v229, v231
	global_store_dwordx4 v177, v[228:231], s[80:81] offset:64
	v_add_u32_e32 v177, 0x20000, v177
	v_max_f32_e32 v68, 0, v68
	v_max_f32_e32 v69, 0, v69
	v_max_f32_e32 v70, 0, v70
	v_max_f32_e32 v71, 0, v71
	v_pk_mul_f32 v[68:69], v[68:69], v[68:69]
	v_pk_mul_f32 v[70:71], v[70:71], v[70:71]
	v_cvt_pk_f16_f32 v172, v68, v69
	v_cvt_pk_f16_f32 v173, v70, v71
	v_max_f32_e32 v72, 0, v72
	v_max_f32_e32 v73, 0, v73
	v_max_f32_e32 v74, 0, v74
	v_max_f32_e32 v75, 0, v75
	v_pk_mul_f32 v[72:73], v[72:73], v[72:73]
	v_pk_mul_f32 v[74:75], v[74:75], v[74:75]
	v_cvt_pk_f16_f32 v174, v72, v73
	v_cvt_pk_f16_f32 v175, v74, v75
	s_nop 1
	v_permlane16_swap_b32_e32 v172, v174
	v_permlane16_swap_b32_e32 v173, v175
	global_store_dwordx4 v177, v[172:175], s[80:81]
	v_max_f32_e32 v76, 0, v76
	v_max_f32_e32 v77, 0, v77
	v_max_f32_e32 v78, 0, v78
	v_max_f32_e32 v79, 0, v79
	v_pk_mul_f32 v[76:77], v[76:77], v[76:77]
	v_pk_mul_f32 v[78:79], v[78:79], v[78:79]
	v_cvt_pk_f16_f32 v228, v76, v77
	v_cvt_pk_f16_f32 v229, v78, v79
	v_max_f32_e32 v80, 0, v80
	v_max_f32_e32 v81, 0, v81
	v_max_f32_e32 v82, 0, v82
	v_max_f32_e32 v83, 0, v83
	v_pk_mul_f32 v[80:81], v[80:81], v[80:81]
	v_pk_mul_f32 v[82:83], v[82:83], v[82:83]
	v_cvt_pk_f16_f32 v230, v80, v81
	v_cvt_pk_f16_f32 v231, v82, v83
	s_nop 1
	v_permlane16_swap_b32_e32 v228, v230
	v_permlane16_swap_b32_e32 v229, v231
	global_store_dwordx4 v177, v[228:231], s[80:81] offset:64
	v_add_u32_e32 v177, 0x20000, v177
	v_max_f32_e32 v84, 0, v84
	v_max_f32_e32 v85, 0, v85
	v_max_f32_e32 v86, 0, v86
	v_max_f32_e32 v87, 0, v87
	v_pk_mul_f32 v[84:85], v[84:85], v[84:85]
	v_pk_mul_f32 v[86:87], v[86:87], v[86:87]
	v_cvt_pk_f16_f32 v172, v84, v85
	v_cvt_pk_f16_f32 v173, v86, v87
	v_max_f32_e32 v88, 0, v88
	v_max_f32_e32 v89, 0, v89
	v_max_f32_e32 v90, 0, v90
	v_max_f32_e32 v91, 0, v91
	v_pk_mul_f32 v[88:89], v[88:89], v[88:89]
	v_pk_mul_f32 v[90:91], v[90:91], v[90:91]
	v_cvt_pk_f16_f32 v174, v88, v89
	v_cvt_pk_f16_f32 v175, v90, v91
	s_nop 1
	v_permlane16_swap_b32_e32 v172, v174
	v_permlane16_swap_b32_e32 v173, v175
	global_store_dwordx4 v177, v[172:175], s[80:81]
	v_max_f32_e32 v92, 0, v92
	v_max_f32_e32 v93, 0, v93
	v_max_f32_e32 v94, 0, v94
	v_max_f32_e32 v95, 0, v95
	v_pk_mul_f32 v[92:93], v[92:93], v[92:93]
	v_pk_mul_f32 v[94:95], v[94:95], v[94:95]
	v_cvt_pk_f16_f32 v228, v92, v93
	v_cvt_pk_f16_f32 v229, v94, v95
	v_max_f32_e32 v96, 0, v96
	v_max_f32_e32 v97, 0, v97
	v_max_f32_e32 v98, 0, v98
	v_max_f32_e32 v99, 0, v99
	v_pk_mul_f32 v[96:97], v[96:97], v[96:97]
	v_pk_mul_f32 v[98:99], v[98:99], v[98:99]
	v_cvt_pk_f16_f32 v230, v96, v97
	v_cvt_pk_f16_f32 v231, v98, v99
	s_nop 1
	v_permlane16_swap_b32_e32 v228, v230
	v_permlane16_swap_b32_e32 v229, v231
	global_store_dwordx4 v177, v[228:231], s[80:81] offset:64
	v_add_u32_e32 v177, 0x20000, v177
	v_max_f32_e32 v100, 0, v100
	v_max_f32_e32 v101, 0, v101
	v_max_f32_e32 v102, 0, v102
	v_max_f32_e32 v103, 0, v103
	v_pk_mul_f32 v[100:101], v[100:101], v[100:101]
	v_pk_mul_f32 v[102:103], v[102:103], v[102:103]
	v_cvt_pk_f16_f32 v172, v100, v101
	v_cvt_pk_f16_f32 v173, v102, v103
	v_max_f32_e32 v104, 0, v104
	v_max_f32_e32 v105, 0, v105
	v_max_f32_e32 v106, 0, v106
	v_max_f32_e32 v107, 0, v107
	v_pk_mul_f32 v[104:105], v[104:105], v[104:105]
	v_pk_mul_f32 v[106:107], v[106:107], v[106:107]
	v_cvt_pk_f16_f32 v174, v104, v105
	v_cvt_pk_f16_f32 v175, v106, v107
	s_nop 1
	v_permlane16_swap_b32_e32 v172, v174
	v_permlane16_swap_b32_e32 v173, v175
	global_store_dwordx4 v177, v[172:175], s[80:81]
	v_max_f32_e32 v108, 0, v108
	v_max_f32_e32 v109, 0, v109
	v_max_f32_e32 v110, 0, v110
	v_max_f32_e32 v111, 0, v111
	v_pk_mul_f32 v[108:109], v[108:109], v[108:109]
	v_pk_mul_f32 v[110:111], v[110:111], v[110:111]
	v_cvt_pk_f16_f32 v228, v108, v109
	v_cvt_pk_f16_f32 v229, v110, v111
	v_max_f32_e32 v112, 0, v112
	v_max_f32_e32 v113, 0, v113
	v_max_f32_e32 v114, 0, v114
	v_max_f32_e32 v115, 0, v115
	v_pk_mul_f32 v[112:113], v[112:113], v[112:113]
	v_pk_mul_f32 v[114:115], v[114:115], v[114:115]
	v_cvt_pk_f16_f32 v230, v112, v113
	v_cvt_pk_f16_f32 v231, v114, v115
	s_nop 1
	v_permlane16_swap_b32_e32 v228, v230
	v_permlane16_swap_b32_e32 v229, v231
	global_store_dwordx4 v177, v[228:231], s[80:81] offset:64
	v_add_u32_e32 v177, 0x20000, v177
	v_max_f32_e32 v116, 0, v116
	v_max_f32_e32 v117, 0, v117
	v_max_f32_e32 v118, 0, v118
	v_max_f32_e32 v119, 0, v119
	v_pk_mul_f32 v[116:117], v[116:117], v[116:117]
	v_pk_mul_f32 v[118:119], v[118:119], v[118:119]
	v_cvt_pk_f16_f32 v172, v116, v117
	v_cvt_pk_f16_f32 v173, v118, v119
	v_max_f32_e32 v120, 0, v120
	v_max_f32_e32 v121, 0, v121
	v_max_f32_e32 v122, 0, v122
	v_max_f32_e32 v123, 0, v123
	v_pk_mul_f32 v[120:121], v[120:121], v[120:121]
	v_pk_mul_f32 v[122:123], v[122:123], v[122:123]
	v_cvt_pk_f16_f32 v174, v120, v121
	v_cvt_pk_f16_f32 v175, v122, v123
	s_nop 1
	v_permlane16_swap_b32_e32 v172, v174
	v_permlane16_swap_b32_e32 v173, v175
	global_store_dwordx4 v177, v[172:175], s[80:81]
	v_max_f32_e32 v124, 0, v124
	v_max_f32_e32 v125, 0, v125
	v_max_f32_e32 v126, 0, v126
	v_max_f32_e32 v127, 0, v127
	v_pk_mul_f32 v[124:125], v[124:125], v[124:125]
	v_pk_mul_f32 v[126:127], v[126:127], v[126:127]
	v_cvt_pk_f16_f32 v228, v124, v125
	v_cvt_pk_f16_f32 v229, v126, v127
	v_max_f32_e32 v128, 0, v128
	v_max_f32_e32 v129, 0, v129
	v_max_f32_e32 v130, 0, v130
	v_max_f32_e32 v131, 0, v131
	v_pk_mul_f32 v[128:129], v[128:129], v[128:129]
	v_pk_mul_f32 v[130:131], v[130:131], v[130:131]
	v_cvt_pk_f16_f32 v230, v128, v129
	v_cvt_pk_f16_f32 v231, v130, v131
	s_nop 1
	v_permlane16_swap_b32_e32 v228, v230
	v_permlane16_swap_b32_e32 v229, v231
	global_store_dwordx4 v177, v[228:231], s[80:81] offset:64
	s_nop 1
	s_add_i32 s56, s56, s76
	s_cmp_ge_i32 s56, s58
	s_cbranch_scc1 .LBB0_127
	s_branch .LBB0_111

.Lt_out1:
	v_add_u32_e32 v169, s37, v164
	v_mfma_f32_16x16x32_f16 v[4:7], v[132:135], v[184:187], v[4:7]
	ds_read_b128 v[238:241], v169 offset:4112
	v_mfma_f32_16x16x32_f16 v[8:11], v[136:139], v[184:187], v[8:11]
	ds_read_b128 v[242:245], v169 offset:5136
	v_mfma_f32_16x16x32_f16 v[12:15], v[140:143], v[184:187], v[12:15]
	ds_read_b128 v[246:249], v169 offset:6160
	v_mfma_f32_16x16x32_f16 v[16:19], v[144:147], v[184:187], v[16:19]
	ds_read_b128 v[250:253], v169 offset:7184
	v_mfma_f32_16x16x32_f16 v[20:23], v[132:135], v[188:191], v[20:23]
	v_mfma_f32_16x16x32_f16 v[24:27], v[136:139], v[188:191], v[24:27]
	v_mfma_f32_16x16x32_f16 v[28:31], v[140:143], v[188:191], v[28:31]
	v_mfma_f32_16x16x32_f16 v[32:35], v[144:147], v[188:191], v[32:35]
	v_mfma_f32_16x16x32_f16 v[36:39], v[132:135], v[192:195], v[36:39]
	v_mfma_f32_16x16x32_f16 v[40:43], v[136:139], v[192:195], v[40:43]
	v_mfma_f32_16x16x32_f16 v[44:47], v[140:143], v[192:195], v[44:47]
	v_mfma_f32_16x16x32_f16 v[48:51], v[144:147], v[192:195], v[48:51]
	v_mfma_f32_16x16x32_f16 v[52:55], v[132:135], v[196:199], v[52:55]
	v_mfma_f32_16x16x32_f16 v[56:59], v[136:139], v[196:199], v[56:59]
	v_mfma_f32_16x16x32_f16 v[60:63], v[140:143], v[196:199], v[60:63]
	v_mfma_f32_16x16x32_f16 v[64:67], v[144:147], v[196:199], v[64:67]
	s_waitcnt vmcnt(8) lgkmcnt(0)
	s_barrier
	s_add_i32 s52, s37, 0x8000
	s_cmp_lg_u32 s37, 0x18000
	s_cselect_b32 s52, s52, 0
	v_add_u32_e32 v168, s52, v165
	v_add_u32_e32 v169, s52, v164
	s_add_u32 vcc_lo, s32, s37
	v_mfma_f32_16x16x32_f16 v[68:71], v[132:135], v[238:241], v[68:71]
	ds_read_b128 v[148:151], v168 offset:16
	ds_read_b128 v[184:187], v169 offset:16
	s_mov_b32 m0, vcc_lo
	s_nop 0
	global_load_lds_dwordx4 v170, s[28:29]
	v_mfma_f32_16x16x32_f16 v[72:75], v[136:139], v[238:241], v[72:75]
	ds_read_b128 v[152:155], v168 offset:1040
	ds_read_b128 v[188:191], v169 offset:1040
	s_add_u32 m0, vcc_lo, 0x400
	s_nop 0
	global_load_lds_dwordx4 v171, s[28:29]
	v_mfma_f32_16x16x32_f16 v[76:79], v[140:143], v[238:241], v[76:79]
	ds_read_b128 v[156:159], v168 offset:2064
	ds_read_b128 v[192:195], v169 offset:2064
	s_add_u32 m0, vcc_lo, 0x4000
	s_nop 0
	global_load_lds_dwordx4 v170, s[30:31]
	v_mfma_f32_16x16x32_f16 v[80:83], v[144:147], v[238:241], v[80:83]
	ds_read_b128 v[160:163], v168 offset:3088
	ds_read_b128 v[196:199], v169 offset:3088
	s_add_u32 m0, vcc_lo, 0x4400
	s_nop 0
	global_load_lds_dwordx4 v171, s[30:31]
	v_mfma_f32_16x16x32_f16 v[84:87], v[132:135], v[242:245], v[84:87]
	v_mfma_f32_16x16x32_f16 v[88:91], v[136:139], v[242:245], v[88:91]
	v_mfma_f32_16x16x32_f16 v[92:95], v[140:143], v[242:245], v[92:95]
	v_mfma_f32_16x16x32_f16 v[96:99], v[144:147], v[242:245], v[96:99]
	v_mfma_f32_16x16x32_f16 v[100:103], v[132:135], v[246:249], v[100:103]
	v_mfma_f32_16x16x32_f16 v[104:107], v[136:139], v[246:249], v[104:107]
	v_mfma_f32_16x16x32_f16 v[108:111], v[140:143], v[246:249], v[108:111]
	v_mfma_f32_16x16x32_f16 v[112:115], v[144:147], v[246:249], v[112:115]
	v_mfma_f32_16x16x32_f16 v[116:119], v[132:135], v[250:253], v[116:119]
	v_mfma_f32_16x16x32_f16 v[120:123], v[136:139], v[250:253], v[120:123]
	v_mfma_f32_16x16x32_f16 v[124:127], v[140:143], v[250:253], v[124:127]
	v_mfma_f32_16x16x32_f16 v[128:131], v[144:147], v[250:253], v[128:131]
	s_waitcnt lgkmcnt(0)
	s_mov_b32 s37, s52
	s_add_u32 s28, s28, 64
	s_addc_u32 s29, s29, 0
	s_add_u32 s30, s30, 64
	s_addc_u32 s31, s31, 0
	v_add_u32_e32 v169, s37, v164
	v_mfma_f32_16x16x32_f16 v[4:7], v[148:151], v[184:187], v[4:7]
	ds_read_b128 v[238:241], v169 offset:4112
	v_mfma_f32_16x16x32_f16 v[8:11], v[152:155], v[184:187], v[8:11]
	ds_read_b128 v[242:245], v169 offset:5136
	v_mfma_f32_16x16x32_f16 v[12:15], v[156:159], v[184:187], v[12:15]
	ds_read_b128 v[246:249], v169 offset:6160
	v_mfma_f32_16x16x32_f16 v[16:19], v[160:163], v[184:187], v[16:19]
	ds_read_b128 v[250:253], v169 offset:7184
	v_mfma_f32_16x16x32_f16 v[20:23], v[148:151], v[188:191], v[20:23]
	v_mfma_f32_16x16x32_f16 v[24:27], v[152:155], v[188:191], v[24:27]
	v_mfma_f32_16x16x32_f16 v[28:31], v[156:159], v[188:191], v[28:31]
	v_mfma_f32_16x16x32_f16 v[32:35], v[160:163], v[188:191], v[32:35]
	v_mfma_f32_16x16x32_f16 v[36:39], v[148:151], v[192:195], v[36:39]
	v_mfma_f32_16x16x32_f16 v[40:43], v[152:155], v[192:195], v[40:43]
	v_mfma_f32_16x16x32_f16 v[44:47], v[156:159], v[192:195], v[44:47]
	v_mfma_f32_16x16x32_f16 v[48:51], v[160:163], v[192:195], v[48:51]
	v_mfma_f32_16x16x32_f16 v[52:55], v[148:151], v[196:199], v[52:55]
	v_mfma_f32_16x16x32_f16 v[56:59], v[152:155], v[196:199], v[56:59]
	v_mfma_f32_16x16x32_f16 v[60:63], v[156:159], v[196:199], v[60:63]
	v_mfma_f32_16x16x32_f16 v[64:67], v[160:163], v[196:199], v[64:67]
	s_waitcnt vmcnt(8) lgkmcnt(0)
	s_barrier
	s_add_i32 s52, s37, 0x8000
	s_cmp_lg_u32 s37, 0x18000
	s_cselect_b32 s52, s52, 0
	v_add_u32_e32 v168, s52, v165
	v_add_u32_e32 v169, s52, v164
	s_add_u32 vcc_lo, s32, s37
	v_mfma_f32_16x16x32_f16 v[68:71], v[148:151], v[238:241], v[68:71]
	ds_read_b128 v[132:135], v168 offset:16
	ds_read_b128 v[184:187], v169 offset:16
	s_mov_b32 m0, vcc_lo
	s_nop 0
	global_load_lds_dwordx4 v170, s[28:29]
	v_mfma_f32_16x16x32_f16 v[72:75], v[152:155], v[238:241], v[72:75]
	ds_read_b128 v[136:139], v168 offset:1040
	ds_read_b128 v[188:191], v169 offset:1040
	s_add_u32 m0, vcc_lo, 0x400
	s_nop 0
	global_load_lds_dwordx4 v171, s[28:29]
	v_mfma_f32_16x16x32_f16 v[76:79], v[156:159], v[238:241], v[76:79]
	ds_read_b128 v[140:143], v168 offset:2064
	ds_read_b128 v[192:195], v169 offset:2064
	s_add_u32 m0, vcc_lo, 0x4000
	s_nop 0
	global_load_lds_dwordx4 v170, s[30:31]
	v_mfma_f32_16x16x32_f16 v[80:83], v[160:163], v[238:241], v[80:83]
	ds_read_b128 v[144:147], v168 offset:3088
	ds_read_b128 v[196:199], v169 offset:3088
	s_add_u32 m0, vcc_lo, 0x4400
	s_nop 0
	global_load_lds_dwordx4 v171, s[30:31]
	v_mfma_f32_16x16x32_f16 v[84:87], v[148:151], v[242:245], v[84:87]
	v_mfma_f32_16x16x32_f16 v[88:91], v[152:155], v[242:245], v[88:91]
	v_mfma_f32_16x16x32_f16 v[92:95], v[156:159], v[242:245], v[92:95]
	v_mfma_f32_16x16x32_f16 v[96:99], v[160:163], v[242:245], v[96:99]
	v_mfma_f32_16x16x32_f16 v[100:103], v[148:151], v[246:249], v[100:103]
	v_mfma_f32_16x16x32_f16 v[104:107], v[152:155], v[246:249], v[104:107]
	v_mfma_f32_16x16x32_f16 v[108:111], v[156:159], v[246:249], v[108:111]
	v_mfma_f32_16x16x32_f16 v[112:115], v[160:163], v[246:249], v[112:115]
	v_mfma_f32_16x16x32_f16 v[116:119], v[148:151], v[250:253], v[116:119]
	v_mfma_f32_16x16x32_f16 v[120:123], v[152:155], v[250:253], v[120:123]
	v_mfma_f32_16x16x32_f16 v[124:127], v[156:159], v[250:253], v[124:127]
	v_mfma_f32_16x16x32_f16 v[128:131], v[160:163], v[250:253], v[128:131]
	s_waitcnt lgkmcnt(0)
	s_mov_b32 s37, s52
	s_add_u32 s28, s28, 64
	s_addc_u32 s29, s29, 0
	s_add_u32 s30, s30, 64
	s_addc_u32 s31, s31, 0
	s_add_i32 s53, s53, 2
	s_cmp_lt_u32 s53, 28
	s_cbranch_scc1 .Lt_out1
	v_add_u32_e32 v169, s37, v164
	v_mfma_f32_16x16x32_f16 v[4:7], v[132:135], v[184:187], v[4:7]
	ds_read_b128 v[238:241], v169 offset:4112
	v_mfma_f32_16x16x32_f16 v[8:11], v[136:139], v[184:187], v[8:11]
	ds_read_b128 v[242:245], v169 offset:5136
	v_mfma_f32_16x16x32_f16 v[12:15], v[140:143], v[184:187], v[12:15]
	ds_read_b128 v[246:249], v169 offset:6160
	v_mfma_f32_16x16x32_f16 v[16:19], v[144:147], v[184:187], v[16:19]
	ds_read_b128 v[250:253], v169 offset:7184
	v_mfma_f32_16x16x32_f16 v[20:23], v[132:135], v[188:191], v[20:23]
	v_mfma_f32_16x16x32_f16 v[24:27], v[136:139], v[188:191], v[24:27]
	v_mfma_f32_16x16x32_f16 v[28:31], v[140:143], v[188:191], v[28:31]
	v_mfma_f32_16x16x32_f16 v[32:35], v[144:147], v[188:191], v[32:35]
	v_mfma_f32_16x16x32_f16 v[36:39], v[132:135], v[192:195], v[36:39]
	v_mfma_f32_16x16x32_f16 v[40:43], v[136:139], v[192:195], v[40:43]
	v_mfma_f32_16x16x32_f16 v[44:47], v[140:143], v[192:195], v[44:47]
	v_mfma_f32_16x16x32_f16 v[48:51], v[144:147], v[192:195], v[48:51]
	v_mfma_f32_16x16x32_f16 v[52:55], v[132:135], v[196:199], v[52:55]
	v_mfma_f32_16x16x32_f16 v[56:59], v[136:139], v[196:199], v[56:59]
	v_mfma_f32_16x16x32_f16 v[60:63], v[140:143], v[196:199], v[60:63]
	v_mfma_f32_16x16x32_f16 v[64:67], v[144:147], v[196:199], v[64:67]
	s_waitcnt vmcnt(8) lgkmcnt(0)
	s_barrier
	s_add_i32 s52, s37, 0x8000
	s_cmp_lg_u32 s37, 0x18000
	s_cselect_b32 s52, s52, 0
	v_add_u32_e32 v168, s52, v165
	v_add_u32_e32 v169, s52, v164
	v_mfma_f32_16x16x32_f16 v[68:71], v[132:135], v[238:241], v[68:71]
	ds_read_b128 v[148:151], v168 offset:16
	ds_read_b128 v[184:187], v169 offset:16
	v_mfma_f32_16x16x32_f16 v[72:75], v[136:139], v[238:241], v[72:75]
	ds_read_b128 v[152:155], v168 offset:1040
	ds_read_b128 v[188:191], v169 offset:1040
	v_mfma_f32_16x16x32_f16 v[76:79], v[140:143], v[238:241], v[76:79]
	ds_read_b128 v[156:159], v168 offset:2064
	ds_read_b128 v[192:195], v169 offset:2064
	v_mfma_f32_16x16x32_f16 v[80:83], v[144:147], v[238:241], v[80:83]
	ds_read_b128 v[160:163], v168 offset:3088
	ds_read_b128 v[196:199], v169 offset:3088
	v_mfma_f32_16x16x32_f16 v[84:87], v[132:135], v[242:245], v[84:87]
	v_mfma_f32_16x16x32_f16 v[88:91], v[136:139], v[242:245], v[88:91]
	v_mfma_f32_16x16x32_f16 v[92:95], v[140:143], v[242:245], v[92:95]
	v_mfma_f32_16x16x32_f16 v[96:99], v[144:147], v[242:245], v[96:99]
	v_mfma_f32_16x16x32_f16 v[100:103], v[132:135], v[246:249], v[100:103]
	v_mfma_f32_16x16x32_f16 v[104:107], v[136:139], v[246:249], v[104:107]
	v_mfma_f32_16x16x32_f16 v[108:111], v[140:143], v[246:249], v[108:111]
	v_mfma_f32_16x16x32_f16 v[112:115], v[144:147], v[246:249], v[112:115]
	v_mfma_f32_16x16x32_f16 v[116:119], v[132:135], v[250:253], v[116:119]
	v_mfma_f32_16x16x32_f16 v[120:123], v[136:139], v[250:253], v[120:123]
	v_mfma_f32_16x16x32_f16 v[124:127], v[140:143], v[250:253], v[124:127]
	v_mfma_f32_16x16x32_f16 v[128:131], v[144:147], v[250:253], v[128:131]
	s_waitcnt lgkmcnt(0)
	s_mov_b32 s37, s52
	v_add_u32_e32 v169, s37, v164
	v_mfma_f32_16x16x32_f16 v[4:7], v[148:151], v[184:187], v[4:7]
	ds_read_b128 v[238:241], v169 offset:4112
	v_mfma_f32_16x16x32_f16 v[8:11], v[152:155], v[184:187], v[8:11]
	ds_read_b128 v[242:245], v169 offset:5136
	v_mfma_f32_16x16x32_f16 v[12:15], v[156:159], v[184:187], v[12:15]
	ds_read_b128 v[246:249], v169 offset:6160
	v_mfma_f32_16x16x32_f16 v[16:19], v[160:163], v[184:187], v[16:19]
	ds_read_b128 v[250:253], v169 offset:7184
	v_mfma_f32_16x16x32_f16 v[20:23], v[148:151], v[188:191], v[20:23]
	v_mfma_f32_16x16x32_f16 v[24:27], v[152:155], v[188:191], v[24:27]
	v_mfma_f32_16x16x32_f16 v[28:31], v[156:159], v[188:191], v[28:31]
	v_mfma_f32_16x16x32_f16 v[32:35], v[160:163], v[188:191], v[32:35]
	v_mfma_f32_16x16x32_f16 v[36:39], v[148:151], v[192:195], v[36:39]
	v_mfma_f32_16x16x32_f16 v[40:43], v[152:155], v[192:195], v[40:43]
	v_mfma_f32_16x16x32_f16 v[44:47], v[156:159], v[192:195], v[44:47]
	v_mfma_f32_16x16x32_f16 v[48:51], v[160:163], v[192:195], v[48:51]
	v_mfma_f32_16x16x32_f16 v[52:55], v[148:151], v[196:199], v[52:55]
	v_mfma_f32_16x16x32_f16 v[56:59], v[152:155], v[196:199], v[56:59]
	v_mfma_f32_16x16x32_f16 v[60:63], v[156:159], v[196:199], v[60:63]
	v_mfma_f32_16x16x32_f16 v[64:67], v[160:163], v[196:199], v[64:67]
	s_waitcnt vmcnt(4) lgkmcnt(0)
	s_barrier
	s_add_i32 s52, s37, 0x8000
	s_cmp_lg_u32 s37, 0x18000
	s_cselect_b32 s52, s52, 0
	v_add_u32_e32 v168, s52, v165
	v_add_u32_e32 v169, s52, v164
	v_mfma_f32_16x16x32_f16 v[68:71], v[148:151], v[238:241], v[68:71]
	ds_read_b128 v[132:135], v168 offset:16
	ds_read_b128 v[184:187], v169 offset:16
	v_mfma_f32_16x16x32_f16 v[72:75], v[152:155], v[238:241], v[72:75]
	ds_read_b128 v[136:139], v168 offset:1040
	ds_read_b128 v[188:191], v169 offset:1040
	v_mfma_f32_16x16x32_f16 v[76:79], v[156:159], v[238:241], v[76:79]
	ds_read_b128 v[140:143], v168 offset:2064
	ds_read_b128 v[192:195], v169 offset:2064
	v_mfma_f32_16x16x32_f16 v[80:83], v[160:163], v[238:241], v[80:83]
	ds_read_b128 v[144:147], v168 offset:3088
	ds_read_b128 v[196:199], v169 offset:3088
	v_mfma_f32_16x16x32_f16 v[84:87], v[148:151], v[242:245], v[84:87]
	v_mfma_f32_16x16x32_f16 v[88:91], v[152:155], v[242:245], v[88:91]
	v_mfma_f32_16x16x32_f16 v[92:95], v[156:159], v[242:245], v[92:95]
	v_mfma_f32_16x16x32_f16 v[96:99], v[160:163], v[242:245], v[96:99]
	v_mfma_f32_16x16x32_f16 v[100:103], v[148:151], v[246:249], v[100:103]
	v_mfma_f32_16x16x32_f16 v[104:107], v[152:155], v[246:249], v[104:107]
	v_mfma_f32_16x16x32_f16 v[108:111], v[156:159], v[246:249], v[108:111]
	v_mfma_f32_16x16x32_f16 v[112:115], v[160:163], v[246:249], v[112:115]
	v_mfma_f32_16x16x32_f16 v[116:119], v[148:151], v[250:253], v[116:119]
	v_mfma_f32_16x16x32_f16 v[120:123], v[152:155], v[250:253], v[120:123]
	v_mfma_f32_16x16x32_f16 v[124:127], v[156:159], v[250:253], v[124:127]
	v_mfma_f32_16x16x32_f16 v[128:131], v[160:163], v[250:253], v[128:131]
	s_waitcnt lgkmcnt(0)
	s_mov_b32 s37, s52
	v_add_u32_e32 v169, s37, v164
	v_mfma_f32_16x16x32_f16 v[4:7], v[132:135], v[184:187], v[4:7]
	ds_read_b128 v[238:241], v169 offset:4112
	v_mfma_f32_16x16x32_f16 v[8:11], v[136:139], v[184:187], v[8:11]
	ds_read_b128 v[242:245], v169 offset:5136
	v_mfma_f32_16x16x32_f16 v[12:15], v[140:143], v[184:187], v[12:15]
	ds_read_b128 v[246:249], v169 offset:6160
	v_mfma_f32_16x16x32_f16 v[16:19], v[144:147], v[184:187], v[16:19]
	ds_read_b128 v[250:253], v169 offset:7184
	v_mfma_f32_16x16x32_f16 v[20:23], v[132:135], v[188:191], v[20:23]
	v_mfma_f32_16x16x32_f16 v[24:27], v[136:139], v[188:191], v[24:27]
	v_mfma_f32_16x16x32_f16 v[28:31], v[140:143], v[188:191], v[28:31]
	v_mfma_f32_16x16x32_f16 v[32:35], v[144:147], v[188:191], v[32:35]
	v_mfma_f32_16x16x32_f16 v[36:39], v[132:135], v[192:195], v[36:39]
	v_mfma_f32_16x16x32_f16 v[40:43], v[136:139], v[192:195], v[40:43]
	v_mfma_f32_16x16x32_f16 v[44:47], v[140:143], v[192:195], v[44:47]
	v_mfma_f32_16x16x32_f16 v[48:51], v[144:147], v[192:195], v[48:51]
	v_mfma_f32_16x16x32_f16 v[52:55], v[132:135], v[196:199], v[52:55]
	v_mfma_f32_16x16x32_f16 v[56:59], v[136:139], v[196:199], v[56:59]
	v_mfma_f32_16x16x32_f16 v[60:63], v[140:143], v[196:199], v[60:63]
	v_mfma_f32_16x16x32_f16 v[64:67], v[144:147], v[196:199], v[64:67]
	s_waitcnt vmcnt(0) lgkmcnt(0)
	s_barrier
	s_add_i32 s52, s37, 0x8000
	s_cmp_lg_u32 s37, 0x18000
	s_cselect_b32 s52, s52, 0
	v_add_u32_e32 v168, s52, v165
	v_add_u32_e32 v169, s52, v164
	v_mfma_f32_16x16x32_f16 v[68:71], v[132:135], v[238:241], v[68:71]
	ds_read_b128 v[148:151], v168 offset:16
	ds_read_b128 v[184:187], v169 offset:16
	v_mfma_f32_16x16x32_f16 v[72:75], v[136:139], v[238:241], v[72:75]
	ds_read_b128 v[152:155], v168 offset:1040
	ds_read_b128 v[188:191], v169 offset:1040
	v_mfma_f32_16x16x32_f16 v[76:79], v[140:143], v[238:241], v[76:79]
	ds_read_b128 v[156:159], v168 offset:2064
	ds_read_b128 v[192:195], v169 offset:2064
	v_mfma_f32_16x16x32_f16 v[80:83], v[144:147], v[238:241], v[80:83]
	ds_read_b128 v[160:163], v168 offset:3088
	ds_read_b128 v[196:199], v169 offset:3088
	v_mfma_f32_16x16x32_f16 v[84:87], v[132:135], v[242:245], v[84:87]
	v_mfma_f32_16x16x32_f16 v[88:91], v[136:139], v[242:245], v[88:91]
	v_mfma_f32_16x16x32_f16 v[92:95], v[140:143], v[242:245], v[92:95]
	v_mfma_f32_16x16x32_f16 v[96:99], v[144:147], v[242:245], v[96:99]
	v_mfma_f32_16x16x32_f16 v[100:103], v[132:135], v[246:249], v[100:103]
	v_mfma_f32_16x16x32_f16 v[104:107], v[136:139], v[246:249], v[104:107]
	v_mfma_f32_16x16x32_f16 v[108:111], v[140:143], v[246:249], v[108:111]
	v_mfma_f32_16x16x32_f16 v[112:115], v[144:147], v[246:249], v[112:115]
	v_mfma_f32_16x16x32_f16 v[116:119], v[132:135], v[250:253], v[116:119]
	v_mfma_f32_16x16x32_f16 v[120:123], v[136:139], v[250:253], v[120:123]
	v_mfma_f32_16x16x32_f16 v[124:127], v[140:143], v[250:253], v[124:127]
	v_mfma_f32_16x16x32_f16 v[128:131], v[144:147], v[250:253], v[128:131]
	s_waitcnt lgkmcnt(0)
	s_mov_b32 s37, s52
	v_add_u32_e32 v169, s37, v164
	v_mfma_f32_16x16x32_f16 v[4:7], v[148:151], v[184:187], v[4:7]
	ds_read_b128 v[238:241], v169 offset:4112
	v_mfma_f32_16x16x32_f16 v[8:11], v[152:155], v[184:187], v[8:11]
	ds_read_b128 v[242:245], v169 offset:5136
	v_mfma_f32_16x16x32_f16 v[12:15], v[156:159], v[184:187], v[12:15]
	ds_read_b128 v[246:249], v169 offset:6160
	v_mfma_f32_16x16x32_f16 v[16:19], v[160:163], v[184:187], v[16:19]
	ds_read_b128 v[250:253], v169 offset:7184
	v_mfma_f32_16x16x32_f16 v[20:23], v[148:151], v[188:191], v[20:23]
	v_mfma_f32_16x16x32_f16 v[24:27], v[152:155], v[188:191], v[24:27]
	v_mfma_f32_16x16x32_f16 v[28:31], v[156:159], v[188:191], v[28:31]
	v_mfma_f32_16x16x32_f16 v[32:35], v[160:163], v[188:191], v[32:35]
	v_mfma_f32_16x16x32_f16 v[36:39], v[148:151], v[192:195], v[36:39]
	v_mfma_f32_16x16x32_f16 v[40:43], v[152:155], v[192:195], v[40:43]
	v_mfma_f32_16x16x32_f16 v[44:47], v[156:159], v[192:195], v[44:47]
	v_mfma_f32_16x16x32_f16 v[48:51], v[160:163], v[192:195], v[48:51]
	v_mfma_f32_16x16x32_f16 v[52:55], v[148:151], v[196:199], v[52:55]
	v_mfma_f32_16x16x32_f16 v[56:59], v[152:155], v[196:199], v[56:59]
	v_mfma_f32_16x16x32_f16 v[60:63], v[156:159], v[196:199], v[60:63]
	v_mfma_f32_16x16x32_f16 v[64:67], v[160:163], v[196:199], v[64:67]
	s_waitcnt lgkmcnt(0)
	s_barrier
	v_mfma_f32_16x16x32_f16 v[68:71], v[148:151], v[238:241], v[68:71]
	v_mfma_f32_16x16x32_f16 v[72:75], v[152:155], v[238:241], v[72:75]
	v_mfma_f32_16x16x32_f16 v[76:79], v[156:159], v[238:241], v[76:79]
	v_mfma_f32_16x16x32_f16 v[80:83], v[160:163], v[238:241], v[80:83]
	v_mfma_f32_16x16x32_f16 v[84:87], v[148:151], v[242:245], v[84:87]
	v_mfma_f32_16x16x32_f16 v[88:91], v[152:155], v[242:245], v[88:91]
	v_mfma_f32_16x16x32_f16 v[92:95], v[156:159], v[242:245], v[92:95]
	v_mfma_f32_16x16x32_f16 v[96:99], v[160:163], v[242:245], v[96:99]
	v_mfma_f32_16x16x32_f16 v[100:103], v[148:151], v[246:249], v[100:103]
	v_mfma_f32_16x16x32_f16 v[104:107], v[152:155], v[246:249], v[104:107]
	v_mfma_f32_16x16x32_f16 v[108:111], v[156:159], v[246:249], v[108:111]
	v_mfma_f32_16x16x32_f16 v[112:115], v[160:163], v[246:249], v[112:115]
	v_mfma_f32_16x16x32_f16 v[116:119], v[148:151], v[250:253], v[116:119]
	v_mfma_f32_16x16x32_f16 v[120:123], v[152:155], v[250:253], v[120:123]
	v_mfma_f32_16x16x32_f16 v[124:127], v[156:159], v[250:253], v[124:127]
	v_mfma_f32_16x16x32_f16 v[128:131], v[160:163], v[250:253], v[128:131]
	s_sub_u32 s77, s36, 0x1000
	s_lshr_b32 s77, s77, 12
	s_add_u32 s77, s77, 1
	s_cmp_lt_u32 s36, 0x1000
	s_cselect_b32 s77, 0, s77
	s_mul_i32 s77, s77, 0x6000
	s_add_u32 s68, s26, s77
	s_addc_u32 s69, s27, 0
	s_add_u32 s68, s68, 0x20000
	s_addc_u32 s69, s69, 0
	s_lshl_b32 s82, s36, 11
	s_add_u32 s80, s46, s82
	s_addc_u32 s81, s47, 0
	s_lshl_b32 s82, s35, 1
	s_add_u32 s80, s80, s82
	s_addc_u32 s81, s81, 0
	v_and_b32_e32 v172, 15, v200
	v_bfe_u32 v173, v200, 4, 2
	v_bfe_u32 v174, v200, 6, 2
	v_bfe_u32 v175, v200, 8, 1
	v_lshlrev_b32_e32 v176, 6, v174
	v_lshl_or_b32 v176, v173, 2, v176
	v_lshl_or_b32 v175, v175, 7, v172
	v_lshlrev_b32_e32 v175, 11, v175
	v_lshl_add_u32 v177, v176, 1, v175
	v_add_u32_e32 v176, s35, v176
	v_lshlrev_b32_e32 v176, 2, v176
	global_load_dwordx4 v[132:135], v176, s[68:69]
	global_load_dwordx4 v[136:139], v176, s[68:69] offset:64
	global_load_dwordx4 v[140:143], v176, s[68:69] offset:128
	global_load_dwordx4 v[144:147], v176, s[68:69] offset:192
	v_and_b32_e32 v172, 1, v173
	v_mul_u32_u24_e32 v172, 24, v172
	v_add_u32_e32 v177, v177, v172
	v_mov_b32_e32 v178, v177
	global_load_dwordx4 v[184:187], v178, s[80:81]
	global_load_dwordx4 v[188:191], v178, s[80:81] offset:64
	v_add_u32_e32 v178, 0x8000, v178
	global_load_dwordx4 v[238:241], v178, s[80:81]
	global_load_dwordx4 v[242:245], v178, s[80:81] offset:64
	s_waitcnt vmcnt(3)
	v_permlane16_swap_b32_e32 v184, v186
	v_permlane16_swap_b32_e32 v185, v187
	v_cvt_f32_f16_e32 v164, v184
	v_cvt_f32_f16_sdwa v165, v184 dst_sel:DWORD dst_unused:UNUSED_PAD src0_sel:WORD_1
	v_cvt_f32_f16_e32 v166, v185
	v_cvt_f32_f16_sdwa v167, v185 dst_sel:DWORD dst_unused:UNUSED_PAD src0_sel:WORD_1
	v_pk_mul_f32 v[164:165], v[164:165], s[84:85] op_sel_hi:[1,0]
	v_pk_mul_f32 v[166:167], v[166:167], s[84:85] op_sel_hi:[1,0]
	v_pk_fma_f32 v[4:5], v[4:5], v[132:133], v[164:165]
	v_pk_fma_f32 v[6:7], v[6:7], v[134:135], v[166:167]
	v_cvt_pk_f16_f32 v172, v4, v5
	v_cvt_pk_f16_f32 v173, v6, v7
	v_cvt_f32_f16_e32 v164, v186
	v_cvt_f32_f16_sdwa v165, v186 dst_sel:DWORD dst_unused:UNUSED_PAD src0_sel:WORD_1
	v_cvt_f32_f16_e32 v166, v187
	v_cvt_f32_f16_sdwa v167, v187 dst_sel:DWORD dst_unused:UNUSED_PAD src0_sel:WORD_1
	v_pk_mul_f32 v[164:165], v[164:165], s[84:85] op_sel_hi:[1,0]
	v_pk_mul_f32 v[166:167], v[166:167], s[84:85] op_sel_hi:[1,0]
	v_pk_fma_f32 v[8:9], v[8:9], v[136:137], v[164:165]
	v_pk_fma_f32 v[10:11], v[10:11], v[138:139], v[166:167]
	v_cvt_pk_f16_f32 v174, v8, v9
	v_cvt_pk_f16_f32 v175, v10, v11
	s_nop 1
	v_permlane16_swap_b32_e32 v172, v174
	v_permlane16_swap_b32_e32 v173, v175
	global_store_dwordx4 v177, v[172:175], s[80:81]
	s_waitcnt vmcnt(3)
	v_permlane16_swap_b32_e32 v188, v190
	v_permlane16_swap_b32_e32 v189, v191
	v_cvt_f32_f16_e32 v164, v188
	v_cvt_f32_f16_sdwa v165, v188 dst_sel:DWORD dst_unused:UNUSED_PAD src0_sel:WORD_1
	v_cvt_f32_f16_e32 v166, v189
	v_cvt_f32_f16_sdwa v167, v189 dst_sel:DWORD dst_unused:UNUSED_PAD src0_sel:WORD_1
	v_pk_mul_f32 v[164:165], v[164:165], s[84:85] op_sel_hi:[1,0]
	v_pk_mul_f32 v[166:167], v[166:167], s[84:85] op_sel_hi:[1,0]
	v_pk_fma_f32 v[12:13], v[12:13], v[140:141], v[164:165]
	v_pk_fma_f32 v[14:15], v[14:15], v[142:143], v[166:167]
	v_cvt_pk_f16_f32 v228, v12, v13
	v_cvt_pk_f16_f32 v229, v14, v15
	v_cvt_f32_f16_e32 v164, v190
	v_cvt_f32_f16_sdwa v165, v190 dst_sel:DWORD dst_unused:UNUSED_PAD src0_sel:WORD_1
	v_cvt_f32_f16_e32 v166, v191
	v_cvt_f32_f16_sdwa v167, v191 dst_sel:DWORD dst_unused:UNUSED_PAD src0_sel:WORD_1
	v_pk_mul_f32 v[164:165], v[164:165], s[84:85] op_sel_hi:[1,0]
	v_pk_mul_f32 v[166:167], v[166:167], s[84:85] op_sel_hi:[1,0]
	v_pk_fma_f32 v[16:17], v[16:17], v[144:145], v[164:165]
	v_pk_fma_f32 v[18:19], v[18:19], v[146:147], v[166:167]
	v_cvt_pk_f16_f32 v230, v16, v17
	v_cvt_pk_f16_f32 v231, v18, v19
	s_nop 1
	v_permlane16_swap_b32_e32 v228, v230
	v_permlane16_swap_b32_e32 v229, v231
	global_store_dwordx4 v177, v[228:231], s[80:81] offset:64
	v_add_u32_e32 v177, 0x8000, v177
	v_add_u32_e32 v178, 0x8000, v178
	global_load_dwordx4 v[184:187], v178, s[80:81]
	global_load_dwordx4 v[188:191], v178, s[80:81] offset:64
	s_waitcnt vmcnt(5)
	v_permlane16_swap_b32_e32 v238, v240
	v_permlane16_swap_b32_e32 v239, v241
	v_cvt_f32_f16_e32 v164, v238
	v_cvt_f32_f16_sdwa v165, v238 dst_sel:DWORD dst_unused:UNUSED_PAD src0_sel:WORD_1
	v_cvt_f32_f16_e32 v166, v239
	v_cvt_f32_f16_sdwa v167, v239 dst_sel:DWORD dst_unused:UNUSED_PAD src0_sel:WORD_1
	v_pk_mul_f32 v[164:165], v[164:165], s[84:85] op_sel_hi:[1,0]
	v_pk_mul_f32 v[166:167], v[166:167], s[84:85] op_sel_hi:[1,0]
	v_pk_fma_f32 v[20:21], v[20:21], v[132:133], v[164:165]
	v_pk_fma_f32 v[22:23], v[22:23], v[134:135], v[166:167]
	v_cvt_pk_f16_f32 v172, v20, v21
	v_cvt_pk_f16_f32 v173, v22, v23
	v_cvt_f32_f16_e32 v164, v240
	v_cvt_f32_f16_sdwa v165, v240 dst_sel:DWORD dst_unused:UNUSED_PAD src0_sel:WORD_1
	v_cvt_f32_f16_e32 v166, v241
	v_cvt_f32_f16_sdwa v167, v241 dst_sel:DWORD dst_unused:UNUSED_PAD src0_sel:WORD_1
	v_pk_mul_f32 v[164:165], v[164:165], s[84:85] op_sel_hi:[1,0]
	v_pk_mul_f32 v[166:167], v[166:167], s[84:85] op_sel_hi:[1,0]
	v_pk_fma_f32 v[24:25], v[24:25], v[136:137], v[164:165]
	v_pk_fma_f32 v[26:27], v[26:27], v[138:139], v[166:167]
	v_cvt_pk_f16_f32 v174, v24, v25
	v_cvt_pk_f16_f32 v175, v26, v27
	s_nop 1
	v_permlane16_swap_b32_e32 v172, v174
	v_permlane16_swap_b32_e32 v173, v175
	global_store_dwordx4 v177, v[172:175], s[80:81]
	s_waitcnt vmcnt(5)
	v_permlane16_swap_b32_e32 v242, v244
	v_permlane16_swap_b32_e32 v243, v245
	v_cvt_f32_f16_e32 v164, v242
	v_cvt_f32_f16_sdwa v165, v242 dst_sel:DWORD dst_unused:UNUSED_PAD src0_sel:WORD_1
	v_cvt_f32_f16_e32 v166, v243
	v_cvt_f32_f16_sdwa v167, v243 dst_sel:DWORD dst_unused:UNUSED_PAD src0_sel:WORD_1
	v_pk_mul_f32 v[164:165], v[164:165], s[84:85] op_sel_hi:[1,0]
	v_pk_mul_f32 v[166:167], v[166:167], s[84:85] op_sel_hi:[1,0]
	v_pk_fma_f32 v[28:29], v[28:29], v[140:141], v[164:165]
	v_pk_fma_f32 v[30:31], v[30:31], v[142:143], v[166:167]
	v_cvt_pk_f16_f32 v228, v28, v29
	v_cvt_pk_f16_f32 v229, v30, v31
	v_cvt_f32_f16_e32 v164, v244
	v_cvt_f32_f16_sdwa v165, v244 dst_sel:DWORD dst_unused:UNUSED_PAD src0_sel:WORD_1
	v_cvt_f32_f16_e32 v166, v245
	v_cvt_f32_f16_sdwa v167, v245 dst_sel:DWORD dst_unused:UNUSED_PAD src0_sel:WORD_1
	v_pk_mul_f32 v[164:165], v[164:165], s[84:85] op_sel_hi:[1,0]
	v_pk_mul_f32 v[166:167], v[166:167], s[84:85] op_sel_hi:[1,0]
	v_pk_fma_f32 v[32:33], v[32:33], v[144:145], v[164:165]
	v_pk_fma_f32 v[34:35], v[34:35], v[146:147], v[166:167]
	v_cvt_pk_f16_f32 v230, v32, v33
	v_cvt_pk_f16_f32 v231, v34, v35
	s_nop 1
	v_permlane16_swap_b32_e32 v228, v230
	v_permlane16_swap_b32_e32 v229, v231
	global_store_dwordx4 v177, v[228:231], s[80:81] offset:64
	v_add_u32_e32 v177, 0x8000, v177
	v_add_u32_e32 v178, 0x8000, v178
	global_load_dwordx4 v[238:241], v178, s[80:81]
	global_load_dwordx4 v[242:245], v178, s[80:81] offset:64
	s_waitcnt vmcnt(5)
	v_permlane16_swap_b32_e32 v184, v186
	v_permlane16_swap_b32_e32 v185, v187
	v_cvt_f32_f16_e32 v164, v184
	v_cvt_f32_f16_sdwa v165, v184 dst_sel:DWORD dst_unused:UNUSED_PAD src0_sel:WORD_1
	v_cvt_f32_f16_e32 v166, v185
	v_cvt_f32_f16_sdwa v167, v185 dst_sel:DWORD dst_unused:UNUSED_PAD src0_sel:WORD_1
	v_pk_mul_f32 v[164:165], v[164:165], s[84:85] op_sel_hi:[1,0]
	v_pk_mul_f32 v[166:167], v[166:167], s[84:85] op_sel_hi:[1,0]
	v_pk_fma_f32 v[36:37], v[36:37], v[132:133], v[164:165]
	v_pk_fma_f32 v[38:39], v[38:39], v[134:135], v[166:167]
	v_cvt_pk_f16_f32 v172, v36, v37
	v_cvt_pk_f16_f32 v173, v38, v39
	v_cvt_f32_f16_e32 v164, v186
	v_cvt_f32_f16_sdwa v165, v186 dst_sel:DWORD dst_unused:UNUSED_PAD src0_sel:WORD_1
	v_cvt_f32_f16_e32 v166, v187
	v_cvt_f32_f16_sdwa v167, v187 dst_sel:DWORD dst_unused:UNUSED_PAD src0_sel:WORD_1
	v_pk_mul_f32 v[164:165], v[164:165], s[84:85] op_sel_hi:[1,0]
	v_pk_mul_f32 v[166:167], v[166:167], s[84:85] op_sel_hi:[1,0]
	v_pk_fma_f32 v[40:41], v[40:41], v[136:137], v[164:165]
	v_pk_fma_f32 v[42:43], v[42:43], v[138:139], v[166:167]
	v_cvt_pk_f16_f32 v174, v40, v41
	v_cvt_pk_f16_f32 v175, v42, v43
	s_nop 1
	v_permlane16_swap_b32_e32 v172, v174
	v_permlane16_swap_b32_e32 v173, v175
	global_store_dwordx4 v177, v[172:175], s[80:81]
	s_waitcnt vmcnt(5)
	v_permlane16_swap_b32_e32 v188, v190
	v_permlane16_swap_b32_e32 v189, v191
	v_cvt_f32_f16_e32 v164, v188
	v_cvt_f32_f16_sdwa v165, v188 dst_sel:DWORD dst_unused:UNUSED_PAD src0_sel:WORD_1
	v_cvt_f32_f16_e32 v166, v189
	v_cvt_f32_f16_sdwa v167, v189 dst_sel:DWORD dst_unused:UNUSED_PAD src0_sel:WORD_1
	v_pk_mul_f32 v[164:165], v[164:165], s[84:85] op_sel_hi:[1,0]
	v_pk_mul_f32 v[166:167], v[166:167], s[84:85] op_sel_hi:[1,0]
	v_pk_fma_f32 v[44:45], v[44:45], v[140:141], v[164:165]
	v_pk_fma_f32 v[46:47], v[46:47], v[142:143], v[166:167]
	v_cvt_pk_f16_f32 v228, v44, v45
	v_cvt_pk_f16_f32 v229, v46, v47
	v_cvt_f32_f16_e32 v164, v190
	v_cvt_f32_f16_sdwa v165, v190 dst_sel:DWORD dst_unused:UNUSED_PAD src0_sel:WORD_1
	v_cvt_f32_f16_e32 v166, v191
	v_cvt_f32_f16_sdwa v167, v191 dst_sel:DWORD dst_unused:UNUSED_PAD src0_sel:WORD_1
	v_pk_mul_f32 v[164:165], v[164:165], s[84:85] op_sel_hi:[1,0]
	v_pk_mul_f32 v[166:167], v[166:167], s[84:85] op_sel_hi:[1,0]
	v_pk_fma_f32 v[48:49], v[48:49], v[144:145], v[164:165]
	v_pk_fma_f32 v[50:51], v[50:51], v[146:147], v[166:167]
	v_cvt_pk_f16_f32 v230, v48, v49
	v_cvt_pk_f16_f32 v231, v50, v51
	s_nop 1
	v_permlane16_swap_b32_e32 v228, v230
	v_permlane16_swap_b32_e32 v229, v231
	global_store_dwordx4 v177, v[228:231], s[80:81] offset:64
	v_add_u32_e32 v177, 0x8000, v177
	v_add_u32_e32 v178, 0x8000, v178
	global_load_dwordx4 v[184:187], v178, s[80:81]
	global_load_dwordx4 v[188:191], v178, s[80:81] offset:64
	s_waitcnt vmcnt(5)
	v_permlane16_swap_b32_e32 v238, v240
	v_permlane16_swap_b32_e32 v239, v241
	v_cvt_f32_f16_e32 v164, v238
	v_cvt_f32_f16_sdwa v165, v238 dst_sel:DWORD dst_unused:UNUSED_PAD src0_sel:WORD_1
	v_cvt_f32_f16_e32 v166, v239
	v_cvt_f32_f16_sdwa v167, v239 dst_sel:DWORD dst_unused:UNUSED_PAD src0_sel:WORD_1
	v_pk_mul_f32 v[164:165], v[164:165], s[84:85] op_sel_hi:[1,0]
	v_pk_mul_f32 v[166:167], v[166:167], s[84:85] op_sel_hi:[1,0]
	v_pk_fma_f32 v[52:53], v[52:53], v[132:133], v[164:165]
	v_pk_fma_f32 v[54:55], v[54:55], v[134:135], v[166:167]
	v_cvt_pk_f16_f32 v172, v52, v53
	v_cvt_pk_f16_f32 v173, v54, v55
	v_cvt_f32_f16_e32 v164, v240
	v_cvt_f32_f16_sdwa v165, v240 dst_sel:DWORD dst_unused:UNUSED_PAD src0_sel:WORD_1
	v_cvt_f32_f16_e32 v166, v241
	v_cvt_f32_f16_sdwa v167, v241 dst_sel:DWORD dst_unused:UNUSED_PAD src0_sel:WORD_1
	v_pk_mul_f32 v[164:165], v[164:165], s[84:85] op_sel_hi:[1,0]
	v_pk_mul_f32 v[166:167], v[166:167], s[84:85] op_sel_hi:[1,0]
	v_pk_fma_f32 v[56:57], v[56:57], v[136:137], v[164:165]
	v_pk_fma_f32 v[58:59], v[58:59], v[138:139], v[166:167]
	v_cvt_pk_f16_f32 v174, v56, v57
	v_cvt_pk_f16_f32 v175, v58, v59
	s_nop 1
	v_permlane16_swap_b32_e32 v172, v174
	v_permlane16_swap_b32_e32 v173, v175
	global_store_dwordx4 v177, v[172:175], s[80:81]
	s_waitcnt vmcnt(5)
	v_permlane16_swap_b32_e32 v242, v244
	v_permlane16_swap_b32_e32 v243, v245
	v_cvt_f32_f16_e32 v164, v242
	v_cvt_f32_f16_sdwa v165, v242 dst_sel:DWORD dst_unused:UNUSED_PAD src0_sel:WORD_1
	v_cvt_f32_f16_e32 v166, v243
	v_cvt_f32_f16_sdwa v167, v243 dst_sel:DWORD dst_unused:UNUSED_PAD src0_sel:WORD_1
	v_pk_mul_f32 v[164:165], v[164:165], s[84:85] op_sel_hi:[1,0]
	v_pk_mul_f32 v[166:167], v[166:167], s[84:85] op_sel_hi:[1,0]
	v_pk_fma_f32 v[60:61], v[60:61], v[140:141], v[164:165]
	v_pk_fma_f32 v[62:63], v[62:63], v[142:143], v[166:167]
	v_cvt_pk_f16_f32 v228, v60, v61
	v_cvt_pk_f16_f32 v229, v62, v63
	v_cvt_f32_f16_e32 v164, v244
	v_cvt_f32_f16_sdwa v165, v244 dst_sel:DWORD dst_unused:UNUSED_PAD src0_sel:WORD_1
	v_cvt_f32_f16_e32 v166, v245
	v_cvt_f32_f16_sdwa v167, v245 dst_sel:DWORD dst_unused:UNUSED_PAD src0_sel:WORD_1
	v_pk_mul_f32 v[164:165], v[164:165], s[84:85] op_sel_hi:[1,0]
	v_pk_mul_f32 v[166:167], v[166:167], s[84:85] op_sel_hi:[1,0]
	v_pk_fma_f32 v[64:65], v[64:65], v[144:145], v[164:165]
	v_pk_fma_f32 v[66:67], v[66:67], v[146:147], v[166:167]
	v_cvt_pk_f16_f32 v230, v64, v65
	v_cvt_pk_f16_f32 v231, v66, v67
	s_nop 1
	v_permlane16_swap_b32_e32 v228, v230
	v_permlane16_swap_b32_e32 v229, v231
	global_store_dwordx4 v177, v[228:231], s[80:81] offset:64
	v_add_u32_e32 v177, 0x8000, v177
	v_add_u32_e32 v178, 0x8000, v178
	global_load_dwordx4 v[238:241], v178, s[80:81]
	global_load_dwordx4 v[242:245], v178, s[80:81] offset:64
	s_waitcnt vmcnt(5)
	v_permlane16_swap_b32_e32 v184, v186
	v_permlane16_swap_b32_e32 v185, v187
	v_cvt_f32_f16_e32 v164, v184
	v_cvt_f32_f16_sdwa v165, v184 dst_sel:DWORD dst_unused:UNUSED_PAD src0_sel:WORD_1
	v_cvt_f32_f16_e32 v166, v185
	v_cvt_f32_f16_sdwa v167, v185 dst_sel:DWORD dst_unused:UNUSED_PAD src0_sel:WORD_1
	v_pk_mul_f32 v[164:165], v[164:165], s[84:85] op_sel_hi:[1,0]
	v_pk_mul_f32 v[166:167], v[166:167], s[84:85] op_sel_hi:[1,0]
	v_pk_fma_f32 v[68:69], v[68:69], v[132:133], v[164:165]
	v_pk_fma_f32 v[70:71], v[70:71], v[134:135], v[166:167]
	v_cvt_pk_f16_f32 v172, v68, v69
	v_cvt_pk_f16_f32 v173, v70, v71
	v_cvt_f32_f16_e32 v164, v186
	v_cvt_f32_f16_sdwa v165, v186 dst_sel:DWORD dst_unused:UNUSED_PAD src0_sel:WORD_1
	v_cvt_f32_f16_e32 v166, v187
	v_cvt_f32_f16_sdwa v167, v187 dst_sel:DWORD dst_unused:UNUSED_PAD src0_sel:WORD_1
	v_pk_mul_f32 v[164:165], v[164:165], s[84:85] op_sel_hi:[1,0]
	v_pk_mul_f32 v[166:167], v[166:167], s[84:85] op_sel_hi:[1,0]
	v_pk_fma_f32 v[72:73], v[72:73], v[136:137], v[164:165]
	v_pk_fma_f32 v[74:75], v[74:75], v[138:139], v[166:167]
	v_cvt_pk_f16_f32 v174, v72, v73
	v_cvt_pk_f16_f32 v175, v74, v75
	s_nop 1
	v_permlane16_swap_b32_e32 v172, v174
	v_permlane16_swap_b32_e32 v173, v175
	global_store_dwordx4 v177, v[172:175], s[80:81]
	s_waitcnt vmcnt(5)
	v_permlane16_swap_b32_e32 v188, v190
	v_permlane16_swap_b32_e32 v189, v191
	v_cvt_f32_f16_e32 v164, v188
	v_cvt_f32_f16_sdwa v165, v188 dst_sel:DWORD dst_unused:UNUSED_PAD src0_sel:WORD_1
	v_cvt_f32_f16_e32 v166, v189
	v_cvt_f32_f16_sdwa v167, v189 dst_sel:DWORD dst_unused:UNUSED_PAD src0_sel:WORD_1
	v_pk_mul_f32 v[164:165], v[164:165], s[84:85] op_sel_hi:[1,0]
	v_pk_mul_f32 v[166:167], v[166:167], s[84:85] op_sel_hi:[1,0]
	v_pk_fma_f32 v[76:77], v[76:77], v[140:141], v[164:165]
	v_pk_fma_f32 v[78:79], v[78:79], v[142:143], v[166:167]
	v_cvt_pk_f16_f32 v228, v76, v77
	v_cvt_pk_f16_f32 v229, v78, v79
	v_cvt_f32_f16_e32 v164, v190
	v_cvt_f32_f16_sdwa v165, v190 dst_sel:DWORD dst_unused:UNUSED_PAD src0_sel:WORD_1
	v_cvt_f32_f16_e32 v166, v191
	v_cvt_f32_f16_sdwa v167, v191 dst_sel:DWORD dst_unused:UNUSED_PAD src0_sel:WORD_1
	v_pk_mul_f32 v[164:165], v[164:165], s[84:85] op_sel_hi:[1,0]
	v_pk_mul_f32 v[166:167], v[166:167], s[84:85] op_sel_hi:[1,0]
	v_pk_fma_f32 v[80:81], v[80:81], v[144:145], v[164:165]
	v_pk_fma_f32 v[82:83], v[82:83], v[146:147], v[166:167]
	v_cvt_pk_f16_f32 v230, v80, v81
	v_cvt_pk_f16_f32 v231, v82, v83
	s_nop 1
	v_permlane16_swap_b32_e32 v228, v230
	v_permlane16_swap_b32_e32 v229, v231
	global_store_dwordx4 v177, v[228:231], s[80:81] offset:64
	v_add_u32_e32 v177, 0x8000, v177
	v_add_u32_e32 v178, 0x8000, v178
	global_load_dwordx4 v[184:187], v178, s[80:81]
	global_load_dwordx4 v[188:191], v178, s[80:81] offset:64
	s_waitcnt vmcnt(5)
	v_permlane16_swap_b32_e32 v238, v240
	v_permlane16_swap_b32_e32 v239, v241
	v_cvt_f32_f16_e32 v164, v238
	v_cvt_f32_f16_sdwa v165, v238 dst_sel:DWORD dst_unused:UNUSED_PAD src0_sel:WORD_1
	v_cvt_f32_f16_e32 v166, v239
	v_cvt_f32_f16_sdwa v167, v239 dst_sel:DWORD dst_unused:UNUSED_PAD src0_sel:WORD_1
	v_pk_mul_f32 v[164:165], v[164:165], s[84:85] op_sel_hi:[1,0]
	v_pk_mul_f32 v[166:167], v[166:167], s[84:85] op_sel_hi:[1,0]
	v_pk_fma_f32 v[84:85], v[84:85], v[132:133], v[164:165]
	v_pk_fma_f32 v[86:87], v[86:87], v[134:135], v[166:167]
	v_cvt_pk_f16_f32 v172, v84, v85
	v_cvt_pk_f16_f32 v173, v86, v87
	v_cvt_f32_f16_e32 v164, v240
	v_cvt_f32_f16_sdwa v165, v240 dst_sel:DWORD dst_unused:UNUSED_PAD src0_sel:WORD_1
	v_cvt_f32_f16_e32 v166, v241
	v_cvt_f32_f16_sdwa v167, v241 dst_sel:DWORD dst_unused:UNUSED_PAD src0_sel:WORD_1
	v_pk_mul_f32 v[164:165], v[164:165], s[84:85] op_sel_hi:[1,0]
	v_pk_mul_f32 v[166:167], v[166:167], s[84:85] op_sel_hi:[1,0]
	v_pk_fma_f32 v[88:89], v[88:89], v[136:137], v[164:165]
	v_pk_fma_f32 v[90:91], v[90:91], v[138:139], v[166:167]
	v_cvt_pk_f16_f32 v174, v88, v89
	v_cvt_pk_f16_f32 v175, v90, v91
	s_nop 1
	v_permlane16_swap_b32_e32 v172, v174
	v_permlane16_swap_b32_e32 v173, v175
	global_store_dwordx4 v177, v[172:175], s[80:81]
	s_waitcnt vmcnt(5)
	v_permlane16_swap_b32_e32 v242, v244
	v_permlane16_swap_b32_e32 v243, v245
	v_cvt_f32_f16_e32 v164, v242
	v_cvt_f32_f16_sdwa v165, v242 dst_sel:DWORD dst_unused:UNUSED_PAD src0_sel:WORD_1
	v_cvt_f32_f16_e32 v166, v243
	v_cvt_f32_f16_sdwa v167, v243 dst_sel:DWORD dst_unused:UNUSED_PAD src0_sel:WORD_1
	v_pk_mul_f32 v[164:165], v[164:165], s[84:85] op_sel_hi:[1,0]
	v_pk_mul_f32 v[166:167], v[166:167], s[84:85] op_sel_hi:[1,0]
	v_pk_fma_f32 v[92:93], v[92:93], v[140:141], v[164:165]
	v_pk_fma_f32 v[94:95], v[94:95], v[142:143], v[166:167]
	v_cvt_pk_f16_f32 v228, v92, v93
	v_cvt_pk_f16_f32 v229, v94, v95
	v_cvt_f32_f16_e32 v164, v244
	v_cvt_f32_f16_sdwa v165, v244 dst_sel:DWORD dst_unused:UNUSED_PAD src0_sel:WORD_1
	v_cvt_f32_f16_e32 v166, v245
	v_cvt_f32_f16_sdwa v167, v245 dst_sel:DWORD dst_unused:UNUSED_PAD src0_sel:WORD_1
	v_pk_mul_f32 v[164:165], v[164:165], s[84:85] op_sel_hi:[1,0]
	v_pk_mul_f32 v[166:167], v[166:167], s[84:85] op_sel_hi:[1,0]
	v_pk_fma_f32 v[96:97], v[96:97], v[144:145], v[164:165]
	v_pk_fma_f32 v[98:99], v[98:99], v[146:147], v[166:167]
	v_cvt_pk_f16_f32 v230, v96, v97
	v_cvt_pk_f16_f32 v231, v98, v99
	s_nop 1
	v_permlane16_swap_b32_e32 v228, v230
	v_permlane16_swap_b32_e32 v229, v231
	global_store_dwordx4 v177, v[228:231], s[80:81] offset:64
	v_add_u32_e32 v177, 0x8000, v177
	v_add_u32_e32 v178, 0x8000, v178
	global_load_dwordx4 v[238:241], v178, s[80:81]
	global_load_dwordx4 v[242:245], v178, s[80:81] offset:64
	s_waitcnt vmcnt(5)
	v_permlane16_swap_b32_e32 v184, v186
	v_permlane16_swap_b32_e32 v185, v187
	v_cvt_f32_f16_e32 v164, v184
	v_cvt_f32_f16_sdwa v165, v184 dst_sel:DWORD dst_unused:UNUSED_PAD src0_sel:WORD_1
	v_cvt_f32_f16_e32 v166, v185
	v_cvt_f32_f16_sdwa v167, v185 dst_sel:DWORD dst_unused:UNUSED_PAD src0_sel:WORD_1
	v_pk_mul_f32 v[164:165], v[164:165], s[84:85] op_sel_hi:[1,0]
	v_pk_mul_f32 v[166:167], v[166:167], s[84:85] op_sel_hi:[1,0]
	v_pk_fma_f32 v[100:101], v[100:101], v[132:133], v[164:165]
	v_pk_fma_f32 v[102:103], v[102:103], v[134:135], v[166:167]
	v_cvt_pk_f16_f32 v172, v100, v101
	v_cvt_pk_f16_f32 v173, v102, v103
	v_cvt_f32_f16_e32 v164, v186
	v_cvt_f32_f16_sdwa v165, v186 dst_sel:DWORD dst_unused:UNUSED_PAD src0_sel:WORD_1
	v_cvt_f32_f16_e32 v166, v187
	v_cvt_f32_f16_sdwa v167, v187 dst_sel:DWORD dst_unused:UNUSED_PAD src0_sel:WORD_1
	v_pk_mul_f32 v[164:165], v[164:165], s[84:85] op_sel_hi:[1,0]
	v_pk_mul_f32 v[166:167], v[166:167], s[84:85] op_sel_hi:[1,0]
	v_pk_fma_f32 v[104:105], v[104:105], v[136:137], v[164:165]
	v_pk_fma_f32 v[106:107], v[106:107], v[138:139], v[166:167]
	v_cvt_pk_f16_f32 v174, v104, v105
	v_cvt_pk_f16_f32 v175, v106, v107
	s_nop 1
	v_permlane16_swap_b32_e32 v172, v174
	v_permlane16_swap_b32_e32 v173, v175
	global_store_dwordx4 v177, v[172:175], s[80:81]
	s_waitcnt vmcnt(5)
	v_permlane16_swap_b32_e32 v188, v190
	v_permlane16_swap_b32_e32 v189, v191
	v_cvt_f32_f16_e32 v164, v188
	v_cvt_f32_f16_sdwa v165, v188 dst_sel:DWORD dst_unused:UNUSED_PAD src0_sel:WORD_1
	v_cvt_f32_f16_e32 v166, v189
	v_cvt_f32_f16_sdwa v167, v189 dst_sel:DWORD dst_unused:UNUSED_PAD src0_sel:WORD_1
	v_pk_mul_f32 v[164:165], v[164:165], s[84:85] op_sel_hi:[1,0]
	v_pk_mul_f32 v[166:167], v[166:167], s[84:85] op_sel_hi:[1,0]
	v_pk_fma_f32 v[108:109], v[108:109], v[140:141], v[164:165]
	v_pk_fma_f32 v[110:111], v[110:111], v[142:143], v[166:167]
	v_cvt_pk_f16_f32 v228, v108, v109
	v_cvt_pk_f16_f32 v229, v110, v111
	v_cvt_f32_f16_e32 v164, v190
	v_cvt_f32_f16_sdwa v165, v190 dst_sel:DWORD dst_unused:UNUSED_PAD src0_sel:WORD_1
	v_cvt_f32_f16_e32 v166, v191
	v_cvt_f32_f16_sdwa v167, v191 dst_sel:DWORD dst_unused:UNUSED_PAD src0_sel:WORD_1
	v_pk_mul_f32 v[164:165], v[164:165], s[84:85] op_sel_hi:[1,0]
	v_pk_mul_f32 v[166:167], v[166:167], s[84:85] op_sel_hi:[1,0]
	v_pk_fma_f32 v[112:113], v[112:113], v[144:145], v[164:165]
	v_pk_fma_f32 v[114:115], v[114:115], v[146:147], v[166:167]
	v_cvt_pk_f16_f32 v230, v112, v113
	v_cvt_pk_f16_f32 v231, v114, v115
	s_nop 1
	v_permlane16_swap_b32_e32 v228, v230
	v_permlane16_swap_b32_e32 v229, v231
	global_store_dwordx4 v177, v[228:231], s[80:81] offset:64
	v_add_u32_e32 v177, 0x8000, v177
	s_waitcnt vmcnt(3)
	v_permlane16_swap_b32_e32 v238, v240
	v_permlane16_swap_b32_e32 v239, v241
	v_cvt_f32_f16_e32 v164, v238
	v_cvt_f32_f16_sdwa v165, v238 dst_sel:DWORD dst_unused:UNUSED_PAD src0_sel:WORD_1
	v_cvt_f32_f16_e32 v166, v239
	v_cvt_f32_f16_sdwa v167, v239 dst_sel:DWORD dst_unused:UNUSED_PAD src0_sel:WORD_1
	v_pk_mul_f32 v[164:165], v[164:165], s[84:85] op_sel_hi:[1,0]
	v_pk_mul_f32 v[166:167], v[166:167], s[84:85] op_sel_hi:[1,0]
	v_pk_fma_f32 v[116:117], v[116:117], v[132:133], v[164:165]
	v_pk_fma_f32 v[118:119], v[118:119], v[134:135], v[166:167]
	v_cvt_pk_f16_f32 v172, v116, v117
	v_cvt_pk_f16_f32 v173, v118, v119
	v_cvt_f32_f16_e32 v164, v240
	v_cvt_f32_f16_sdwa v165, v240 dst_sel:DWORD dst_unused:UNUSED_PAD src0_sel:WORD_1
	v_cvt_f32_f16_e32 v166, v241
	v_cvt_f32_f16_sdwa v167, v241 dst_sel:DWORD dst_unused:UNUSED_PAD src0_sel:WORD_1
	v_pk_mul_f32 v[164:165], v[164:165], s[84:85] op_sel_hi:[1,0]
	v_pk_mul_f32 v[166:167], v[166:167], s[84:85] op_sel_hi:[1,0]
	v_pk_fma_f32 v[120:121], v[120:121], v[136:137], v[164:165]
	v_pk_fma_f32 v[122:123], v[122:123], v[138:139], v[166:167]
	v_cvt_pk_f16_f32 v174, v120, v121
	v_cvt_pk_f16_f32 v175, v122, v123
	s_nop 1
	v_permlane16_swap_b32_e32 v172, v174
	v_permlane16_swap_b32_e32 v173, v175
	global_store_dwordx4 v177, v[172:175], s[80:81]
	s_waitcnt vmcnt(3)
	v_permlane16_swap_b32_e32 v242, v244
	v_permlane16_swap_b32_e32 v243, v245
	v_cvt_f32_f16_e32 v164, v242
	v_cvt_f32_f16_sdwa v165, v242 dst_sel:DWORD dst_unused:UNUSED_PAD src0_sel:WORD_1
	v_cvt_f32_f16_e32 v166, v243
	v_cvt_f32_f16_sdwa v167, v243 dst_sel:DWORD dst_unused:UNUSED_PAD src0_sel:WORD_1
	v_pk_mul_f32 v[164:165], v[164:165], s[84:85] op_sel_hi:[1,0]
	v_pk_mul_f32 v[166:167], v[166:167], s[84:85] op_sel_hi:[1,0]
	v_pk_fma_f32 v[124:125], v[124:125], v[140:141], v[164:165]
	v_pk_fma_f32 v[126:127], v[126:127], v[142:143], v[166:167]
	v_cvt_pk_f16_f32 v228, v124, v125
	v_cvt_pk_f16_f32 v229, v126, v127
	v_cvt_f32_f16_e32 v164, v244
	v_cvt_f32_f16_sdwa v165, v244 dst_sel:DWORD dst_unused:UNUSED_PAD src0_sel:WORD_1
	v_cvt_f32_f16_e32 v166, v245
	v_cvt_f32_f16_sdwa v167, v245 dst_sel:DWORD dst_unused:UNUSED_PAD src0_sel:WORD_1
	v_pk_mul_f32 v[164:165], v[164:165], s[84:85] op_sel_hi:[1,0]
	v_pk_mul_f32 v[166:167], v[166:167], s[84:85] op_sel_hi:[1,0]
	v_pk_fma_f32 v[128:129], v[128:129], v[144:145], v[164:165]
	v_pk_fma_f32 v[130:131], v[130:131], v[146:147], v[166:167]
	v_cvt_pk_f16_f32 v230, v128, v129
	v_cvt_pk_f16_f32 v231, v130, v131
	s_nop 1
	v_permlane16_swap_b32_e32 v228, v230
	v_permlane16_swap_b32_e32 v229, v231
	global_store_dwordx4 v177, v[228:231], s[80:81] offset:64
	s_nop 1
	s_branch .LBB0_743

.Lt_qkv_v:
	v_add_u32_e32 v169, s42, v164
	v_mfma_f32_16x16x32_f16 v[4:7], v[184:187], v[132:135], v[4:7]
	ds_read_b128 v[238:241], v169 offset:4112
	v_mfma_f32_16x16x32_f16 v[8:11], v[184:187], v[136:139], v[8:11]
	ds_read_b128 v[242:245], v169 offset:5136
	v_mfma_f32_16x16x32_f16 v[12:15], v[184:187], v[140:143], v[12:15]
	ds_read_b128 v[246:249], v169 offset:6160
	v_mfma_f32_16x16x32_f16 v[16:19], v[184:187], v[144:147], v[16:19]
	ds_read_b128 v[250:253], v169 offset:7184
	v_mfma_f32_16x16x32_f16 v[20:23], v[188:191], v[132:135], v[20:23]
	v_mfma_f32_16x16x32_f16 v[24:27], v[188:191], v[136:139], v[24:27]
	v_mfma_f32_16x16x32_f16 v[28:31], v[188:191], v[140:143], v[28:31]
	v_mfma_f32_16x16x32_f16 v[32:35], v[188:191], v[144:147], v[32:35]
	v_mfma_f32_16x16x32_f16 v[36:39], v[192:195], v[132:135], v[36:39]
	v_mfma_f32_16x16x32_f16 v[40:43], v[192:195], v[136:139], v[40:43]
	v_mfma_f32_16x16x32_f16 v[44:47], v[192:195], v[140:143], v[44:47]
	v_mfma_f32_16x16x32_f16 v[48:51], v[192:195], v[144:147], v[48:51]
	v_mfma_f32_16x16x32_f16 v[52:55], v[196:199], v[132:135], v[52:55]
	v_mfma_f32_16x16x32_f16 v[56:59], v[196:199], v[136:139], v[56:59]
	v_mfma_f32_16x16x32_f16 v[60:63], v[196:199], v[140:143], v[60:63]
	v_mfma_f32_16x16x32_f16 v[64:67], v[196:199], v[144:147], v[64:67]
	s_waitcnt vmcnt(8) lgkmcnt(0)
	s_barrier
	s_add_i32 s43, s42, 0x8000
	s_cmp_lg_u32 s42, 0x18000
	s_cselect_b32 s43, s43, 0
	v_add_u32_e32 v168, s43, v165
	v_add_u32_e32 v169, s43, v164
	s_add_u32 vcc_lo, s32, s42
	v_mfma_f32_16x16x32_f16 v[68:71], v[238:241], v[132:135], v[68:71]
	ds_read_b128 v[148:151], v168 offset:16
	ds_read_b128 v[184:187], v169 offset:16
	s_mov_b32 m0, vcc_lo
	s_nop 0
	global_load_lds_dwordx4 v170, s[24:25]
	v_mfma_f32_16x16x32_f16 v[72:75], v[238:241], v[136:139], v[72:75]
	ds_read_b128 v[152:155], v168 offset:1040
	ds_read_b128 v[188:191], v169 offset:1040
	s_add_u32 m0, vcc_lo, 0x400
	s_nop 0
	global_load_lds_dwordx4 v171, s[24:25]
	v_mfma_f32_16x16x32_f16 v[76:79], v[238:241], v[140:143], v[76:79]
	ds_read_b128 v[156:159], v168 offset:2064
	ds_read_b128 v[192:195], v169 offset:2064
	s_add_u32 m0, vcc_lo, 0x4000
	s_nop 0
	global_load_lds_dwordx4 v170, s[28:29]
	v_mfma_f32_16x16x32_f16 v[80:83], v[238:241], v[144:147], v[80:83]
	ds_read_b128 v[160:163], v168 offset:3088
	ds_read_b128 v[196:199], v169 offset:3088
	s_add_u32 m0, vcc_lo, 0x4400
	s_nop 0
	global_load_lds_dwordx4 v171, s[28:29]
	v_mfma_f32_16x16x32_f16 v[84:87], v[242:245], v[132:135], v[84:87]
	v_mfma_f32_16x16x32_f16 v[88:91], v[242:245], v[136:139], v[88:91]
	v_mfma_f32_16x16x32_f16 v[92:95], v[242:245], v[140:143], v[92:95]
	v_mfma_f32_16x16x32_f16 v[96:99], v[242:245], v[144:147], v[96:99]
	v_mfma_f32_16x16x32_f16 v[100:103], v[246:249], v[132:135], v[100:103]
	v_mfma_f32_16x16x32_f16 v[104:107], v[246:249], v[136:139], v[104:107]
	v_mfma_f32_16x16x32_f16 v[108:111], v[246:249], v[140:143], v[108:111]
	v_mfma_f32_16x16x32_f16 v[112:115], v[246:249], v[144:147], v[112:115]
	v_mfma_f32_16x16x32_f16 v[116:119], v[250:253], v[132:135], v[116:119]
	v_mfma_f32_16x16x32_f16 v[120:123], v[250:253], v[136:139], v[120:123]
	v_mfma_f32_16x16x32_f16 v[124:127], v[250:253], v[140:143], v[124:127]
	v_mfma_f32_16x16x32_f16 v[128:131], v[250:253], v[144:147], v[128:131]
	s_waitcnt lgkmcnt(0)
	s_mov_b32 s42, s43
	s_add_u32 s24, s24, 64
	s_addc_u32 s25, s25, 0
	s_add_u32 s28, s28, 64
	s_addc_u32 s29, s29, 0
	v_add_u32_e32 v169, s42, v164
	v_mfma_f32_16x16x32_f16 v[4:7], v[184:187], v[148:151], v[4:7]
	ds_read_b128 v[238:241], v169 offset:4112
	v_mfma_f32_16x16x32_f16 v[8:11], v[184:187], v[152:155], v[8:11]
	ds_read_b128 v[242:245], v169 offset:5136
	v_mfma_f32_16x16x32_f16 v[12:15], v[184:187], v[156:159], v[12:15]
	ds_read_b128 v[246:249], v169 offset:6160
	v_mfma_f32_16x16x32_f16 v[16:19], v[184:187], v[160:163], v[16:19]
	ds_read_b128 v[250:253], v169 offset:7184
	v_mfma_f32_16x16x32_f16 v[20:23], v[188:191], v[148:151], v[20:23]
	v_mfma_f32_16x16x32_f16 v[24:27], v[188:191], v[152:155], v[24:27]
	v_mfma_f32_16x16x32_f16 v[28:31], v[188:191], v[156:159], v[28:31]
	v_mfma_f32_16x16x32_f16 v[32:35], v[188:191], v[160:163], v[32:35]
	v_mfma_f32_16x16x32_f16 v[36:39], v[192:195], v[148:151], v[36:39]
	v_mfma_f32_16x16x32_f16 v[40:43], v[192:195], v[152:155], v[40:43]
	v_mfma_f32_16x16x32_f16 v[44:47], v[192:195], v[156:159], v[44:47]
	v_mfma_f32_16x16x32_f16 v[48:51], v[192:195], v[160:163], v[48:51]
	v_mfma_f32_16x16x32_f16 v[52:55], v[196:199], v[148:151], v[52:55]
	v_mfma_f32_16x16x32_f16 v[56:59], v[196:199], v[152:155], v[56:59]
	v_mfma_f32_16x16x32_f16 v[60:63], v[196:199], v[156:159], v[60:63]
	v_mfma_f32_16x16x32_f16 v[64:67], v[196:199], v[160:163], v[64:67]
	s_waitcnt vmcnt(8) lgkmcnt(0)
	s_barrier
	s_add_i32 s43, s42, 0x8000
	s_cmp_lg_u32 s42, 0x18000
	s_cselect_b32 s43, s43, 0
	v_add_u32_e32 v168, s43, v165
	v_add_u32_e32 v169, s43, v164
	s_add_u32 vcc_lo, s32, s42
	v_mfma_f32_16x16x32_f16 v[68:71], v[238:241], v[148:151], v[68:71]
	ds_read_b128 v[132:135], v168 offset:16
	ds_read_b128 v[184:187], v169 offset:16
	s_mov_b32 m0, vcc_lo
	s_nop 0
	global_load_lds_dwordx4 v170, s[24:25]
	v_mfma_f32_16x16x32_f16 v[72:75], v[238:241], v[152:155], v[72:75]
	ds_read_b128 v[136:139], v168 offset:1040
	ds_read_b128 v[188:191], v169 offset:1040
	s_add_u32 m0, vcc_lo, 0x400
	s_nop 0
	global_load_lds_dwordx4 v171, s[24:25]
	v_mfma_f32_16x16x32_f16 v[76:79], v[238:241], v[156:159], v[76:79]
	ds_read_b128 v[140:143], v168 offset:2064
	ds_read_b128 v[192:195], v169 offset:2064
	s_add_u32 m0, vcc_lo, 0x4000
	s_nop 0
	global_load_lds_dwordx4 v170, s[28:29]
	v_mfma_f32_16x16x32_f16 v[80:83], v[238:241], v[160:163], v[80:83]
	ds_read_b128 v[144:147], v168 offset:3088
	ds_read_b128 v[196:199], v169 offset:3088
	s_add_u32 m0, vcc_lo, 0x4400
	s_nop 0
	global_load_lds_dwordx4 v171, s[28:29]
	v_mfma_f32_16x16x32_f16 v[84:87], v[242:245], v[148:151], v[84:87]
	v_mfma_f32_16x16x32_f16 v[88:91], v[242:245], v[152:155], v[88:91]
	v_mfma_f32_16x16x32_f16 v[92:95], v[242:245], v[156:159], v[92:95]
	v_mfma_f32_16x16x32_f16 v[96:99], v[242:245], v[160:163], v[96:99]
	v_mfma_f32_16x16x32_f16 v[100:103], v[246:249], v[148:151], v[100:103]
	v_mfma_f32_16x16x32_f16 v[104:107], v[246:249], v[152:155], v[104:107]
	v_mfma_f32_16x16x32_f16 v[108:111], v[246:249], v[156:159], v[108:111]
	v_mfma_f32_16x16x32_f16 v[112:115], v[246:249], v[160:163], v[112:115]
	v_mfma_f32_16x16x32_f16 v[116:119], v[250:253], v[148:151], v[116:119]
	v_mfma_f32_16x16x32_f16 v[120:123], v[250:253], v[152:155], v[120:123]
	v_mfma_f32_16x16x32_f16 v[124:127], v[250:253], v[156:159], v[124:127]
	v_mfma_f32_16x16x32_f16 v[128:131], v[250:253], v[160:163], v[128:131]
	s_waitcnt lgkmcnt(0)
	s_mov_b32 s42, s43
	s_add_u32 s24, s24, 64
	s_addc_u32 s25, s25, 0
	s_add_u32 s28, s28, 64
	s_addc_u32 s29, s29, 0
	s_add_i32 s44, s44, 2
	s_cmp_lt_u32 s44, 28
	s_cbranch_scc1 .Lt_qkv_v
	v_add_u32_e32 v169, s42, v164
	v_mfma_f32_16x16x32_f16 v[4:7], v[184:187], v[132:135], v[4:7]
	ds_read_b128 v[238:241], v169 offset:4112
	v_mfma_f32_16x16x32_f16 v[8:11], v[184:187], v[136:139], v[8:11]
	ds_read_b128 v[242:245], v169 offset:5136
	v_mfma_f32_16x16x32_f16 v[12:15], v[184:187], v[140:143], v[12:15]
	ds_read_b128 v[246:249], v169 offset:6160
	v_mfma_f32_16x16x32_f16 v[16:19], v[184:187], v[144:147], v[16:19]
	ds_read_b128 v[250:253], v169 offset:7184
	v_mfma_f32_16x16x32_f16 v[20:23], v[188:191], v[132:135], v[20:23]
	v_mfma_f32_16x16x32_f16 v[24:27], v[188:191], v[136:139], v[24:27]
	v_mfma_f32_16x16x32_f16 v[28:31], v[188:191], v[140:143], v[28:31]
	v_mfma_f32_16x16x32_f16 v[32:35], v[188:191], v[144:147], v[32:35]
	v_mfma_f32_16x16x32_f16 v[36:39], v[192:195], v[132:135], v[36:39]
	v_mfma_f32_16x16x32_f16 v[40:43], v[192:195], v[136:139], v[40:43]
	v_mfma_f32_16x16x32_f16 v[44:47], v[192:195], v[140:143], v[44:47]
	v_mfma_f32_16x16x32_f16 v[48:51], v[192:195], v[144:147], v[48:51]
	v_mfma_f32_16x16x32_f16 v[52:55], v[196:199], v[132:135], v[52:55]
	v_mfma_f32_16x16x32_f16 v[56:59], v[196:199], v[136:139], v[56:59]
	v_mfma_f32_16x16x32_f16 v[60:63], v[196:199], v[140:143], v[60:63]
	v_mfma_f32_16x16x32_f16 v[64:67], v[196:199], v[144:147], v[64:67]
	s_waitcnt vmcnt(8) lgkmcnt(0)
	s_barrier
	s_add_i32 s43, s42, 0x8000
	s_cmp_lg_u32 s42, 0x18000
	s_cselect_b32 s43, s43, 0
	v_add_u32_e32 v168, s43, v165
	v_add_u32_e32 v169, s43, v164
	v_mfma_f32_16x16x32_f16 v[68:71], v[238:241], v[132:135], v[68:71]
	ds_read_b128 v[148:151], v168 offset:16
	ds_read_b128 v[184:187], v169 offset:16
	v_mfma_f32_16x16x32_f16 v[72:75], v[238:241], v[136:139], v[72:75]
	ds_read_b128 v[152:155], v168 offset:1040
	ds_read_b128 v[188:191], v169 offset:1040
	v_mfma_f32_16x16x32_f16 v[76:79], v[238:241], v[140:143], v[76:79]
	ds_read_b128 v[156:159], v168 offset:2064
	ds_read_b128 v[192:195], v169 offset:2064
	v_mfma_f32_16x16x32_f16 v[80:83], v[238:241], v[144:147], v[80:83]
	ds_read_b128 v[160:163], v168 offset:3088
	ds_read_b128 v[196:199], v169 offset:3088
	v_mfma_f32_16x16x32_f16 v[84:87], v[242:245], v[132:135], v[84:87]
	v_mfma_f32_16x16x32_f16 v[88:91], v[242:245], v[136:139], v[88:91]
	v_mfma_f32_16x16x32_f16 v[92:95], v[242:245], v[140:143], v[92:95]
	v_mfma_f32_16x16x32_f16 v[96:99], v[242:245], v[144:147], v[96:99]
	v_mfma_f32_16x16x32_f16 v[100:103], v[246:249], v[132:135], v[100:103]
	v_mfma_f32_16x16x32_f16 v[104:107], v[246:249], v[136:139], v[104:107]
	v_mfma_f32_16x16x32_f16 v[108:111], v[246:249], v[140:143], v[108:111]
	v_mfma_f32_16x16x32_f16 v[112:115], v[246:249], v[144:147], v[112:115]
	v_mfma_f32_16x16x32_f16 v[116:119], v[250:253], v[132:135], v[116:119]
	v_mfma_f32_16x16x32_f16 v[120:123], v[250:253], v[136:139], v[120:123]
	v_mfma_f32_16x16x32_f16 v[124:127], v[250:253], v[140:143], v[124:127]
	v_mfma_f32_16x16x32_f16 v[128:131], v[250:253], v[144:147], v[128:131]
	s_waitcnt lgkmcnt(0)
	s_mov_b32 s42, s43
	v_add_u32_e32 v169, s42, v164
	v_mfma_f32_16x16x32_f16 v[4:7], v[184:187], v[148:151], v[4:7]
	ds_read_b128 v[238:241], v169 offset:4112
	v_mfma_f32_16x16x32_f16 v[8:11], v[184:187], v[152:155], v[8:11]
	ds_read_b128 v[242:245], v169 offset:5136
	v_mfma_f32_16x16x32_f16 v[12:15], v[184:187], v[156:159], v[12:15]
	ds_read_b128 v[246:249], v169 offset:6160
	v_mfma_f32_16x16x32_f16 v[16:19], v[184:187], v[160:163], v[16:19]
	ds_read_b128 v[250:253], v169 offset:7184
	v_mfma_f32_16x16x32_f16 v[20:23], v[188:191], v[148:151], v[20:23]
	v_mfma_f32_16x16x32_f16 v[24:27], v[188:191], v[152:155], v[24:27]
	v_mfma_f32_16x16x32_f16 v[28:31], v[188:191], v[156:159], v[28:31]
	v_mfma_f32_16x16x32_f16 v[32:35], v[188:191], v[160:163], v[32:35]
	v_mfma_f32_16x16x32_f16 v[36:39], v[192:195], v[148:151], v[36:39]
	v_mfma_f32_16x16x32_f16 v[40:43], v[192:195], v[152:155], v[40:43]
	v_mfma_f32_16x16x32_f16 v[44:47], v[192:195], v[156:159], v[44:47]
	v_mfma_f32_16x16x32_f16 v[48:51], v[192:195], v[160:163], v[48:51]
	v_mfma_f32_16x16x32_f16 v[52:55], v[196:199], v[148:151], v[52:55]
	v_mfma_f32_16x16x32_f16 v[56:59], v[196:199], v[152:155], v[56:59]
	v_mfma_f32_16x16x32_f16 v[60:63], v[196:199], v[156:159], v[60:63]
	v_mfma_f32_16x16x32_f16 v[64:67], v[196:199], v[160:163], v[64:67]
	s_waitcnt vmcnt(4) lgkmcnt(0)
	s_barrier
	s_add_i32 s43, s42, 0x8000
	s_cmp_lg_u32 s42, 0x18000
	s_cselect_b32 s43, s43, 0
	v_add_u32_e32 v168, s43, v165
	v_add_u32_e32 v169, s43, v164
	v_mfma_f32_16x16x32_f16 v[68:71], v[238:241], v[148:151], v[68:71]
	ds_read_b128 v[132:135], v168 offset:16
	ds_read_b128 v[184:187], v169 offset:16
	v_mfma_f32_16x16x32_f16 v[72:75], v[238:241], v[152:155], v[72:75]
	ds_read_b128 v[136:139], v168 offset:1040
	ds_read_b128 v[188:191], v169 offset:1040
	v_mfma_f32_16x16x32_f16 v[76:79], v[238:241], v[156:159], v[76:79]
	ds_read_b128 v[140:143], v168 offset:2064
	ds_read_b128 v[192:195], v169 offset:2064
	v_mfma_f32_16x16x32_f16 v[80:83], v[238:241], v[160:163], v[80:83]
	ds_read_b128 v[144:147], v168 offset:3088
	ds_read_b128 v[196:199], v169 offset:3088
	v_mfma_f32_16x16x32_f16 v[84:87], v[242:245], v[148:151], v[84:87]
	v_mfma_f32_16x16x32_f16 v[88:91], v[242:245], v[152:155], v[88:91]
	v_mfma_f32_16x16x32_f16 v[92:95], v[242:245], v[156:159], v[92:95]
	v_mfma_f32_16x16x32_f16 v[96:99], v[242:245], v[160:163], v[96:99]
	v_mfma_f32_16x16x32_f16 v[100:103], v[246:249], v[148:151], v[100:103]
	v_mfma_f32_16x16x32_f16 v[104:107], v[246:249], v[152:155], v[104:107]
	v_mfma_f32_16x16x32_f16 v[108:111], v[246:249], v[156:159], v[108:111]
	v_mfma_f32_16x16x32_f16 v[112:115], v[246:249], v[160:163], v[112:115]
	v_mfma_f32_16x16x32_f16 v[116:119], v[250:253], v[148:151], v[116:119]
	v_mfma_f32_16x16x32_f16 v[120:123], v[250:253], v[152:155], v[120:123]
	v_mfma_f32_16x16x32_f16 v[124:127], v[250:253], v[156:159], v[124:127]
	v_mfma_f32_16x16x32_f16 v[128:131], v[250:253], v[160:163], v[128:131]
	s_waitcnt lgkmcnt(0)
	s_mov_b32 s42, s43
	v_add_u32_e32 v169, s42, v164
	v_mfma_f32_16x16x32_f16 v[4:7], v[184:187], v[132:135], v[4:7]
	ds_read_b128 v[238:241], v169 offset:4112
	v_mfma_f32_16x16x32_f16 v[8:11], v[184:187], v[136:139], v[8:11]
	ds_read_b128 v[242:245], v169 offset:5136
	v_mfma_f32_16x16x32_f16 v[12:15], v[184:187], v[140:143], v[12:15]
	ds_read_b128 v[246:249], v169 offset:6160
	v_mfma_f32_16x16x32_f16 v[16:19], v[184:187], v[144:147], v[16:19]
	ds_read_b128 v[250:253], v169 offset:7184
	v_mfma_f32_16x16x32_f16 v[20:23], v[188:191], v[132:135], v[20:23]
	v_mfma_f32_16x16x32_f16 v[24:27], v[188:191], v[136:139], v[24:27]
	v_mfma_f32_16x16x32_f16 v[28:31], v[188:191], v[140:143], v[28:31]
	v_mfma_f32_16x16x32_f16 v[32:35], v[188:191], v[144:147], v[32:35]
	v_mfma_f32_16x16x32_f16 v[36:39], v[192:195], v[132:135], v[36:39]
	v_mfma_f32_16x16x32_f16 v[40:43], v[192:195], v[136:139], v[40:43]
	v_mfma_f32_16x16x32_f16 v[44:47], v[192:195], v[140:143], v[44:47]
	v_mfma_f32_16x16x32_f16 v[48:51], v[192:195], v[144:147], v[48:51]
	v_mfma_f32_16x16x32_f16 v[52:55], v[196:199], v[132:135], v[52:55]
	v_mfma_f32_16x16x32_f16 v[56:59], v[196:199], v[136:139], v[56:59]
	v_mfma_f32_16x16x32_f16 v[60:63], v[196:199], v[140:143], v[60:63]
	v_mfma_f32_16x16x32_f16 v[64:67], v[196:199], v[144:147], v[64:67]
	s_waitcnt vmcnt(0) lgkmcnt(0)
	s_barrier
	s_add_i32 s43, s42, 0x8000
	s_cmp_lg_u32 s42, 0x18000
	s_cselect_b32 s43, s43, 0
	v_add_u32_e32 v168, s43, v165
	v_add_u32_e32 v169, s43, v164
	v_mfma_f32_16x16x32_f16 v[68:71], v[238:241], v[132:135], v[68:71]
	ds_read_b128 v[148:151], v168 offset:16
	ds_read_b128 v[184:187], v169 offset:16
	v_mfma_f32_16x16x32_f16 v[72:75], v[238:241], v[136:139], v[72:75]
	ds_read_b128 v[152:155], v168 offset:1040
	ds_read_b128 v[188:191], v169 offset:1040
	v_mfma_f32_16x16x32_f16 v[76:79], v[238:241], v[140:143], v[76:79]
	ds_read_b128 v[156:159], v168 offset:2064
	ds_read_b128 v[192:195], v169 offset:2064
	v_mfma_f32_16x16x32_f16 v[80:83], v[238:241], v[144:147], v[80:83]
	ds_read_b128 v[160:163], v168 offset:3088
	ds_read_b128 v[196:199], v169 offset:3088
	v_mfma_f32_16x16x32_f16 v[84:87], v[242:245], v[132:135], v[84:87]
	v_mfma_f32_16x16x32_f16 v[88:91], v[242:245], v[136:139], v[88:91]
	v_mfma_f32_16x16x32_f16 v[92:95], v[242:245], v[140:143], v[92:95]
	v_mfma_f32_16x16x32_f16 v[96:99], v[242:245], v[144:147], v[96:99]
	v_mfma_f32_16x16x32_f16 v[100:103], v[246:249], v[132:135], v[100:103]
	v_mfma_f32_16x16x32_f16 v[104:107], v[246:249], v[136:139], v[104:107]
	v_mfma_f32_16x16x32_f16 v[108:111], v[246:249], v[140:143], v[108:111]
	v_mfma_f32_16x16x32_f16 v[112:115], v[246:249], v[144:147], v[112:115]
	v_mfma_f32_16x16x32_f16 v[116:119], v[250:253], v[132:135], v[116:119]
	v_mfma_f32_16x16x32_f16 v[120:123], v[250:253], v[136:139], v[120:123]
	v_mfma_f32_16x16x32_f16 v[124:127], v[250:253], v[140:143], v[124:127]
	v_mfma_f32_16x16x32_f16 v[128:131], v[250:253], v[144:147], v[128:131]
	s_waitcnt lgkmcnt(0)
	s_mov_b32 s42, s43
	v_add_u32_e32 v169, s42, v164
	v_mfma_f32_16x16x32_f16 v[4:7], v[184:187], v[148:151], v[4:7]
	ds_read_b128 v[238:241], v169 offset:4112
	v_mfma_f32_16x16x32_f16 v[8:11], v[184:187], v[152:155], v[8:11]
	ds_read_b128 v[242:245], v169 offset:5136
	v_mfma_f32_16x16x32_f16 v[12:15], v[184:187], v[156:159], v[12:15]
	ds_read_b128 v[246:249], v169 offset:6160
	v_mfma_f32_16x16x32_f16 v[16:19], v[184:187], v[160:163], v[16:19]
	ds_read_b128 v[250:253], v169 offset:7184
	v_mfma_f32_16x16x32_f16 v[20:23], v[188:191], v[148:151], v[20:23]
	v_mfma_f32_16x16x32_f16 v[24:27], v[188:191], v[152:155], v[24:27]
	v_mfma_f32_16x16x32_f16 v[28:31], v[188:191], v[156:159], v[28:31]
	v_mfma_f32_16x16x32_f16 v[32:35], v[188:191], v[160:163], v[32:35]
	v_mfma_f32_16x16x32_f16 v[36:39], v[192:195], v[148:151], v[36:39]
	v_mfma_f32_16x16x32_f16 v[40:43], v[192:195], v[152:155], v[40:43]
	v_mfma_f32_16x16x32_f16 v[44:47], v[192:195], v[156:159], v[44:47]
	v_mfma_f32_16x16x32_f16 v[48:51], v[192:195], v[160:163], v[48:51]
	v_mfma_f32_16x16x32_f16 v[52:55], v[196:199], v[148:151], v[52:55]
	v_mfma_f32_16x16x32_f16 v[56:59], v[196:199], v[152:155], v[56:59]
	v_mfma_f32_16x16x32_f16 v[60:63], v[196:199], v[156:159], v[60:63]
	v_mfma_f32_16x16x32_f16 v[64:67], v[196:199], v[160:163], v[64:67]
	s_waitcnt lgkmcnt(0)
	s_barrier
	v_mfma_f32_16x16x32_f16 v[68:71], v[238:241], v[148:151], v[68:71]
	v_mfma_f32_16x16x32_f16 v[72:75], v[238:241], v[152:155], v[72:75]
	v_mfma_f32_16x16x32_f16 v[76:79], v[238:241], v[156:159], v[76:79]
	v_mfma_f32_16x16x32_f16 v[80:83], v[238:241], v[160:163], v[80:83]
	v_mfma_f32_16x16x32_f16 v[84:87], v[242:245], v[148:151], v[84:87]
	v_mfma_f32_16x16x32_f16 v[88:91], v[242:245], v[152:155], v[88:91]
	v_mfma_f32_16x16x32_f16 v[92:95], v[242:245], v[156:159], v[92:95]
	v_mfma_f32_16x16x32_f16 v[96:99], v[242:245], v[160:163], v[96:99]
	v_mfma_f32_16x16x32_f16 v[100:103], v[246:249], v[148:151], v[100:103]
	v_mfma_f32_16x16x32_f16 v[104:107], v[246:249], v[152:155], v[104:107]
	v_mfma_f32_16x16x32_f16 v[108:111], v[246:249], v[156:159], v[108:111]
	v_mfma_f32_16x16x32_f16 v[112:115], v[246:249], v[160:163], v[112:115]
	v_mfma_f32_16x16x32_f16 v[116:119], v[250:253], v[148:151], v[116:119]
	v_mfma_f32_16x16x32_f16 v[120:123], v[250:253], v[152:155], v[120:123]
	v_mfma_f32_16x16x32_f16 v[124:127], v[250:253], v[156:159], v[124:127]
	v_mfma_f32_16x16x32_f16 v[128:131], v[250:253], v[160:163], v[128:131]
	s_sub_i32 s43, s48, 8
	s_lshl_b32 s43, s43, 2
	s_cmp_lt_u32 s83, 0x1000
	s_cbranch_scc0 .Lqv_lat
	s_lshr_b32 s44, s83, 4
	s_add_u32 s44, s44, s43
	s_lshl_b32 s42, s44, 16
	s_add_u32 s28, s70, s42
	s_addc_u32 s29, s71, 0
	s_lshl_b32 s44, s44, 15
	s_add_u32 s24, s58, s44
	s_addc_u32 s25, s59, 0
	s_mov_b32 s32, 9
	s_branch .Lqv_addr

.Lt_qkv_qk:
	v_add_u32_e32 v169, s42, v164
	v_mfma_f32_16x16x32_f16 v[4:7], v[132:135], v[184:187], v[4:7]
	ds_read_b128 v[238:241], v169 offset:4112
	v_mfma_f32_16x16x32_f16 v[8:11], v[136:139], v[184:187], v[8:11]
	ds_read_b128 v[242:245], v169 offset:5136
	v_mfma_f32_16x16x32_f16 v[12:15], v[140:143], v[184:187], v[12:15]
	ds_read_b128 v[246:249], v169 offset:6160
	v_mfma_f32_16x16x32_f16 v[16:19], v[144:147], v[184:187], v[16:19]
	ds_read_b128 v[250:253], v169 offset:7184
	v_mfma_f32_16x16x32_f16 v[20:23], v[132:135], v[188:191], v[20:23]
	v_mfma_f32_16x16x32_f16 v[24:27], v[136:139], v[188:191], v[24:27]
	v_mfma_f32_16x16x32_f16 v[28:31], v[140:143], v[188:191], v[28:31]
	v_mfma_f32_16x16x32_f16 v[32:35], v[144:147], v[188:191], v[32:35]
	v_mfma_f32_16x16x32_f16 v[36:39], v[132:135], v[192:195], v[36:39]
	v_mfma_f32_16x16x32_f16 v[40:43], v[136:139], v[192:195], v[40:43]
	v_mfma_f32_16x16x32_f16 v[44:47], v[140:143], v[192:195], v[44:47]
	v_mfma_f32_16x16x32_f16 v[48:51], v[144:147], v[192:195], v[48:51]
	v_mfma_f32_16x16x32_f16 v[52:55], v[132:135], v[196:199], v[52:55]
	v_mfma_f32_16x16x32_f16 v[56:59], v[136:139], v[196:199], v[56:59]
	v_mfma_f32_16x16x32_f16 v[60:63], v[140:143], v[196:199], v[60:63]
	v_mfma_f32_16x16x32_f16 v[64:67], v[144:147], v[196:199], v[64:67]
	s_waitcnt vmcnt(8) lgkmcnt(0)
	s_barrier
	s_add_i32 s43, s42, 0x8000
	s_cmp_lg_u32 s42, 0x18000
	s_cselect_b32 s43, s43, 0
	v_add_u32_e32 v168, s43, v165
	v_add_u32_e32 v169, s43, v164
	s_add_u32 vcc_lo, s32, s42
	v_mfma_f32_16x16x32_f16 v[68:71], v[132:135], v[238:241], v[68:71]
	ds_read_b128 v[148:151], v168 offset:16
	ds_read_b128 v[184:187], v169 offset:16
	s_mov_b32 m0, vcc_lo
	s_nop 0
	global_load_lds_dwordx4 v170, s[24:25]
	v_mfma_f32_16x16x32_f16 v[72:75], v[136:139], v[238:241], v[72:75]
	ds_read_b128 v[152:155], v168 offset:1040
	ds_read_b128 v[188:191], v169 offset:1040
	s_add_u32 m0, vcc_lo, 0x400
	s_nop 0
	global_load_lds_dwordx4 v171, s[24:25]
	v_mfma_f32_16x16x32_f16 v[76:79], v[140:143], v[238:241], v[76:79]
	ds_read_b128 v[156:159], v168 offset:2064
	ds_read_b128 v[192:195], v169 offset:2064
	s_add_u32 m0, vcc_lo, 0x4000
	s_nop 0
	global_load_lds_dwordx4 v170, s[28:29]
	v_mfma_f32_16x16x32_f16 v[80:83], v[144:147], v[238:241], v[80:83]
	ds_read_b128 v[160:163], v168 offset:3088
	ds_read_b128 v[196:199], v169 offset:3088
	s_add_u32 m0, vcc_lo, 0x4400
	s_nop 0
	global_load_lds_dwordx4 v171, s[28:29]
	v_mfma_f32_16x16x32_f16 v[84:87], v[132:135], v[242:245], v[84:87]
	v_mfma_f32_16x16x32_f16 v[88:91], v[136:139], v[242:245], v[88:91]
	v_mfma_f32_16x16x32_f16 v[92:95], v[140:143], v[242:245], v[92:95]
	v_mfma_f32_16x16x32_f16 v[96:99], v[144:147], v[242:245], v[96:99]
	v_mfma_f32_16x16x32_f16 v[100:103], v[132:135], v[246:249], v[100:103]
	v_mfma_f32_16x16x32_f16 v[104:107], v[136:139], v[246:249], v[104:107]
	v_mfma_f32_16x16x32_f16 v[108:111], v[140:143], v[246:249], v[108:111]
	v_mfma_f32_16x16x32_f16 v[112:115], v[144:147], v[246:249], v[112:115]
	v_mfma_f32_16x16x32_f16 v[116:119], v[132:135], v[250:253], v[116:119]
	v_mfma_f32_16x16x32_f16 v[120:123], v[136:139], v[250:253], v[120:123]
	v_mfma_f32_16x16x32_f16 v[124:127], v[140:143], v[250:253], v[124:127]
	v_mfma_f32_16x16x32_f16 v[128:131], v[144:147], v[250:253], v[128:131]
	s_waitcnt lgkmcnt(0)
	s_mov_b32 s42, s43
	s_add_u32 s24, s24, 64
	s_addc_u32 s25, s25, 0
	s_add_u32 s28, s28, 64
	s_addc_u32 s29, s29, 0
	v_add_u32_e32 v169, s42, v164
	v_mfma_f32_16x16x32_f16 v[4:7], v[148:151], v[184:187], v[4:7]
	ds_read_b128 v[238:241], v169 offset:4112
	v_mfma_f32_16x16x32_f16 v[8:11], v[152:155], v[184:187], v[8:11]
	ds_read_b128 v[242:245], v169 offset:5136
	v_mfma_f32_16x16x32_f16 v[12:15], v[156:159], v[184:187], v[12:15]
	ds_read_b128 v[246:249], v169 offset:6160
	v_mfma_f32_16x16x32_f16 v[16:19], v[160:163], v[184:187], v[16:19]
	ds_read_b128 v[250:253], v169 offset:7184
	v_mfma_f32_16x16x32_f16 v[20:23], v[148:151], v[188:191], v[20:23]
	v_mfma_f32_16x16x32_f16 v[24:27], v[152:155], v[188:191], v[24:27]
	v_mfma_f32_16x16x32_f16 v[28:31], v[156:159], v[188:191], v[28:31]
	v_mfma_f32_16x16x32_f16 v[32:35], v[160:163], v[188:191], v[32:35]
	v_mfma_f32_16x16x32_f16 v[36:39], v[148:151], v[192:195], v[36:39]
	v_mfma_f32_16x16x32_f16 v[40:43], v[152:155], v[192:195], v[40:43]
	v_mfma_f32_16x16x32_f16 v[44:47], v[156:159], v[192:195], v[44:47]
	v_mfma_f32_16x16x32_f16 v[48:51], v[160:163], v[192:195], v[48:51]
	v_mfma_f32_16x16x32_f16 v[52:55], v[148:151], v[196:199], v[52:55]
	v_mfma_f32_16x16x32_f16 v[56:59], v[152:155], v[196:199], v[56:59]
	v_mfma_f32_16x16x32_f16 v[60:63], v[156:159], v[196:199], v[60:63]
	v_mfma_f32_16x16x32_f16 v[64:67], v[160:163], v[196:199], v[64:67]
	s_waitcnt vmcnt(8) lgkmcnt(0)
	s_barrier
	s_add_i32 s43, s42, 0x8000
	s_cmp_lg_u32 s42, 0x18000
	s_cselect_b32 s43, s43, 0
	v_add_u32_e32 v168, s43, v165
	v_add_u32_e32 v169, s43, v164
	s_add_u32 vcc_lo, s32, s42
	v_mfma_f32_16x16x32_f16 v[68:71], v[148:151], v[238:241], v[68:71]
	ds_read_b128 v[132:135], v168 offset:16
	ds_read_b128 v[184:187], v169 offset:16
	s_mov_b32 m0, vcc_lo
	s_nop 0
	global_load_lds_dwordx4 v170, s[24:25]
	v_mfma_f32_16x16x32_f16 v[72:75], v[152:155], v[238:241], v[72:75]
	ds_read_b128 v[136:139], v168 offset:1040
	ds_read_b128 v[188:191], v169 offset:1040
	s_add_u32 m0, vcc_lo, 0x400
	s_nop 0
	global_load_lds_dwordx4 v171, s[24:25]
	v_mfma_f32_16x16x32_f16 v[76:79], v[156:159], v[238:241], v[76:79]
	ds_read_b128 v[140:143], v168 offset:2064
	ds_read_b128 v[192:195], v169 offset:2064
	s_add_u32 m0, vcc_lo, 0x4000
	s_nop 0
	global_load_lds_dwordx4 v170, s[28:29]
	v_mfma_f32_16x16x32_f16 v[80:83], v[160:163], v[238:241], v[80:83]
	ds_read_b128 v[144:147], v168 offset:3088
	ds_read_b128 v[196:199], v169 offset:3088
	s_add_u32 m0, vcc_lo, 0x4400
	s_nop 0
	global_load_lds_dwordx4 v171, s[28:29]
	v_mfma_f32_16x16x32_f16 v[84:87], v[148:151], v[242:245], v[84:87]
	v_mfma_f32_16x16x32_f16 v[88:91], v[152:155], v[242:245], v[88:91]
	v_mfma_f32_16x16x32_f16 v[92:95], v[156:159], v[242:245], v[92:95]
	v_mfma_f32_16x16x32_f16 v[96:99], v[160:163], v[242:245], v[96:99]
	v_mfma_f32_16x16x32_f16 v[100:103], v[148:151], v[246:249], v[100:103]
	v_mfma_f32_16x16x32_f16 v[104:107], v[152:155], v[246:249], v[104:107]
	v_mfma_f32_16x16x32_f16 v[108:111], v[156:159], v[246:249], v[108:111]
	v_mfma_f32_16x16x32_f16 v[112:115], v[160:163], v[246:249], v[112:115]
	v_mfma_f32_16x16x32_f16 v[116:119], v[148:151], v[250:253], v[116:119]
	v_mfma_f32_16x16x32_f16 v[120:123], v[152:155], v[250:253], v[120:123]
	v_mfma_f32_16x16x32_f16 v[124:127], v[156:159], v[250:253], v[124:127]
	v_mfma_f32_16x16x32_f16 v[128:131], v[160:163], v[250:253], v[128:131]
	s_waitcnt lgkmcnt(0)
	s_mov_b32 s42, s43
	s_add_u32 s24, s24, 64
	s_addc_u32 s25, s25, 0
	s_add_u32 s28, s28, 64
	s_addc_u32 s29, s29, 0
	s_add_i32 s44, s44, 2
	s_cmp_lt_u32 s44, 28
	s_cbranch_scc1 .Lt_qkv_qk
	v_add_u32_e32 v169, s42, v164
	v_mfma_f32_16x16x32_f16 v[4:7], v[132:135], v[184:187], v[4:7]
	ds_read_b128 v[238:241], v169 offset:4112
	v_mfma_f32_16x16x32_f16 v[8:11], v[136:139], v[184:187], v[8:11]
	ds_read_b128 v[242:245], v169 offset:5136
	v_mfma_f32_16x16x32_f16 v[12:15], v[140:143], v[184:187], v[12:15]
	ds_read_b128 v[246:249], v169 offset:6160
	v_mfma_f32_16x16x32_f16 v[16:19], v[144:147], v[184:187], v[16:19]
	ds_read_b128 v[250:253], v169 offset:7184
	v_mfma_f32_16x16x32_f16 v[20:23], v[132:135], v[188:191], v[20:23]
	v_mfma_f32_16x16x32_f16 v[24:27], v[136:139], v[188:191], v[24:27]
	v_mfma_f32_16x16x32_f16 v[28:31], v[140:143], v[188:191], v[28:31]
	v_mfma_f32_16x16x32_f16 v[32:35], v[144:147], v[188:191], v[32:35]
	v_mfma_f32_16x16x32_f16 v[36:39], v[132:135], v[192:195], v[36:39]
	v_mfma_f32_16x16x32_f16 v[40:43], v[136:139], v[192:195], v[40:43]
	v_mfma_f32_16x16x32_f16 v[44:47], v[140:143], v[192:195], v[44:47]
	v_mfma_f32_16x16x32_f16 v[48:51], v[144:147], v[192:195], v[48:51]
	v_mfma_f32_16x16x32_f16 v[52:55], v[132:135], v[196:199], v[52:55]
	v_mfma_f32_16x16x32_f16 v[56:59], v[136:139], v[196:199], v[56:59]
	v_mfma_f32_16x16x32_f16 v[60:63], v[140:143], v[196:199], v[60:63]
	v_mfma_f32_16x16x32_f16 v[64:67], v[144:147], v[196:199], v[64:67]
	s_waitcnt vmcnt(8) lgkmcnt(0)
	s_barrier
	s_add_i32 s43, s42, 0x8000
	s_cmp_lg_u32 s42, 0x18000
	s_cselect_b32 s43, s43, 0
	v_add_u32_e32 v168, s43, v165
	v_add_u32_e32 v169, s43, v164
	v_mfma_f32_16x16x32_f16 v[68:71], v[132:135], v[238:241], v[68:71]
	ds_read_b128 v[148:151], v168 offset:16
	ds_read_b128 v[184:187], v169 offset:16
	v_mfma_f32_16x16x32_f16 v[72:75], v[136:139], v[238:241], v[72:75]
	ds_read_b128 v[152:155], v168 offset:1040
	ds_read_b128 v[188:191], v169 offset:1040
	v_mfma_f32_16x16x32_f16 v[76:79], v[140:143], v[238:241], v[76:79]
	ds_read_b128 v[156:159], v168 offset:2064
	ds_read_b128 v[192:195], v169 offset:2064
	v_mfma_f32_16x16x32_f16 v[80:83], v[144:147], v[238:241], v[80:83]
	ds_read_b128 v[160:163], v168 offset:3088
	ds_read_b128 v[196:199], v169 offset:3088
	v_mfma_f32_16x16x32_f16 v[84:87], v[132:135], v[242:245], v[84:87]
	v_mfma_f32_16x16x32_f16 v[88:91], v[136:139], v[242:245], v[88:91]
	v_mfma_f32_16x16x32_f16 v[92:95], v[140:143], v[242:245], v[92:95]
	v_mfma_f32_16x16x32_f16 v[96:99], v[144:147], v[242:245], v[96:99]
	v_mfma_f32_16x16x32_f16 v[100:103], v[132:135], v[246:249], v[100:103]
	v_mfma_f32_16x16x32_f16 v[104:107], v[136:139], v[246:249], v[104:107]
	v_mfma_f32_16x16x32_f16 v[108:111], v[140:143], v[246:249], v[108:111]
	v_mfma_f32_16x16x32_f16 v[112:115], v[144:147], v[246:249], v[112:115]
	v_mfma_f32_16x16x32_f16 v[116:119], v[132:135], v[250:253], v[116:119]
	v_mfma_f32_16x16x32_f16 v[120:123], v[136:139], v[250:253], v[120:123]
	v_mfma_f32_16x16x32_f16 v[124:127], v[140:143], v[250:253], v[124:127]
	v_mfma_f32_16x16x32_f16 v[128:131], v[144:147], v[250:253], v[128:131]
	s_waitcnt lgkmcnt(0)
	s_mov_b32 s42, s43
	v_add_u32_e32 v169, s42, v164
	v_mfma_f32_16x16x32_f16 v[4:7], v[148:151], v[184:187], v[4:7]
	ds_read_b128 v[238:241], v169 offset:4112
	v_mfma_f32_16x16x32_f16 v[8:11], v[152:155], v[184:187], v[8:11]
	ds_read_b128 v[242:245], v169 offset:5136
	v_mfma_f32_16x16x32_f16 v[12:15], v[156:159], v[184:187], v[12:15]
	ds_read_b128 v[246:249], v169 offset:6160
	v_mfma_f32_16x16x32_f16 v[16:19], v[160:163], v[184:187], v[16:19]
	ds_read_b128 v[250:253], v169 offset:7184
	v_mfma_f32_16x16x32_f16 v[20:23], v[148:151], v[188:191], v[20:23]
	v_mfma_f32_16x16x32_f16 v[24:27], v[152:155], v[188:191], v[24:27]
	v_mfma_f32_16x16x32_f16 v[28:31], v[156:159], v[188:191], v[28:31]
	v_mfma_f32_16x16x32_f16 v[32:35], v[160:163], v[188:191], v[32:35]
	v_mfma_f32_16x16x32_f16 v[36:39], v[148:151], v[192:195], v[36:39]
	v_mfma_f32_16x16x32_f16 v[40:43], v[152:155], v[192:195], v[40:43]
	v_mfma_f32_16x16x32_f16 v[44:47], v[156:159], v[192:195], v[44:47]
	v_mfma_f32_16x16x32_f16 v[48:51], v[160:163], v[192:195], v[48:51]
	v_mfma_f32_16x16x32_f16 v[52:55], v[148:151], v[196:199], v[52:55]
	v_mfma_f32_16x16x32_f16 v[56:59], v[152:155], v[196:199], v[56:59]
	v_mfma_f32_16x16x32_f16 v[60:63], v[156:159], v[196:199], v[60:63]
	v_mfma_f32_16x16x32_f16 v[64:67], v[160:163], v[196:199], v[64:67]
	s_waitcnt vmcnt(4) lgkmcnt(0)
	s_barrier
	s_add_i32 s43, s42, 0x8000
	s_cmp_lg_u32 s42, 0x18000
	s_cselect_b32 s43, s43, 0
	v_add_u32_e32 v168, s43, v165
	v_add_u32_e32 v169, s43, v164
	v_mfma_f32_16x16x32_f16 v[68:71], v[148:151], v[238:241], v[68:71]
	ds_read_b128 v[132:135], v168 offset:16
	ds_read_b128 v[184:187], v169 offset:16
	v_mfma_f32_16x16x32_f16 v[72:75], v[152:155], v[238:241], v[72:75]
	ds_read_b128 v[136:139], v168 offset:1040
	ds_read_b128 v[188:191], v169 offset:1040
	v_mfma_f32_16x16x32_f16 v[76:79], v[156:159], v[238:241], v[76:79]
	ds_read_b128 v[140:143], v168 offset:2064
	ds_read_b128 v[192:195], v169 offset:2064
	v_mfma_f32_16x16x32_f16 v[80:83], v[160:163], v[238:241], v[80:83]
	ds_read_b128 v[144:147], v168 offset:3088
	ds_read_b128 v[196:199], v169 offset:3088
	v_mfma_f32_16x16x32_f16 v[84:87], v[148:151], v[242:245], v[84:87]
	v_mfma_f32_16x16x32_f16 v[88:91], v[152:155], v[242:245], v[88:91]
	v_mfma_f32_16x16x32_f16 v[92:95], v[156:159], v[242:245], v[92:95]
	v_mfma_f32_16x16x32_f16 v[96:99], v[160:163], v[242:245], v[96:99]
	v_mfma_f32_16x16x32_f16 v[100:103], v[148:151], v[246:249], v[100:103]
	v_mfma_f32_16x16x32_f16 v[104:107], v[152:155], v[246:249], v[104:107]
	v_mfma_f32_16x16x32_f16 v[108:111], v[156:159], v[246:249], v[108:111]
	v_mfma_f32_16x16x32_f16 v[112:115], v[160:163], v[246:249], v[112:115]
	v_mfma_f32_16x16x32_f16 v[116:119], v[148:151], v[250:253], v[116:119]
	v_mfma_f32_16x16x32_f16 v[120:123], v[152:155], v[250:253], v[120:123]
	v_mfma_f32_16x16x32_f16 v[124:127], v[156:159], v[250:253], v[124:127]
	v_mfma_f32_16x16x32_f16 v[128:131], v[160:163], v[250:253], v[128:131]
	s_waitcnt lgkmcnt(0)
	s_mov_b32 s42, s43
	v_add_u32_e32 v169, s42, v164
	v_mfma_f32_16x16x32_f16 v[4:7], v[132:135], v[184:187], v[4:7]
	ds_read_b128 v[238:241], v169 offset:4112
	v_mfma_f32_16x16x32_f16 v[8:11], v[136:139], v[184:187], v[8:11]
	ds_read_b128 v[242:245], v169 offset:5136
	v_mfma_f32_16x16x32_f16 v[12:15], v[140:143], v[184:187], v[12:15]
	ds_read_b128 v[246:249], v169 offset:6160
	v_mfma_f32_16x16x32_f16 v[16:19], v[144:147], v[184:187], v[16:19]
	ds_read_b128 v[250:253], v169 offset:7184
	v_mfma_f32_16x16x32_f16 v[20:23], v[132:135], v[188:191], v[20:23]
	v_mfma_f32_16x16x32_f16 v[24:27], v[136:139], v[188:191], v[24:27]
	v_mfma_f32_16x16x32_f16 v[28:31], v[140:143], v[188:191], v[28:31]
	v_mfma_f32_16x16x32_f16 v[32:35], v[144:147], v[188:191], v[32:35]
	v_mfma_f32_16x16x32_f16 v[36:39], v[132:135], v[192:195], v[36:39]
	v_mfma_f32_16x16x32_f16 v[40:43], v[136:139], v[192:195], v[40:43]
	v_mfma_f32_16x16x32_f16 v[44:47], v[140:143], v[192:195], v[44:47]
	v_mfma_f32_16x16x32_f16 v[48:51], v[144:147], v[192:195], v[48:51]
	v_mfma_f32_16x16x32_f16 v[52:55], v[132:135], v[196:199], v[52:55]
	v_mfma_f32_16x16x32_f16 v[56:59], v[136:139], v[196:199], v[56:59]
	v_mfma_f32_16x16x32_f16 v[60:63], v[140:143], v[196:199], v[60:63]
	v_mfma_f32_16x16x32_f16 v[64:67], v[144:147], v[196:199], v[64:67]
	s_waitcnt vmcnt(0) lgkmcnt(0)
	s_barrier
	s_add_i32 s43, s42, 0x8000
	s_cmp_lg_u32 s42, 0x18000
	s_cselect_b32 s43, s43, 0
	v_add_u32_e32 v168, s43, v165
	v_add_u32_e32 v169, s43, v164
	v_mfma_f32_16x16x32_f16 v[68:71], v[132:135], v[238:241], v[68:71]
	ds_read_b128 v[148:151], v168 offset:16
	ds_read_b128 v[184:187], v169 offset:16
	v_mfma_f32_16x16x32_f16 v[72:75], v[136:139], v[238:241], v[72:75]
	ds_read_b128 v[152:155], v168 offset:1040
	ds_read_b128 v[188:191], v169 offset:1040
	v_mfma_f32_16x16x32_f16 v[76:79], v[140:143], v[238:241], v[76:79]
	ds_read_b128 v[156:159], v168 offset:2064
	ds_read_b128 v[192:195], v169 offset:2064
	v_mfma_f32_16x16x32_f16 v[80:83], v[144:147], v[238:241], v[80:83]
	ds_read_b128 v[160:163], v168 offset:3088
	ds_read_b128 v[196:199], v169 offset:3088
	v_mfma_f32_16x16x32_f16 v[84:87], v[132:135], v[242:245], v[84:87]
	v_mfma_f32_16x16x32_f16 v[88:91], v[136:139], v[242:245], v[88:91]
	v_mfma_f32_16x16x32_f16 v[92:95], v[140:143], v[242:245], v[92:95]
	v_mfma_f32_16x16x32_f16 v[96:99], v[144:147], v[242:245], v[96:99]
	v_mfma_f32_16x16x32_f16 v[100:103], v[132:135], v[246:249], v[100:103]
	v_mfma_f32_16x16x32_f16 v[104:107], v[136:139], v[246:249], v[104:107]
	v_mfma_f32_16x16x32_f16 v[108:111], v[140:143], v[246:249], v[108:111]
	v_mfma_f32_16x16x32_f16 v[112:115], v[144:147], v[246:249], v[112:115]
	v_mfma_f32_16x16x32_f16 v[116:119], v[132:135], v[250:253], v[116:119]
	v_mfma_f32_16x16x32_f16 v[120:123], v[136:139], v[250:253], v[120:123]
	v_mfma_f32_16x16x32_f16 v[124:127], v[140:143], v[250:253], v[124:127]
	v_mfma_f32_16x16x32_f16 v[128:131], v[144:147], v[250:253], v[128:131]
	s_waitcnt lgkmcnt(0)
	s_mov_b32 s42, s43
	v_add_u32_e32 v169, s42, v164
	v_mfma_f32_16x16x32_f16 v[4:7], v[148:151], v[184:187], v[4:7]
	ds_read_b128 v[238:241], v169 offset:4112
	v_mfma_f32_16x16x32_f16 v[8:11], v[152:155], v[184:187], v[8:11]
	ds_read_b128 v[242:245], v169 offset:5136
	v_mfma_f32_16x16x32_f16 v[12:15], v[156:159], v[184:187], v[12:15]
	ds_read_b128 v[246:249], v169 offset:6160
	v_mfma_f32_16x16x32_f16 v[16:19], v[160:163], v[184:187], v[16:19]
	ds_read_b128 v[250:253], v169 offset:7184
	v_mfma_f32_16x16x32_f16 v[20:23], v[148:151], v[188:191], v[20:23]
	v_mfma_f32_16x16x32_f16 v[24:27], v[152:155], v[188:191], v[24:27]
	v_mfma_f32_16x16x32_f16 v[28:31], v[156:159], v[188:191], v[28:31]
	v_mfma_f32_16x16x32_f16 v[32:35], v[160:163], v[188:191], v[32:35]
	v_mfma_f32_16x16x32_f16 v[36:39], v[148:151], v[192:195], v[36:39]
	v_mfma_f32_16x16x32_f16 v[40:43], v[152:155], v[192:195], v[40:43]
	v_mfma_f32_16x16x32_f16 v[44:47], v[156:159], v[192:195], v[44:47]
	v_mfma_f32_16x16x32_f16 v[48:51], v[160:163], v[192:195], v[48:51]
	v_mfma_f32_16x16x32_f16 v[52:55], v[148:151], v[196:199], v[52:55]
	v_mfma_f32_16x16x32_f16 v[56:59], v[152:155], v[196:199], v[56:59]
	v_mfma_f32_16x16x32_f16 v[60:63], v[156:159], v[196:199], v[60:63]
	v_mfma_f32_16x16x32_f16 v[64:67], v[160:163], v[196:199], v[64:67]
	s_waitcnt lgkmcnt(0)
	s_barrier
	v_mfma_f32_16x16x32_f16 v[68:71], v[148:151], v[238:241], v[68:71]
	v_mfma_f32_16x16x32_f16 v[72:75], v[152:155], v[238:241], v[72:75]
	v_mfma_f32_16x16x32_f16 v[76:79], v[156:159], v[238:241], v[76:79]
	v_mfma_f32_16x16x32_f16 v[80:83], v[160:163], v[238:241], v[80:83]
	v_mfma_f32_16x16x32_f16 v[84:87], v[148:151], v[242:245], v[84:87]
	v_mfma_f32_16x16x32_f16 v[88:91], v[152:155], v[242:245], v[88:91]
	v_mfma_f32_16x16x32_f16 v[92:95], v[156:159], v[242:245], v[92:95]
	v_mfma_f32_16x16x32_f16 v[96:99], v[160:163], v[242:245], v[96:99]
	v_mfma_f32_16x16x32_f16 v[100:103], v[148:151], v[246:249], v[100:103]
	v_mfma_f32_16x16x32_f16 v[104:107], v[152:155], v[246:249], v[104:107]
	v_mfma_f32_16x16x32_f16 v[108:111], v[156:159], v[246:249], v[108:111]
	v_mfma_f32_16x16x32_f16 v[112:115], v[160:163], v[246:249], v[112:115]
	v_mfma_f32_16x16x32_f16 v[116:119], v[148:151], v[250:253], v[116:119]
	v_mfma_f32_16x16x32_f16 v[120:123], v[152:155], v[250:253], v[120:123]
	v_mfma_f32_16x16x32_f16 v[124:127], v[156:159], v[250:253], v[124:127]
	v_mfma_f32_16x16x32_f16 v[128:131], v[160:163], v[250:253], v[128:131]
	s_and_b32 s32, s48, 3
	s_lshl_b32 s32, s32, 9
	s_lshl_b32 s42, s83, 11
	s_add_u32 s32, s32, s42
	s_cmp_lt_u32 s48, 4
	s_cselect_b32 s42, 0, 0x2800000
	s_add_u32 s32, s32, s42
	s_add_u32 s24, s80, s32
	s_addc_u32 s25, s81, 0
	v_and_b32_e32 v172, 15, v200
	v_bfe_u32 v173, v200, 4, 2
	v_bfe_u32 v174, v200, 6, 2
	v_bfe_u32 v175, v200, 8, 1
	v_lshl_or_b32 v175, v175, 7, v172
	v_lshlrev_b32_e32 v176, 16, v174
	v_lshl_add_u32 v176, v175, 8, v176
	v_lshl_add_u32 v176, v173, 4, v176
	v_lshlrev_b32_e32 v177, 11, v175
	v_lshl_or_b32 v174, v174, 4, v173
	v_lshl_add_u32 v177, v174, 3, v177
	v_and_b32_e32 v172, 1, v173
	v_mul_u32_u24_e32 v172, 24, v172
	v_add_u32_e32 v177, v177, v172
	s_cmp_lt_u32 s48, 4
	s_cbranch_scc0 .Lqk_k
	v_pk_mul_f32 v[4:5], v[4:5], s[12:13] op_sel_hi:[1,0]
	v_pk_mul_f32 v[6:7], v[6:7], s[12:13] op_sel_hi:[1,0]
	v_pk_mul_f32 v[8:9], v[8:9], s[12:13] op_sel_hi:[1,0]
	v_pk_mul_f32 v[10:11], v[10:11], s[12:13] op_sel_hi:[1,0]
	v_pk_mul_f32 v[12:13], v[12:13], s[12:13] op_sel_hi:[1,0]
	v_pk_mul_f32 v[14:15], v[14:15], s[12:13] op_sel_hi:[1,0]
	v_pk_mul_f32 v[16:17], v[16:17], s[12:13] op_sel_hi:[1,0]
	v_pk_mul_f32 v[18:19], v[18:19], s[12:13] op_sel_hi:[1,0]
	v_pk_mul_f32 v[20:21], v[20:21], s[12:13] op_sel_hi:[1,0]
	v_pk_mul_f32 v[22:23], v[22:23], s[12:13] op_sel_hi:[1,0]
	v_pk_mul_f32 v[24:25], v[24:25], s[12:13] op_sel_hi:[1,0]
	v_pk_mul_f32 v[26:27], v[26:27], s[12:13] op_sel_hi:[1,0]
	v_pk_mul_f32 v[28:29], v[28:29], s[12:13] op_sel_hi:[1,0]
	v_pk_mul_f32 v[30:31], v[30:31], s[12:13] op_sel_hi:[1,0]
	v_pk_mul_f32 v[32:33], v[32:33], s[12:13] op_sel_hi:[1,0]
	v_pk_mul_f32 v[34:35], v[34:35], s[12:13] op_sel_hi:[1,0]
	v_pk_mul_f32 v[36:37], v[36:37], s[12:13] op_sel_hi:[1,0]
	v_pk_mul_f32 v[38:39], v[38:39], s[12:13] op_sel_hi:[1,0]
	v_pk_mul_f32 v[40:41], v[40:41], s[12:13] op_sel_hi:[1,0]
	v_pk_mul_f32 v[42:43], v[42:43], s[12:13] op_sel_hi:[1,0]
	v_pk_mul_f32 v[44:45], v[44:45], s[12:13] op_sel_hi:[1,0]
	v_pk_mul_f32 v[46:47], v[46:47], s[12:13] op_sel_hi:[1,0]
	v_pk_mul_f32 v[48:49], v[48:49], s[12:13] op_sel_hi:[1,0]
	v_pk_mul_f32 v[50:51], v[50:51], s[12:13] op_sel_hi:[1,0]
	v_pk_mul_f32 v[52:53], v[52:53], s[12:13] op_sel_hi:[1,0]
	v_pk_mul_f32 v[54:55], v[54:55], s[12:13] op_sel_hi:[1,0]
	v_pk_mul_f32 v[56:57], v[56:57], s[12:13] op_sel_hi:[1,0]
	v_pk_mul_f32 v[58:59], v[58:59], s[12:13] op_sel_hi:[1,0]
	v_pk_mul_f32 v[60:61], v[60:61], s[12:13] op_sel_hi:[1,0]
	v_pk_mul_f32 v[62:63], v[62:63], s[12:13] op_sel_hi:[1,0]
	v_pk_mul_f32 v[64:65], v[64:65], s[12:13] op_sel_hi:[1,0]
	v_pk_mul_f32 v[66:67], v[66:67], s[12:13] op_sel_hi:[1,0]
	v_pk_mul_f32 v[68:69], v[68:69], s[12:13] op_sel_hi:[1,0]
	v_pk_mul_f32 v[70:71], v[70:71], s[12:13] op_sel_hi:[1,0]
	v_pk_mul_f32 v[72:73], v[72:73], s[12:13] op_sel_hi:[1,0]
	v_pk_mul_f32 v[74:75], v[74:75], s[12:13] op_sel_hi:[1,0]
	v_pk_mul_f32 v[76:77], v[76:77], s[12:13] op_sel_hi:[1,0]
	v_pk_mul_f32 v[78:79], v[78:79], s[12:13] op_sel_hi:[1,0]
	v_pk_mul_f32 v[80:81], v[80:81], s[12:13] op_sel_hi:[1,0]
	v_pk_mul_f32 v[82:83], v[82:83], s[12:13] op_sel_hi:[1,0]
	v_pk_mul_f32 v[84:85], v[84:85], s[12:13] op_sel_hi:[1,0]
	v_pk_mul_f32 v[86:87], v[86:87], s[12:13] op_sel_hi:[1,0]
	v_pk_mul_f32 v[88:89], v[88:89], s[12:13] op_sel_hi:[1,0]
	v_pk_mul_f32 v[90:91], v[90:91], s[12:13] op_sel_hi:[1,0]
	v_pk_mul_f32 v[92:93], v[92:93], s[12:13] op_sel_hi:[1,0]
	v_pk_mul_f32 v[94:95], v[94:95], s[12:13] op_sel_hi:[1,0]
	v_pk_mul_f32 v[96:97], v[96:97], s[12:13] op_sel_hi:[1,0]
	v_pk_mul_f32 v[98:99], v[98:99], s[12:13] op_sel_hi:[1,0]
	v_pk_mul_f32 v[100:101], v[100:101], s[12:13] op_sel_hi:[1,0]
	v_pk_mul_f32 v[102:103], v[102:103], s[12:13] op_sel_hi:[1,0]
	v_pk_mul_f32 v[104:105], v[104:105], s[12:13] op_sel_hi:[1,0]
	v_pk_mul_f32 v[106:107], v[106:107], s[12:13] op_sel_hi:[1,0]
	v_pk_mul_f32 v[108:109], v[108:109], s[12:13] op_sel_hi:[1,0]
	v_pk_mul_f32 v[110:111], v[110:111], s[12:13] op_sel_hi:[1,0]
	v_pk_mul_f32 v[112:113], v[112:113], s[12:13] op_sel_hi:[1,0]
	v_pk_mul_f32 v[114:115], v[114:115], s[12:13] op_sel_hi:[1,0]
	v_pk_mul_f32 v[116:117], v[116:117], s[12:13] op_sel_hi:[1,0]
	v_pk_mul_f32 v[118:119], v[118:119], s[12:13] op_sel_hi:[1,0]
	v_pk_mul_f32 v[120:121], v[120:121], s[12:13] op_sel_hi:[1,0]
	v_pk_mul_f32 v[122:123], v[122:123], s[12:13] op_sel_hi:[1,0]
	v_pk_mul_f32 v[124:125], v[124:125], s[12:13] op_sel_hi:[1,0]
	v_pk_mul_f32 v[126:127], v[126:127], s[12:13] op_sel_hi:[1,0]
	v_pk_mul_f32 v[128:129], v[128:129], s[12:13] op_sel_hi:[1,0]
	v_pk_mul_f32 v[130:131], v[130:131], s[12:13] op_sel_hi:[1,0]
	s_branch .Lqk_pack

.Lt_mlp1a:
	v_add_u32_e32 v169, s37, v164
	v_mfma_f32_16x16x32_f16 v[4:7], v[132:135], v[184:187], v[4:7]
	ds_read_b128 v[238:241], v169 offset:4112
	v_mfma_f32_16x16x32_f16 v[8:11], v[136:139], v[184:187], v[8:11]
	ds_read_b128 v[242:245], v169 offset:5136
	v_mfma_f32_16x16x32_f16 v[12:15], v[140:143], v[184:187], v[12:15]
	ds_read_b128 v[246:249], v169 offset:6160
	v_mfma_f32_16x16x32_f16 v[16:19], v[144:147], v[184:187], v[16:19]
	ds_read_b128 v[250:253], v169 offset:7184
	v_mfma_f32_16x16x32_f16 v[20:23], v[132:135], v[188:191], v[20:23]
	v_mfma_f32_16x16x32_f16 v[24:27], v[136:139], v[188:191], v[24:27]
	v_mfma_f32_16x16x32_f16 v[28:31], v[140:143], v[188:191], v[28:31]
	v_mfma_f32_16x16x32_f16 v[32:35], v[144:147], v[188:191], v[32:35]
	v_mfma_f32_16x16x32_f16 v[36:39], v[132:135], v[192:195], v[36:39]
	v_mfma_f32_16x16x32_f16 v[40:43], v[136:139], v[192:195], v[40:43]
	v_mfma_f32_16x16x32_f16 v[44:47], v[140:143], v[192:195], v[44:47]
	v_mfma_f32_16x16x32_f16 v[48:51], v[144:147], v[192:195], v[48:51]
	v_mfma_f32_16x16x32_f16 v[52:55], v[132:135], v[196:199], v[52:55]
	v_mfma_f32_16x16x32_f16 v[56:59], v[136:139], v[196:199], v[56:59]
	v_mfma_f32_16x16x32_f16 v[60:63], v[140:143], v[196:199], v[60:63]
	v_mfma_f32_16x16x32_f16 v[64:67], v[144:147], v[196:199], v[64:67]
	s_waitcnt vmcnt(8) lgkmcnt(0)
	s_barrier
	s_add_i32 s53, s37, 0x8000
	s_cmp_lg_u32 s37, 0x18000
	s_cselect_b32 s53, s53, 0
	v_add_u32_e32 v168, s53, v165
	v_add_u32_e32 v169, s53, v164
	s_add_u32 vcc_lo, s32, s37
	v_mfma_f32_16x16x32_f16 v[68:71], v[132:135], v[238:241], v[68:71]
	ds_read_b128 v[148:151], v168 offset:16
	ds_read_b128 v[184:187], v169 offset:16
	s_mov_b32 m0, vcc_lo
	s_nop 0
	global_load_lds_dwordx4 v170, s[30:31]
	v_mfma_f32_16x16x32_f16 v[72:75], v[136:139], v[238:241], v[72:75]
	ds_read_b128 v[152:155], v168 offset:1040
	ds_read_b128 v[188:191], v169 offset:1040
	s_add_u32 m0, vcc_lo, 0x400
	s_nop 0
	global_load_lds_dwordx4 v171, s[30:31]
	v_mfma_f32_16x16x32_f16 v[76:79], v[140:143], v[238:241], v[76:79]
	ds_read_b128 v[156:159], v168 offset:2064
	ds_read_b128 v[192:195], v169 offset:2064
	s_add_u32 m0, vcc_lo, 0x4000
	s_nop 0
	global_load_lds_dwordx4 v170, s[56:57]
	v_mfma_f32_16x16x32_f16 v[80:83], v[144:147], v[238:241], v[80:83]
	ds_read_b128 v[160:163], v168 offset:3088
	ds_read_b128 v[196:199], v169 offset:3088
	s_add_u32 m0, vcc_lo, 0x4400
	s_nop 0
	global_load_lds_dwordx4 v171, s[56:57]
	v_mfma_f32_16x16x32_f16 v[84:87], v[132:135], v[242:245], v[84:87]
	v_mfma_f32_16x16x32_f16 v[88:91], v[136:139], v[242:245], v[88:91]
	v_mfma_f32_16x16x32_f16 v[92:95], v[140:143], v[242:245], v[92:95]
	v_mfma_f32_16x16x32_f16 v[96:99], v[144:147], v[242:245], v[96:99]
	v_mfma_f32_16x16x32_f16 v[100:103], v[132:135], v[246:249], v[100:103]
	v_mfma_f32_16x16x32_f16 v[104:107], v[136:139], v[246:249], v[104:107]
	v_mfma_f32_16x16x32_f16 v[108:111], v[140:143], v[246:249], v[108:111]
	v_mfma_f32_16x16x32_f16 v[112:115], v[144:147], v[246:249], v[112:115]
	v_mfma_f32_16x16x32_f16 v[116:119], v[132:135], v[250:253], v[116:119]
	v_mfma_f32_16x16x32_f16 v[120:123], v[136:139], v[250:253], v[120:123]
	v_mfma_f32_16x16x32_f16 v[124:127], v[140:143], v[250:253], v[124:127]
	v_mfma_f32_16x16x32_f16 v[128:131], v[144:147], v[250:253], v[128:131]
	s_waitcnt lgkmcnt(0)
	s_mov_b32 s37, s53
	s_add_u32 s30, s30, 64
	s_addc_u32 s31, s31, 0
	s_add_u32 s56, s56, 64
	s_addc_u32 s57, s57, 0
	v_add_u32_e32 v169, s37, v164
	v_mfma_f32_16x16x32_f16 v[4:7], v[148:151], v[184:187], v[4:7]
	ds_read_b128 v[238:241], v169 offset:4112
	v_mfma_f32_16x16x32_f16 v[8:11], v[152:155], v[184:187], v[8:11]
	ds_read_b128 v[242:245], v169 offset:5136
	v_mfma_f32_16x16x32_f16 v[12:15], v[156:159], v[184:187], v[12:15]
	ds_read_b128 v[246:249], v169 offset:6160
	v_mfma_f32_16x16x32_f16 v[16:19], v[160:163], v[184:187], v[16:19]
	ds_read_b128 v[250:253], v169 offset:7184
	v_mfma_f32_16x16x32_f16 v[20:23], v[148:151], v[188:191], v[20:23]
	v_mfma_f32_16x16x32_f16 v[24:27], v[152:155], v[188:191], v[24:27]
	v_mfma_f32_16x16x32_f16 v[28:31], v[156:159], v[188:191], v[28:31]
	v_mfma_f32_16x16x32_f16 v[32:35], v[160:163], v[188:191], v[32:35]
	v_mfma_f32_16x16x32_f16 v[36:39], v[148:151], v[192:195], v[36:39]
	v_mfma_f32_16x16x32_f16 v[40:43], v[152:155], v[192:195], v[40:43]
	v_mfma_f32_16x16x32_f16 v[44:47], v[156:159], v[192:195], v[44:47]
	v_mfma_f32_16x16x32_f16 v[48:51], v[160:163], v[192:195], v[48:51]
	v_mfma_f32_16x16x32_f16 v[52:55], v[148:151], v[196:199], v[52:55]
	v_mfma_f32_16x16x32_f16 v[56:59], v[152:155], v[196:199], v[56:59]
	v_mfma_f32_16x16x32_f16 v[60:63], v[156:159], v[196:199], v[60:63]
	v_mfma_f32_16x16x32_f16 v[64:67], v[160:163], v[196:199], v[64:67]
	s_waitcnt vmcnt(8) lgkmcnt(0)
	s_barrier
	s_add_i32 s53, s37, 0x8000
	s_cmp_lg_u32 s37, 0x18000
	s_cselect_b32 s53, s53, 0
	v_add_u32_e32 v168, s53, v165
	v_add_u32_e32 v169, s53, v164
	s_add_u32 vcc_lo, s32, s37
	v_mfma_f32_16x16x32_f16 v[68:71], v[148:151], v[238:241], v[68:71]
	ds_read_b128 v[132:135], v168 offset:16
	ds_read_b128 v[184:187], v169 offset:16
	s_mov_b32 m0, vcc_lo
	s_nop 0
	global_load_lds_dwordx4 v170, s[30:31]
	v_mfma_f32_16x16x32_f16 v[72:75], v[152:155], v[238:241], v[72:75]
	ds_read_b128 v[136:139], v168 offset:1040
	ds_read_b128 v[188:191], v169 offset:1040
	s_add_u32 m0, vcc_lo, 0x400
	s_nop 0
	global_load_lds_dwordx4 v171, s[30:31]
	v_mfma_f32_16x16x32_f16 v[76:79], v[156:159], v[238:241], v[76:79]
	ds_read_b128 v[140:143], v168 offset:2064
	ds_read_b128 v[192:195], v169 offset:2064
	s_add_u32 m0, vcc_lo, 0x4000
	s_nop 0
	global_load_lds_dwordx4 v170, s[56:57]
	v_mfma_f32_16x16x32_f16 v[80:83], v[160:163], v[238:241], v[80:83]
	ds_read_b128 v[144:147], v168 offset:3088
	ds_read_b128 v[196:199], v169 offset:3088
	s_add_u32 m0, vcc_lo, 0x4400
	s_nop 0
	global_load_lds_dwordx4 v171, s[56:57]
	v_mfma_f32_16x16x32_f16 v[84:87], v[148:151], v[242:245], v[84:87]
	v_mfma_f32_16x16x32_f16 v[88:91], v[152:155], v[242:245], v[88:91]
	v_mfma_f32_16x16x32_f16 v[92:95], v[156:159], v[242:245], v[92:95]
	v_mfma_f32_16x16x32_f16 v[96:99], v[160:163], v[242:245], v[96:99]
	v_mfma_f32_16x16x32_f16 v[100:103], v[148:151], v[246:249], v[100:103]
	v_mfma_f32_16x16x32_f16 v[104:107], v[152:155], v[246:249], v[104:107]
	v_mfma_f32_16x16x32_f16 v[108:111], v[156:159], v[246:249], v[108:111]
	v_mfma_f32_16x16x32_f16 v[112:115], v[160:163], v[246:249], v[112:115]
	v_mfma_f32_16x16x32_f16 v[116:119], v[148:151], v[250:253], v[116:119]
	v_mfma_f32_16x16x32_f16 v[120:123], v[152:155], v[250:253], v[120:123]
	v_mfma_f32_16x16x32_f16 v[124:127], v[156:159], v[250:253], v[124:127]
	v_mfma_f32_16x16x32_f16 v[128:131], v[160:163], v[250:253], v[128:131]
	s_waitcnt lgkmcnt(0)
	s_mov_b32 s37, s53
	s_add_u32 s30, s30, 64
	s_addc_u32 s31, s31, 0
	s_add_u32 s56, s56, 64
	s_addc_u32 s57, s57, 0
	s_add_i32 s55, s55, 2
	s_cmp_lt_u32 s55, 28
	s_cbranch_scc1 .Lt_mlp1a
	v_add_u32_e32 v169, s37, v164
	v_mfma_f32_16x16x32_f16 v[4:7], v[132:135], v[184:187], v[4:7]
	ds_read_b128 v[238:241], v169 offset:4112
	v_mfma_f32_16x16x32_f16 v[8:11], v[136:139], v[184:187], v[8:11]
	ds_read_b128 v[242:245], v169 offset:5136
	v_mfma_f32_16x16x32_f16 v[12:15], v[140:143], v[184:187], v[12:15]
	ds_read_b128 v[246:249], v169 offset:6160
	v_mfma_f32_16x16x32_f16 v[16:19], v[144:147], v[184:187], v[16:19]
	ds_read_b128 v[250:253], v169 offset:7184
	v_mfma_f32_16x16x32_f16 v[20:23], v[132:135], v[188:191], v[20:23]
	v_mfma_f32_16x16x32_f16 v[24:27], v[136:139], v[188:191], v[24:27]
	v_mfma_f32_16x16x32_f16 v[28:31], v[140:143], v[188:191], v[28:31]
	v_mfma_f32_16x16x32_f16 v[32:35], v[144:147], v[188:191], v[32:35]
	v_mfma_f32_16x16x32_f16 v[36:39], v[132:135], v[192:195], v[36:39]
	v_mfma_f32_16x16x32_f16 v[40:43], v[136:139], v[192:195], v[40:43]
	v_mfma_f32_16x16x32_f16 v[44:47], v[140:143], v[192:195], v[44:47]
	v_mfma_f32_16x16x32_f16 v[48:51], v[144:147], v[192:195], v[48:51]
	v_mfma_f32_16x16x32_f16 v[52:55], v[132:135], v[196:199], v[52:55]
	v_mfma_f32_16x16x32_f16 v[56:59], v[136:139], v[196:199], v[56:59]
	v_mfma_f32_16x16x32_f16 v[60:63], v[140:143], v[196:199], v[60:63]
	v_mfma_f32_16x16x32_f16 v[64:67], v[144:147], v[196:199], v[64:67]
	s_waitcnt vmcnt(8) lgkmcnt(0)
	s_barrier
	s_add_i32 s53, s37, 0x8000
	s_cmp_lg_u32 s37, 0x18000
	s_cselect_b32 s53, s53, 0
	v_add_u32_e32 v168, s53, v165
	v_add_u32_e32 v169, s53, v164
	v_mfma_f32_16x16x32_f16 v[68:71], v[132:135], v[238:241], v[68:71]
	ds_read_b128 v[148:151], v168 offset:16
	ds_read_b128 v[184:187], v169 offset:16
	v_mfma_f32_16x16x32_f16 v[72:75], v[136:139], v[238:241], v[72:75]
	ds_read_b128 v[152:155], v168 offset:1040
	ds_read_b128 v[188:191], v169 offset:1040
	v_mfma_f32_16x16x32_f16 v[76:79], v[140:143], v[238:241], v[76:79]
	ds_read_b128 v[156:159], v168 offset:2064
	ds_read_b128 v[192:195], v169 offset:2064
	v_mfma_f32_16x16x32_f16 v[80:83], v[144:147], v[238:241], v[80:83]
	ds_read_b128 v[160:163], v168 offset:3088
	ds_read_b128 v[196:199], v169 offset:3088
	v_mfma_f32_16x16x32_f16 v[84:87], v[132:135], v[242:245], v[84:87]
	v_mfma_f32_16x16x32_f16 v[88:91], v[136:139], v[242:245], v[88:91]
	v_mfma_f32_16x16x32_f16 v[92:95], v[140:143], v[242:245], v[92:95]
	v_mfma_f32_16x16x32_f16 v[96:99], v[144:147], v[242:245], v[96:99]
	v_mfma_f32_16x16x32_f16 v[100:103], v[132:135], v[246:249], v[100:103]
	v_mfma_f32_16x16x32_f16 v[104:107], v[136:139], v[246:249], v[104:107]
	v_mfma_f32_16x16x32_f16 v[108:111], v[140:143], v[246:249], v[108:111]
	v_mfma_f32_16x16x32_f16 v[112:115], v[144:147], v[246:249], v[112:115]
	v_mfma_f32_16x16x32_f16 v[116:119], v[132:135], v[250:253], v[116:119]
	v_mfma_f32_16x16x32_f16 v[120:123], v[136:139], v[250:253], v[120:123]
	v_mfma_f32_16x16x32_f16 v[124:127], v[140:143], v[250:253], v[124:127]
	v_mfma_f32_16x16x32_f16 v[128:131], v[144:147], v[250:253], v[128:131]
	s_waitcnt lgkmcnt(0)
	s_mov_b32 s37, s53
	v_add_u32_e32 v169, s37, v164
	v_mfma_f32_16x16x32_f16 v[4:7], v[148:151], v[184:187], v[4:7]
	ds_read_b128 v[238:241], v169 offset:4112
	v_mfma_f32_16x16x32_f16 v[8:11], v[152:155], v[184:187], v[8:11]
	ds_read_b128 v[242:245], v169 offset:5136
	v_mfma_f32_16x16x32_f16 v[12:15], v[156:159], v[184:187], v[12:15]
	ds_read_b128 v[246:249], v169 offset:6160
	v_mfma_f32_16x16x32_f16 v[16:19], v[160:163], v[184:187], v[16:19]
	ds_read_b128 v[250:253], v169 offset:7184
	v_mfma_f32_16x16x32_f16 v[20:23], v[148:151], v[188:191], v[20:23]
	v_mfma_f32_16x16x32_f16 v[24:27], v[152:155], v[188:191], v[24:27]
	v_mfma_f32_16x16x32_f16 v[28:31], v[156:159], v[188:191], v[28:31]
	v_mfma_f32_16x16x32_f16 v[32:35], v[160:163], v[188:191], v[32:35]
	v_mfma_f32_16x16x32_f16 v[36:39], v[148:151], v[192:195], v[36:39]
	v_mfma_f32_16x16x32_f16 v[40:43], v[152:155], v[192:195], v[40:43]
	v_mfma_f32_16x16x32_f16 v[44:47], v[156:159], v[192:195], v[44:47]
	v_mfma_f32_16x16x32_f16 v[48:51], v[160:163], v[192:195], v[48:51]
	v_mfma_f32_16x16x32_f16 v[52:55], v[148:151], v[196:199], v[52:55]
	v_mfma_f32_16x16x32_f16 v[56:59], v[152:155], v[196:199], v[56:59]
	v_mfma_f32_16x16x32_f16 v[60:63], v[156:159], v[196:199], v[60:63]
	v_mfma_f32_16x16x32_f16 v[64:67], v[160:163], v[196:199], v[64:67]
	s_waitcnt vmcnt(4) lgkmcnt(0)
	s_barrier
	s_add_i32 s53, s37, 0x8000
	s_cmp_lg_u32 s37, 0x18000
	s_cselect_b32 s53, s53, 0
	v_add_u32_e32 v168, s53, v165
	v_add_u32_e32 v169, s53, v164
	v_mfma_f32_16x16x32_f16 v[68:71], v[148:151], v[238:241], v[68:71]
	ds_read_b128 v[132:135], v168 offset:16
	ds_read_b128 v[184:187], v169 offset:16
	v_mfma_f32_16x16x32_f16 v[72:75], v[152:155], v[238:241], v[72:75]
	ds_read_b128 v[136:139], v168 offset:1040
	ds_read_b128 v[188:191], v169 offset:1040
	v_mfma_f32_16x16x32_f16 v[76:79], v[156:159], v[238:241], v[76:79]
	ds_read_b128 v[140:143], v168 offset:2064
	ds_read_b128 v[192:195], v169 offset:2064
	v_mfma_f32_16x16x32_f16 v[80:83], v[160:163], v[238:241], v[80:83]
	ds_read_b128 v[144:147], v168 offset:3088
	ds_read_b128 v[196:199], v169 offset:3088
	v_mfma_f32_16x16x32_f16 v[84:87], v[148:151], v[242:245], v[84:87]
	v_mfma_f32_16x16x32_f16 v[88:91], v[152:155], v[242:245], v[88:91]
	v_mfma_f32_16x16x32_f16 v[92:95], v[156:159], v[242:245], v[92:95]
	v_mfma_f32_16x16x32_f16 v[96:99], v[160:163], v[242:245], v[96:99]
	v_mfma_f32_16x16x32_f16 v[100:103], v[148:151], v[246:249], v[100:103]
	v_mfma_f32_16x16x32_f16 v[104:107], v[152:155], v[246:249], v[104:107]
	v_mfma_f32_16x16x32_f16 v[108:111], v[156:159], v[246:249], v[108:111]
	v_mfma_f32_16x16x32_f16 v[112:115], v[160:163], v[246:249], v[112:115]
	v_mfma_f32_16x16x32_f16 v[116:119], v[148:151], v[250:253], v[116:119]
	v_mfma_f32_16x16x32_f16 v[120:123], v[152:155], v[250:253], v[120:123]
	v_mfma_f32_16x16x32_f16 v[124:127], v[156:159], v[250:253], v[124:127]
	v_mfma_f32_16x16x32_f16 v[128:131], v[160:163], v[250:253], v[128:131]
	s_waitcnt lgkmcnt(0)
	s_mov_b32 s37, s53
	v_add_u32_e32 v169, s37, v164
	v_mfma_f32_16x16x32_f16 v[4:7], v[132:135], v[184:187], v[4:7]
	ds_read_b128 v[238:241], v169 offset:4112
	v_mfma_f32_16x16x32_f16 v[8:11], v[136:139], v[184:187], v[8:11]
	ds_read_b128 v[242:245], v169 offset:5136
	v_mfma_f32_16x16x32_f16 v[12:15], v[140:143], v[184:187], v[12:15]
	ds_read_b128 v[246:249], v169 offset:6160
	v_mfma_f32_16x16x32_f16 v[16:19], v[144:147], v[184:187], v[16:19]
	ds_read_b128 v[250:253], v169 offset:7184
	v_mfma_f32_16x16x32_f16 v[20:23], v[132:135], v[188:191], v[20:23]
	v_mfma_f32_16x16x32_f16 v[24:27], v[136:139], v[188:191], v[24:27]
	v_mfma_f32_16x16x32_f16 v[28:31], v[140:143], v[188:191], v[28:31]
	v_mfma_f32_16x16x32_f16 v[32:35], v[144:147], v[188:191], v[32:35]
	v_mfma_f32_16x16x32_f16 v[36:39], v[132:135], v[192:195], v[36:39]
	v_mfma_f32_16x16x32_f16 v[40:43], v[136:139], v[192:195], v[40:43]
	v_mfma_f32_16x16x32_f16 v[44:47], v[140:143], v[192:195], v[44:47]
	v_mfma_f32_16x16x32_f16 v[48:51], v[144:147], v[192:195], v[48:51]
	v_mfma_f32_16x16x32_f16 v[52:55], v[132:135], v[196:199], v[52:55]
	v_mfma_f32_16x16x32_f16 v[56:59], v[136:139], v[196:199], v[56:59]
	v_mfma_f32_16x16x32_f16 v[60:63], v[140:143], v[196:199], v[60:63]
	v_mfma_f32_16x16x32_f16 v[64:67], v[144:147], v[196:199], v[64:67]
	s_waitcnt vmcnt(0) lgkmcnt(0)
	s_barrier
	s_add_i32 s53, s37, 0x8000
	s_cmp_lg_u32 s37, 0x18000
	s_cselect_b32 s53, s53, 0
	v_add_u32_e32 v168, s53, v165
	v_add_u32_e32 v169, s53, v164
	v_mfma_f32_16x16x32_f16 v[68:71], v[132:135], v[238:241], v[68:71]
	ds_read_b128 v[148:151], v168 offset:16
	ds_read_b128 v[184:187], v169 offset:16
	v_mfma_f32_16x16x32_f16 v[72:75], v[136:139], v[238:241], v[72:75]
	ds_read_b128 v[152:155], v168 offset:1040
	ds_read_b128 v[188:191], v169 offset:1040
	v_mfma_f32_16x16x32_f16 v[76:79], v[140:143], v[238:241], v[76:79]
	ds_read_b128 v[156:159], v168 offset:2064
	ds_read_b128 v[192:195], v169 offset:2064
	v_mfma_f32_16x16x32_f16 v[80:83], v[144:147], v[238:241], v[80:83]
	ds_read_b128 v[160:163], v168 offset:3088
	ds_read_b128 v[196:199], v169 offset:3088
	v_mfma_f32_16x16x32_f16 v[84:87], v[132:135], v[242:245], v[84:87]
	v_mfma_f32_16x16x32_f16 v[88:91], v[136:139], v[242:245], v[88:91]
	v_mfma_f32_16x16x32_f16 v[92:95], v[140:143], v[242:245], v[92:95]
	v_mfma_f32_16x16x32_f16 v[96:99], v[144:147], v[242:245], v[96:99]
	v_mfma_f32_16x16x32_f16 v[100:103], v[132:135], v[246:249], v[100:103]
	v_mfma_f32_16x16x32_f16 v[104:107], v[136:139], v[246:249], v[104:107]
	v_mfma_f32_16x16x32_f16 v[108:111], v[140:143], v[246:249], v[108:111]
	v_mfma_f32_16x16x32_f16 v[112:115], v[144:147], v[246:249], v[112:115]
	v_mfma_f32_16x16x32_f16 v[116:119], v[132:135], v[250:253], v[116:119]
	v_mfma_f32_16x16x32_f16 v[120:123], v[136:139], v[250:253], v[120:123]
	v_mfma_f32_16x16x32_f16 v[124:127], v[140:143], v[250:253], v[124:127]
	v_mfma_f32_16x16x32_f16 v[128:131], v[144:147], v[250:253], v[128:131]
	s_waitcnt lgkmcnt(0)
	s_mov_b32 s37, s53
	v_add_u32_e32 v169, s37, v164
	v_mfma_f32_16x16x32_f16 v[4:7], v[148:151], v[184:187], v[4:7]
	ds_read_b128 v[238:241], v169 offset:4112
	v_mfma_f32_16x16x32_f16 v[8:11], v[152:155], v[184:187], v[8:11]
	ds_read_b128 v[242:245], v169 offset:5136
	v_mfma_f32_16x16x32_f16 v[12:15], v[156:159], v[184:187], v[12:15]
	ds_read_b128 v[246:249], v169 offset:6160
	v_mfma_f32_16x16x32_f16 v[16:19], v[160:163], v[184:187], v[16:19]
	ds_read_b128 v[250:253], v169 offset:7184
	v_mfma_f32_16x16x32_f16 v[20:23], v[148:151], v[188:191], v[20:23]
	v_mfma_f32_16x16x32_f16 v[24:27], v[152:155], v[188:191], v[24:27]
	v_mfma_f32_16x16x32_f16 v[28:31], v[156:159], v[188:191], v[28:31]
	v_mfma_f32_16x16x32_f16 v[32:35], v[160:163], v[188:191], v[32:35]
	v_mfma_f32_16x16x32_f16 v[36:39], v[148:151], v[192:195], v[36:39]
	v_mfma_f32_16x16x32_f16 v[40:43], v[152:155], v[192:195], v[40:43]
	v_mfma_f32_16x16x32_f16 v[44:47], v[156:159], v[192:195], v[44:47]
	v_mfma_f32_16x16x32_f16 v[48:51], v[160:163], v[192:195], v[48:51]
	v_mfma_f32_16x16x32_f16 v[52:55], v[148:151], v[196:199], v[52:55]
	v_mfma_f32_16x16x32_f16 v[56:59], v[152:155], v[196:199], v[56:59]
	v_mfma_f32_16x16x32_f16 v[60:63], v[156:159], v[196:199], v[60:63]
	v_mfma_f32_16x16x32_f16 v[64:67], v[160:163], v[196:199], v[64:67]
	s_waitcnt lgkmcnt(0)
	s_barrier
	v_mfma_f32_16x16x32_f16 v[68:71], v[148:151], v[238:241], v[68:71]
	v_mfma_f32_16x16x32_f16 v[72:75], v[152:155], v[238:241], v[72:75]
	v_mfma_f32_16x16x32_f16 v[76:79], v[156:159], v[238:241], v[76:79]
	v_mfma_f32_16x16x32_f16 v[80:83], v[160:163], v[238:241], v[80:83]
	v_mfma_f32_16x16x32_f16 v[84:87], v[148:151], v[242:245], v[84:87]
	v_mfma_f32_16x16x32_f16 v[88:91], v[152:155], v[242:245], v[88:91]
	v_mfma_f32_16x16x32_f16 v[92:95], v[156:159], v[242:245], v[92:95]
	v_mfma_f32_16x16x32_f16 v[96:99], v[160:163], v[242:245], v[96:99]
	v_mfma_f32_16x16x32_f16 v[100:103], v[148:151], v[246:249], v[100:103]
	v_mfma_f32_16x16x32_f16 v[104:107], v[152:155], v[246:249], v[104:107]
	v_mfma_f32_16x16x32_f16 v[108:111], v[156:159], v[246:249], v[108:111]
	v_mfma_f32_16x16x32_f16 v[112:115], v[160:163], v[246:249], v[112:115]
	v_mfma_f32_16x16x32_f16 v[116:119], v[148:151], v[250:253], v[116:119]
	v_mfma_f32_16x16x32_f16 v[120:123], v[152:155], v[250:253], v[120:123]
	v_mfma_f32_16x16x32_f16 v[124:127], v[156:159], v[250:253], v[124:127]
	v_mfma_f32_16x16x32_f16 v[128:131], v[160:163], v[250:253], v[128:131]
	s_lshl_b64 s[80:81], s[28:29], 13
	s_add_u32 s80, s80, s34
	s_addc_u32 s81, s81, s35
	s_lshl_b32 s82, s65, 1
	s_add_u32 s80, s80, s82
	s_addc_u32 s81, s81, 0
	v_and_b32_e32 v172, 15, v200
	v_bfe_u32 v173, v200, 4, 2
	v_bfe_u32 v174, v200, 6, 2
	v_bfe_u32 v175, v200, 8, 1
	v_lshl_or_b32 v175, v175, 7, v172
	v_lshlrev_b32_e32 v175, 13, v175
	v_lshlrev_b32_e32 v174, 6, v174
	v_lshl_or_b32 v174, v173, 2, v174
	v_lshl_add_u32 v177, v174, 1, v175
	v_and_b32_e32 v172, 1, v173
	v_mul_u32_u24_e32 v172, 24, v172
	v_add_u32_e32 v177, v177, v172
	v_max_f32_e32 v4, 0, v4
	v_max_f32_e32 v5, 0, v5
	v_max_f32_e32 v6, 0, v6
	v_max_f32_e32 v7, 0, v7
	v_pk_mul_f32 v[4:5], v[4:5], v[4:5]
	v_pk_mul_f32 v[6:7], v[6:7], v[6:7]
	v_cvt_pk_f16_f32 v172, v4, v5
	v_cvt_pk_f16_f32 v173, v6, v7
	v_max_f32_e32 v8, 0, v8
	v_max_f32_e32 v9, 0, v9
	v_max_f32_e32 v10, 0, v10
	v_max_f32_e32 v11, 0, v11
	v_pk_mul_f32 v[8:9], v[8:9], v[8:9]
	v_pk_mul_f32 v[10:11], v[10:11], v[10:11]
	v_cvt_pk_f16_f32 v174, v8, v9
	v_cvt_pk_f16_f32 v175, v10, v11
	s_nop 1
	v_permlane16_swap_b32_e32 v172, v174
	v_permlane16_swap_b32_e32 v173, v175
	global_store_dwordx4 v177, v[172:175], s[80:81]
	v_max_f32_e32 v12, 0, v12
	v_max_f32_e32 v13, 0, v13
	v_max_f32_e32 v14, 0, v14
	v_max_f32_e32 v15, 0, v15
	v_pk_mul_f32 v[12:13], v[12:13], v[12:13]
	v_pk_mul_f32 v[14:15], v[14:15], v[14:15]
	v_cvt_pk_f16_f32 v228, v12, v13
	v_cvt_pk_f16_f32 v229, v14, v15
	v_max_f32_e32 v16, 0, v16
	v_max_f32_e32 v17, 0, v17
	v_max_f32_e32 v18, 0, v18
	v_max_f32_e32 v19, 0, v19
	v_pk_mul_f32 v[16:17], v[16:17], v[16:17]
	v_pk_mul_f32 v[18:19], v[18:19], v[18:19]
	v_cvt_pk_f16_f32 v230, v16, v17
	v_cvt_pk_f16_f32 v231, v18, v19
	s_nop 1
	v_permlane16_swap_b32_e32 v228, v230
	v_permlane16_swap_b32_e32 v229, v231
	global_store_dwordx4 v177, v[228:231], s[80:81] offset:64
	v_add_u32_e32 v177, 0x20000, v177
	v_max_f32_e32 v20, 0, v20
	v_max_f32_e32 v21, 0, v21
	v_max_f32_e32 v22, 0, v22
	v_max_f32_e32 v23, 0, v23
	v_pk_mul_f32 v[20:21], v[20:21], v[20:21]
	v_pk_mul_f32 v[22:23], v[22:23], v[22:23]
	v_cvt_pk_f16_f32 v172, v20, v21
	v_cvt_pk_f16_f32 v173, v22, v23
	v_max_f32_e32 v24, 0, v24
	v_max_f32_e32 v25, 0, v25
	v_max_f32_e32 v26, 0, v26
	v_max_f32_e32 v27, 0, v27
	v_pk_mul_f32 v[24:25], v[24:25], v[24:25]
	v_pk_mul_f32 v[26:27], v[26:27], v[26:27]
	v_cvt_pk_f16_f32 v174, v24, v25
	v_cvt_pk_f16_f32 v175, v26, v27
	s_nop 1
	v_permlane16_swap_b32_e32 v172, v174
	v_permlane16_swap_b32_e32 v173, v175
	global_store_dwordx4 v177, v[172:175], s[80:81]
	v_max_f32_e32 v28, 0, v28
	v_max_f32_e32 v29, 0, v29
	v_max_f32_e32 v30, 0, v30
	v_max_f32_e32 v31, 0, v31
	v_pk_mul_f32 v[28:29], v[28:29], v[28:29]
	v_pk_mul_f32 v[30:31], v[30:31], v[30:31]
	v_cvt_pk_f16_f32 v228, v28, v29
	v_cvt_pk_f16_f32 v229, v30, v31
	v_max_f32_e32 v32, 0, v32
	v_max_f32_e32 v33, 0, v33
	v_max_f32_e32 v34, 0, v34
	v_max_f32_e32 v35, 0, v35
	v_pk_mul_f32 v[32:33], v[32:33], v[32:33]
	v_pk_mul_f32 v[34:35], v[34:35], v[34:35]
	v_cvt_pk_f16_f32 v230, v32, v33
	v_cvt_pk_f16_f32 v231, v34, v35
	s_nop 1
	v_permlane16_swap_b32_e32 v228, v230
	v_permlane16_swap_b32_e32 v229, v231
	global_store_dwordx4 v177, v[228:231], s[80:81] offset:64
	v_add_u32_e32 v177, 0x20000, v177
	v_max_f32_e32 v36, 0, v36
	v_max_f32_e32 v37, 0, v37
	v_max_f32_e32 v38, 0, v38
	v_max_f32_e32 v39, 0, v39
	v_pk_mul_f32 v[36:37], v[36:37], v[36:37]
	v_pk_mul_f32 v[38:39], v[38:39], v[38:39]
	v_cvt_pk_f16_f32 v172, v36, v37
	v_cvt_pk_f16_f32 v173, v38, v39
	v_max_f32_e32 v40, 0, v40
	v_max_f32_e32 v41, 0, v41
	v_max_f32_e32 v42, 0, v42
	v_max_f32_e32 v43, 0, v43
	v_pk_mul_f32 v[40:41], v[40:41], v[40:41]
	v_pk_mul_f32 v[42:43], v[42:43], v[42:43]
	v_cvt_pk_f16_f32 v174, v40, v41
	v_cvt_pk_f16_f32 v175, v42, v43
	s_nop 1
	v_permlane16_swap_b32_e32 v172, v174
	v_permlane16_swap_b32_e32 v173, v175
	global_store_dwordx4 v177, v[172:175], s[80:81]
	v_max_f32_e32 v44, 0, v44
	v_max_f32_e32 v45, 0, v45
	v_max_f32_e32 v46, 0, v46
	v_max_f32_e32 v47, 0, v47
	v_pk_mul_f32 v[44:45], v[44:45], v[44:45]
	v_pk_mul_f32 v[46:47], v[46:47], v[46:47]
	v_cvt_pk_f16_f32 v228, v44, v45
	v_cvt_pk_f16_f32 v229, v46, v47
	v_max_f32_e32 v48, 0, v48
	v_max_f32_e32 v49, 0, v49
	v_max_f32_e32 v50, 0, v50
	v_max_f32_e32 v51, 0, v51
	v_pk_mul_f32 v[48:49], v[48:49], v[48:49]
	v_pk_mul_f32 v[50:51], v[50:51], v[50:51]
	v_cvt_pk_f16_f32 v230, v48, v49
	v_cvt_pk_f16_f32 v231, v50, v51
	s_nop 1
	v_permlane16_swap_b32_e32 v228, v230
	v_permlane16_swap_b32_e32 v229, v231
	global_store_dwordx4 v177, v[228:231], s[80:81] offset:64
	v_add_u32_e32 v177, 0x20000, v177
	v_max_f32_e32 v52, 0, v52
	v_max_f32_e32 v53, 0, v53
	v_max_f32_e32 v54, 0, v54
	v_max_f32_e32 v55, 0, v55
	v_pk_mul_f32 v[52:53], v[52:53], v[52:53]
	v_pk_mul_f32 v[54:55], v[54:55], v[54:55]
	v_cvt_pk_f16_f32 v172, v52, v53
	v_cvt_pk_f16_f32 v173, v54, v55
	v_max_f32_e32 v56, 0, v56
	v_max_f32_e32 v57, 0, v57
	v_max_f32_e32 v58, 0, v58
	v_max_f32_e32 v59, 0, v59
	v_pk_mul_f32 v[56:57], v[56:57], v[56:57]
	v_pk_mul_f32 v[58:59], v[58:59], v[58:59]
	v_cvt_pk_f16_f32 v174, v56, v57
	v_cvt_pk_f16_f32 v175, v58, v59
	s_nop 1
	v_permlane16_swap_b32_e32 v172, v174
	v_permlane16_swap_b32_e32 v173, v175
	global_store_dwordx4 v177, v[172:175], s[80:81]
	v_max_f32_e32 v60, 0, v60
	v_max_f32_e32 v61, 0, v61
	v_max_f32_e32 v62, 0, v62
	v_max_f32_e32 v63, 0, v63
	v_pk_mul_f32 v[60:61], v[60:61], v[60:61]
	v_pk_mul_f32 v[62:63], v[62:63], v[62:63]
	v_cvt_pk_f16_f32 v228, v60, v61
	v_cvt_pk_f16_f32 v229, v62, v63
	v_max_f32_e32 v64, 0, v64
	v_max_f32_e32 v65, 0, v65
	v_max_f32_e32 v66, 0, v66
	v_max_f32_e32 v67, 0, v67
	v_pk_mul_f32 v[64:65], v[64:65], v[64:65]
	v_pk_mul_f32 v[66:67], v[66:67], v[66:67]
	v_cvt_pk_f16_f32 v230, v64, v65
	v_cvt_pk_f16_f32 v231, v66, v67
	s_nop 1
	v_permlane16_swap_b32_e32 v228, v230
	v_permlane16_swap_b32_e32 v229, v231
	global_store_dwordx4 v177, v[228:231], s[80:81] offset:64
	v_add_u32_e32 v177, 0x20000, v177
	v_max_f32_e32 v68, 0, v68
	v_max_f32_e32 v69, 0, v69
	v_max_f32_e32 v70, 0, v70
	v_max_f32_e32 v71, 0, v71
	v_pk_mul_f32 v[68:69], v[68:69], v[68:69]
	v_pk_mul_f32 v[70:71], v[70:71], v[70:71]
	v_cvt_pk_f16_f32 v172, v68, v69
	v_cvt_pk_f16_f32 v173, v70, v71
	v_max_f32_e32 v72, 0, v72
	v_max_f32_e32 v73, 0, v73
	v_max_f32_e32 v74, 0, v74
	v_max_f32_e32 v75, 0, v75
	v_pk_mul_f32 v[72:73], v[72:73], v[72:73]
	v_pk_mul_f32 v[74:75], v[74:75], v[74:75]
	v_cvt_pk_f16_f32 v174, v72, v73
	v_cvt_pk_f16_f32 v175, v74, v75
	s_nop 1
	v_permlane16_swap_b32_e32 v172, v174
	v_permlane16_swap_b32_e32 v173, v175
	global_store_dwordx4 v177, v[172:175], s[80:81]
	v_max_f32_e32 v76, 0, v76
	v_max_f32_e32 v77, 0, v77
	v_max_f32_e32 v78, 0, v78
	v_max_f32_e32 v79, 0, v79
	v_pk_mul_f32 v[76:77], v[76:77], v[76:77]
	v_pk_mul_f32 v[78:79], v[78:79], v[78:79]
	v_cvt_pk_f16_f32 v228, v76, v77
	v_cvt_pk_f16_f32 v229, v78, v79
	v_max_f32_e32 v80, 0, v80
	v_max_f32_e32 v81, 0, v81
	v_max_f32_e32 v82, 0, v82
	v_max_f32_e32 v83, 0, v83
	v_pk_mul_f32 v[80:81], v[80:81], v[80:81]
	v_pk_mul_f32 v[82:83], v[82:83], v[82:83]
	v_cvt_pk_f16_f32 v230, v80, v81
	v_cvt_pk_f16_f32 v231, v82, v83
	s_nop 1
	v_permlane16_swap_b32_e32 v228, v230
	v_permlane16_swap_b32_e32 v229, v231
	global_store_dwordx4 v177, v[228:231], s[80:81] offset:64
	v_add_u32_e32 v177, 0x20000, v177
	v_max_f32_e32 v84, 0, v84
	v_max_f32_e32 v85, 0, v85
	v_max_f32_e32 v86, 0, v86
	v_max_f32_e32 v87, 0, v87
	v_pk_mul_f32 v[84:85], v[84:85], v[84:85]
	v_pk_mul_f32 v[86:87], v[86:87], v[86:87]
	v_cvt_pk_f16_f32 v172, v84, v85
	v_cvt_pk_f16_f32 v173, v86, v87
	v_max_f32_e32 v88, 0, v88
	v_max_f32_e32 v89, 0, v89
	v_max_f32_e32 v90, 0, v90
	v_max_f32_e32 v91, 0, v91
	v_pk_mul_f32 v[88:89], v[88:89], v[88:89]
	v_pk_mul_f32 v[90:91], v[90:91], v[90:91]
	v_cvt_pk_f16_f32 v174, v88, v89
	v_cvt_pk_f16_f32 v175, v90, v91
	s_nop 1
	v_permlane16_swap_b32_e32 v172, v174
	v_permlane16_swap_b32_e32 v173, v175
	global_store_dwordx4 v177, v[172:175], s[80:81]
	v_max_f32_e32 v92, 0, v92
	v_max_f32_e32 v93, 0, v93
	v_max_f32_e32 v94, 0, v94
	v_max_f32_e32 v95, 0, v95
	v_pk_mul_f32 v[92:93], v[92:93], v[92:93]
	v_pk_mul_f32 v[94:95], v[94:95], v[94:95]
	v_cvt_pk_f16_f32 v228, v92, v93
	v_cvt_pk_f16_f32 v229, v94, v95
	v_max_f32_e32 v96, 0, v96
	v_max_f32_e32 v97, 0, v97
	v_max_f32_e32 v98, 0, v98
	v_max_f32_e32 v99, 0, v99
	v_pk_mul_f32 v[96:97], v[96:97], v[96:97]
	v_pk_mul_f32 v[98:99], v[98:99], v[98:99]
	v_cvt_pk_f16_f32 v230, v96, v97
	v_cvt_pk_f16_f32 v231, v98, v99
	s_nop 1
	v_permlane16_swap_b32_e32 v228, v230
	v_permlane16_swap_b32_e32 v229, v231
	global_store_dwordx4 v177, v[228:231], s[80:81] offset:64
	v_add_u32_e32 v177, 0x20000, v177
	v_max_f32_e32 v100, 0, v100
	v_max_f32_e32 v101, 0, v101
	v_max_f32_e32 v102, 0, v102
	v_max_f32_e32 v103, 0, v103
	v_pk_mul_f32 v[100:101], v[100:101], v[100:101]
	v_pk_mul_f32 v[102:103], v[102:103], v[102:103]
	v_cvt_pk_f16_f32 v172, v100, v101
	v_cvt_pk_f16_f32 v173, v102, v103
	v_max_f32_e32 v104, 0, v104
	v_max_f32_e32 v105, 0, v105
	v_max_f32_e32 v106, 0, v106
	v_max_f32_e32 v107, 0, v107
	v_pk_mul_f32 v[104:105], v[104:105], v[104:105]
	v_pk_mul_f32 v[106:107], v[106:107], v[106:107]
	v_cvt_pk_f16_f32 v174, v104, v105
	v_cvt_pk_f16_f32 v175, v106, v107
	s_nop 1
	v_permlane16_swap_b32_e32 v172, v174
	v_permlane16_swap_b32_e32 v173, v175
	global_store_dwordx4 v177, v[172:175], s[80:81]
	v_max_f32_e32 v108, 0, v108
	v_max_f32_e32 v109, 0, v109
	v_max_f32_e32 v110, 0, v110
	v_max_f32_e32 v111, 0, v111
	v_pk_mul_f32 v[108:109], v[108:109], v[108:109]
	v_pk_mul_f32 v[110:111], v[110:111], v[110:111]
	v_cvt_pk_f16_f32 v228, v108, v109
	v_cvt_pk_f16_f32 v229, v110, v111
	v_max_f32_e32 v112, 0, v112
	v_max_f32_e32 v113, 0, v113
	v_max_f32_e32 v114, 0, v114
	v_max_f32_e32 v115, 0, v115
	v_pk_mul_f32 v[112:113], v[112:113], v[112:113]
	v_pk_mul_f32 v[114:115], v[114:115], v[114:115]
	v_cvt_pk_f16_f32 v230, v112, v113
	v_cvt_pk_f16_f32 v231, v114, v115
	s_nop 1
	v_permlane16_swap_b32_e32 v228, v230
	v_permlane16_swap_b32_e32 v229, v231
	global_store_dwordx4 v177, v[228:231], s[80:81] offset:64
	v_add_u32_e32 v177, 0x20000, v177
	v_max_f32_e32 v116, 0, v116
	v_max_f32_e32 v117, 0, v117
	v_max_f32_e32 v118, 0, v118
	v_max_f32_e32 v119, 0, v119
	v_pk_mul_f32 v[116:117], v[116:117], v[116:117]
	v_pk_mul_f32 v[118:119], v[118:119], v[118:119]
	v_cvt_pk_f16_f32 v172, v116, v117
	v_cvt_pk_f16_f32 v173, v118, v119
	v_max_f32_e32 v120, 0, v120
	v_max_f32_e32 v121, 0, v121
	v_max_f32_e32 v122, 0, v122
	v_max_f32_e32 v123, 0, v123
	v_pk_mul_f32 v[120:121], v[120:121], v[120:121]
	v_pk_mul_f32 v[122:123], v[122:123], v[122:123]
	v_cvt_pk_f16_f32 v174, v120, v121
	v_cvt_pk_f16_f32 v175, v122, v123
	s_nop 1
	v_permlane16_swap_b32_e32 v172, v174
	v_permlane16_swap_b32_e32 v173, v175
	global_store_dwordx4 v177, v[172:175], s[80:81]
	v_max_f32_e32 v124, 0, v124
	v_max_f32_e32 v125, 0, v125
	v_max_f32_e32 v126, 0, v126
	v_max_f32_e32 v127, 0, v127
	v_pk_mul_f32 v[124:125], v[124:125], v[124:125]
	v_pk_mul_f32 v[126:127], v[126:127], v[126:127]
	v_cvt_pk_f16_f32 v228, v124, v125
	v_cvt_pk_f16_f32 v229, v126, v127
	v_max_f32_e32 v128, 0, v128
	v_max_f32_e32 v129, 0, v129
	v_max_f32_e32 v130, 0, v130
	v_max_f32_e32 v131, 0, v131
	v_pk_mul_f32 v[128:129], v[128:129], v[128:129]
	v_pk_mul_f32 v[130:131], v[130:131], v[130:131]
	v_cvt_pk_f16_f32 v230, v128, v129
	v_cvt_pk_f16_f32 v231, v130, v131
	s_nop 1
	v_permlane16_swap_b32_e32 v228, v230
	v_permlane16_swap_b32_e32 v229, v231
	global_store_dwordx4 v177, v[228:231], s[80:81] offset:64
	s_nop 1
	s_add_i32 s54, s54, s76
	s_cmp_ge_i32 s54, s58
	s_cbranch_scc1 .LBB0_780
	s_branch .LBB0_725

.Lt_mlp2a:
	v_add_u32_e32 v169, s32, v164
	v_mfma_f32_16x16x32_f16 v[4:7], v[132:135], v[184:187], v[4:7]
	ds_read_b128 v[238:241], v169 offset:4112
	v_mfma_f32_16x16x32_f16 v[8:11], v[136:139], v[184:187], v[8:11]
	ds_read_b128 v[242:245], v169 offset:5136
	v_mfma_f32_16x16x32_f16 v[12:15], v[140:143], v[184:187], v[12:15]
	ds_read_b128 v[246:249], v169 offset:6160
	v_mfma_f32_16x16x32_f16 v[16:19], v[144:147], v[184:187], v[16:19]
	ds_read_b128 v[250:253], v169 offset:7184
	v_mfma_f32_16x16x32_f16 v[20:23], v[132:135], v[188:191], v[20:23]
	v_mfma_f32_16x16x32_f16 v[24:27], v[136:139], v[188:191], v[24:27]
	v_mfma_f32_16x16x32_f16 v[28:31], v[140:143], v[188:191], v[28:31]
	v_mfma_f32_16x16x32_f16 v[32:35], v[144:147], v[188:191], v[32:35]
	v_mfma_f32_16x16x32_f16 v[36:39], v[132:135], v[192:195], v[36:39]
	v_mfma_f32_16x16x32_f16 v[40:43], v[136:139], v[192:195], v[40:43]
	v_mfma_f32_16x16x32_f16 v[44:47], v[140:143], v[192:195], v[44:47]
	v_mfma_f32_16x16x32_f16 v[48:51], v[144:147], v[192:195], v[48:51]
	v_mfma_f32_16x16x32_f16 v[52:55], v[132:135], v[196:199], v[52:55]
	v_mfma_f32_16x16x32_f16 v[56:59], v[136:139], v[196:199], v[56:59]
	v_mfma_f32_16x16x32_f16 v[60:63], v[140:143], v[196:199], v[60:63]
	v_mfma_f32_16x16x32_f16 v[64:67], v[144:147], v[196:199], v[64:67]
	s_waitcnt vmcnt(8) lgkmcnt(0)
	s_barrier
	s_add_i32 s34, s32, 0x8000
	s_cmp_lg_u32 s32, 0x18000
	s_cselect_b32 s34, s34, 0
	v_add_u32_e32 v168, s34, v165
	v_add_u32_e32 v169, s34, v164
	s_add_u32 vcc_lo, s31, s32
	v_mfma_f32_16x16x32_f16 v[68:71], v[132:135], v[238:241], v[68:71]
	ds_read_b128 v[148:151], v168 offset:16
	ds_read_b128 v[184:187], v169 offset:16
	s_mov_b32 m0, vcc_lo
	s_nop 0
	global_load_lds_dwordx4 v170, s[36:37]
	v_mfma_f32_16x16x32_f16 v[72:75], v[136:139], v[238:241], v[72:75]
	ds_read_b128 v[152:155], v168 offset:1040
	ds_read_b128 v[188:191], v169 offset:1040
	s_add_u32 m0, vcc_lo, 0x400
	s_nop 0
	global_load_lds_dwordx4 v171, s[36:37]
	v_mfma_f32_16x16x32_f16 v[76:79], v[140:143], v[238:241], v[76:79]
	ds_read_b128 v[156:159], v168 offset:2064
	ds_read_b128 v[192:195], v169 offset:2064
	s_add_u32 m0, vcc_lo, 0x4000
	s_nop 0
	global_load_lds_dwordx4 v170, s[50:51]
	v_mfma_f32_16x16x32_f16 v[80:83], v[144:147], v[238:241], v[80:83]
	ds_read_b128 v[160:163], v168 offset:3088
	ds_read_b128 v[196:199], v169 offset:3088
	s_add_u32 m0, vcc_lo, 0x4400
	s_nop 0
	global_load_lds_dwordx4 v171, s[50:51]
	v_mfma_f32_16x16x32_f16 v[84:87], v[132:135], v[242:245], v[84:87]
	v_mfma_f32_16x16x32_f16 v[88:91], v[136:139], v[242:245], v[88:91]
	v_mfma_f32_16x16x32_f16 v[92:95], v[140:143], v[242:245], v[92:95]
	v_mfma_f32_16x16x32_f16 v[96:99], v[144:147], v[242:245], v[96:99]
	v_mfma_f32_16x16x32_f16 v[100:103], v[132:135], v[246:249], v[100:103]
	v_mfma_f32_16x16x32_f16 v[104:107], v[136:139], v[246:249], v[104:107]
	v_mfma_f32_16x16x32_f16 v[108:111], v[140:143], v[246:249], v[108:111]
	v_mfma_f32_16x16x32_f16 v[112:115], v[144:147], v[246:249], v[112:115]
	v_mfma_f32_16x16x32_f16 v[116:119], v[132:135], v[250:253], v[116:119]
	v_mfma_f32_16x16x32_f16 v[120:123], v[136:139], v[250:253], v[120:123]
	v_mfma_f32_16x16x32_f16 v[124:127], v[140:143], v[250:253], v[124:127]
	v_mfma_f32_16x16x32_f16 v[128:131], v[144:147], v[250:253], v[128:131]
	s_waitcnt lgkmcnt(0)
	s_mov_b32 s32, s34
	s_add_u32 s36, s36, 64
	s_addc_u32 s37, s37, 0
	s_add_u32 s50, s50, 64
	s_addc_u32 s51, s51, 0
	v_add_u32_e32 v169, s32, v164
	v_mfma_f32_16x16x32_f16 v[4:7], v[148:151], v[184:187], v[4:7]
	ds_read_b128 v[238:241], v169 offset:4112
	v_mfma_f32_16x16x32_f16 v[8:11], v[152:155], v[184:187], v[8:11]
	ds_read_b128 v[242:245], v169 offset:5136
	v_mfma_f32_16x16x32_f16 v[12:15], v[156:159], v[184:187], v[12:15]
	ds_read_b128 v[246:249], v169 offset:6160
	v_mfma_f32_16x16x32_f16 v[16:19], v[160:163], v[184:187], v[16:19]
	ds_read_b128 v[250:253], v169 offset:7184
	v_mfma_f32_16x16x32_f16 v[20:23], v[148:151], v[188:191], v[20:23]
	v_mfma_f32_16x16x32_f16 v[24:27], v[152:155], v[188:191], v[24:27]
	v_mfma_f32_16x16x32_f16 v[28:31], v[156:159], v[188:191], v[28:31]
	v_mfma_f32_16x16x32_f16 v[32:35], v[160:163], v[188:191], v[32:35]
	v_mfma_f32_16x16x32_f16 v[36:39], v[148:151], v[192:195], v[36:39]
	v_mfma_f32_16x16x32_f16 v[40:43], v[152:155], v[192:195], v[40:43]
	v_mfma_f32_16x16x32_f16 v[44:47], v[156:159], v[192:195], v[44:47]
	v_mfma_f32_16x16x32_f16 v[48:51], v[160:163], v[192:195], v[48:51]
	v_mfma_f32_16x16x32_f16 v[52:55], v[148:151], v[196:199], v[52:55]
	v_mfma_f32_16x16x32_f16 v[56:59], v[152:155], v[196:199], v[56:59]
	v_mfma_f32_16x16x32_f16 v[60:63], v[156:159], v[196:199], v[60:63]
	v_mfma_f32_16x16x32_f16 v[64:67], v[160:163], v[196:199], v[64:67]
	s_waitcnt vmcnt(8) lgkmcnt(0)
	s_barrier
	s_add_i32 s34, s32, 0x8000
	s_cmp_lg_u32 s32, 0x18000
	s_cselect_b32 s34, s34, 0
	v_add_u32_e32 v168, s34, v165
	v_add_u32_e32 v169, s34, v164
	s_add_u32 vcc_lo, s31, s32
	v_mfma_f32_16x16x32_f16 v[68:71], v[148:151], v[238:241], v[68:71]
	ds_read_b128 v[132:135], v168 offset:16
	ds_read_b128 v[184:187], v169 offset:16
	s_mov_b32 m0, vcc_lo
	s_nop 0
	global_load_lds_dwordx4 v170, s[36:37]
	v_mfma_f32_16x16x32_f16 v[72:75], v[152:155], v[238:241], v[72:75]
	ds_read_b128 v[136:139], v168 offset:1040
	ds_read_b128 v[188:191], v169 offset:1040
	s_add_u32 m0, vcc_lo, 0x400
	s_nop 0
	global_load_lds_dwordx4 v171, s[36:37]
	v_mfma_f32_16x16x32_f16 v[76:79], v[156:159], v[238:241], v[76:79]
	ds_read_b128 v[140:143], v168 offset:2064
	ds_read_b128 v[192:195], v169 offset:2064
	s_add_u32 m0, vcc_lo, 0x4000
	s_nop 0
	global_load_lds_dwordx4 v170, s[50:51]
	v_mfma_f32_16x16x32_f16 v[80:83], v[160:163], v[238:241], v[80:83]
	ds_read_b128 v[144:147], v168 offset:3088
	ds_read_b128 v[196:199], v169 offset:3088
	s_add_u32 m0, vcc_lo, 0x4400
	s_nop 0
	global_load_lds_dwordx4 v171, s[50:51]
	v_mfma_f32_16x16x32_f16 v[84:87], v[148:151], v[242:245], v[84:87]
	v_mfma_f32_16x16x32_f16 v[88:91], v[152:155], v[242:245], v[88:91]
	v_mfma_f32_16x16x32_f16 v[92:95], v[156:159], v[242:245], v[92:95]
	v_mfma_f32_16x16x32_f16 v[96:99], v[160:163], v[242:245], v[96:99]
	v_mfma_f32_16x16x32_f16 v[100:103], v[148:151], v[246:249], v[100:103]
	v_mfma_f32_16x16x32_f16 v[104:107], v[152:155], v[246:249], v[104:107]
	v_mfma_f32_16x16x32_f16 v[108:111], v[156:159], v[246:249], v[108:111]
	v_mfma_f32_16x16x32_f16 v[112:115], v[160:163], v[246:249], v[112:115]
	v_mfma_f32_16x16x32_f16 v[116:119], v[148:151], v[250:253], v[116:119]
	v_mfma_f32_16x16x32_f16 v[120:123], v[152:155], v[250:253], v[120:123]
	v_mfma_f32_16x16x32_f16 v[124:127], v[156:159], v[250:253], v[124:127]
	v_mfma_f32_16x16x32_f16 v[128:131], v[160:163], v[250:253], v[128:131]
	s_waitcnt lgkmcnt(0)
	s_mov_b32 s32, s34
	s_add_u32 s36, s36, 64
	s_addc_u32 s37, s37, 0
	s_add_u32 s50, s50, 64
	s_addc_u32 s51, s51, 0
	s_add_i32 s52, s52, 2
	s_cmp_lt_u32 s52, 124
	s_cbranch_scc1 .Lt_mlp2a
	v_add_u32_e32 v169, s32, v164
	v_mfma_f32_16x16x32_f16 v[4:7], v[132:135], v[184:187], v[4:7]
	ds_read_b128 v[238:241], v169 offset:4112
	v_mfma_f32_16x16x32_f16 v[8:11], v[136:139], v[184:187], v[8:11]
	ds_read_b128 v[242:245], v169 offset:5136
	v_mfma_f32_16x16x32_f16 v[12:15], v[140:143], v[184:187], v[12:15]
	ds_read_b128 v[246:249], v169 offset:6160
	v_mfma_f32_16x16x32_f16 v[16:19], v[144:147], v[184:187], v[16:19]
	ds_read_b128 v[250:253], v169 offset:7184
	v_mfma_f32_16x16x32_f16 v[20:23], v[132:135], v[188:191], v[20:23]
	v_mfma_f32_16x16x32_f16 v[24:27], v[136:139], v[188:191], v[24:27]
	v_mfma_f32_16x16x32_f16 v[28:31], v[140:143], v[188:191], v[28:31]
	v_mfma_f32_16x16x32_f16 v[32:35], v[144:147], v[188:191], v[32:35]
	v_mfma_f32_16x16x32_f16 v[36:39], v[132:135], v[192:195], v[36:39]
	v_mfma_f32_16x16x32_f16 v[40:43], v[136:139], v[192:195], v[40:43]
	v_mfma_f32_16x16x32_f16 v[44:47], v[140:143], v[192:195], v[44:47]
	v_mfma_f32_16x16x32_f16 v[48:51], v[144:147], v[192:195], v[48:51]
	v_mfma_f32_16x16x32_f16 v[52:55], v[132:135], v[196:199], v[52:55]
	v_mfma_f32_16x16x32_f16 v[56:59], v[136:139], v[196:199], v[56:59]
	v_mfma_f32_16x16x32_f16 v[60:63], v[140:143], v[196:199], v[60:63]
	v_mfma_f32_16x16x32_f16 v[64:67], v[144:147], v[196:199], v[64:67]
	s_waitcnt vmcnt(8) lgkmcnt(0)
	s_barrier
	s_add_i32 s34, s32, 0x8000
	s_cmp_lg_u32 s32, 0x18000
	s_cselect_b32 s34, s34, 0
	v_add_u32_e32 v168, s34, v165
	v_add_u32_e32 v169, s34, v164
	v_mfma_f32_16x16x32_f16 v[68:71], v[132:135], v[238:241], v[68:71]
	ds_read_b128 v[148:151], v168 offset:16
	ds_read_b128 v[184:187], v169 offset:16
	v_mfma_f32_16x16x32_f16 v[72:75], v[136:139], v[238:241], v[72:75]
	ds_read_b128 v[152:155], v168 offset:1040
	ds_read_b128 v[188:191], v169 offset:1040
	v_mfma_f32_16x16x32_f16 v[76:79], v[140:143], v[238:241], v[76:79]
	ds_read_b128 v[156:159], v168 offset:2064
	ds_read_b128 v[192:195], v169 offset:2064
	v_mfma_f32_16x16x32_f16 v[80:83], v[144:147], v[238:241], v[80:83]
	ds_read_b128 v[160:163], v168 offset:3088
	ds_read_b128 v[196:199], v169 offset:3088
	v_mfma_f32_16x16x32_f16 v[84:87], v[132:135], v[242:245], v[84:87]
	v_mfma_f32_16x16x32_f16 v[88:91], v[136:139], v[242:245], v[88:91]
	v_mfma_f32_16x16x32_f16 v[92:95], v[140:143], v[242:245], v[92:95]
	v_mfma_f32_16x16x32_f16 v[96:99], v[144:147], v[242:245], v[96:99]
	v_mfma_f32_16x16x32_f16 v[100:103], v[132:135], v[246:249], v[100:103]
	v_mfma_f32_16x16x32_f16 v[104:107], v[136:139], v[246:249], v[104:107]
	v_mfma_f32_16x16x32_f16 v[108:111], v[140:143], v[246:249], v[108:111]
	v_mfma_f32_16x16x32_f16 v[112:115], v[144:147], v[246:249], v[112:115]
	v_mfma_f32_16x16x32_f16 v[116:119], v[132:135], v[250:253], v[116:119]
	v_mfma_f32_16x16x32_f16 v[120:123], v[136:139], v[250:253], v[120:123]
	v_mfma_f32_16x16x32_f16 v[124:127], v[140:143], v[250:253], v[124:127]
	v_mfma_f32_16x16x32_f16 v[128:131], v[144:147], v[250:253], v[128:131]
	s_waitcnt lgkmcnt(0)
	s_mov_b32 s32, s34
	v_add_u32_e32 v169, s32, v164
	v_mfma_f32_16x16x32_f16 v[4:7], v[148:151], v[184:187], v[4:7]
	ds_read_b128 v[238:241], v169 offset:4112
	v_mfma_f32_16x16x32_f16 v[8:11], v[152:155], v[184:187], v[8:11]
	ds_read_b128 v[242:245], v169 offset:5136
	v_mfma_f32_16x16x32_f16 v[12:15], v[156:159], v[184:187], v[12:15]
	ds_read_b128 v[246:249], v169 offset:6160
	v_mfma_f32_16x16x32_f16 v[16:19], v[160:163], v[184:187], v[16:19]
	ds_read_b128 v[250:253], v169 offset:7184
	v_mfma_f32_16x16x32_f16 v[20:23], v[148:151], v[188:191], v[20:23]
	v_mfma_f32_16x16x32_f16 v[24:27], v[152:155], v[188:191], v[24:27]
	v_mfma_f32_16x16x32_f16 v[28:31], v[156:159], v[188:191], v[28:31]
	v_mfma_f32_16x16x32_f16 v[32:35], v[160:163], v[188:191], v[32:35]
	v_mfma_f32_16x16x32_f16 v[36:39], v[148:151], v[192:195], v[36:39]
	v_mfma_f32_16x16x32_f16 v[40:43], v[152:155], v[192:195], v[40:43]
	v_mfma_f32_16x16x32_f16 v[44:47], v[156:159], v[192:195], v[44:47]
	v_mfma_f32_16x16x32_f16 v[48:51], v[160:163], v[192:195], v[48:51]
	v_mfma_f32_16x16x32_f16 v[52:55], v[148:151], v[196:199], v[52:55]
	v_mfma_f32_16x16x32_f16 v[56:59], v[152:155], v[196:199], v[56:59]
	v_mfma_f32_16x16x32_f16 v[60:63], v[156:159], v[196:199], v[60:63]
	v_mfma_f32_16x16x32_f16 v[64:67], v[160:163], v[196:199], v[64:67]
	s_waitcnt vmcnt(4) lgkmcnt(0)
	s_barrier
	s_add_i32 s34, s32, 0x8000
	s_cmp_lg_u32 s32, 0x18000
	s_cselect_b32 s34, s34, 0
	v_add_u32_e32 v168, s34, v165
	v_add_u32_e32 v169, s34, v164
	v_mfma_f32_16x16x32_f16 v[68:71], v[148:151], v[238:241], v[68:71]
	ds_read_b128 v[132:135], v168 offset:16
	ds_read_b128 v[184:187], v169 offset:16
	v_mfma_f32_16x16x32_f16 v[72:75], v[152:155], v[238:241], v[72:75]
	ds_read_b128 v[136:139], v168 offset:1040
	ds_read_b128 v[188:191], v169 offset:1040
	v_mfma_f32_16x16x32_f16 v[76:79], v[156:159], v[238:241], v[76:79]
	ds_read_b128 v[140:143], v168 offset:2064
	ds_read_b128 v[192:195], v169 offset:2064
	v_mfma_f32_16x16x32_f16 v[80:83], v[160:163], v[238:241], v[80:83]
	ds_read_b128 v[144:147], v168 offset:3088
	ds_read_b128 v[196:199], v169 offset:3088
	v_mfma_f32_16x16x32_f16 v[84:87], v[148:151], v[242:245], v[84:87]
	v_mfma_f32_16x16x32_f16 v[88:91], v[152:155], v[242:245], v[88:91]
	v_mfma_f32_16x16x32_f16 v[92:95], v[156:159], v[242:245], v[92:95]
	v_mfma_f32_16x16x32_f16 v[96:99], v[160:163], v[242:245], v[96:99]
	v_mfma_f32_16x16x32_f16 v[100:103], v[148:151], v[246:249], v[100:103]
	v_mfma_f32_16x16x32_f16 v[104:107], v[152:155], v[246:249], v[104:107]
	v_mfma_f32_16x16x32_f16 v[108:111], v[156:159], v[246:249], v[108:111]
	v_mfma_f32_16x16x32_f16 v[112:115], v[160:163], v[246:249], v[112:115]
	v_mfma_f32_16x16x32_f16 v[116:119], v[148:151], v[250:253], v[116:119]
	v_mfma_f32_16x16x32_f16 v[120:123], v[152:155], v[250:253], v[120:123]
	v_mfma_f32_16x16x32_f16 v[124:127], v[156:159], v[250:253], v[124:127]
	v_mfma_f32_16x16x32_f16 v[128:131], v[160:163], v[250:253], v[128:131]
	s_waitcnt lgkmcnt(0)
	s_mov_b32 s32, s34
	v_add_u32_e32 v169, s32, v164
	v_mfma_f32_16x16x32_f16 v[4:7], v[132:135], v[184:187], v[4:7]
	ds_read_b128 v[238:241], v169 offset:4112
	v_mfma_f32_16x16x32_f16 v[8:11], v[136:139], v[184:187], v[8:11]
	ds_read_b128 v[242:245], v169 offset:5136
	v_mfma_f32_16x16x32_f16 v[12:15], v[140:143], v[184:187], v[12:15]
	ds_read_b128 v[246:249], v169 offset:6160
	v_mfma_f32_16x16x32_f16 v[16:19], v[144:147], v[184:187], v[16:19]
	ds_read_b128 v[250:253], v169 offset:7184
	v_mfma_f32_16x16x32_f16 v[20:23], v[132:135], v[188:191], v[20:23]
	v_mfma_f32_16x16x32_f16 v[24:27], v[136:139], v[188:191], v[24:27]
	v_mfma_f32_16x16x32_f16 v[28:31], v[140:143], v[188:191], v[28:31]
	v_mfma_f32_16x16x32_f16 v[32:35], v[144:147], v[188:191], v[32:35]
	v_mfma_f32_16x16x32_f16 v[36:39], v[132:135], v[192:195], v[36:39]
	v_mfma_f32_16x16x32_f16 v[40:43], v[136:139], v[192:195], v[40:43]
	v_mfma_f32_16x16x32_f16 v[44:47], v[140:143], v[192:195], v[44:47]
	v_mfma_f32_16x16x32_f16 v[48:51], v[144:147], v[192:195], v[48:51]
	v_mfma_f32_16x16x32_f16 v[52:55], v[132:135], v[196:199], v[52:55]
	v_mfma_f32_16x16x32_f16 v[56:59], v[136:139], v[196:199], v[56:59]
	v_mfma_f32_16x16x32_f16 v[60:63], v[140:143], v[196:199], v[60:63]
	v_mfma_f32_16x16x32_f16 v[64:67], v[144:147], v[196:199], v[64:67]
	s_waitcnt vmcnt(0) lgkmcnt(0)
	s_barrier
	s_add_i32 s34, s32, 0x8000
	s_cmp_lg_u32 s32, 0x18000
	s_cselect_b32 s34, s34, 0
	v_add_u32_e32 v168, s34, v165
	v_add_u32_e32 v169, s34, v164
	v_mfma_f32_16x16x32_f16 v[68:71], v[132:135], v[238:241], v[68:71]
	ds_read_b128 v[148:151], v168 offset:16
	ds_read_b128 v[184:187], v169 offset:16
	v_mfma_f32_16x16x32_f16 v[72:75], v[136:139], v[238:241], v[72:75]
	ds_read_b128 v[152:155], v168 offset:1040
	ds_read_b128 v[188:191], v169 offset:1040
	v_mfma_f32_16x16x32_f16 v[76:79], v[140:143], v[238:241], v[76:79]
	ds_read_b128 v[156:159], v168 offset:2064
	ds_read_b128 v[192:195], v169 offset:2064
	v_mfma_f32_16x16x32_f16 v[80:83], v[144:147], v[238:241], v[80:83]
	ds_read_b128 v[160:163], v168 offset:3088
	ds_read_b128 v[196:199], v169 offset:3088
	v_mfma_f32_16x16x32_f16 v[84:87], v[132:135], v[242:245], v[84:87]
	v_mfma_f32_16x16x32_f16 v[88:91], v[136:139], v[242:245], v[88:91]
	v_mfma_f32_16x16x32_f16 v[92:95], v[140:143], v[242:245], v[92:95]
	v_mfma_f32_16x16x32_f16 v[96:99], v[144:147], v[242:245], v[96:99]
	v_mfma_f32_16x16x32_f16 v[100:103], v[132:135], v[246:249], v[100:103]
	v_mfma_f32_16x16x32_f16 v[104:107], v[136:139], v[246:249], v[104:107]
	v_mfma_f32_16x16x32_f16 v[108:111], v[140:143], v[246:249], v[108:111]
	v_mfma_f32_16x16x32_f16 v[112:115], v[144:147], v[246:249], v[112:115]
	v_mfma_f32_16x16x32_f16 v[116:119], v[132:135], v[250:253], v[116:119]
	v_mfma_f32_16x16x32_f16 v[120:123], v[136:139], v[250:253], v[120:123]
	v_mfma_f32_16x16x32_f16 v[124:127], v[140:143], v[250:253], v[124:127]
	v_mfma_f32_16x16x32_f16 v[128:131], v[144:147], v[250:253], v[128:131]
	s_waitcnt lgkmcnt(0)
	s_mov_b32 s32, s34
	v_add_u32_e32 v169, s32, v164
	v_mfma_f32_16x16x32_f16 v[4:7], v[148:151], v[184:187], v[4:7]
	ds_read_b128 v[238:241], v169 offset:4112
	v_mfma_f32_16x16x32_f16 v[8:11], v[152:155], v[184:187], v[8:11]
	ds_read_b128 v[242:245], v169 offset:5136
	v_mfma_f32_16x16x32_f16 v[12:15], v[156:159], v[184:187], v[12:15]
	ds_read_b128 v[246:249], v169 offset:6160
	v_mfma_f32_16x16x32_f16 v[16:19], v[160:163], v[184:187], v[16:19]
	ds_read_b128 v[250:253], v169 offset:7184
	v_mfma_f32_16x16x32_f16 v[20:23], v[148:151], v[188:191], v[20:23]
	v_mfma_f32_16x16x32_f16 v[24:27], v[152:155], v[188:191], v[24:27]
	v_mfma_f32_16x16x32_f16 v[28:31], v[156:159], v[188:191], v[28:31]
	v_mfma_f32_16x16x32_f16 v[32:35], v[160:163], v[188:191], v[32:35]
	v_mfma_f32_16x16x32_f16 v[36:39], v[148:151], v[192:195], v[36:39]
	v_mfma_f32_16x16x32_f16 v[40:43], v[152:155], v[192:195], v[40:43]
	v_mfma_f32_16x16x32_f16 v[44:47], v[156:159], v[192:195], v[44:47]
	v_mfma_f32_16x16x32_f16 v[48:51], v[160:163], v[192:195], v[48:51]
	v_mfma_f32_16x16x32_f16 v[52:55], v[148:151], v[196:199], v[52:55]
	v_mfma_f32_16x16x32_f16 v[56:59], v[152:155], v[196:199], v[56:59]
	v_mfma_f32_16x16x32_f16 v[60:63], v[156:159], v[196:199], v[60:63]
	v_mfma_f32_16x16x32_f16 v[64:67], v[160:163], v[196:199], v[64:67]
	s_waitcnt lgkmcnt(0)
	s_barrier
	v_mfma_f32_16x16x32_f16 v[68:71], v[148:151], v[238:241], v[68:71]
	v_mfma_f32_16x16x32_f16 v[72:75], v[152:155], v[238:241], v[72:75]
	v_mfma_f32_16x16x32_f16 v[76:79], v[156:159], v[238:241], v[76:79]
	v_mfma_f32_16x16x32_f16 v[80:83], v[160:163], v[238:241], v[80:83]
	v_mfma_f32_16x16x32_f16 v[84:87], v[148:151], v[242:245], v[84:87]
	v_mfma_f32_16x16x32_f16 v[88:91], v[152:155], v[242:245], v[88:91]
	v_mfma_f32_16x16x32_f16 v[92:95], v[156:159], v[242:245], v[92:95]
	v_mfma_f32_16x16x32_f16 v[96:99], v[160:163], v[242:245], v[96:99]
	v_mfma_f32_16x16x32_f16 v[100:103], v[148:151], v[246:249], v[100:103]
	v_mfma_f32_16x16x32_f16 v[104:107], v[152:155], v[246:249], v[104:107]
	v_mfma_f32_16x16x32_f16 v[108:111], v[156:159], v[246:249], v[108:111]
	v_mfma_f32_16x16x32_f16 v[112:115], v[160:163], v[246:249], v[112:115]
	v_mfma_f32_16x16x32_f16 v[116:119], v[148:151], v[250:253], v[116:119]
	v_mfma_f32_16x16x32_f16 v[120:123], v[152:155], v[250:253], v[120:123]
	v_mfma_f32_16x16x32_f16 v[124:127], v[156:159], v[250:253], v[124:127]
	v_mfma_f32_16x16x32_f16 v[128:131], v[160:163], v[250:253], v[128:131]
	s_sub_u32 s77, s35, 0x1000
	s_lshr_b32 s77, s77, 12
	s_add_u32 s77, s77, 1
	s_cmp_lt_u32 s35, 0x1000
	s_cselect_b32 s77, 0, s77
	s_mul_i32 s77, s77, 0x6000
	s_add_u32 s68, s44, s77
	s_addc_u32 s69, s45, 0
	s_add_u32 s68, s68, 0xfa10600
	s_addc_u32 s69, s69, 0
	s_lshl_b32 s82, s35, 11
	s_add_u32 s80, s46, s82
	s_addc_u32 s81, s47, 0
	s_lshl_b32 s82, s30, 1
	s_add_u32 s80, s80, s82
	s_addc_u32 s81, s81, 0
	v_and_b32_e32 v172, 15, v200
	v_bfe_u32 v173, v200, 4, 2
	v_bfe_u32 v174, v200, 6, 2
	v_bfe_u32 v175, v200, 8, 1
	v_lshlrev_b32_e32 v176, 6, v174
	v_lshl_or_b32 v176, v173, 2, v176
	v_lshl_or_b32 v175, v175, 7, v172
	v_lshlrev_b32_e32 v175, 11, v175
	v_lshl_add_u32 v177, v176, 1, v175
	v_add_u32_e32 v176, s30, v176
	v_lshlrev_b32_e32 v176, 2, v176
	global_load_dwordx4 v[132:135], v176, s[68:69]
	global_load_dwordx4 v[136:139], v176, s[68:69] offset:64
	global_load_dwordx4 v[140:143], v176, s[68:69] offset:128
	global_load_dwordx4 v[144:147], v176, s[68:69] offset:192
	v_and_b32_e32 v172, 1, v173
	v_mul_u32_u24_e32 v172, 24, v172
	v_add_u32_e32 v177, v177, v172
	v_mov_b32_e32 v178, v177
	global_load_dwordx4 v[184:187], v178, s[80:81]
	global_load_dwordx4 v[188:191], v178, s[80:81] offset:64
	v_add_u32_e32 v178, 0x8000, v178
	global_load_dwordx4 v[238:241], v178, s[80:81]
	global_load_dwordx4 v[242:245], v178, s[80:81] offset:64
	s_waitcnt vmcnt(3)
	v_permlane16_swap_b32_e32 v184, v186
	v_permlane16_swap_b32_e32 v185, v187
	v_cvt_f32_f16_e32 v164, v184
	v_cvt_f32_f16_sdwa v165, v184 dst_sel:DWORD dst_unused:UNUSED_PAD src0_sel:WORD_1
	v_cvt_f32_f16_e32 v166, v185
	v_cvt_f32_f16_sdwa v167, v185 dst_sel:DWORD dst_unused:UNUSED_PAD src0_sel:WORD_1
	v_pk_mul_f32 v[164:165], v[164:165], s[84:85] op_sel_hi:[1,0]
	v_pk_mul_f32 v[166:167], v[166:167], s[84:85] op_sel_hi:[1,0]
	v_pk_fma_f32 v[4:5], v[4:5], v[132:133], v[164:165]
	v_pk_fma_f32 v[6:7], v[6:7], v[134:135], v[166:167]
	v_cvt_pk_f16_f32 v172, v4, v5
	v_cvt_pk_f16_f32 v173, v6, v7
	v_cvt_f32_f16_e32 v164, v186
	v_cvt_f32_f16_sdwa v165, v186 dst_sel:DWORD dst_unused:UNUSED_PAD src0_sel:WORD_1
	v_cvt_f32_f16_e32 v166, v187
	v_cvt_f32_f16_sdwa v167, v187 dst_sel:DWORD dst_unused:UNUSED_PAD src0_sel:WORD_1
	v_pk_mul_f32 v[164:165], v[164:165], s[84:85] op_sel_hi:[1,0]
	v_pk_mul_f32 v[166:167], v[166:167], s[84:85] op_sel_hi:[1,0]
	v_pk_fma_f32 v[8:9], v[8:9], v[136:137], v[164:165]
	v_pk_fma_f32 v[10:11], v[10:11], v[138:139], v[166:167]
	v_cvt_pk_f16_f32 v174, v8, v9
	v_cvt_pk_f16_f32 v175, v10, v11
	s_nop 1
	v_permlane16_swap_b32_e32 v172, v174
	v_permlane16_swap_b32_e32 v173, v175
	global_store_dwordx4 v177, v[172:175], s[80:81]
	s_waitcnt vmcnt(3)
	v_permlane16_swap_b32_e32 v188, v190
	v_permlane16_swap_b32_e32 v189, v191
	v_cvt_f32_f16_e32 v164, v188
	v_cvt_f32_f16_sdwa v165, v188 dst_sel:DWORD dst_unused:UNUSED_PAD src0_sel:WORD_1
	v_cvt_f32_f16_e32 v166, v189
	v_cvt_f32_f16_sdwa v167, v189 dst_sel:DWORD dst_unused:UNUSED_PAD src0_sel:WORD_1
	v_pk_mul_f32 v[164:165], v[164:165], s[84:85] op_sel_hi:[1,0]
	v_pk_mul_f32 v[166:167], v[166:167], s[84:85] op_sel_hi:[1,0]
	v_pk_fma_f32 v[12:13], v[12:13], v[140:141], v[164:165]
	v_pk_fma_f32 v[14:15], v[14:15], v[142:143], v[166:167]
	v_cvt_pk_f16_f32 v228, v12, v13
	v_cvt_pk_f16_f32 v229, v14, v15
	v_cvt_f32_f16_e32 v164, v190
	v_cvt_f32_f16_sdwa v165, v190 dst_sel:DWORD dst_unused:UNUSED_PAD src0_sel:WORD_1
	v_cvt_f32_f16_e32 v166, v191
	v_cvt_f32_f16_sdwa v167, v191 dst_sel:DWORD dst_unused:UNUSED_PAD src0_sel:WORD_1
	v_pk_mul_f32 v[164:165], v[164:165], s[84:85] op_sel_hi:[1,0]
	v_pk_mul_f32 v[166:167], v[166:167], s[84:85] op_sel_hi:[1,0]
	v_pk_fma_f32 v[16:17], v[16:17], v[144:145], v[164:165]
	v_pk_fma_f32 v[18:19], v[18:19], v[146:147], v[166:167]
	v_cvt_pk_f16_f32 v230, v16, v17
	v_cvt_pk_f16_f32 v231, v18, v19
	s_nop 1
	v_permlane16_swap_b32_e32 v228, v230
	v_permlane16_swap_b32_e32 v229, v231
	global_store_dwordx4 v177, v[228:231], s[80:81] offset:64
	v_add_u32_e32 v177, 0x8000, v177
	v_add_u32_e32 v178, 0x8000, v178
	global_load_dwordx4 v[184:187], v178, s[80:81]
	global_load_dwordx4 v[188:191], v178, s[80:81] offset:64
	s_waitcnt vmcnt(5)
	v_permlane16_swap_b32_e32 v238, v240
	v_permlane16_swap_b32_e32 v239, v241
	v_cvt_f32_f16_e32 v164, v238
	v_cvt_f32_f16_sdwa v165, v238 dst_sel:DWORD dst_unused:UNUSED_PAD src0_sel:WORD_1
	v_cvt_f32_f16_e32 v166, v239
	v_cvt_f32_f16_sdwa v167, v239 dst_sel:DWORD dst_unused:UNUSED_PAD src0_sel:WORD_1
	v_pk_mul_f32 v[164:165], v[164:165], s[84:85] op_sel_hi:[1,0]
	v_pk_mul_f32 v[166:167], v[166:167], s[84:85] op_sel_hi:[1,0]
	v_pk_fma_f32 v[20:21], v[20:21], v[132:133], v[164:165]
	v_pk_fma_f32 v[22:23], v[22:23], v[134:135], v[166:167]
	v_cvt_pk_f16_f32 v172, v20, v21
	v_cvt_pk_f16_f32 v173, v22, v23
	v_cvt_f32_f16_e32 v164, v240
	v_cvt_f32_f16_sdwa v165, v240 dst_sel:DWORD dst_unused:UNUSED_PAD src0_sel:WORD_1
	v_cvt_f32_f16_e32 v166, v241
	v_cvt_f32_f16_sdwa v167, v241 dst_sel:DWORD dst_unused:UNUSED_PAD src0_sel:WORD_1
	v_pk_mul_f32 v[164:165], v[164:165], s[84:85] op_sel_hi:[1,0]
	v_pk_mul_f32 v[166:167], v[166:167], s[84:85] op_sel_hi:[1,0]
	v_pk_fma_f32 v[24:25], v[24:25], v[136:137], v[164:165]
	v_pk_fma_f32 v[26:27], v[26:27], v[138:139], v[166:167]
	v_cvt_pk_f16_f32 v174, v24, v25
	v_cvt_pk_f16_f32 v175, v26, v27
	s_nop 1
	v_permlane16_swap_b32_e32 v172, v174
	v_permlane16_swap_b32_e32 v173, v175
	global_store_dwordx4 v177, v[172:175], s[80:81]
	s_waitcnt vmcnt(5)
	v_permlane16_swap_b32_e32 v242, v244
	v_permlane16_swap_b32_e32 v243, v245
	v_cvt_f32_f16_e32 v164, v242
	v_cvt_f32_f16_sdwa v165, v242 dst_sel:DWORD dst_unused:UNUSED_PAD src0_sel:WORD_1
	v_cvt_f32_f16_e32 v166, v243
	v_cvt_f32_f16_sdwa v167, v243 dst_sel:DWORD dst_unused:UNUSED_PAD src0_sel:WORD_1
	v_pk_mul_f32 v[164:165], v[164:165], s[84:85] op_sel_hi:[1,0]
	v_pk_mul_f32 v[166:167], v[166:167], s[84:85] op_sel_hi:[1,0]
	v_pk_fma_f32 v[28:29], v[28:29], v[140:141], v[164:165]
	v_pk_fma_f32 v[30:31], v[30:31], v[142:143], v[166:167]
	v_cvt_pk_f16_f32 v228, v28, v29
	v_cvt_pk_f16_f32 v229, v30, v31
	v_cvt_f32_f16_e32 v164, v244
	v_cvt_f32_f16_sdwa v165, v244 dst_sel:DWORD dst_unused:UNUSED_PAD src0_sel:WORD_1
	v_cvt_f32_f16_e32 v166, v245
	v_cvt_f32_f16_sdwa v167, v245 dst_sel:DWORD dst_unused:UNUSED_PAD src0_sel:WORD_1
	v_pk_mul_f32 v[164:165], v[164:165], s[84:85] op_sel_hi:[1,0]
	v_pk_mul_f32 v[166:167], v[166:167], s[84:85] op_sel_hi:[1,0]
	v_pk_fma_f32 v[32:33], v[32:33], v[144:145], v[164:165]
	v_pk_fma_f32 v[34:35], v[34:35], v[146:147], v[166:167]
	v_cvt_pk_f16_f32 v230, v32, v33
	v_cvt_pk_f16_f32 v231, v34, v35
	s_nop 1
	v_permlane16_swap_b32_e32 v228, v230
	v_permlane16_swap_b32_e32 v229, v231
	global_store_dwordx4 v177, v[228:231], s[80:81] offset:64
	v_add_u32_e32 v177, 0x8000, v177
	v_add_u32_e32 v178, 0x8000, v178
	global_load_dwordx4 v[238:241], v178, s[80:81]
	global_load_dwordx4 v[242:245], v178, s[80:81] offset:64
	s_waitcnt vmcnt(5)
	v_permlane16_swap_b32_e32 v184, v186
	v_permlane16_swap_b32_e32 v185, v187
	v_cvt_f32_f16_e32 v164, v184
	v_cvt_f32_f16_sdwa v165, v184 dst_sel:DWORD dst_unused:UNUSED_PAD src0_sel:WORD_1
	v_cvt_f32_f16_e32 v166, v185
	v_cvt_f32_f16_sdwa v167, v185 dst_sel:DWORD dst_unused:UNUSED_PAD src0_sel:WORD_1
	v_pk_mul_f32 v[164:165], v[164:165], s[84:85] op_sel_hi:[1,0]
	v_pk_mul_f32 v[166:167], v[166:167], s[84:85] op_sel_hi:[1,0]
	v_pk_fma_f32 v[36:37], v[36:37], v[132:133], v[164:165]
	v_pk_fma_f32 v[38:39], v[38:39], v[134:135], v[166:167]
	v_cvt_pk_f16_f32 v172, v36, v37
	v_cvt_pk_f16_f32 v173, v38, v39
	v_cvt_f32_f16_e32 v164, v186
	v_cvt_f32_f16_sdwa v165, v186 dst_sel:DWORD dst_unused:UNUSED_PAD src0_sel:WORD_1
	v_cvt_f32_f16_e32 v166, v187
	v_cvt_f32_f16_sdwa v167, v187 dst_sel:DWORD dst_unused:UNUSED_PAD src0_sel:WORD_1
	v_pk_mul_f32 v[164:165], v[164:165], s[84:85] op_sel_hi:[1,0]
	v_pk_mul_f32 v[166:167], v[166:167], s[84:85] op_sel_hi:[1,0]
	v_pk_fma_f32 v[40:41], v[40:41], v[136:137], v[164:165]
	v_pk_fma_f32 v[42:43], v[42:43], v[138:139], v[166:167]
	v_cvt_pk_f16_f32 v174, v40, v41
	v_cvt_pk_f16_f32 v175, v42, v43
	s_nop 1
	v_permlane16_swap_b32_e32 v172, v174
	v_permlane16_swap_b32_e32 v173, v175
	global_store_dwordx4 v177, v[172:175], s[80:81]
	s_waitcnt vmcnt(5)
	v_permlane16_swap_b32_e32 v188, v190
	v_permlane16_swap_b32_e32 v189, v191
	v_cvt_f32_f16_e32 v164, v188
	v_cvt_f32_f16_sdwa v165, v188 dst_sel:DWORD dst_unused:UNUSED_PAD src0_sel:WORD_1
	v_cvt_f32_f16_e32 v166, v189
	v_cvt_f32_f16_sdwa v167, v189 dst_sel:DWORD dst_unused:UNUSED_PAD src0_sel:WORD_1
	v_pk_mul_f32 v[164:165], v[164:165], s[84:85] op_sel_hi:[1,0]
	v_pk_mul_f32 v[166:167], v[166:167], s[84:85] op_sel_hi:[1,0]
	v_pk_fma_f32 v[44:45], v[44:45], v[140:141], v[164:165]
	v_pk_fma_f32 v[46:47], v[46:47], v[142:143], v[166:167]
	v_cvt_pk_f16_f32 v228, v44, v45
	v_cvt_pk_f16_f32 v229, v46, v47
	v_cvt_f32_f16_e32 v164, v190
	v_cvt_f32_f16_sdwa v165, v190 dst_sel:DWORD dst_unused:UNUSED_PAD src0_sel:WORD_1
	v_cvt_f32_f16_e32 v166, v191
	v_cvt_f32_f16_sdwa v167, v191 dst_sel:DWORD dst_unused:UNUSED_PAD src0_sel:WORD_1
	v_pk_mul_f32 v[164:165], v[164:165], s[84:85] op_sel_hi:[1,0]
	v_pk_mul_f32 v[166:167], v[166:167], s[84:85] op_sel_hi:[1,0]
	v_pk_fma_f32 v[48:49], v[48:49], v[144:145], v[164:165]
	v_pk_fma_f32 v[50:51], v[50:51], v[146:147], v[166:167]
	v_cvt_pk_f16_f32 v230, v48, v49
	v_cvt_pk_f16_f32 v231, v50, v51
	s_nop 1
	v_permlane16_swap_b32_e32 v228, v230
	v_permlane16_swap_b32_e32 v229, v231
	global_store_dwordx4 v177, v[228:231], s[80:81] offset:64
	v_add_u32_e32 v177, 0x8000, v177
	v_add_u32_e32 v178, 0x8000, v178
	global_load_dwordx4 v[184:187], v178, s[80:81]
	global_load_dwordx4 v[188:191], v178, s[80:81] offset:64
	s_waitcnt vmcnt(5)
	v_permlane16_swap_b32_e32 v238, v240
	v_permlane16_swap_b32_e32 v239, v241
	v_cvt_f32_f16_e32 v164, v238
	v_cvt_f32_f16_sdwa v165, v238 dst_sel:DWORD dst_unused:UNUSED_PAD src0_sel:WORD_1
	v_cvt_f32_f16_e32 v166, v239
	v_cvt_f32_f16_sdwa v167, v239 dst_sel:DWORD dst_unused:UNUSED_PAD src0_sel:WORD_1
	v_pk_mul_f32 v[164:165], v[164:165], s[84:85] op_sel_hi:[1,0]
	v_pk_mul_f32 v[166:167], v[166:167], s[84:85] op_sel_hi:[1,0]
	v_pk_fma_f32 v[52:53], v[52:53], v[132:133], v[164:165]
	v_pk_fma_f32 v[54:55], v[54:55], v[134:135], v[166:167]
	v_cvt_pk_f16_f32 v172, v52, v53
	v_cvt_pk_f16_f32 v173, v54, v55
	v_cvt_f32_f16_e32 v164, v240
	v_cvt_f32_f16_sdwa v165, v240 dst_sel:DWORD dst_unused:UNUSED_PAD src0_sel:WORD_1
	v_cvt_f32_f16_e32 v166, v241
	v_cvt_f32_f16_sdwa v167, v241 dst_sel:DWORD dst_unused:UNUSED_PAD src0_sel:WORD_1
	v_pk_mul_f32 v[164:165], v[164:165], s[84:85] op_sel_hi:[1,0]
	v_pk_mul_f32 v[166:167], v[166:167], s[84:85] op_sel_hi:[1,0]
	v_pk_fma_f32 v[56:57], v[56:57], v[136:137], v[164:165]
	v_pk_fma_f32 v[58:59], v[58:59], v[138:139], v[166:167]
	v_cvt_pk_f16_f32 v174, v56, v57
	v_cvt_pk_f16_f32 v175, v58, v59
	s_nop 1
	v_permlane16_swap_b32_e32 v172, v174
	v_permlane16_swap_b32_e32 v173, v175
	global_store_dwordx4 v177, v[172:175], s[80:81]
	s_waitcnt vmcnt(5)
	v_permlane16_swap_b32_e32 v242, v244
	v_permlane16_swap_b32_e32 v243, v245
	v_cvt_f32_f16_e32 v164, v242
	v_cvt_f32_f16_sdwa v165, v242 dst_sel:DWORD dst_unused:UNUSED_PAD src0_sel:WORD_1
	v_cvt_f32_f16_e32 v166, v243
	v_cvt_f32_f16_sdwa v167, v243 dst_sel:DWORD dst_unused:UNUSED_PAD src0_sel:WORD_1
	v_pk_mul_f32 v[164:165], v[164:165], s[84:85] op_sel_hi:[1,0]
	v_pk_mul_f32 v[166:167], v[166:167], s[84:85] op_sel_hi:[1,0]
	v_pk_fma_f32 v[60:61], v[60:61], v[140:141], v[164:165]
	v_pk_fma_f32 v[62:63], v[62:63], v[142:143], v[166:167]
	v_cvt_pk_f16_f32 v228, v60, v61
	v_cvt_pk_f16_f32 v229, v62, v63
	v_cvt_f32_f16_e32 v164, v244
	v_cvt_f32_f16_sdwa v165, v244 dst_sel:DWORD dst_unused:UNUSED_PAD src0_sel:WORD_1
	v_cvt_f32_f16_e32 v166, v245
	v_cvt_f32_f16_sdwa v167, v245 dst_sel:DWORD dst_unused:UNUSED_PAD src0_sel:WORD_1
	v_pk_mul_f32 v[164:165], v[164:165], s[84:85] op_sel_hi:[1,0]
	v_pk_mul_f32 v[166:167], v[166:167], s[84:85] op_sel_hi:[1,0]
	v_pk_fma_f32 v[64:65], v[64:65], v[144:145], v[164:165]
	v_pk_fma_f32 v[66:67], v[66:67], v[146:147], v[166:167]
	v_cvt_pk_f16_f32 v230, v64, v65
	v_cvt_pk_f16_f32 v231, v66, v67
	s_nop 1
	v_permlane16_swap_b32_e32 v228, v230
	v_permlane16_swap_b32_e32 v229, v231
	global_store_dwordx4 v177, v[228:231], s[80:81] offset:64
	v_add_u32_e32 v177, 0x8000, v177
	v_add_u32_e32 v178, 0x8000, v178
	global_load_dwordx4 v[238:241], v178, s[80:81]
	global_load_dwordx4 v[242:245], v178, s[80:81] offset:64
	s_waitcnt vmcnt(5)
	v_permlane16_swap_b32_e32 v184, v186
	v_permlane16_swap_b32_e32 v185, v187
	v_cvt_f32_f16_e32 v164, v184
	v_cvt_f32_f16_sdwa v165, v184 dst_sel:DWORD dst_unused:UNUSED_PAD src0_sel:WORD_1
	v_cvt_f32_f16_e32 v166, v185
	v_cvt_f32_f16_sdwa v167, v185 dst_sel:DWORD dst_unused:UNUSED_PAD src0_sel:WORD_1
	v_pk_mul_f32 v[164:165], v[164:165], s[84:85] op_sel_hi:[1,0]
	v_pk_mul_f32 v[166:167], v[166:167], s[84:85] op_sel_hi:[1,0]
	v_pk_fma_f32 v[68:69], v[68:69], v[132:133], v[164:165]
	v_pk_fma_f32 v[70:71], v[70:71], v[134:135], v[166:167]
	v_cvt_pk_f16_f32 v172, v68, v69
	v_cvt_pk_f16_f32 v173, v70, v71
	v_cvt_f32_f16_e32 v164, v186
	v_cvt_f32_f16_sdwa v165, v186 dst_sel:DWORD dst_unused:UNUSED_PAD src0_sel:WORD_1
	v_cvt_f32_f16_e32 v166, v187
	v_cvt_f32_f16_sdwa v167, v187 dst_sel:DWORD dst_unused:UNUSED_PAD src0_sel:WORD_1
	v_pk_mul_f32 v[164:165], v[164:165], s[84:85] op_sel_hi:[1,0]
	v_pk_mul_f32 v[166:167], v[166:167], s[84:85] op_sel_hi:[1,0]
	v_pk_fma_f32 v[72:73], v[72:73], v[136:137], v[164:165]
	v_pk_fma_f32 v[74:75], v[74:75], v[138:139], v[166:167]
	v_cvt_pk_f16_f32 v174, v72, v73
	v_cvt_pk_f16_f32 v175, v74, v75
	s_nop 1
	v_permlane16_swap_b32_e32 v172, v174
	v_permlane16_swap_b32_e32 v173, v175
	global_store_dwordx4 v177, v[172:175], s[80:81]
	s_waitcnt vmcnt(5)
	v_permlane16_swap_b32_e32 v188, v190
	v_permlane16_swap_b32_e32 v189, v191
	v_cvt_f32_f16_e32 v164, v188
	v_cvt_f32_f16_sdwa v165, v188 dst_sel:DWORD dst_unused:UNUSED_PAD src0_sel:WORD_1
	v_cvt_f32_f16_e32 v166, v189
	v_cvt_f32_f16_sdwa v167, v189 dst_sel:DWORD dst_unused:UNUSED_PAD src0_sel:WORD_1
	v_pk_mul_f32 v[164:165], v[164:165], s[84:85] op_sel_hi:[1,0]
	v_pk_mul_f32 v[166:167], v[166:167], s[84:85] op_sel_hi:[1,0]
	v_pk_fma_f32 v[76:77], v[76:77], v[140:141], v[164:165]
	v_pk_fma_f32 v[78:79], v[78:79], v[142:143], v[166:167]
	v_cvt_pk_f16_f32 v228, v76, v77
	v_cvt_pk_f16_f32 v229, v78, v79
	v_cvt_f32_f16_e32 v164, v190
	v_cvt_f32_f16_sdwa v165, v190 dst_sel:DWORD dst_unused:UNUSED_PAD src0_sel:WORD_1
	v_cvt_f32_f16_e32 v166, v191
	v_cvt_f32_f16_sdwa v167, v191 dst_sel:DWORD dst_unused:UNUSED_PAD src0_sel:WORD_1
	v_pk_mul_f32 v[164:165], v[164:165], s[84:85] op_sel_hi:[1,0]
	v_pk_mul_f32 v[166:167], v[166:167], s[84:85] op_sel_hi:[1,0]
	v_pk_fma_f32 v[80:81], v[80:81], v[144:145], v[164:165]
	v_pk_fma_f32 v[82:83], v[82:83], v[146:147], v[166:167]
	v_cvt_pk_f16_f32 v230, v80, v81
	v_cvt_pk_f16_f32 v231, v82, v83
	s_nop 1
	v_permlane16_swap_b32_e32 v228, v230
	v_permlane16_swap_b32_e32 v229, v231
	global_store_dwordx4 v177, v[228:231], s[80:81] offset:64
	v_add_u32_e32 v177, 0x8000, v177
	v_add_u32_e32 v178, 0x8000, v178
	global_load_dwordx4 v[184:187], v178, s[80:81]
	global_load_dwordx4 v[188:191], v178, s[80:81] offset:64
	s_waitcnt vmcnt(5)
	v_permlane16_swap_b32_e32 v238, v240
	v_permlane16_swap_b32_e32 v239, v241
	v_cvt_f32_f16_e32 v164, v238
	v_cvt_f32_f16_sdwa v165, v238 dst_sel:DWORD dst_unused:UNUSED_PAD src0_sel:WORD_1
	v_cvt_f32_f16_e32 v166, v239
	v_cvt_f32_f16_sdwa v167, v239 dst_sel:DWORD dst_unused:UNUSED_PAD src0_sel:WORD_1
	v_pk_mul_f32 v[164:165], v[164:165], s[84:85] op_sel_hi:[1,0]
	v_pk_mul_f32 v[166:167], v[166:167], s[84:85] op_sel_hi:[1,0]
	v_pk_fma_f32 v[84:85], v[84:85], v[132:133], v[164:165]
	v_pk_fma_f32 v[86:87], v[86:87], v[134:135], v[166:167]
	v_cvt_pk_f16_f32 v172, v84, v85
	v_cvt_pk_f16_f32 v173, v86, v87
	v_cvt_f32_f16_e32 v164, v240
	v_cvt_f32_f16_sdwa v165, v240 dst_sel:DWORD dst_unused:UNUSED_PAD src0_sel:WORD_1
	v_cvt_f32_f16_e32 v166, v241
	v_cvt_f32_f16_sdwa v167, v241 dst_sel:DWORD dst_unused:UNUSED_PAD src0_sel:WORD_1
	v_pk_mul_f32 v[164:165], v[164:165], s[84:85] op_sel_hi:[1,0]
	v_pk_mul_f32 v[166:167], v[166:167], s[84:85] op_sel_hi:[1,0]
	v_pk_fma_f32 v[88:89], v[88:89], v[136:137], v[164:165]
	v_pk_fma_f32 v[90:91], v[90:91], v[138:139], v[166:167]
	v_cvt_pk_f16_f32 v174, v88, v89
	v_cvt_pk_f16_f32 v175, v90, v91
	s_nop 1
	v_permlane16_swap_b32_e32 v172, v174
	v_permlane16_swap_b32_e32 v173, v175
	global_store_dwordx4 v177, v[172:175], s[80:81]
	s_waitcnt vmcnt(5)
	v_permlane16_swap_b32_e32 v242, v244
	v_permlane16_swap_b32_e32 v243, v245
	v_cvt_f32_f16_e32 v164, v242
	v_cvt_f32_f16_sdwa v165, v242 dst_sel:DWORD dst_unused:UNUSED_PAD src0_sel:WORD_1
	v_cvt_f32_f16_e32 v166, v243
	v_cvt_f32_f16_sdwa v167, v243 dst_sel:DWORD dst_unused:UNUSED_PAD src0_sel:WORD_1
	v_pk_mul_f32 v[164:165], v[164:165], s[84:85] op_sel_hi:[1,0]
	v_pk_mul_f32 v[166:167], v[166:167], s[84:85] op_sel_hi:[1,0]
	v_pk_fma_f32 v[92:93], v[92:93], v[140:141], v[164:165]
	v_pk_fma_f32 v[94:95], v[94:95], v[142:143], v[166:167]
	v_cvt_pk_f16_f32 v228, v92, v93
	v_cvt_pk_f16_f32 v229, v94, v95
	v_cvt_f32_f16_e32 v164, v244
	v_cvt_f32_f16_sdwa v165, v244 dst_sel:DWORD dst_unused:UNUSED_PAD src0_sel:WORD_1
	v_cvt_f32_f16_e32 v166, v245
	v_cvt_f32_f16_sdwa v167, v245 dst_sel:DWORD dst_unused:UNUSED_PAD src0_sel:WORD_1
	v_pk_mul_f32 v[164:165], v[164:165], s[84:85] op_sel_hi:[1,0]
	v_pk_mul_f32 v[166:167], v[166:167], s[84:85] op_sel_hi:[1,0]
	v_pk_fma_f32 v[96:97], v[96:97], v[144:145], v[164:165]
	v_pk_fma_f32 v[98:99], v[98:99], v[146:147], v[166:167]
	v_cvt_pk_f16_f32 v230, v96, v97
	v_cvt_pk_f16_f32 v231, v98, v99
	s_nop 1
	v_permlane16_swap_b32_e32 v228, v230
	v_permlane16_swap_b32_e32 v229, v231
	global_store_dwordx4 v177, v[228:231], s[80:81] offset:64
	v_add_u32_e32 v177, 0x8000, v177
	v_add_u32_e32 v178, 0x8000, v178
	global_load_dwordx4 v[238:241], v178, s[80:81]
	global_load_dwordx4 v[242:245], v178, s[80:81] offset:64
	s_waitcnt vmcnt(5)
	v_permlane16_swap_b32_e32 v184, v186
	v_permlane16_swap_b32_e32 v185, v187
	v_cvt_f32_f16_e32 v164, v184
	v_cvt_f32_f16_sdwa v165, v184 dst_sel:DWORD dst_unused:UNUSED_PAD src0_sel:WORD_1
	v_cvt_f32_f16_e32 v166, v185
	v_cvt_f32_f16_sdwa v167, v185 dst_sel:DWORD dst_unused:UNUSED_PAD src0_sel:WORD_1
	v_pk_mul_f32 v[164:165], v[164:165], s[84:85] op_sel_hi:[1,0]
	v_pk_mul_f32 v[166:167], v[166:167], s[84:85] op_sel_hi:[1,0]
	v_pk_fma_f32 v[100:101], v[100:101], v[132:133], v[164:165]
	v_pk_fma_f32 v[102:103], v[102:103], v[134:135], v[166:167]
	v_cvt_pk_f16_f32 v172, v100, v101
	v_cvt_pk_f16_f32 v173, v102, v103
	v_cvt_f32_f16_e32 v164, v186
	v_cvt_f32_f16_sdwa v165, v186 dst_sel:DWORD dst_unused:UNUSED_PAD src0_sel:WORD_1
	v_cvt_f32_f16_e32 v166, v187
	v_cvt_f32_f16_sdwa v167, v187 dst_sel:DWORD dst_unused:UNUSED_PAD src0_sel:WORD_1
	v_pk_mul_f32 v[164:165], v[164:165], s[84:85] op_sel_hi:[1,0]
	v_pk_mul_f32 v[166:167], v[166:167], s[84:85] op_sel_hi:[1,0]
	v_pk_fma_f32 v[104:105], v[104:105], v[136:137], v[164:165]
	v_pk_fma_f32 v[106:107], v[106:107], v[138:139], v[166:167]
	v_cvt_pk_f16_f32 v174, v104, v105
	v_cvt_pk_f16_f32 v175, v106, v107
	s_nop 1
	v_permlane16_swap_b32_e32 v172, v174
	v_permlane16_swap_b32_e32 v173, v175
	global_store_dwordx4 v177, v[172:175], s[80:81]
	s_waitcnt vmcnt(5)
	v_permlane16_swap_b32_e32 v188, v190
	v_permlane16_swap_b32_e32 v189, v191
	v_cvt_f32_f16_e32 v164, v188
	v_cvt_f32_f16_sdwa v165, v188 dst_sel:DWORD dst_unused:UNUSED_PAD src0_sel:WORD_1
	v_cvt_f32_f16_e32 v166, v189
	v_cvt_f32_f16_sdwa v167, v189 dst_sel:DWORD dst_unused:UNUSED_PAD src0_sel:WORD_1
	v_pk_mul_f32 v[164:165], v[164:165], s[84:85] op_sel_hi:[1,0]
	v_pk_mul_f32 v[166:167], v[166:167], s[84:85] op_sel_hi:[1,0]
	v_pk_fma_f32 v[108:109], v[108:109], v[140:141], v[164:165]
	v_pk_fma_f32 v[110:111], v[110:111], v[142:143], v[166:167]
	v_cvt_pk_f16_f32 v228, v108, v109
	v_cvt_pk_f16_f32 v229, v110, v111
	v_cvt_f32_f16_e32 v164, v190
	v_cvt_f32_f16_sdwa v165, v190 dst_sel:DWORD dst_unused:UNUSED_PAD src0_sel:WORD_1
	v_cvt_f32_f16_e32 v166, v191
	v_cvt_f32_f16_sdwa v167, v191 dst_sel:DWORD dst_unused:UNUSED_PAD src0_sel:WORD_1
	v_pk_mul_f32 v[164:165], v[164:165], s[84:85] op_sel_hi:[1,0]
	v_pk_mul_f32 v[166:167], v[166:167], s[84:85] op_sel_hi:[1,0]
	v_pk_fma_f32 v[112:113], v[112:113], v[144:145], v[164:165]
	v_pk_fma_f32 v[114:115], v[114:115], v[146:147], v[166:167]
	v_cvt_pk_f16_f32 v230, v112, v113
	v_cvt_pk_f16_f32 v231, v114, v115
	s_nop 1
	v_permlane16_swap_b32_e32 v228, v230
	v_permlane16_swap_b32_e32 v229, v231
	global_store_dwordx4 v177, v[228:231], s[80:81] offset:64
	v_add_u32_e32 v177, 0x8000, v177
	s_waitcnt vmcnt(3)
	v_permlane16_swap_b32_e32 v238, v240
	v_permlane16_swap_b32_e32 v239, v241
	v_cvt_f32_f16_e32 v164, v238
	v_cvt_f32_f16_sdwa v165, v238 dst_sel:DWORD dst_unused:UNUSED_PAD src0_sel:WORD_1
	v_cvt_f32_f16_e32 v166, v239
	v_cvt_f32_f16_sdwa v167, v239 dst_sel:DWORD dst_unused:UNUSED_PAD src0_sel:WORD_1
	v_pk_mul_f32 v[164:165], v[164:165], s[84:85] op_sel_hi:[1,0]
	v_pk_mul_f32 v[166:167], v[166:167], s[84:85] op_sel_hi:[1,0]
	v_pk_fma_f32 v[116:117], v[116:117], v[132:133], v[164:165]
	v_pk_fma_f32 v[118:119], v[118:119], v[134:135], v[166:167]
	v_cvt_pk_f16_f32 v172, v116, v117
	v_cvt_pk_f16_f32 v173, v118, v119
	v_cvt_f32_f16_e32 v164, v240
	v_cvt_f32_f16_sdwa v165, v240 dst_sel:DWORD dst_unused:UNUSED_PAD src0_sel:WORD_1
	v_cvt_f32_f16_e32 v166, v241
	v_cvt_f32_f16_sdwa v167, v241 dst_sel:DWORD dst_unused:UNUSED_PAD src0_sel:WORD_1
	v_pk_mul_f32 v[164:165], v[164:165], s[84:85] op_sel_hi:[1,0]
	v_pk_mul_f32 v[166:167], v[166:167], s[84:85] op_sel_hi:[1,0]
	v_pk_fma_f32 v[120:121], v[120:121], v[136:137], v[164:165]
	v_pk_fma_f32 v[122:123], v[122:123], v[138:139], v[166:167]
	v_cvt_pk_f16_f32 v174, v120, v121
	v_cvt_pk_f16_f32 v175, v122, v123
	s_nop 1
	v_permlane16_swap_b32_e32 v172, v174
	v_permlane16_swap_b32_e32 v173, v175
	global_store_dwordx4 v177, v[172:175], s[80:81]
	s_waitcnt vmcnt(3)
	v_permlane16_swap_b32_e32 v242, v244
	v_permlane16_swap_b32_e32 v243, v245
	v_cvt_f32_f16_e32 v164, v242
	v_cvt_f32_f16_sdwa v165, v242 dst_sel:DWORD dst_unused:UNUSED_PAD src0_sel:WORD_1
	v_cvt_f32_f16_e32 v166, v243
	v_cvt_f32_f16_sdwa v167, v243 dst_sel:DWORD dst_unused:UNUSED_PAD src0_sel:WORD_1
	v_pk_mul_f32 v[164:165], v[164:165], s[84:85] op_sel_hi:[1,0]
	v_pk_mul_f32 v[166:167], v[166:167], s[84:85] op_sel_hi:[1,0]
	v_pk_fma_f32 v[124:125], v[124:125], v[140:141], v[164:165]
	v_pk_fma_f32 v[126:127], v[126:127], v[142:143], v[166:167]
	v_cvt_pk_f16_f32 v228, v124, v125
	v_cvt_pk_f16_f32 v229, v126, v127
	v_cvt_f32_f16_e32 v164, v244
	v_cvt_f32_f16_sdwa v165, v244 dst_sel:DWORD dst_unused:UNUSED_PAD src0_sel:WORD_1
	v_cvt_f32_f16_e32 v166, v245
	v_cvt_f32_f16_sdwa v167, v245 dst_sel:DWORD dst_unused:UNUSED_PAD src0_sel:WORD_1
	v_pk_mul_f32 v[164:165], v[164:165], s[84:85] op_sel_hi:[1,0]
	v_pk_mul_f32 v[166:167], v[166:167], s[84:85] op_sel_hi:[1,0]
	v_pk_fma_f32 v[128:129], v[128:129], v[144:145], v[164:165]
	v_pk_fma_f32 v[130:131], v[130:131], v[146:147], v[166:167]
	v_cvt_pk_f16_f32 v230, v128, v129
	v_cvt_pk_f16_f32 v231, v130, v131
	s_nop 1
	v_permlane16_swap_b32_e32 v228, v230
	v_permlane16_swap_b32_e32 v229, v231
	global_store_dwordx4 v177, v[228:231], s[80:81] offset:64
	s_nop 1
	s_branch .LBB0_814

.Lt_gin:
	v_add_u32_e32 v169, s47, v164
	v_mfma_f32_16x16x32_f16 v[4:7], v[132:135], v[184:187], v[4:7]
	ds_read_b128 v[238:241], v169 offset:4112
	v_mfma_f32_16x16x32_f16 v[8:11], v[136:139], v[184:187], v[8:11]
	ds_read_b128 v[242:245], v169 offset:5136
	v_mfma_f32_16x16x32_f16 v[12:15], v[140:143], v[184:187], v[12:15]
	ds_read_b128 v[246:249], v169 offset:6160
	v_mfma_f32_16x16x32_f16 v[16:19], v[144:147], v[184:187], v[16:19]
	ds_read_b128 v[250:253], v169 offset:7184
	v_mfma_f32_16x16x32_f16 v[20:23], v[132:135], v[188:191], v[20:23]
	v_mfma_f32_16x16x32_f16 v[24:27], v[136:139], v[188:191], v[24:27]
	v_mfma_f32_16x16x32_f16 v[28:31], v[140:143], v[188:191], v[28:31]
	v_mfma_f32_16x16x32_f16 v[32:35], v[144:147], v[188:191], v[32:35]
	v_mfma_f32_16x16x32_f16 v[36:39], v[132:135], v[192:195], v[36:39]
	v_mfma_f32_16x16x32_f16 v[40:43], v[136:139], v[192:195], v[40:43]
	v_mfma_f32_16x16x32_f16 v[44:47], v[140:143], v[192:195], v[44:47]
	v_mfma_f32_16x16x32_f16 v[48:51], v[144:147], v[192:195], v[48:51]
	v_mfma_f32_16x16x32_f16 v[52:55], v[132:135], v[196:199], v[52:55]
	v_mfma_f32_16x16x32_f16 v[56:59], v[136:139], v[196:199], v[56:59]
	v_mfma_f32_16x16x32_f16 v[60:63], v[140:143], v[196:199], v[60:63]
	v_mfma_f32_16x16x32_f16 v[64:67], v[144:147], v[196:199], v[64:67]
	s_waitcnt vmcnt(8) lgkmcnt(0)
	s_barrier
	s_add_i32 s48, s47, 0x8000
	s_cmp_lg_u32 s47, 0x18000
	s_cselect_b32 s48, s48, 0
	v_add_u32_e32 v168, s48, v165
	v_add_u32_e32 v169, s48, v164
	s_add_u32 vcc_lo, s32, s47
	v_mfma_f32_16x16x32_f16 v[68:71], v[132:135], v[238:241], v[68:71]
	ds_read_b128 v[148:151], v168 offset:16
	ds_read_b128 v[184:187], v169 offset:16
	s_mov_b32 m0, vcc_lo
	s_nop 0
	global_load_lds_dwordx4 v170, s[36:37]
	v_mfma_f32_16x16x32_f16 v[72:75], v[136:139], v[238:241], v[72:75]
	ds_read_b128 v[152:155], v168 offset:1040
	ds_read_b128 v[188:191], v169 offset:1040
	s_add_u32 m0, vcc_lo, 0x400
	s_nop 0
	global_load_lds_dwordx4 v171, s[36:37]
	v_mfma_f32_16x16x32_f16 v[76:79], v[140:143], v[238:241], v[76:79]
	ds_read_b128 v[156:159], v168 offset:2064
	ds_read_b128 v[192:195], v169 offset:2064
	s_add_u32 m0, vcc_lo, 0x4000
	s_nop 0
	global_load_lds_dwordx4 v170, s[42:43]
	v_mfma_f32_16x16x32_f16 v[80:83], v[144:147], v[238:241], v[80:83]
	ds_read_b128 v[160:163], v168 offset:3088
	ds_read_b128 v[196:199], v169 offset:3088
	s_add_u32 m0, vcc_lo, 0x4400
	s_nop 0
	global_load_lds_dwordx4 v171, s[42:43]
	v_mfma_f32_16x16x32_f16 v[84:87], v[132:135], v[242:245], v[84:87]
	v_mfma_f32_16x16x32_f16 v[88:91], v[136:139], v[242:245], v[88:91]
	v_mfma_f32_16x16x32_f16 v[92:95], v[140:143], v[242:245], v[92:95]
	v_mfma_f32_16x16x32_f16 v[96:99], v[144:147], v[242:245], v[96:99]
	v_mfma_f32_16x16x32_f16 v[100:103], v[132:135], v[246:249], v[100:103]
	v_mfma_f32_16x16x32_f16 v[104:107], v[136:139], v[246:249], v[104:107]
	v_mfma_f32_16x16x32_f16 v[108:111], v[140:143], v[246:249], v[108:111]
	v_mfma_f32_16x16x32_f16 v[112:115], v[144:147], v[246:249], v[112:115]
	v_mfma_f32_16x16x32_f16 v[116:119], v[132:135], v[250:253], v[116:119]
	v_mfma_f32_16x16x32_f16 v[120:123], v[136:139], v[250:253], v[120:123]
	v_mfma_f32_16x16x32_f16 v[124:127], v[140:143], v[250:253], v[124:127]
	v_mfma_f32_16x16x32_f16 v[128:131], v[144:147], v[250:253], v[128:131]
	s_waitcnt lgkmcnt(0)
	s_mov_b32 s47, s48
	s_add_u32 s36, s36, 64
	s_addc_u32 s37, s37, 0
	s_add_u32 s42, s42, 64
	s_addc_u32 s43, s43, 0
	v_add_u32_e32 v169, s47, v164
	v_mfma_f32_16x16x32_f16 v[4:7], v[148:151], v[184:187], v[4:7]
	ds_read_b128 v[238:241], v169 offset:4112
	v_mfma_f32_16x16x32_f16 v[8:11], v[152:155], v[184:187], v[8:11]
	ds_read_b128 v[242:245], v169 offset:5136
	v_mfma_f32_16x16x32_f16 v[12:15], v[156:159], v[184:187], v[12:15]
	ds_read_b128 v[246:249], v169 offset:6160
	v_mfma_f32_16x16x32_f16 v[16:19], v[160:163], v[184:187], v[16:19]
	ds_read_b128 v[250:253], v169 offset:7184
	v_mfma_f32_16x16x32_f16 v[20:23], v[148:151], v[188:191], v[20:23]
	v_mfma_f32_16x16x32_f16 v[24:27], v[152:155], v[188:191], v[24:27]
	v_mfma_f32_16x16x32_f16 v[28:31], v[156:159], v[188:191], v[28:31]
	v_mfma_f32_16x16x32_f16 v[32:35], v[160:163], v[188:191], v[32:35]
	v_mfma_f32_16x16x32_f16 v[36:39], v[148:151], v[192:195], v[36:39]
	v_mfma_f32_16x16x32_f16 v[40:43], v[152:155], v[192:195], v[40:43]
	v_mfma_f32_16x16x32_f16 v[44:47], v[156:159], v[192:195], v[44:47]
	v_mfma_f32_16x16x32_f16 v[48:51], v[160:163], v[192:195], v[48:51]
	v_mfma_f32_16x16x32_f16 v[52:55], v[148:151], v[196:199], v[52:55]
	v_mfma_f32_16x16x32_f16 v[56:59], v[152:155], v[196:199], v[56:59]
	v_mfma_f32_16x16x32_f16 v[60:63], v[156:159], v[196:199], v[60:63]
	v_mfma_f32_16x16x32_f16 v[64:67], v[160:163], v[196:199], v[64:67]
	s_waitcnt vmcnt(8) lgkmcnt(0)
	s_barrier
	s_add_i32 s48, s47, 0x8000
	s_cmp_lg_u32 s47, 0x18000
	s_cselect_b32 s48, s48, 0
	v_add_u32_e32 v168, s48, v165
	v_add_u32_e32 v169, s48, v164
	s_add_u32 vcc_lo, s32, s47
	v_mfma_f32_16x16x32_f16 v[68:71], v[148:151], v[238:241], v[68:71]
	ds_read_b128 v[132:135], v168 offset:16
	ds_read_b128 v[184:187], v169 offset:16
	s_mov_b32 m0, vcc_lo
	s_nop 0
	global_load_lds_dwordx4 v170, s[36:37]
	v_mfma_f32_16x16x32_f16 v[72:75], v[152:155], v[238:241], v[72:75]
	ds_read_b128 v[136:139], v168 offset:1040
	ds_read_b128 v[188:191], v169 offset:1040
	s_add_u32 m0, vcc_lo, 0x400
	s_nop 0
	global_load_lds_dwordx4 v171, s[36:37]
	v_mfma_f32_16x16x32_f16 v[76:79], v[156:159], v[238:241], v[76:79]
	ds_read_b128 v[140:143], v168 offset:2064
	ds_read_b128 v[192:195], v169 offset:2064
	s_add_u32 m0, vcc_lo, 0x4000
	s_nop 0
	global_load_lds_dwordx4 v170, s[42:43]
	v_mfma_f32_16x16x32_f16 v[80:83], v[160:163], v[238:241], v[80:83]
	ds_read_b128 v[144:147], v168 offset:3088
	ds_read_b128 v[196:199], v169 offset:3088
	s_add_u32 m0, vcc_lo, 0x4400
	s_nop 0
	global_load_lds_dwordx4 v171, s[42:43]
	v_mfma_f32_16x16x32_f16 v[84:87], v[148:151], v[242:245], v[84:87]
	v_mfma_f32_16x16x32_f16 v[88:91], v[152:155], v[242:245], v[88:91]
	v_mfma_f32_16x16x32_f16 v[92:95], v[156:159], v[242:245], v[92:95]
	v_mfma_f32_16x16x32_f16 v[96:99], v[160:163], v[242:245], v[96:99]
	v_mfma_f32_16x16x32_f16 v[100:103], v[148:151], v[246:249], v[100:103]
	v_mfma_f32_16x16x32_f16 v[104:107], v[152:155], v[246:249], v[104:107]
	v_mfma_f32_16x16x32_f16 v[108:111], v[156:159], v[246:249], v[108:111]
	v_mfma_f32_16x16x32_f16 v[112:115], v[160:163], v[246:249], v[112:115]
	v_mfma_f32_16x16x32_f16 v[116:119], v[148:151], v[250:253], v[116:119]
	v_mfma_f32_16x16x32_f16 v[120:123], v[152:155], v[250:253], v[120:123]
	v_mfma_f32_16x16x32_f16 v[124:127], v[156:159], v[250:253], v[124:127]
	v_mfma_f32_16x16x32_f16 v[128:131], v[160:163], v[250:253], v[128:131]
	s_waitcnt lgkmcnt(0)
	s_mov_b32 s47, s48
	s_add_u32 s36, s36, 64
	s_addc_u32 s37, s37, 0
	s_add_u32 s42, s42, 64
	s_addc_u32 s43, s43, 0
	s_add_i32 s49, s49, 2
	s_cmp_lt_u32 s49, 28
	s_cbranch_scc1 .Lt_gin
	v_add_u32_e32 v169, s47, v164
	v_mfma_f32_16x16x32_f16 v[4:7], v[132:135], v[184:187], v[4:7]
	ds_read_b128 v[238:241], v169 offset:4112
	v_mfma_f32_16x16x32_f16 v[8:11], v[136:139], v[184:187], v[8:11]
	ds_read_b128 v[242:245], v169 offset:5136
	v_mfma_f32_16x16x32_f16 v[12:15], v[140:143], v[184:187], v[12:15]
	ds_read_b128 v[246:249], v169 offset:6160
	v_mfma_f32_16x16x32_f16 v[16:19], v[144:147], v[184:187], v[16:19]
	ds_read_b128 v[250:253], v169 offset:7184
	v_mfma_f32_16x16x32_f16 v[20:23], v[132:135], v[188:191], v[20:23]
	v_mfma_f32_16x16x32_f16 v[24:27], v[136:139], v[188:191], v[24:27]
	v_mfma_f32_16x16x32_f16 v[28:31], v[140:143], v[188:191], v[28:31]
	v_mfma_f32_16x16x32_f16 v[32:35], v[144:147], v[188:191], v[32:35]
	v_mfma_f32_16x16x32_f16 v[36:39], v[132:135], v[192:195], v[36:39]
	v_mfma_f32_16x16x32_f16 v[40:43], v[136:139], v[192:195], v[40:43]
	v_mfma_f32_16x16x32_f16 v[44:47], v[140:143], v[192:195], v[44:47]
	v_mfma_f32_16x16x32_f16 v[48:51], v[144:147], v[192:195], v[48:51]
	v_mfma_f32_16x16x32_f16 v[52:55], v[132:135], v[196:199], v[52:55]
	v_mfma_f32_16x16x32_f16 v[56:59], v[136:139], v[196:199], v[56:59]
	v_mfma_f32_16x16x32_f16 v[60:63], v[140:143], v[196:199], v[60:63]
	v_mfma_f32_16x16x32_f16 v[64:67], v[144:147], v[196:199], v[64:67]
	s_waitcnt vmcnt(8) lgkmcnt(0)
	s_barrier
	s_add_i32 s48, s47, 0x8000
	s_cmp_lg_u32 s47, 0x18000
	s_cselect_b32 s48, s48, 0
	v_add_u32_e32 v168, s48, v165
	v_add_u32_e32 v169, s48, v164
	v_mfma_f32_16x16x32_f16 v[68:71], v[132:135], v[238:241], v[68:71]
	ds_read_b128 v[148:151], v168 offset:16
	ds_read_b128 v[184:187], v169 offset:16
	v_mfma_f32_16x16x32_f16 v[72:75], v[136:139], v[238:241], v[72:75]
	ds_read_b128 v[152:155], v168 offset:1040
	ds_read_b128 v[188:191], v169 offset:1040
	v_mfma_f32_16x16x32_f16 v[76:79], v[140:143], v[238:241], v[76:79]
	ds_read_b128 v[156:159], v168 offset:2064
	ds_read_b128 v[192:195], v169 offset:2064
	v_mfma_f32_16x16x32_f16 v[80:83], v[144:147], v[238:241], v[80:83]
	ds_read_b128 v[160:163], v168 offset:3088
	ds_read_b128 v[196:199], v169 offset:3088
	v_mfma_f32_16x16x32_f16 v[84:87], v[132:135], v[242:245], v[84:87]
	v_mfma_f32_16x16x32_f16 v[88:91], v[136:139], v[242:245], v[88:91]
	v_mfma_f32_16x16x32_f16 v[92:95], v[140:143], v[242:245], v[92:95]
	v_mfma_f32_16x16x32_f16 v[96:99], v[144:147], v[242:245], v[96:99]
	v_mfma_f32_16x16x32_f16 v[100:103], v[132:135], v[246:249], v[100:103]
	v_mfma_f32_16x16x32_f16 v[104:107], v[136:139], v[246:249], v[104:107]
	v_mfma_f32_16x16x32_f16 v[108:111], v[140:143], v[246:249], v[108:111]
	v_mfma_f32_16x16x32_f16 v[112:115], v[144:147], v[246:249], v[112:115]
	v_mfma_f32_16x16x32_f16 v[116:119], v[132:135], v[250:253], v[116:119]
	v_mfma_f32_16x16x32_f16 v[120:123], v[136:139], v[250:253], v[120:123]
	v_mfma_f32_16x16x32_f16 v[124:127], v[140:143], v[250:253], v[124:127]
	v_mfma_f32_16x16x32_f16 v[128:131], v[144:147], v[250:253], v[128:131]
	s_waitcnt lgkmcnt(0)
	s_mov_b32 s47, s48
	v_add_u32_e32 v169, s47, v164
	v_mfma_f32_16x16x32_f16 v[4:7], v[148:151], v[184:187], v[4:7]
	ds_read_b128 v[238:241], v169 offset:4112
	v_mfma_f32_16x16x32_f16 v[8:11], v[152:155], v[184:187], v[8:11]
	ds_read_b128 v[242:245], v169 offset:5136
	v_mfma_f32_16x16x32_f16 v[12:15], v[156:159], v[184:187], v[12:15]
	ds_read_b128 v[246:249], v169 offset:6160
	v_mfma_f32_16x16x32_f16 v[16:19], v[160:163], v[184:187], v[16:19]
	ds_read_b128 v[250:253], v169 offset:7184
	v_mfma_f32_16x16x32_f16 v[20:23], v[148:151], v[188:191], v[20:23]
	v_mfma_f32_16x16x32_f16 v[24:27], v[152:155], v[188:191], v[24:27]
	v_mfma_f32_16x16x32_f16 v[28:31], v[156:159], v[188:191], v[28:31]
	v_mfma_f32_16x16x32_f16 v[32:35], v[160:163], v[188:191], v[32:35]
	v_mfma_f32_16x16x32_f16 v[36:39], v[148:151], v[192:195], v[36:39]
	v_mfma_f32_16x16x32_f16 v[40:43], v[152:155], v[192:195], v[40:43]
	v_mfma_f32_16x16x32_f16 v[44:47], v[156:159], v[192:195], v[44:47]
	v_mfma_f32_16x16x32_f16 v[48:51], v[160:163], v[192:195], v[48:51]
	v_mfma_f32_16x16x32_f16 v[52:55], v[148:151], v[196:199], v[52:55]
	v_mfma_f32_16x16x32_f16 v[56:59], v[152:155], v[196:199], v[56:59]
	v_mfma_f32_16x16x32_f16 v[60:63], v[156:159], v[196:199], v[60:63]
	v_mfma_f32_16x16x32_f16 v[64:67], v[160:163], v[196:199], v[64:67]
	s_waitcnt vmcnt(4) lgkmcnt(0)
	s_barrier
	s_add_i32 s48, s47, 0x8000
	s_cmp_lg_u32 s47, 0x18000
	s_cselect_b32 s48, s48, 0
	v_add_u32_e32 v168, s48, v165
	v_add_u32_e32 v169, s48, v164
	v_mfma_f32_16x16x32_f16 v[68:71], v[148:151], v[238:241], v[68:71]
	ds_read_b128 v[132:135], v168 offset:16
	ds_read_b128 v[184:187], v169 offset:16
	v_mfma_f32_16x16x32_f16 v[72:75], v[152:155], v[238:241], v[72:75]
	ds_read_b128 v[136:139], v168 offset:1040
	ds_read_b128 v[188:191], v169 offset:1040
	v_mfma_f32_16x16x32_f16 v[76:79], v[156:159], v[238:241], v[76:79]
	ds_read_b128 v[140:143], v168 offset:2064
	ds_read_b128 v[192:195], v169 offset:2064
	v_mfma_f32_16x16x32_f16 v[80:83], v[160:163], v[238:241], v[80:83]
	ds_read_b128 v[144:147], v168 offset:3088
	ds_read_b128 v[196:199], v169 offset:3088
	v_mfma_f32_16x16x32_f16 v[84:87], v[148:151], v[242:245], v[84:87]
	v_mfma_f32_16x16x32_f16 v[88:91], v[152:155], v[242:245], v[88:91]
	v_mfma_f32_16x16x32_f16 v[92:95], v[156:159], v[242:245], v[92:95]
	v_mfma_f32_16x16x32_f16 v[96:99], v[160:163], v[242:245], v[96:99]
	v_mfma_f32_16x16x32_f16 v[100:103], v[148:151], v[246:249], v[100:103]
	v_mfma_f32_16x16x32_f16 v[104:107], v[152:155], v[246:249], v[104:107]
	v_mfma_f32_16x16x32_f16 v[108:111], v[156:159], v[246:249], v[108:111]
	v_mfma_f32_16x16x32_f16 v[112:115], v[160:163], v[246:249], v[112:115]
	v_mfma_f32_16x16x32_f16 v[116:119], v[148:151], v[250:253], v[116:119]
	v_mfma_f32_16x16x32_f16 v[120:123], v[152:155], v[250:253], v[120:123]
	v_mfma_f32_16x16x32_f16 v[124:127], v[156:159], v[250:253], v[124:127]
	v_mfma_f32_16x16x32_f16 v[128:131], v[160:163], v[250:253], v[128:131]
	s_waitcnt lgkmcnt(0)
	s_mov_b32 s47, s48
	v_add_u32_e32 v169, s47, v164
	v_mfma_f32_16x16x32_f16 v[4:7], v[132:135], v[184:187], v[4:7]
	ds_read_b128 v[238:241], v169 offset:4112
	v_mfma_f32_16x16x32_f16 v[8:11], v[136:139], v[184:187], v[8:11]
	ds_read_b128 v[242:245], v169 offset:5136
	v_mfma_f32_16x16x32_f16 v[12:15], v[140:143], v[184:187], v[12:15]
	ds_read_b128 v[246:249], v169 offset:6160
	v_mfma_f32_16x16x32_f16 v[16:19], v[144:147], v[184:187], v[16:19]
	ds_read_b128 v[250:253], v169 offset:7184
	v_mfma_f32_16x16x32_f16 v[20:23], v[132:135], v[188:191], v[20:23]
	v_mfma_f32_16x16x32_f16 v[24:27], v[136:139], v[188:191], v[24:27]
	v_mfma_f32_16x16x32_f16 v[28:31], v[140:143], v[188:191], v[28:31]
	v_mfma_f32_16x16x32_f16 v[32:35], v[144:147], v[188:191], v[32:35]
	v_mfma_f32_16x16x32_f16 v[36:39], v[132:135], v[192:195], v[36:39]
	v_mfma_f32_16x16x32_f16 v[40:43], v[136:139], v[192:195], v[40:43]
	v_mfma_f32_16x16x32_f16 v[44:47], v[140:143], v[192:195], v[44:47]
	v_mfma_f32_16x16x32_f16 v[48:51], v[144:147], v[192:195], v[48:51]
	v_mfma_f32_16x16x32_f16 v[52:55], v[132:135], v[196:199], v[52:55]
	v_mfma_f32_16x16x32_f16 v[56:59], v[136:139], v[196:199], v[56:59]
	v_mfma_f32_16x16x32_f16 v[60:63], v[140:143], v[196:199], v[60:63]
	v_mfma_f32_16x16x32_f16 v[64:67], v[144:147], v[196:199], v[64:67]
	s_waitcnt vmcnt(0) lgkmcnt(0)
	s_barrier
	s_add_i32 s48, s47, 0x8000
	s_cmp_lg_u32 s47, 0x18000
	s_cselect_b32 s48, s48, 0
	v_add_u32_e32 v168, s48, v165
	v_add_u32_e32 v169, s48, v164
	v_mfma_f32_16x16x32_f16 v[68:71], v[132:135], v[238:241], v[68:71]
	ds_read_b128 v[148:151], v168 offset:16
	ds_read_b128 v[184:187], v169 offset:16
	v_mfma_f32_16x16x32_f16 v[72:75], v[136:139], v[238:241], v[72:75]
	ds_read_b128 v[152:155], v168 offset:1040
	ds_read_b128 v[188:191], v169 offset:1040
	v_mfma_f32_16x16x32_f16 v[76:79], v[140:143], v[238:241], v[76:79]
	ds_read_b128 v[156:159], v168 offset:2064
	ds_read_b128 v[192:195], v169 offset:2064
	v_mfma_f32_16x16x32_f16 v[80:83], v[144:147], v[238:241], v[80:83]
	ds_read_b128 v[160:163], v168 offset:3088
	ds_read_b128 v[196:199], v169 offset:3088
	v_mfma_f32_16x16x32_f16 v[84:87], v[132:135], v[242:245], v[84:87]
	v_mfma_f32_16x16x32_f16 v[88:91], v[136:139], v[242:245], v[88:91]
	v_mfma_f32_16x16x32_f16 v[92:95], v[140:143], v[242:245], v[92:95]
	v_mfma_f32_16x16x32_f16 v[96:99], v[144:147], v[242:245], v[96:99]
	v_mfma_f32_16x16x32_f16 v[100:103], v[132:135], v[246:249], v[100:103]
	v_mfma_f32_16x16x32_f16 v[104:107], v[136:139], v[246:249], v[104:107]
	v_mfma_f32_16x16x32_f16 v[108:111], v[140:143], v[246:249], v[108:111]
	v_mfma_f32_16x16x32_f16 v[112:115], v[144:147], v[246:249], v[112:115]
	v_mfma_f32_16x16x32_f16 v[116:119], v[132:135], v[250:253], v[116:119]
	v_mfma_f32_16x16x32_f16 v[120:123], v[136:139], v[250:253], v[120:123]
	v_mfma_f32_16x16x32_f16 v[124:127], v[140:143], v[250:253], v[124:127]
	v_mfma_f32_16x16x32_f16 v[128:131], v[144:147], v[250:253], v[128:131]
	s_waitcnt lgkmcnt(0)
	s_mov_b32 s47, s48
	v_add_u32_e32 v169, s47, v164
	v_mfma_f32_16x16x32_f16 v[4:7], v[148:151], v[184:187], v[4:7]
	ds_read_b128 v[238:241], v169 offset:4112
	v_mfma_f32_16x16x32_f16 v[8:11], v[152:155], v[184:187], v[8:11]
	ds_read_b128 v[242:245], v169 offset:5136
	v_mfma_f32_16x16x32_f16 v[12:15], v[156:159], v[184:187], v[12:15]
	ds_read_b128 v[246:249], v169 offset:6160
	v_mfma_f32_16x16x32_f16 v[16:19], v[160:163], v[184:187], v[16:19]
	ds_read_b128 v[250:253], v169 offset:7184
	v_mfma_f32_16x16x32_f16 v[20:23], v[148:151], v[188:191], v[20:23]
	v_mfma_f32_16x16x32_f16 v[24:27], v[152:155], v[188:191], v[24:27]
	v_mfma_f32_16x16x32_f16 v[28:31], v[156:159], v[188:191], v[28:31]
	v_mfma_f32_16x16x32_f16 v[32:35], v[160:163], v[188:191], v[32:35]
	v_mfma_f32_16x16x32_f16 v[36:39], v[148:151], v[192:195], v[36:39]
	v_mfma_f32_16x16x32_f16 v[40:43], v[152:155], v[192:195], v[40:43]
	v_mfma_f32_16x16x32_f16 v[44:47], v[156:159], v[192:195], v[44:47]
	v_mfma_f32_16x16x32_f16 v[48:51], v[160:163], v[192:195], v[48:51]
	v_mfma_f32_16x16x32_f16 v[52:55], v[148:151], v[196:199], v[52:55]
	v_mfma_f32_16x16x32_f16 v[56:59], v[152:155], v[196:199], v[56:59]
	v_mfma_f32_16x16x32_f16 v[60:63], v[156:159], v[196:199], v[60:63]
	v_mfma_f32_16x16x32_f16 v[64:67], v[160:163], v[196:199], v[64:67]
	s_waitcnt lgkmcnt(0)
	s_barrier
	v_mfma_f32_16x16x32_f16 v[68:71], v[148:151], v[238:241], v[68:71]
	v_mfma_f32_16x16x32_f16 v[72:75], v[152:155], v[238:241], v[72:75]
	v_mfma_f32_16x16x32_f16 v[76:79], v[156:159], v[238:241], v[76:79]
	v_mfma_f32_16x16x32_f16 v[80:83], v[160:163], v[238:241], v[80:83]
	v_mfma_f32_16x16x32_f16 v[84:87], v[148:151], v[242:245], v[84:87]
	v_mfma_f32_16x16x32_f16 v[88:91], v[152:155], v[242:245], v[88:91]
	v_mfma_f32_16x16x32_f16 v[92:95], v[156:159], v[242:245], v[92:95]
	v_mfma_f32_16x16x32_f16 v[96:99], v[160:163], v[242:245], v[96:99]
	v_mfma_f32_16x16x32_f16 v[100:103], v[148:151], v[246:249], v[100:103]
	v_mfma_f32_16x16x32_f16 v[104:107], v[152:155], v[246:249], v[104:107]
	v_mfma_f32_16x16x32_f16 v[108:111], v[156:159], v[246:249], v[108:111]
	v_mfma_f32_16x16x32_f16 v[112:115], v[160:163], v[246:249], v[112:115]
	v_mfma_f32_16x16x32_f16 v[116:119], v[148:151], v[250:253], v[116:119]
	v_mfma_f32_16x16x32_f16 v[120:123], v[152:155], v[250:253], v[120:123]
	v_mfma_f32_16x16x32_f16 v[124:127], v[156:159], v[250:253], v[124:127]
	v_mfma_f32_16x16x32_f16 v[128:131], v[160:163], v[250:253], v[128:131]
	s_mul_i32 s82, s52, 0xc00
	s_add_u32 s80, s28, s82
	s_addc_u32 s81, s29, 0
	s_lshl_b32 s82, s51, 1
	s_add_u32 s80, s80, s82
	s_addc_u32 s81, s81, 0
	v_and_b32_e32 v172, 15, v200
	v_bfe_u32 v173, v200, 4, 2
	v_bfe_u32 v174, v200, 6, 2
	v_bfe_u32 v175, v200, 8, 1
	v_lshl_or_b32 v175, v175, 7, v172
	v_mul_u32_u24_e32 v175, 0xc00, v175
	v_lshlrev_b32_e32 v174, 6, v174
	v_lshl_or_b32 v174, v173, 2, v174
	v_lshl_add_u32 v177, v174, 1, v175
	v_and_b32_e32 v172, 1, v173
	v_mul_u32_u24_e32 v172, 24, v172
	v_add_u32_e32 v177, v177, v172
	v_cvt_pk_f16_f32 v172, v4, v5
	v_cvt_pk_f16_f32 v173, v6, v7
	v_cvt_pk_f16_f32 v174, v8, v9
	v_cvt_pk_f16_f32 v175, v10, v11
	s_nop 1
	v_permlane16_swap_b32_e32 v172, v174
	v_permlane16_swap_b32_e32 v173, v175
	global_store_dwordx4 v177, v[172:175], s[80:81]
	v_cvt_pk_f16_f32 v228, v12, v13
	v_cvt_pk_f16_f32 v229, v14, v15
	v_cvt_pk_f16_f32 v230, v16, v17
	v_cvt_pk_f16_f32 v231, v18, v19
	s_nop 1
	v_permlane16_swap_b32_e32 v228, v230
	v_permlane16_swap_b32_e32 v229, v231
	global_store_dwordx4 v177, v[228:231], s[80:81] offset:64
	v_add_u32_e32 v177, 0xc000, v177
	v_cvt_pk_f16_f32 v172, v20, v21
	v_cvt_pk_f16_f32 v173, v22, v23
	v_cvt_pk_f16_f32 v174, v24, v25
	v_cvt_pk_f16_f32 v175, v26, v27
	s_nop 1
	v_permlane16_swap_b32_e32 v172, v174
	v_permlane16_swap_b32_e32 v173, v175
	global_store_dwordx4 v177, v[172:175], s[80:81]
	v_cvt_pk_f16_f32 v228, v28, v29
	v_cvt_pk_f16_f32 v229, v30, v31
	v_cvt_pk_f16_f32 v230, v32, v33
	v_cvt_pk_f16_f32 v231, v34, v35
	s_nop 1
	v_permlane16_swap_b32_e32 v228, v230
	v_permlane16_swap_b32_e32 v229, v231
	global_store_dwordx4 v177, v[228:231], s[80:81] offset:64
	v_add_u32_e32 v177, 0xc000, v177
	v_cvt_pk_f16_f32 v172, v36, v37
	v_cvt_pk_f16_f32 v173, v38, v39
	v_cvt_pk_f16_f32 v174, v40, v41
	v_cvt_pk_f16_f32 v175, v42, v43
	s_nop 1
	v_permlane16_swap_b32_e32 v172, v174
	v_permlane16_swap_b32_e32 v173, v175
	global_store_dwordx4 v177, v[172:175], s[80:81]
	v_cvt_pk_f16_f32 v228, v44, v45
	v_cvt_pk_f16_f32 v229, v46, v47
	v_cvt_pk_f16_f32 v230, v48, v49
	v_cvt_pk_f16_f32 v231, v50, v51
	s_nop 1
	v_permlane16_swap_b32_e32 v228, v230
	v_permlane16_swap_b32_e32 v229, v231
	global_store_dwordx4 v177, v[228:231], s[80:81] offset:64
	v_add_u32_e32 v177, 0xc000, v177
	v_cvt_pk_f16_f32 v172, v52, v53
	v_cvt_pk_f16_f32 v173, v54, v55
	v_cvt_pk_f16_f32 v174, v56, v57
	v_cvt_pk_f16_f32 v175, v58, v59
	s_nop 1
	v_permlane16_swap_b32_e32 v172, v174
	v_permlane16_swap_b32_e32 v173, v175
	global_store_dwordx4 v177, v[172:175], s[80:81]
	v_cvt_pk_f16_f32 v228, v60, v61
	v_cvt_pk_f16_f32 v229, v62, v63
	v_cvt_pk_f16_f32 v230, v64, v65
	v_cvt_pk_f16_f32 v231, v66, v67
	s_nop 1
	v_permlane16_swap_b32_e32 v228, v230
	v_permlane16_swap_b32_e32 v229, v231
	global_store_dwordx4 v177, v[228:231], s[80:81] offset:64
	v_add_u32_e32 v177, 0xc000, v177
	v_cvt_pk_f16_f32 v172, v68, v69
	v_cvt_pk_f16_f32 v173, v70, v71
	v_cvt_pk_f16_f32 v174, v72, v73
	v_cvt_pk_f16_f32 v175, v74, v75
	s_nop 1
	v_permlane16_swap_b32_e32 v172, v174
	v_permlane16_swap_b32_e32 v173, v175
	global_store_dwordx4 v177, v[172:175], s[80:81]
	v_cvt_pk_f16_f32 v228, v76, v77
	v_cvt_pk_f16_f32 v229, v78, v79
	v_cvt_pk_f16_f32 v230, v80, v81
	v_cvt_pk_f16_f32 v231, v82, v83
	s_nop 1
	v_permlane16_swap_b32_e32 v228, v230
	v_permlane16_swap_b32_e32 v229, v231
	global_store_dwordx4 v177, v[228:231], s[80:81] offset:64
	v_add_u32_e32 v177, 0xc000, v177
	v_cvt_pk_f16_f32 v172, v84, v85
	v_cvt_pk_f16_f32 v173, v86, v87
	v_cvt_pk_f16_f32 v174, v88, v89
	v_cvt_pk_f16_f32 v175, v90, v91
	s_nop 1
	v_permlane16_swap_b32_e32 v172, v174
	v_permlane16_swap_b32_e32 v173, v175
	global_store_dwordx4 v177, v[172:175], s[80:81]
	v_cvt_pk_f16_f32 v228, v92, v93
	v_cvt_pk_f16_f32 v229, v94, v95
	v_cvt_pk_f16_f32 v230, v96, v97
	v_cvt_pk_f16_f32 v231, v98, v99
	s_nop 1
	v_permlane16_swap_b32_e32 v228, v230
	v_permlane16_swap_b32_e32 v229, v231
	global_store_dwordx4 v177, v[228:231], s[80:81] offset:64
	v_add_u32_e32 v177, 0xc000, v177
	v_cvt_pk_f16_f32 v172, v100, v101
	v_cvt_pk_f16_f32 v173, v102, v103
	v_cvt_pk_f16_f32 v174, v104, v105
	v_cvt_pk_f16_f32 v175, v106, v107
	s_nop 1
	v_permlane16_swap_b32_e32 v172, v174
	v_permlane16_swap_b32_e32 v173, v175
	global_store_dwordx4 v177, v[172:175], s[80:81]
	v_cvt_pk_f16_f32 v228, v108, v109
	v_cvt_pk_f16_f32 v229, v110, v111
	v_cvt_pk_f16_f32 v230, v112, v113
	v_cvt_pk_f16_f32 v231, v114, v115
	s_nop 1
	v_permlane16_swap_b32_e32 v228, v230
	v_permlane16_swap_b32_e32 v229, v231
	global_store_dwordx4 v177, v[228:231], s[80:81] offset:64
	v_add_u32_e32 v177, 0xc000, v177
	v_cvt_pk_f16_f32 v172, v116, v117
	v_cvt_pk_f16_f32 v173, v118, v119
	v_cvt_pk_f16_f32 v174, v120, v121
	v_cvt_pk_f16_f32 v175, v122, v123
	s_nop 1
	v_permlane16_swap_b32_e32 v172, v174
	v_permlane16_swap_b32_e32 v173, v175
	global_store_dwordx4 v177, v[172:175], s[80:81]
	v_cvt_pk_f16_f32 v228, v124, v125
	v_cvt_pk_f16_f32 v229, v126, v127
	v_cvt_pk_f16_f32 v230, v128, v129
	v_cvt_pk_f16_f32 v231, v130, v131
	s_nop 1
	v_permlane16_swap_b32_e32 v228, v230
	v_permlane16_swap_b32_e32 v229, v231
	global_store_dwordx4 v177, v[228:231], s[80:81] offset:64
	s_nop 1
	s_add_i32 s46, s46, s76
	s_cmp_ge_i32 s46, s59
	s_cbranch_scc1 .LBB0_1133
	s_branch .LBB0_1121

.Lt_out0:
	v_add_u32_e32 v169, s51, v164
	v_mfma_f32_16x16x32_f16 v[4:7], v[132:135], v[184:187], v[4:7]
	ds_read_b128 v[238:241], v169 offset:4112
	v_mfma_f32_16x16x32_f16 v[8:11], v[136:139], v[184:187], v[8:11]
	ds_read_b128 v[242:245], v169 offset:5136
	v_mfma_f32_16x16x32_f16 v[12:15], v[140:143], v[184:187], v[12:15]
	ds_read_b128 v[246:249], v169 offset:6160
	v_mfma_f32_16x16x32_f16 v[16:19], v[144:147], v[184:187], v[16:19]
	ds_read_b128 v[250:253], v169 offset:7184
	v_mfma_f32_16x16x32_f16 v[20:23], v[132:135], v[188:191], v[20:23]
	v_mfma_f32_16x16x32_f16 v[24:27], v[136:139], v[188:191], v[24:27]
	v_mfma_f32_16x16x32_f16 v[28:31], v[140:143], v[188:191], v[28:31]
	v_mfma_f32_16x16x32_f16 v[32:35], v[144:147], v[188:191], v[32:35]
	v_mfma_f32_16x16x32_f16 v[36:39], v[132:135], v[192:195], v[36:39]
	v_mfma_f32_16x16x32_f16 v[40:43], v[136:139], v[192:195], v[40:43]
	v_mfma_f32_16x16x32_f16 v[44:47], v[140:143], v[192:195], v[44:47]
	v_mfma_f32_16x16x32_f16 v[48:51], v[144:147], v[192:195], v[48:51]
	v_mfma_f32_16x16x32_f16 v[52:55], v[132:135], v[196:199], v[52:55]
	v_mfma_f32_16x16x32_f16 v[56:59], v[136:139], v[196:199], v[56:59]
	v_mfma_f32_16x16x32_f16 v[60:63], v[140:143], v[196:199], v[60:63]
	v_mfma_f32_16x16x32_f16 v[64:67], v[144:147], v[196:199], v[64:67]
	s_waitcnt vmcnt(8) lgkmcnt(0)
	s_barrier
	s_add_i32 s52, s51, 0x8000
	s_cmp_lg_u32 s51, 0x18000
	s_cselect_b32 s52, s52, 0
	v_add_u32_e32 v168, s52, v165
	v_add_u32_e32 v169, s52, v164
	s_add_u32 vcc_lo, s32, s51
	v_mfma_f32_16x16x32_f16 v[68:71], v[132:135], v[238:241], v[68:71]
	ds_read_b128 v[148:151], v168 offset:16
	ds_read_b128 v[184:187], v169 offset:16
	s_mov_b32 m0, vcc_lo
	s_nop 0
	global_load_lds_dwordx4 v170, s[28:29]
	v_mfma_f32_16x16x32_f16 v[72:75], v[136:139], v[238:241], v[72:75]
	ds_read_b128 v[152:155], v168 offset:1040
	ds_read_b128 v[188:191], v169 offset:1040
	s_add_u32 m0, vcc_lo, 0x400
	s_nop 0
	global_load_lds_dwordx4 v171, s[28:29]
	v_mfma_f32_16x16x32_f16 v[76:79], v[140:143], v[238:241], v[76:79]
	ds_read_b128 v[156:159], v168 offset:2064
	ds_read_b128 v[192:195], v169 offset:2064
	s_add_u32 m0, vcc_lo, 0x4000
	s_nop 0
	global_load_lds_dwordx4 v170, s[30:31]
	v_mfma_f32_16x16x32_f16 v[80:83], v[144:147], v[238:241], v[80:83]
	ds_read_b128 v[160:163], v168 offset:3088
	ds_read_b128 v[196:199], v169 offset:3088
	s_add_u32 m0, vcc_lo, 0x4400
	s_nop 0
	global_load_lds_dwordx4 v171, s[30:31]
	v_mfma_f32_16x16x32_f16 v[84:87], v[132:135], v[242:245], v[84:87]
	v_mfma_f32_16x16x32_f16 v[88:91], v[136:139], v[242:245], v[88:91]
	v_mfma_f32_16x16x32_f16 v[92:95], v[140:143], v[242:245], v[92:95]
	v_mfma_f32_16x16x32_f16 v[96:99], v[144:147], v[242:245], v[96:99]
	v_mfma_f32_16x16x32_f16 v[100:103], v[132:135], v[246:249], v[100:103]
	v_mfma_f32_16x16x32_f16 v[104:107], v[136:139], v[246:249], v[104:107]
	v_mfma_f32_16x16x32_f16 v[108:111], v[140:143], v[246:249], v[108:111]
	v_mfma_f32_16x16x32_f16 v[112:115], v[144:147], v[246:249], v[112:115]
	v_mfma_f32_16x16x32_f16 v[116:119], v[132:135], v[250:253], v[116:119]
	v_mfma_f32_16x16x32_f16 v[120:123], v[136:139], v[250:253], v[120:123]
	v_mfma_f32_16x16x32_f16 v[124:127], v[140:143], v[250:253], v[124:127]
	v_mfma_f32_16x16x32_f16 v[128:131], v[144:147], v[250:253], v[128:131]
	s_waitcnt lgkmcnt(0)
	s_mov_b32 s51, s52
	s_add_u32 s28, s28, 64
	s_addc_u32 s29, s29, 0
	s_add_u32 s30, s30, 64
	s_addc_u32 s31, s31, 0
	v_add_u32_e32 v169, s51, v164
	v_mfma_f32_16x16x32_f16 v[4:7], v[148:151], v[184:187], v[4:7]
	ds_read_b128 v[238:241], v169 offset:4112
	v_mfma_f32_16x16x32_f16 v[8:11], v[152:155], v[184:187], v[8:11]
	ds_read_b128 v[242:245], v169 offset:5136
	v_mfma_f32_16x16x32_f16 v[12:15], v[156:159], v[184:187], v[12:15]
	ds_read_b128 v[246:249], v169 offset:6160
	v_mfma_f32_16x16x32_f16 v[16:19], v[160:163], v[184:187], v[16:19]
	ds_read_b128 v[250:253], v169 offset:7184
	v_mfma_f32_16x16x32_f16 v[20:23], v[148:151], v[188:191], v[20:23]
	v_mfma_f32_16x16x32_f16 v[24:27], v[152:155], v[188:191], v[24:27]
	v_mfma_f32_16x16x32_f16 v[28:31], v[156:159], v[188:191], v[28:31]
	v_mfma_f32_16x16x32_f16 v[32:35], v[160:163], v[188:191], v[32:35]
	v_mfma_f32_16x16x32_f16 v[36:39], v[148:151], v[192:195], v[36:39]
	v_mfma_f32_16x16x32_f16 v[40:43], v[152:155], v[192:195], v[40:43]
	v_mfma_f32_16x16x32_f16 v[44:47], v[156:159], v[192:195], v[44:47]
	v_mfma_f32_16x16x32_f16 v[48:51], v[160:163], v[192:195], v[48:51]
	v_mfma_f32_16x16x32_f16 v[52:55], v[148:151], v[196:199], v[52:55]
	v_mfma_f32_16x16x32_f16 v[56:59], v[152:155], v[196:199], v[56:59]
	v_mfma_f32_16x16x32_f16 v[60:63], v[156:159], v[196:199], v[60:63]
	v_mfma_f32_16x16x32_f16 v[64:67], v[160:163], v[196:199], v[64:67]
	s_waitcnt vmcnt(8) lgkmcnt(0)
	s_barrier
	s_add_i32 s52, s51, 0x8000
	s_cmp_lg_u32 s51, 0x18000
	s_cselect_b32 s52, s52, 0
	v_add_u32_e32 v168, s52, v165
	v_add_u32_e32 v169, s52, v164
	s_add_u32 vcc_lo, s32, s51
	v_mfma_f32_16x16x32_f16 v[68:71], v[148:151], v[238:241], v[68:71]
	ds_read_b128 v[132:135], v168 offset:16
	ds_read_b128 v[184:187], v169 offset:16
	s_mov_b32 m0, vcc_lo
	s_nop 0
	global_load_lds_dwordx4 v170, s[28:29]
	v_mfma_f32_16x16x32_f16 v[72:75], v[152:155], v[238:241], v[72:75]
	ds_read_b128 v[136:139], v168 offset:1040
	ds_read_b128 v[188:191], v169 offset:1040
	s_add_u32 m0, vcc_lo, 0x400
	s_nop 0
	global_load_lds_dwordx4 v171, s[28:29]
	v_mfma_f32_16x16x32_f16 v[76:79], v[156:159], v[238:241], v[76:79]
	ds_read_b128 v[140:143], v168 offset:2064
	ds_read_b128 v[192:195], v169 offset:2064
	s_add_u32 m0, vcc_lo, 0x4000
	s_nop 0
	global_load_lds_dwordx4 v170, s[30:31]
	v_mfma_f32_16x16x32_f16 v[80:83], v[160:163], v[238:241], v[80:83]
	ds_read_b128 v[144:147], v168 offset:3088
	ds_read_b128 v[196:199], v169 offset:3088
	s_add_u32 m0, vcc_lo, 0x4400
	s_nop 0
	global_load_lds_dwordx4 v171, s[30:31]
	v_mfma_f32_16x16x32_f16 v[84:87], v[148:151], v[242:245], v[84:87]
	v_mfma_f32_16x16x32_f16 v[88:91], v[152:155], v[242:245], v[88:91]
	v_mfma_f32_16x16x32_f16 v[92:95], v[156:159], v[242:245], v[92:95]
	v_mfma_f32_16x16x32_f16 v[96:99], v[160:163], v[242:245], v[96:99]
	v_mfma_f32_16x16x32_f16 v[100:103], v[148:151], v[246:249], v[100:103]
	v_mfma_f32_16x16x32_f16 v[104:107], v[152:155], v[246:249], v[104:107]
	v_mfma_f32_16x16x32_f16 v[108:111], v[156:159], v[246:249], v[108:111]
	v_mfma_f32_16x16x32_f16 v[112:115], v[160:163], v[246:249], v[112:115]
	v_mfma_f32_16x16x32_f16 v[116:119], v[148:151], v[250:253], v[116:119]
	v_mfma_f32_16x16x32_f16 v[120:123], v[152:155], v[250:253], v[120:123]
	v_mfma_f32_16x16x32_f16 v[124:127], v[156:159], v[250:253], v[124:127]
	v_mfma_f32_16x16x32_f16 v[128:131], v[160:163], v[250:253], v[128:131]
	s_waitcnt lgkmcnt(0)
	s_mov_b32 s51, s52
	s_add_u32 s28, s28, 64
	s_addc_u32 s29, s29, 0
	s_add_u32 s30, s30, 64
	s_addc_u32 s31, s31, 0
	s_add_i32 s53, s53, 2
	s_cmp_lt_u32 s53, 28
	s_cbranch_scc1 .Lt_out0
	v_add_u32_e32 v169, s51, v164
	v_mfma_f32_16x16x32_f16 v[4:7], v[132:135], v[184:187], v[4:7]
	ds_read_b128 v[238:241], v169 offset:4112
	v_mfma_f32_16x16x32_f16 v[8:11], v[136:139], v[184:187], v[8:11]
	ds_read_b128 v[242:245], v169 offset:5136
	v_mfma_f32_16x16x32_f16 v[12:15], v[140:143], v[184:187], v[12:15]
	ds_read_b128 v[246:249], v169 offset:6160
	v_mfma_f32_16x16x32_f16 v[16:19], v[144:147], v[184:187], v[16:19]
	ds_read_b128 v[250:253], v169 offset:7184
	v_mfma_f32_16x16x32_f16 v[20:23], v[132:135], v[188:191], v[20:23]
	v_mfma_f32_16x16x32_f16 v[24:27], v[136:139], v[188:191], v[24:27]
	v_mfma_f32_16x16x32_f16 v[28:31], v[140:143], v[188:191], v[28:31]
	v_mfma_f32_16x16x32_f16 v[32:35], v[144:147], v[188:191], v[32:35]
	v_mfma_f32_16x16x32_f16 v[36:39], v[132:135], v[192:195], v[36:39]
	v_mfma_f32_16x16x32_f16 v[40:43], v[136:139], v[192:195], v[40:43]
	v_mfma_f32_16x16x32_f16 v[44:47], v[140:143], v[192:195], v[44:47]
	v_mfma_f32_16x16x32_f16 v[48:51], v[144:147], v[192:195], v[48:51]
	v_mfma_f32_16x16x32_f16 v[52:55], v[132:135], v[196:199], v[52:55]
	v_mfma_f32_16x16x32_f16 v[56:59], v[136:139], v[196:199], v[56:59]
	v_mfma_f32_16x16x32_f16 v[60:63], v[140:143], v[196:199], v[60:63]
	v_mfma_f32_16x16x32_f16 v[64:67], v[144:147], v[196:199], v[64:67]
	s_waitcnt vmcnt(8) lgkmcnt(0)
	s_barrier
	s_add_i32 s52, s51, 0x8000
	s_cmp_lg_u32 s51, 0x18000
	s_cselect_b32 s52, s52, 0
	v_add_u32_e32 v168, s52, v165
	v_add_u32_e32 v169, s52, v164
	v_mfma_f32_16x16x32_f16 v[68:71], v[132:135], v[238:241], v[68:71]
	ds_read_b128 v[148:151], v168 offset:16
	ds_read_b128 v[184:187], v169 offset:16
	v_mfma_f32_16x16x32_f16 v[72:75], v[136:139], v[238:241], v[72:75]
	ds_read_b128 v[152:155], v168 offset:1040
	ds_read_b128 v[188:191], v169 offset:1040
	v_mfma_f32_16x16x32_f16 v[76:79], v[140:143], v[238:241], v[76:79]
	ds_read_b128 v[156:159], v168 offset:2064
	ds_read_b128 v[192:195], v169 offset:2064
	v_mfma_f32_16x16x32_f16 v[80:83], v[144:147], v[238:241], v[80:83]
	ds_read_b128 v[160:163], v168 offset:3088
	ds_read_b128 v[196:199], v169 offset:3088
	v_mfma_f32_16x16x32_f16 v[84:87], v[132:135], v[242:245], v[84:87]
	v_mfma_f32_16x16x32_f16 v[88:91], v[136:139], v[242:245], v[88:91]
	v_mfma_f32_16x16x32_f16 v[92:95], v[140:143], v[242:245], v[92:95]
	v_mfma_f32_16x16x32_f16 v[96:99], v[144:147], v[242:245], v[96:99]
	v_mfma_f32_16x16x32_f16 v[100:103], v[132:135], v[246:249], v[100:103]
	v_mfma_f32_16x16x32_f16 v[104:107], v[136:139], v[246:249], v[104:107]
	v_mfma_f32_16x16x32_f16 v[108:111], v[140:143], v[246:249], v[108:111]
	v_mfma_f32_16x16x32_f16 v[112:115], v[144:147], v[246:249], v[112:115]
	v_mfma_f32_16x16x32_f16 v[116:119], v[132:135], v[250:253], v[116:119]
	v_mfma_f32_16x16x32_f16 v[120:123], v[136:139], v[250:253], v[120:123]
	v_mfma_f32_16x16x32_f16 v[124:127], v[140:143], v[250:253], v[124:127]
	v_mfma_f32_16x16x32_f16 v[128:131], v[144:147], v[250:253], v[128:131]
	s_waitcnt lgkmcnt(0)
	s_mov_b32 s51, s52
	v_add_u32_e32 v169, s51, v164
	v_mfma_f32_16x16x32_f16 v[4:7], v[148:151], v[184:187], v[4:7]
	ds_read_b128 v[238:241], v169 offset:4112
	v_mfma_f32_16x16x32_f16 v[8:11], v[152:155], v[184:187], v[8:11]
	ds_read_b128 v[242:245], v169 offset:5136
	v_mfma_f32_16x16x32_f16 v[12:15], v[156:159], v[184:187], v[12:15]
	ds_read_b128 v[246:249], v169 offset:6160
	v_mfma_f32_16x16x32_f16 v[16:19], v[160:163], v[184:187], v[16:19]
	ds_read_b128 v[250:253], v169 offset:7184
	v_mfma_f32_16x16x32_f16 v[20:23], v[148:151], v[188:191], v[20:23]
	v_mfma_f32_16x16x32_f16 v[24:27], v[152:155], v[188:191], v[24:27]
	v_mfma_f32_16x16x32_f16 v[28:31], v[156:159], v[188:191], v[28:31]
	v_mfma_f32_16x16x32_f16 v[32:35], v[160:163], v[188:191], v[32:35]
	v_mfma_f32_16x16x32_f16 v[36:39], v[148:151], v[192:195], v[36:39]
	v_mfma_f32_16x16x32_f16 v[40:43], v[152:155], v[192:195], v[40:43]
	v_mfma_f32_16x16x32_f16 v[44:47], v[156:159], v[192:195], v[44:47]
	v_mfma_f32_16x16x32_f16 v[48:51], v[160:163], v[192:195], v[48:51]
	v_mfma_f32_16x16x32_f16 v[52:55], v[148:151], v[196:199], v[52:55]
	v_mfma_f32_16x16x32_f16 v[56:59], v[152:155], v[196:199], v[56:59]
	v_mfma_f32_16x16x32_f16 v[60:63], v[156:159], v[196:199], v[60:63]
	v_mfma_f32_16x16x32_f16 v[64:67], v[160:163], v[196:199], v[64:67]
	s_waitcnt vmcnt(4) lgkmcnt(0)
	s_barrier
	s_add_i32 s52, s51, 0x8000
	s_cmp_lg_u32 s51, 0x18000
	s_cselect_b32 s52, s52, 0
	v_add_u32_e32 v168, s52, v165
	v_add_u32_e32 v169, s52, v164
	v_mfma_f32_16x16x32_f16 v[68:71], v[148:151], v[238:241], v[68:71]
	ds_read_b128 v[132:135], v168 offset:16
	ds_read_b128 v[184:187], v169 offset:16
	v_mfma_f32_16x16x32_f16 v[72:75], v[152:155], v[238:241], v[72:75]
	ds_read_b128 v[136:139], v168 offset:1040
	ds_read_b128 v[188:191], v169 offset:1040
	v_mfma_f32_16x16x32_f16 v[76:79], v[156:159], v[238:241], v[76:79]
	ds_read_b128 v[140:143], v168 offset:2064
	ds_read_b128 v[192:195], v169 offset:2064
	v_mfma_f32_16x16x32_f16 v[80:83], v[160:163], v[238:241], v[80:83]
	ds_read_b128 v[144:147], v168 offset:3088
	ds_read_b128 v[196:199], v169 offset:3088
	v_mfma_f32_16x16x32_f16 v[84:87], v[148:151], v[242:245], v[84:87]
	v_mfma_f32_16x16x32_f16 v[88:91], v[152:155], v[242:245], v[88:91]
	v_mfma_f32_16x16x32_f16 v[92:95], v[156:159], v[242:245], v[92:95]
	v_mfma_f32_16x16x32_f16 v[96:99], v[160:163], v[242:245], v[96:99]
	v_mfma_f32_16x16x32_f16 v[100:103], v[148:151], v[246:249], v[100:103]
	v_mfma_f32_16x16x32_f16 v[104:107], v[152:155], v[246:249], v[104:107]
	v_mfma_f32_16x16x32_f16 v[108:111], v[156:159], v[246:249], v[108:111]
	v_mfma_f32_16x16x32_f16 v[112:115], v[160:163], v[246:249], v[112:115]
	v_mfma_f32_16x16x32_f16 v[116:119], v[148:151], v[250:253], v[116:119]
	v_mfma_f32_16x16x32_f16 v[120:123], v[152:155], v[250:253], v[120:123]
	v_mfma_f32_16x16x32_f16 v[124:127], v[156:159], v[250:253], v[124:127]
	v_mfma_f32_16x16x32_f16 v[128:131], v[160:163], v[250:253], v[128:131]
	s_waitcnt lgkmcnt(0)
	s_mov_b32 s51, s52
	v_add_u32_e32 v169, s51, v164
	v_mfma_f32_16x16x32_f16 v[4:7], v[132:135], v[184:187], v[4:7]
	ds_read_b128 v[238:241], v169 offset:4112
	v_mfma_f32_16x16x32_f16 v[8:11], v[136:139], v[184:187], v[8:11]
	ds_read_b128 v[242:245], v169 offset:5136
	v_mfma_f32_16x16x32_f16 v[12:15], v[140:143], v[184:187], v[12:15]
	ds_read_b128 v[246:249], v169 offset:6160
	v_mfma_f32_16x16x32_f16 v[16:19], v[144:147], v[184:187], v[16:19]
	ds_read_b128 v[250:253], v169 offset:7184
	v_mfma_f32_16x16x32_f16 v[20:23], v[132:135], v[188:191], v[20:23]
	v_mfma_f32_16x16x32_f16 v[24:27], v[136:139], v[188:191], v[24:27]
	v_mfma_f32_16x16x32_f16 v[28:31], v[140:143], v[188:191], v[28:31]
	v_mfma_f32_16x16x32_f16 v[32:35], v[144:147], v[188:191], v[32:35]
	v_mfma_f32_16x16x32_f16 v[36:39], v[132:135], v[192:195], v[36:39]
	v_mfma_f32_16x16x32_f16 v[40:43], v[136:139], v[192:195], v[40:43]
	v_mfma_f32_16x16x32_f16 v[44:47], v[140:143], v[192:195], v[44:47]
	v_mfma_f32_16x16x32_f16 v[48:51], v[144:147], v[192:195], v[48:51]
	v_mfma_f32_16x16x32_f16 v[52:55], v[132:135], v[196:199], v[52:55]
	v_mfma_f32_16x16x32_f16 v[56:59], v[136:139], v[196:199], v[56:59]
	v_mfma_f32_16x16x32_f16 v[60:63], v[140:143], v[196:199], v[60:63]
	v_mfma_f32_16x16x32_f16 v[64:67], v[144:147], v[196:199], v[64:67]
	s_waitcnt vmcnt(0) lgkmcnt(0)
	s_barrier
	s_add_i32 s52, s51, 0x8000
	s_cmp_lg_u32 s51, 0x18000
	s_cselect_b32 s52, s52, 0
	v_add_u32_e32 v168, s52, v165
	v_add_u32_e32 v169, s52, v164
	v_mfma_f32_16x16x32_f16 v[68:71], v[132:135], v[238:241], v[68:71]
	ds_read_b128 v[148:151], v168 offset:16
	ds_read_b128 v[184:187], v169 offset:16
	v_mfma_f32_16x16x32_f16 v[72:75], v[136:139], v[238:241], v[72:75]
	ds_read_b128 v[152:155], v168 offset:1040
	ds_read_b128 v[188:191], v169 offset:1040
	v_mfma_f32_16x16x32_f16 v[76:79], v[140:143], v[238:241], v[76:79]
	ds_read_b128 v[156:159], v168 offset:2064
	ds_read_b128 v[192:195], v169 offset:2064
	v_mfma_f32_16x16x32_f16 v[80:83], v[144:147], v[238:241], v[80:83]
	ds_read_b128 v[160:163], v168 offset:3088
	ds_read_b128 v[196:199], v169 offset:3088
	v_mfma_f32_16x16x32_f16 v[84:87], v[132:135], v[242:245], v[84:87]
	v_mfma_f32_16x16x32_f16 v[88:91], v[136:139], v[242:245], v[88:91]
	v_mfma_f32_16x16x32_f16 v[92:95], v[140:143], v[242:245], v[92:95]
	v_mfma_f32_16x16x32_f16 v[96:99], v[144:147], v[242:245], v[96:99]
	v_mfma_f32_16x16x32_f16 v[100:103], v[132:135], v[246:249], v[100:103]
	v_mfma_f32_16x16x32_f16 v[104:107], v[136:139], v[246:249], v[104:107]
	v_mfma_f32_16x16x32_f16 v[108:111], v[140:143], v[246:249], v[108:111]
	v_mfma_f32_16x16x32_f16 v[112:115], v[144:147], v[246:249], v[112:115]
	v_mfma_f32_16x16x32_f16 v[116:119], v[132:135], v[250:253], v[116:119]
	v_mfma_f32_16x16x32_f16 v[120:123], v[136:139], v[250:253], v[120:123]
	v_mfma_f32_16x16x32_f16 v[124:127], v[140:143], v[250:253], v[124:127]
	v_mfma_f32_16x16x32_f16 v[128:131], v[144:147], v[250:253], v[128:131]
	s_waitcnt lgkmcnt(0)
	s_mov_b32 s51, s52
	v_add_u32_e32 v169, s51, v164
	v_mfma_f32_16x16x32_f16 v[4:7], v[148:151], v[184:187], v[4:7]
	ds_read_b128 v[238:241], v169 offset:4112
	v_mfma_f32_16x16x32_f16 v[8:11], v[152:155], v[184:187], v[8:11]
	ds_read_b128 v[242:245], v169 offset:5136
	v_mfma_f32_16x16x32_f16 v[12:15], v[156:159], v[184:187], v[12:15]
	ds_read_b128 v[246:249], v169 offset:6160
	v_mfma_f32_16x16x32_f16 v[16:19], v[160:163], v[184:187], v[16:19]
	ds_read_b128 v[250:253], v169 offset:7184
	v_mfma_f32_16x16x32_f16 v[20:23], v[148:151], v[188:191], v[20:23]
	v_mfma_f32_16x16x32_f16 v[24:27], v[152:155], v[188:191], v[24:27]
	v_mfma_f32_16x16x32_f16 v[28:31], v[156:159], v[188:191], v[28:31]
	v_mfma_f32_16x16x32_f16 v[32:35], v[160:163], v[188:191], v[32:35]
	v_mfma_f32_16x16x32_f16 v[36:39], v[148:151], v[192:195], v[36:39]
	v_mfma_f32_16x16x32_f16 v[40:43], v[152:155], v[192:195], v[40:43]
	v_mfma_f32_16x16x32_f16 v[44:47], v[156:159], v[192:195], v[44:47]
	v_mfma_f32_16x16x32_f16 v[48:51], v[160:163], v[192:195], v[48:51]
	v_mfma_f32_16x16x32_f16 v[52:55], v[148:151], v[196:199], v[52:55]
	v_mfma_f32_16x16x32_f16 v[56:59], v[152:155], v[196:199], v[56:59]
	v_mfma_f32_16x16x32_f16 v[60:63], v[156:159], v[196:199], v[60:63]
	v_mfma_f32_16x16x32_f16 v[64:67], v[160:163], v[196:199], v[64:67]
	s_waitcnt lgkmcnt(0)
	s_barrier
	v_mfma_f32_16x16x32_f16 v[68:71], v[148:151], v[238:241], v[68:71]
	v_mfma_f32_16x16x32_f16 v[72:75], v[152:155], v[238:241], v[72:75]
	v_mfma_f32_16x16x32_f16 v[76:79], v[156:159], v[238:241], v[76:79]
	v_mfma_f32_16x16x32_f16 v[80:83], v[160:163], v[238:241], v[80:83]
	v_mfma_f32_16x16x32_f16 v[84:87], v[148:151], v[242:245], v[84:87]
	v_mfma_f32_16x16x32_f16 v[88:91], v[152:155], v[242:245], v[88:91]
	v_mfma_f32_16x16x32_f16 v[92:95], v[156:159], v[242:245], v[92:95]
	v_mfma_f32_16x16x32_f16 v[96:99], v[160:163], v[242:245], v[96:99]
	v_mfma_f32_16x16x32_f16 v[100:103], v[148:151], v[246:249], v[100:103]
	v_mfma_f32_16x16x32_f16 v[104:107], v[152:155], v[246:249], v[104:107]
	v_mfma_f32_16x16x32_f16 v[108:111], v[156:159], v[246:249], v[108:111]
	v_mfma_f32_16x16x32_f16 v[112:115], v[160:163], v[246:249], v[112:115]
	v_mfma_f32_16x16x32_f16 v[116:119], v[148:151], v[250:253], v[116:119]
	v_mfma_f32_16x16x32_f16 v[120:123], v[152:155], v[250:253], v[120:123]
	v_mfma_f32_16x16x32_f16 v[124:127], v[156:159], v[250:253], v[124:127]
	v_mfma_f32_16x16x32_f16 v[128:131], v[160:163], v[250:253], v[128:131]
	s_sub_u32 s77, s50, 0x1000
	s_lshr_b32 s77, s77, 12
	s_add_u32 s77, s77, 1
	s_cmp_lt_u32 s50, 0x1000
	s_cselect_b32 s77, 0, s77
	s_mul_i32 s77, s77, 0x6000
	s_add_u32 s68, s26, s77
	s_addc_u32 s69, s27, 0
	s_add_u32 s68, s68, 0x2000
	s_addc_u32 s69, s69, 0
	s_lshl_b32 s82, s50, 11
	s_add_u32 s80, s42, s82
	s_addc_u32 s81, s43, 0
	s_lshl_b32 s82, s37, 1
	s_add_u32 s80, s80, s82
	s_addc_u32 s81, s81, 0
	v_and_b32_e32 v172, 15, v200
	v_bfe_u32 v173, v200, 4, 2
	v_bfe_u32 v174, v200, 6, 2
	v_bfe_u32 v175, v200, 8, 1
	v_lshlrev_b32_e32 v176, 6, v174
	v_lshl_or_b32 v176, v173, 2, v176
	v_lshl_or_b32 v175, v175, 7, v172
	v_lshlrev_b32_e32 v175, 11, v175
	v_lshl_add_u32 v177, v176, 1, v175
	v_lshlrev_b32_e32 v178, 1, v175
	v_lshl_add_u32 v178, v176, 2, v178
	s_cmp_lt_u32 s50, 0x1000
	s_cselect_b32 s77, 0, 8
	s_load_dwordx2 s[28:29], s[22:23], s77
	s_sub_u32 s77, s50, 0x1000
	s_cselect_b32 s77, s50, s77
	s_lshl_b32 s77, s77, 12
	s_lshl_b32 s82, s37, 2
	s_add_u32 s77, s77, s82
	s_waitcnt lgkmcnt(0)
	s_add_u32 s28, s28, s77
	s_addc_u32 s29, s29, 0
	v_add_u32_e32 v176, s37, v176
	v_lshlrev_b32_e32 v176, 2, v176
	global_load_dwordx4 v[132:135], v176, s[68:69]
	global_load_dwordx4 v[136:139], v176, s[68:69] offset:64
	global_load_dwordx4 v[140:143], v176, s[68:69] offset:128
	global_load_dwordx4 v[144:147], v176, s[68:69] offset:192
	v_and_b32_e32 v172, 1, v173
	v_mul_u32_u24_e32 v172, 24, v172
	v_add_u32_e32 v177, v177, v172
	global_load_dwordx4 v[184:187], v178, s[28:29]
	global_load_dwordx4 v[188:191], v178, s[28:29] offset:64
	global_load_dwordx4 v[192:195], v178, s[28:29] offset:128
	global_load_dwordx4 v[196:199], v178, s[28:29] offset:192
	v_add_u32_e32 v178, 0x10000, v178
	global_load_dwordx4 v[238:241], v178, s[28:29]
	global_load_dwordx4 v[242:245], v178, s[28:29] offset:64
	global_load_dwordx4 v[246:249], v178, s[28:29] offset:128
	global_load_dwordx4 v[250:253], v178, s[28:29] offset:192
	s_waitcnt vmcnt(6)
	v_pk_mul_f32 v[184:185], v[184:185], s[84:85] op_sel_hi:[1,0]
	v_pk_mul_f32 v[186:187], v[186:187], s[84:85] op_sel_hi:[1,0]
	v_pk_fma_f32 v[4:5], v[4:5], v[132:133], v[184:185]
	v_pk_fma_f32 v[6:7], v[6:7], v[134:135], v[186:187]
	v_cvt_pk_f16_f32 v172, v4, v5
	v_cvt_pk_f16_f32 v173, v6, v7
	v_pk_mul_f32 v[188:189], v[188:189], s[84:85] op_sel_hi:[1,0]
	v_pk_mul_f32 v[190:191], v[190:191], s[84:85] op_sel_hi:[1,0]
	v_pk_fma_f32 v[8:9], v[8:9], v[136:137], v[188:189]
	v_pk_fma_f32 v[10:11], v[10:11], v[138:139], v[190:191]
	v_cvt_pk_f16_f32 v174, v8, v9
	v_cvt_pk_f16_f32 v175, v10, v11
	s_nop 1
	v_permlane16_swap_b32_e32 v172, v174
	v_permlane16_swap_b32_e32 v173, v175
	global_store_dwordx4 v177, v[172:175], s[80:81]
	s_waitcnt vmcnt(5)
	v_pk_mul_f32 v[192:193], v[192:193], s[84:85] op_sel_hi:[1,0]
	v_pk_mul_f32 v[194:195], v[194:195], s[84:85] op_sel_hi:[1,0]
	v_pk_fma_f32 v[12:13], v[12:13], v[140:141], v[192:193]
	v_pk_fma_f32 v[14:15], v[14:15], v[142:143], v[194:195]
	v_cvt_pk_f16_f32 v228, v12, v13
	v_cvt_pk_f16_f32 v229, v14, v15
	v_pk_mul_f32 v[196:197], v[196:197], s[84:85] op_sel_hi:[1,0]
	v_pk_mul_f32 v[198:199], v[198:199], s[84:85] op_sel_hi:[1,0]
	v_pk_fma_f32 v[16:17], v[16:17], v[144:145], v[196:197]
	v_pk_fma_f32 v[18:19], v[18:19], v[146:147], v[198:199]
	v_cvt_pk_f16_f32 v230, v16, v17
	v_cvt_pk_f16_f32 v231, v18, v19
	s_nop 1
	v_permlane16_swap_b32_e32 v228, v230
	v_permlane16_swap_b32_e32 v229, v231
	global_store_dwordx4 v177, v[228:231], s[80:81] offset:64
	v_add_u32_e32 v177, 0x8000, v177
	v_add_u32_e32 v178, 0x10000, v178
	global_load_dwordx4 v[184:187], v178, s[28:29]
	global_load_dwordx4 v[188:191], v178, s[28:29] offset:64
	global_load_dwordx4 v[192:195], v178, s[28:29] offset:128
	global_load_dwordx4 v[196:199], v178, s[28:29] offset:192
	s_waitcnt vmcnt(8)
	v_pk_mul_f32 v[238:239], v[238:239], s[84:85] op_sel_hi:[1,0]
	v_pk_mul_f32 v[240:241], v[240:241], s[84:85] op_sel_hi:[1,0]
	v_pk_fma_f32 v[20:21], v[20:21], v[132:133], v[238:239]
	v_pk_fma_f32 v[22:23], v[22:23], v[134:135], v[240:241]
	v_cvt_pk_f16_f32 v172, v20, v21
	v_cvt_pk_f16_f32 v173, v22, v23
	v_pk_mul_f32 v[242:243], v[242:243], s[84:85] op_sel_hi:[1,0]
	v_pk_mul_f32 v[244:245], v[244:245], s[84:85] op_sel_hi:[1,0]
	v_pk_fma_f32 v[24:25], v[24:25], v[136:137], v[242:243]
	v_pk_fma_f32 v[26:27], v[26:27], v[138:139], v[244:245]
	v_cvt_pk_f16_f32 v174, v24, v25
	v_cvt_pk_f16_f32 v175, v26, v27
	s_nop 1
	v_permlane16_swap_b32_e32 v172, v174
	v_permlane16_swap_b32_e32 v173, v175
	global_store_dwordx4 v177, v[172:175], s[80:81]
	s_waitcnt vmcnt(7)
	v_pk_mul_f32 v[246:247], v[246:247], s[84:85] op_sel_hi:[1,0]
	v_pk_mul_f32 v[248:249], v[248:249], s[84:85] op_sel_hi:[1,0]
	v_pk_fma_f32 v[28:29], v[28:29], v[140:141], v[246:247]
	v_pk_fma_f32 v[30:31], v[30:31], v[142:143], v[248:249]
	v_cvt_pk_f16_f32 v228, v28, v29
	v_cvt_pk_f16_f32 v229, v30, v31
	v_pk_mul_f32 v[250:251], v[250:251], s[84:85] op_sel_hi:[1,0]
	v_pk_mul_f32 v[252:253], v[252:253], s[84:85] op_sel_hi:[1,0]
	v_pk_fma_f32 v[32:33], v[32:33], v[144:145], v[250:251]
	v_pk_fma_f32 v[34:35], v[34:35], v[146:147], v[252:253]
	v_cvt_pk_f16_f32 v230, v32, v33
	v_cvt_pk_f16_f32 v231, v34, v35
	s_nop 1
	v_permlane16_swap_b32_e32 v228, v230
	v_permlane16_swap_b32_e32 v229, v231
	global_store_dwordx4 v177, v[228:231], s[80:81] offset:64
	v_add_u32_e32 v177, 0x8000, v177
	v_add_u32_e32 v178, 0x10000, v178
	global_load_dwordx4 v[238:241], v178, s[28:29]
	global_load_dwordx4 v[242:245], v178, s[28:29] offset:64
	global_load_dwordx4 v[246:249], v178, s[28:29] offset:128
	global_load_dwordx4 v[250:253], v178, s[28:29] offset:192
	s_waitcnt vmcnt(8)
	v_pk_mul_f32 v[184:185], v[184:185], s[84:85] op_sel_hi:[1,0]
	v_pk_mul_f32 v[186:187], v[186:187], s[84:85] op_sel_hi:[1,0]
	v_pk_fma_f32 v[36:37], v[36:37], v[132:133], v[184:185]
	v_pk_fma_f32 v[38:39], v[38:39], v[134:135], v[186:187]
	v_cvt_pk_f16_f32 v172, v36, v37
	v_cvt_pk_f16_f32 v173, v38, v39
	v_pk_mul_f32 v[188:189], v[188:189], s[84:85] op_sel_hi:[1,0]
	v_pk_mul_f32 v[190:191], v[190:191], s[84:85] op_sel_hi:[1,0]
	v_pk_fma_f32 v[40:41], v[40:41], v[136:137], v[188:189]
	v_pk_fma_f32 v[42:43], v[42:43], v[138:139], v[190:191]
	v_cvt_pk_f16_f32 v174, v40, v41
	v_cvt_pk_f16_f32 v175, v42, v43
	s_nop 1
	v_permlane16_swap_b32_e32 v172, v174
	v_permlane16_swap_b32_e32 v173, v175
	global_store_dwordx4 v177, v[172:175], s[80:81]
	s_waitcnt vmcnt(7)
	v_pk_mul_f32 v[192:193], v[192:193], s[84:85] op_sel_hi:[1,0]
	v_pk_mul_f32 v[194:195], v[194:195], s[84:85] op_sel_hi:[1,0]
	v_pk_fma_f32 v[44:45], v[44:45], v[140:141], v[192:193]
	v_pk_fma_f32 v[46:47], v[46:47], v[142:143], v[194:195]
	v_cvt_pk_f16_f32 v228, v44, v45
	v_cvt_pk_f16_f32 v229, v46, v47
	v_pk_mul_f32 v[196:197], v[196:197], s[84:85] op_sel_hi:[1,0]
	v_pk_mul_f32 v[198:199], v[198:199], s[84:85] op_sel_hi:[1,0]
	v_pk_fma_f32 v[48:49], v[48:49], v[144:145], v[196:197]
	v_pk_fma_f32 v[50:51], v[50:51], v[146:147], v[198:199]
	v_cvt_pk_f16_f32 v230, v48, v49
	v_cvt_pk_f16_f32 v231, v50, v51
	s_nop 1
	v_permlane16_swap_b32_e32 v228, v230
	v_permlane16_swap_b32_e32 v229, v231
	global_store_dwordx4 v177, v[228:231], s[80:81] offset:64
	v_add_u32_e32 v177, 0x8000, v177
	v_add_u32_e32 v178, 0x10000, v178
	global_load_dwordx4 v[184:187], v178, s[28:29]
	global_load_dwordx4 v[188:191], v178, s[28:29] offset:64
	global_load_dwordx4 v[192:195], v178, s[28:29] offset:128
	global_load_dwordx4 v[196:199], v178, s[28:29] offset:192
	s_waitcnt vmcnt(8)
	v_pk_mul_f32 v[238:239], v[238:239], s[84:85] op_sel_hi:[1,0]
	v_pk_mul_f32 v[240:241], v[240:241], s[84:85] op_sel_hi:[1,0]
	v_pk_fma_f32 v[52:53], v[52:53], v[132:133], v[238:239]
	v_pk_fma_f32 v[54:55], v[54:55], v[134:135], v[240:241]
	v_cvt_pk_f16_f32 v172, v52, v53
	v_cvt_pk_f16_f32 v173, v54, v55
	v_pk_mul_f32 v[242:243], v[242:243], s[84:85] op_sel_hi:[1,0]
	v_pk_mul_f32 v[244:245], v[244:245], s[84:85] op_sel_hi:[1,0]
	v_pk_fma_f32 v[56:57], v[56:57], v[136:137], v[242:243]
	v_pk_fma_f32 v[58:59], v[58:59], v[138:139], v[244:245]
	v_cvt_pk_f16_f32 v174, v56, v57
	v_cvt_pk_f16_f32 v175, v58, v59
	s_nop 1
	v_permlane16_swap_b32_e32 v172, v174
	v_permlane16_swap_b32_e32 v173, v175
	global_store_dwordx4 v177, v[172:175], s[80:81]
	s_waitcnt vmcnt(7)
	v_pk_mul_f32 v[246:247], v[246:247], s[84:85] op_sel_hi:[1,0]
	v_pk_mul_f32 v[248:249], v[248:249], s[84:85] op_sel_hi:[1,0]
	v_pk_fma_f32 v[60:61], v[60:61], v[140:141], v[246:247]
	v_pk_fma_f32 v[62:63], v[62:63], v[142:143], v[248:249]
	v_cvt_pk_f16_f32 v228, v60, v61
	v_cvt_pk_f16_f32 v229, v62, v63
	v_pk_mul_f32 v[250:251], v[250:251], s[84:85] op_sel_hi:[1,0]
	v_pk_mul_f32 v[252:253], v[252:253], s[84:85] op_sel_hi:[1,0]
	v_pk_fma_f32 v[64:65], v[64:65], v[144:145], v[250:251]
	v_pk_fma_f32 v[66:67], v[66:67], v[146:147], v[252:253]
	v_cvt_pk_f16_f32 v230, v64, v65
	v_cvt_pk_f16_f32 v231, v66, v67
	s_nop 1
	v_permlane16_swap_b32_e32 v228, v230
	v_permlane16_swap_b32_e32 v229, v231
	global_store_dwordx4 v177, v[228:231], s[80:81] offset:64
	v_add_u32_e32 v177, 0x8000, v177
	v_add_u32_e32 v178, 0x10000, v178
	global_load_dwordx4 v[238:241], v178, s[28:29]
	global_load_dwordx4 v[242:245], v178, s[28:29] offset:64
	global_load_dwordx4 v[246:249], v178, s[28:29] offset:128
	global_load_dwordx4 v[250:253], v178, s[28:29] offset:192
	s_waitcnt vmcnt(8)
	v_pk_mul_f32 v[184:185], v[184:185], s[84:85] op_sel_hi:[1,0]
	v_pk_mul_f32 v[186:187], v[186:187], s[84:85] op_sel_hi:[1,0]
	v_pk_fma_f32 v[68:69], v[68:69], v[132:133], v[184:185]
	v_pk_fma_f32 v[70:71], v[70:71], v[134:135], v[186:187]
	v_cvt_pk_f16_f32 v172, v68, v69
	v_cvt_pk_f16_f32 v173, v70, v71
	v_pk_mul_f32 v[188:189], v[188:189], s[84:85] op_sel_hi:[1,0]
	v_pk_mul_f32 v[190:191], v[190:191], s[84:85] op_sel_hi:[1,0]
	v_pk_fma_f32 v[72:73], v[72:73], v[136:137], v[188:189]
	v_pk_fma_f32 v[74:75], v[74:75], v[138:139], v[190:191]
	v_cvt_pk_f16_f32 v174, v72, v73
	v_cvt_pk_f16_f32 v175, v74, v75
	s_nop 1
	v_permlane16_swap_b32_e32 v172, v174
	v_permlane16_swap_b32_e32 v173, v175
	global_store_dwordx4 v177, v[172:175], s[80:81]
	s_waitcnt vmcnt(7)
	v_pk_mul_f32 v[192:193], v[192:193], s[84:85] op_sel_hi:[1,0]
	v_pk_mul_f32 v[194:195], v[194:195], s[84:85] op_sel_hi:[1,0]
	v_pk_fma_f32 v[76:77], v[76:77], v[140:141], v[192:193]
	v_pk_fma_f32 v[78:79], v[78:79], v[142:143], v[194:195]
	v_cvt_pk_f16_f32 v228, v76, v77
	v_cvt_pk_f16_f32 v229, v78, v79
	v_pk_mul_f32 v[196:197], v[196:197], s[84:85] op_sel_hi:[1,0]
	v_pk_mul_f32 v[198:199], v[198:199], s[84:85] op_sel_hi:[1,0]
	v_pk_fma_f32 v[80:81], v[80:81], v[144:145], v[196:197]
	v_pk_fma_f32 v[82:83], v[82:83], v[146:147], v[198:199]
	v_cvt_pk_f16_f32 v230, v80, v81
	v_cvt_pk_f16_f32 v231, v82, v83
	s_nop 1
	v_permlane16_swap_b32_e32 v228, v230
	v_permlane16_swap_b32_e32 v229, v231
	global_store_dwordx4 v177, v[228:231], s[80:81] offset:64
	v_add_u32_e32 v177, 0x8000, v177
	v_add_u32_e32 v178, 0x10000, v178
	global_load_dwordx4 v[184:187], v178, s[28:29]
	global_load_dwordx4 v[188:191], v178, s[28:29] offset:64
	global_load_dwordx4 v[192:195], v178, s[28:29] offset:128
	global_load_dwordx4 v[196:199], v178, s[28:29] offset:192
	s_waitcnt vmcnt(8)
	v_pk_mul_f32 v[238:239], v[238:239], s[84:85] op_sel_hi:[1,0]
	v_pk_mul_f32 v[240:241], v[240:241], s[84:85] op_sel_hi:[1,0]
	v_pk_fma_f32 v[84:85], v[84:85], v[132:133], v[238:239]
	v_pk_fma_f32 v[86:87], v[86:87], v[134:135], v[240:241]
	v_cvt_pk_f16_f32 v172, v84, v85
	v_cvt_pk_f16_f32 v173, v86, v87
	v_pk_mul_f32 v[242:243], v[242:243], s[84:85] op_sel_hi:[1,0]
	v_pk_mul_f32 v[244:245], v[244:245], s[84:85] op_sel_hi:[1,0]
	v_pk_fma_f32 v[88:89], v[88:89], v[136:137], v[242:243]
	v_pk_fma_f32 v[90:91], v[90:91], v[138:139], v[244:245]
	v_cvt_pk_f16_f32 v174, v88, v89
	v_cvt_pk_f16_f32 v175, v90, v91
	s_nop 1
	v_permlane16_swap_b32_e32 v172, v174
	v_permlane16_swap_b32_e32 v173, v175
	global_store_dwordx4 v177, v[172:175], s[80:81]
	s_waitcnt vmcnt(7)
	v_pk_mul_f32 v[246:247], v[246:247], s[84:85] op_sel_hi:[1,0]
	v_pk_mul_f32 v[248:249], v[248:249], s[84:85] op_sel_hi:[1,0]
	v_pk_fma_f32 v[92:93], v[92:93], v[140:141], v[246:247]
	v_pk_fma_f32 v[94:95], v[94:95], v[142:143], v[248:249]
	v_cvt_pk_f16_f32 v228, v92, v93
	v_cvt_pk_f16_f32 v229, v94, v95
	v_pk_mul_f32 v[250:251], v[250:251], s[84:85] op_sel_hi:[1,0]
	v_pk_mul_f32 v[252:253], v[252:253], s[84:85] op_sel_hi:[1,0]
	v_pk_fma_f32 v[96:97], v[96:97], v[144:145], v[250:251]
	v_pk_fma_f32 v[98:99], v[98:99], v[146:147], v[252:253]
	v_cvt_pk_f16_f32 v230, v96, v97
	v_cvt_pk_f16_f32 v231, v98, v99
	s_nop 1
	v_permlane16_swap_b32_e32 v228, v230
	v_permlane16_swap_b32_e32 v229, v231
	global_store_dwordx4 v177, v[228:231], s[80:81] offset:64
	v_add_u32_e32 v177, 0x8000, v177
	v_add_u32_e32 v178, 0x10000, v178
	global_load_dwordx4 v[238:241], v178, s[28:29]
	global_load_dwordx4 v[242:245], v178, s[28:29] offset:64
	global_load_dwordx4 v[246:249], v178, s[28:29] offset:128
	global_load_dwordx4 v[250:253], v178, s[28:29] offset:192
	s_waitcnt vmcnt(8)
	v_pk_mul_f32 v[184:185], v[184:185], s[84:85] op_sel_hi:[1,0]
	v_pk_mul_f32 v[186:187], v[186:187], s[84:85] op_sel_hi:[1,0]
	v_pk_fma_f32 v[100:101], v[100:101], v[132:133], v[184:185]
	v_pk_fma_f32 v[102:103], v[102:103], v[134:135], v[186:187]
	v_cvt_pk_f16_f32 v172, v100, v101
	v_cvt_pk_f16_f32 v173, v102, v103
	v_pk_mul_f32 v[188:189], v[188:189], s[84:85] op_sel_hi:[1,0]
	v_pk_mul_f32 v[190:191], v[190:191], s[84:85] op_sel_hi:[1,0]
	v_pk_fma_f32 v[104:105], v[104:105], v[136:137], v[188:189]
	v_pk_fma_f32 v[106:107], v[106:107], v[138:139], v[190:191]
	v_cvt_pk_f16_f32 v174, v104, v105
	v_cvt_pk_f16_f32 v175, v106, v107
	s_nop 1
	v_permlane16_swap_b32_e32 v172, v174
	v_permlane16_swap_b32_e32 v173, v175
	global_store_dwordx4 v177, v[172:175], s[80:81]
	s_waitcnt vmcnt(7)
	v_pk_mul_f32 v[192:193], v[192:193], s[84:85] op_sel_hi:[1,0]
	v_pk_mul_f32 v[194:195], v[194:195], s[84:85] op_sel_hi:[1,0]
	v_pk_fma_f32 v[108:109], v[108:109], v[140:141], v[192:193]
	v_pk_fma_f32 v[110:111], v[110:111], v[142:143], v[194:195]
	v_cvt_pk_f16_f32 v228, v108, v109
	v_cvt_pk_f16_f32 v229, v110, v111
	v_pk_mul_f32 v[196:197], v[196:197], s[84:85] op_sel_hi:[1,0]
	v_pk_mul_f32 v[198:199], v[198:199], s[84:85] op_sel_hi:[1,0]
	v_pk_fma_f32 v[112:113], v[112:113], v[144:145], v[196:197]
	v_pk_fma_f32 v[114:115], v[114:115], v[146:147], v[198:199]
	v_cvt_pk_f16_f32 v230, v112, v113
	v_cvt_pk_f16_f32 v231, v114, v115
	s_nop 1
	v_permlane16_swap_b32_e32 v228, v230
	v_permlane16_swap_b32_e32 v229, v231
	global_store_dwordx4 v177, v[228:231], s[80:81] offset:64
	v_add_u32_e32 v177, 0x8000, v177
	s_waitcnt vmcnt(4)
	v_pk_mul_f32 v[238:239], v[238:239], s[84:85] op_sel_hi:[1,0]
	v_pk_mul_f32 v[240:241], v[240:241], s[84:85] op_sel_hi:[1,0]
	v_pk_fma_f32 v[116:117], v[116:117], v[132:133], v[238:239]
	v_pk_fma_f32 v[118:119], v[118:119], v[134:135], v[240:241]
	v_cvt_pk_f16_f32 v172, v116, v117
	v_cvt_pk_f16_f32 v173, v118, v119
	v_pk_mul_f32 v[242:243], v[242:243], s[84:85] op_sel_hi:[1,0]
	v_pk_mul_f32 v[244:245], v[244:245], s[84:85] op_sel_hi:[1,0]
	v_pk_fma_f32 v[120:121], v[120:121], v[136:137], v[242:243]
	v_pk_fma_f32 v[122:123], v[122:123], v[138:139], v[244:245]
	v_cvt_pk_f16_f32 v174, v120, v121
	v_cvt_pk_f16_f32 v175, v122, v123
	s_nop 1
	v_permlane16_swap_b32_e32 v172, v174
	v_permlane16_swap_b32_e32 v173, v175
	global_store_dwordx4 v177, v[172:175], s[80:81]
	s_waitcnt vmcnt(3)
	v_pk_mul_f32 v[246:247], v[246:247], s[84:85] op_sel_hi:[1,0]
	v_pk_mul_f32 v[248:249], v[248:249], s[84:85] op_sel_hi:[1,0]
	v_pk_fma_f32 v[124:125], v[124:125], v[140:141], v[246:247]
	v_pk_fma_f32 v[126:127], v[126:127], v[142:143], v[248:249]
	v_cvt_pk_f16_f32 v228, v124, v125
	v_cvt_pk_f16_f32 v229, v126, v127
	v_pk_mul_f32 v[250:251], v[250:251], s[84:85] op_sel_hi:[1,0]
	v_pk_mul_f32 v[252:253], v[252:253], s[84:85] op_sel_hi:[1,0]
	v_pk_fma_f32 v[128:129], v[128:129], v[144:145], v[250:251]
	v_pk_fma_f32 v[130:131], v[130:131], v[146:147], v[252:253]
	v_cvt_pk_f16_f32 v230, v128, v129
	v_cvt_pk_f16_f32 v231, v130, v131
	s_nop 1
	v_permlane16_swap_b32_e32 v228, v230
	v_permlane16_swap_b32_e32 v229, v231
	global_store_dwordx4 v177, v[228:231], s[80:81] offset:64
	s_nop 1
	s_branch .LBB0_1289
